# boff_plus_ntK: wr1 offset barrier moved after unit header in 7 GEMM phases; nt hint on MLP-up epilogue stores
# speedup vs baseline: 1.0079x; 1.0079x over previous
; #define PG8_WAIT_V(n) asm volatile("s_waitcnt vmcnt(" #n ")" ::: "memory")
; template <class Epi, class Sched, bool ALIGN_EPI = false, bool SP2 = false>
; __device__ __forceinline__ void gemm_phase(PG8_LAS unsigned char* lds, const Gemm g, const Sched& S, const Epi& E) {
;     int tid_ = threadIdx.x; asm volatile("" : "+v"(tid_));
;     const int tid = tid_, wid = __builtin_amdgcn_readfirstlane(tid >> 6), lane = tid & 63, wr = wid >> 2, wc = wid & 3, fr = lane & 15, fq = lane >> 4;
;     const int K = g.K, nt = K / BK, LD = g.ld ? g.ld : g.K;
;     unsigned voffA[2], voffB[2];
; #pragma unroll
;     for (int i = 0; i < 2; ++i) { int R, C; stage_rc(tid * 16 + i * 8192, R, C); const int Rb = Epi::PERM ? ((R & ~31) + perm32(R & 31)) : R;
;         voffA[i] = (unsigned)(R * LD + C) * 2u; voffB[i] = (unsigned)(Rb * LD + C) * 2u; }
;     const size_t kstep = (size_t)(BK * 2);
;     const size_t hstep = (size_t)HALF * LD * 2;
;     const size_t tstep = 2 * hstep;
;     const unsigned ldsw = (unsigned)wid * 1024u;
;     const int aoff = lds_byte(wr * 64 + fr, fq * 8), boff = lds_byte(wc * 32 + fr, fq * 8);
;     ...
;     Unit cur, nxt; int ui = 0;
;     if (!S.next(0, cur)) return;
;     f32x4 acc[2][2][4][2];
; #pragma unroll
;     for (int a = 0; a < 2; ++a)
; #pragma unroll
;         for (int b = 0; b < 2; ++b)
; #pragma unroll
;             for (int m = 0; m < 4; ++m)
; #pragma unroll
;                 for (int n = 0; n < 2; ++n) acc[a][b][m][n] = (f32x4){0.f, 0.f, 0.f, 0.f};
;     bf16x8 At[4][2], B0[2][2], B1[2][2];
;     const char* cA = (const char*)g.A + (size_t)cur.pm * tstep; const char* cB = (const char*)g.Bt + (size_t)cur.pn * tstep;
;     S.a_ready(cur);
;     if constexpr (SP2) {
;         PG8_STAGE(PG8_SB(0, 0), cB, voffB); PG8_STAGE(PG8_SB(0, 1), cB + hstep, voffB); PG8_STAGE(PG8_SA(0, 0), cA, voffA); PG8_STAGE(PG8_SA(0, 1), cA + hstep, voffA);
;         if (wr == 1) PG8_BAR;
;         PG8_WAIT_V(2); PG8_BAR;
;         PG8_STAGE(PG8_SB(1, 0), cB + kstep, voffB); PG8_STAGE(PG8_SA(1, 0), cA + kstep, voffA); PG8_STAGE(PG8_SB(1, 1), cB + hstep + kstep, voffB);
;         PG8_WAIT_V(6); PG8_BAR;
;     } else {
;         PG8_STAGE(PG8_SB(0, 0), cB, voffB); PG8_STAGE(PG8_SA(0, 0), cA, voffA); PG8_STAGE(PG8_SB(0, 1), cB + hstep, voffB); PG8_STAGE(PG8_SA(0, 1), cA + hstep, voffA);
;         if (wr == 1) PG8_BAR;
;         PG8_WAIT_V(4); PG8_BAR;
.LBB0_234:
	s_or_b64 exec, exec, s[36:37]
	s_mov_b64 s[4:5], s[72:73]
	v_mov_b32_e32 v10, v242
	s_waitcnt lgkmcnt(0)
	s_barrier
	s_and_b64 vcc, exec, s[58:59]
	v_readfirstlane_b32 s6, v10
	s_cbranch_vccz .LBB0_262
	v_lshlrev_b32_e32 v0, 4, v10
	v_add_u32_e32 v2, 0x2000, v0
	v_ashrrev_i32_e32 v3, 31, v2
	v_lshrrev_b32_e32 v3, 22, v3
	v_add_u32_e32 v3, v2, v3
	v_ashrrev_i32_e32 v11, 10, v3
	v_mul_i32_i24_e32 v3, 0x400, v11
	v_sub_u32_e32 v2, v2, v3
	v_lshrrev_b32_e32 v3, 4, v2
	v_bitop3_b32 v2, v3, v2, 32 bitop3:0x6c
	v_ashrrev_i32_e32 v3, 31, v2
	v_lshrrev_b32_e32 v3, 26, v3
	v_add_u32_e32 v3, v2, v3
	v_lshlrev_b32_e32 v4, 3, v11
	v_ashrrev_i32_e32 v12, 6, v3
	v_and_b32_e32 v4, -16, v4
	v_add_u32_e32 v4, v12, v4
	v_and_b32_e32 v5, 3, v12
	s_mov_b32 s0, 0x1fffe0
	v_lshrrev_b32_e32 v6, 2, v4
	v_lshlrev_b32_e32 v7, 1, v4
	v_and_b32_e32 v3, 0xc0, v3
	v_and_or_b32 v5, v4, s0, v5
	v_and_b32_e32 v6, 4, v6
	v_and_b32_e32 v7, 24, v7
	v_sub_u32_e32 v2, v2, v3
	v_or3_b32 v5, v5, v6, v7
	v_lshlrev_b32_e32 v6, 5, v11
	v_ashrrev_i16_sdwa v2, v241, sext(v2) dst_sel:DWORD dst_unused:UNUSED_PAD src0_sel:DWORD src1_sel:BYTE_0
	v_and_b32_e32 v6, 32, v6
	v_bfe_i32 v13, v2, 0, 16
	v_add_lshl_u32 v2, v6, v13, 1
	v_lshl_add_u32 v130, v5, 11, v2
	v_lshl_add_u32 v132, v4, 11, v2
	v_bfe_i32 v2, v10, 27, 1
	v_lshrrev_b32_e32 v2, 22, v2
	v_add_u32_e32 v2, v0, v2
	v_and_b32_e32 v2, 0xfffffc00, v2
	v_sub_u32_e32 v0, v0, v2
	v_lshrrev_b32_e32 v2, 4, v0
	v_ashrrev_i32_e32 v3, 31, v10
	v_bitop3_b32 v0, v2, v0, 32 bitop3:0x6c
	v_lshrrev_b32_e32 v3, 26, v3
	v_ashrrev_i32_e32 v2, 31, v0
	v_add_u32_e32 v3, v10, v3
	v_lshrrev_b32_e32 v2, 26, v2
	v_ashrrev_i32_e32 v15, 6, v3
	v_add_u32_e32 v2, v0, v2
	v_lshlrev_b32_e32 v3, 3, v15
	s_add_u32 s22, s4, 0x5400000
	v_ashrrev_i32_e32 v14, 6, v2
	v_and_b32_e32 v3, -16, v3
	s_addc_u32 s23, s5, 0
	v_add_u32_e32 v3, v14, v3
	s_add_u32 s24, s4, 0x100000
	v_and_b32_e32 v4, 3, v14
	v_lshrrev_b32_e32 v5, 2, v3
	v_lshlrev_b32_e32 v6, 1, v3
	v_and_b32_e32 v2, 0xc0, v2
	s_addc_u32 s25, s5, 0
	s_ashr_i32 s7, s6, 6
	v_and_or_b32 v4, v3, s0, v4
	v_and_b32_e32 v5, 4, v5
	v_and_b32_e32 v6, 24, v6
	v_sub_u32_e32 v0, v0, v2
	s_ashr_i32 s8, s6, 8
	s_lshl_b32 s26, s7, 10
	v_or3_b32 v4, v4, v5, v6
	v_lshlrev_b32_e32 v5, 5, v15
	v_ashrrev_i16_sdwa v0, v241, sext(v0) dst_sel:DWORD dst_unused:UNUSED_PAD src0_sel:DWORD src1_sel:BYTE_0
	v_readlane_b32 s0, v255, 0
	v_and_b32_e32 v5, 32, v5
	v_bfe_i32 v16, v0, 0, 16
	v_readlane_b32 s1, v255, 1
	s_add_u32 s16, s24, s0
	v_add_lshl_u32 v0, v5, v16, 1
	s_addc_u32 s17, s25, s1
	s_add_i32 s27, s26, 0
	v_lshl_add_u32 v134, v4, 11, v0
	s_add_i32 m0, s27, 0x10000
	v_lshl_add_u32 v136, v3, 11, v0
	global_load_lds_dwordx4 v134, s[16:17]
	s_add_i32 m0, s27, 0x12000
	s_add_u32 s0, s16, 0x40000
	global_load_lds_dwordx4 v130, s[16:17]
	s_addc_u32 s1, s17, 0
	s_add_i32 m0, s27, 0x14000
	v_mov_b32_e32 v135, v1
	global_load_lds_dwordx4 v134, s[0:1]
	s_add_i32 m0, s27, 0x16000
	v_mov_b32_e32 v131, v1
	global_load_lds_dwordx4 v130, s[0:1]
	v_readlane_b32 s0, v254, 62
	v_readlane_b32 s1, v254, 63
	s_add_u32 s18, s22, s0
	s_addc_u32 s19, s23, s1
	s_add_i32 s28, s27, 0x2000
	s_mov_b32 m0, s27
	s_add_u32 s0, s18, 0x40000
	global_load_lds_dwordx4 v136, s[18:19]
	s_mov_b32 m0, s28
	s_addc_u32 s1, s19, 0
	s_add_i32 s29, s27, 0x4000
	global_load_lds_dwordx4 v132, s[18:19]
	s_mov_b32 m0, s29
	s_add_i32 s30, s27, 0x6000
	global_load_lds_dwordx4 v136, s[0:1]
	s_mov_b32 m0, s30
	v_mov_b32_e32 v137, v1
	global_load_lds_dwordx4 v132, s[0:1]
	v_mov_b32_e32 v133, v1
	s_cmp_eq_u32 s8, 1
	s_mov_b32 s51, s66
	v_lshl_add_u64 v[8:9], s[16:17], 0, v[134:135]
	v_lshl_add_u64 v[6:7], s[16:17], 0, v[130:131]
	v_lshl_add_u64 v[2:3], s[18:19], 0, v[136:137]
	s_cselect_b64 s[0:1], -1, 0
	s_cmp_lg_u32 s8, 1
	v_lshl_add_u64 v[4:5], s[18:19], 0, v[132:133]
	s_cbranch_scc1 .LBB0_237
.LBB0_237:
	s_add_u32 s31, s4, 0xd400000
	s_addc_u32 s34, s5, 0
	s_add_u32 s35, s4, 0x23400000
	s_addc_u32 s36, s5, 0
	s_lshl_b32 s7, s7, 5
	s_and_b32 s7, s7, 0x60
	s_add_i32 m0, s27, 0x18000
	v_lshl_add_u64 v[8:9], v[8:9], 0, s[94:95]
	s_lshl_b32 s37, s8, 6
	s_lshl_b32 s10, s8, 13
	s_lshl_b32 s11, s7, 7
	s_waitcnt vmcnt(2)
	s_barrier
	global_load_lds_dwordx4 v[8:9], off
	v_lshl_add_u64 v[6:7], v[6:7], 0, s[94:95]
	s_add_i32 m0, s27, 0x1a000
	s_add_i32 s38, s27, 0x8000
	s_add_i32 s39, s27, 0xa000
	global_load_lds_dwordx4 v[6:7], off
	v_lshl_add_u64 v[2:3], v[2:3], 0, s[94:95]
	s_mov_b32 m0, s38
	s_add_u32 s8, s16, 0x40080
	global_load_lds_dwordx4 v[2:3], off
	v_lshl_add_u64 v[2:3], v[4:5], 0, s[94:95]
	s_mov_b32 m0, s39
	s_addc_u32 s9, s17, 0
	global_load_lds_dwordx4 v[2:3], off
	s_add_i32 m0, s27, 0x1c000
	v_lshl_add_u64 v[2:3], s[8:9], 0, v[134:135]
	global_load_lds_dwordx4 v[2:3], off
	v_lshl_add_u64 v[2:3], s[8:9], 0, v[130:131]
	s_add_i32 m0, s27, 0x1e000
	v_and_b32_e32 v0, 15, v10
	global_load_lds_dwordx4 v[2:3], off
	v_lshrrev_b32_e32 v2, 1, v10
	v_and_b32_e32 v2, 24, v2
	v_lshlrev_b32_e32 v3, 1, v2
	v_lshlrev_b32_e32 v4, 2, v10
	v_or_b32_e32 v139, s37, v0
	v_lshl_or_b32 v3, v0, 6, v3
	v_and_b32_e32 v4, 32, v4
	v_or_b32_e32 v138, s7, v2
	v_mov_b32_e32 v2, 0x7ffa0000
	v_lshlrev_b32_e32 v0, 5, v0
	v_bitop3_b32 v5, v3, s10, v4 bitop3:0xde
	v_bitop3_b32 v147, v3, s11, v4 bitop3:0xde
	v_lshl_or_b32 v155, v138, 8, v2
	v_lshl_add_u64 v[2:3], s[4:5], 0, v[0:1]
	v_and_b32_e32 v0, 16, v10
	v_lshl_add_u64 v[2:3], v[2:3], 0, v[0:1]
	v_lshlrev_b32_e32 v0, 14, v15
	s_mov_b64 s[4:5], 0x19400000
	v_and_b32_e32 v0, 0xffff8000, v0
	v_lshl_add_u64 v[140:141], v[2:3], 0, s[4:5]
	v_lshl_add_u32 v0, v14, 11, v0
	v_and_b32_e32 v2, 1, v15
	v_lshl_or_b32 v0, v2, 6, v0
	v_lshl_add_u32 v142, v16, 1, v0
	v_lshlrev_b32_e32 v0, 14, v11
	v_and_b32_e32 v0, 0xffff8000, v0
	s_waitcnt vmcnt(6)
	v_lshl_add_u32 v0, v12, 11, v0
	v_and_b32_e32 v2, 1, v11
	s_cmpk_lt_u32 s6, 0x100
	v_lshl_or_b32 v0, v2, 6, v0
	v_readlane_b32 s4, v254, 60
	s_cselect_b64 s[6:7], -1, 0
	v_or_b32_e32 v148, 16, v139
	v_or_b32_e32 v149, 32, v139
	v_or_b32_e32 v150, 48, v139
	v_add_u32_e32 v151, 0x80, v139
	v_add_u32_e32 v152, 0x90, v139
	v_add_u32_e32 v153, 0xa0, v139
	v_add_u32_e32 v154, 0xb0, v139
	s_or_b32 s55, s37, 16
	s_or_b32 s97, s37, 32
	s_or_b32 s85, s37, 48
	v_mov_b32_e32 v143, v1
	v_lshl_add_u32 v144, v13, 1, v0
	v_mov_b32_e32 v145, v1
	s_mov_b32 s66, 0
	v_add_u32_e32 v156, 0, v5
	v_readlane_b32 s56, v254, 59
	s_mov_b32 s33, s4
	s_barrier
	v_readlane_b32 s5, v254, 61
	s_branch .LBB0_240

;     __device__ __forceinline__ bool next(int i, Unit& u) const { const int L = i * G + c; if (L >= 512) return false; u.pm = L; u.pn = L >> 4; return true; }
; #define PG8_STAGE(bufoff, gbase, voff) do { _Pragma("unroll") for (int _i = 0; _i < 2; ++_i) \
;         __builtin_amdgcn_global_load_lds((const unsigned*)((const char*)(gbase) + (voff)[_i]), (PG8_LAS unsigned*)(lds + (bufoff) + ldsw + _i * 8192), 16, 0, 0); } while (0)
; #define PG8_LDA(dst, b, h) do { _Pragma("unroll") for (int m = 0; m < 4; ++m) _Pragma("unroll") for (int k = 0; k < 2; ++k) dst[m][k] = *(const PG8_LAS bf16x8*)(lds + PG8_SA(b, h) + aoff + m * 2048 + k * 1024); } while (0)
; #define PG8_LDB(dst, b, h) do { _Pragma("unroll") for (int n = 0; n < 2; ++n) _Pragma("unroll") for (int k = 0; k < 2; ++k) dst[n][k] = *(const PG8_LAS bf16x8*)(lds + PG8_SB(b, h) + boff + n * 2048 + k * 1024); } while (0)
; template <class Epi, class Sched, bool ALIGN_EPI = false, bool SP2 = false>
; __device__ __forceinline__ void gemm_phase(PG8_LAS unsigned char* lds, const Gemm g, const Sched& S, const Epi& E) {
;     ...
;         const bool has_next = S.next(ui + 1, nxt);
;         const char* nA = has_next ? (const char*)g.A + (size_t)nxt.pm * tstep : cA; const char* nB = has_next ? (const char*)g.Bt + (size_t)nxt.pn * tstep : cB;
;         for (int t = 0; t < nt; t += 2) {
;             const bool last = (t == nt - 2);
;             const char* a1 = cA + (size_t)(t + 1) * kstep;
;             const char* a2 = last ? nA : cA + (size_t)(t + 2) * kstep; const char* b2 = last ? nB : cB + (size_t)(t + 2) * kstep;
;             const char* a3 = a2 + kstep; const char* b3 = b2 + kstep;
;             if (last && has_next) S.a_ready(nxt);
;             if constexpr (SP2) {
;             PG8_LDB(B0, 0, 0); PG8_LDB(B1, 0, 1); PG8_SCHED; PG8_LDA(At, 0, 0); PG8_STAGE(PG8_SA(1, 1), a1 + hstep, voffA);
;             PG8_WAIT_V(8); PG8_WAIT_L(0); PG8_BAR; PG8_MMA(0, 0, At, B0); PG8_MMA(0, 1, At, B1); PG8_BAR; PG8_SCHED;
;     ...
;         for (int a = 0; a < 2; ++a)
; #pragma unroll
;             for (int b = 0; b < 2; ++b)
; #pragma unroll
;                 for (int m = 0; m < 4; ++m)
; #pragma unroll
;                     for (int n = 0; n < 2; ++n) acc[a][b][m][n] = (f32x4){0.f, 0.f, 0.f, 0.f};
;         cur = nxt; cA = nA; cB = nB; ++ui;
;         if constexpr (ALIGN_EPI) { if (wr == 1) PG8_BAR; }
.LBB0_246:
	s_ashr_i32 s11, s10, 31
	s_lshl_b64 s[12:13], s[10:11], 19
	s_add_u32 s12, s22, s12
	s_addc_u32 s13, s23, s13
	s_and_b64 s[14:15], s[4:5], exec
	s_cselect_b32 s11, s13, s19
	s_cselect_b32 s46, s12, s18
	s_ashr_i32 s9, s8, 31
	s_lshl_b64 s[14:15], s[8:9], 19
	s_add_u32 s14, s24, s14
	s_addc_u32 s15, s25, s15
	s_and_b64 s[20:21], s[4:5], exec
	s_cselect_b32 s9, s15, s17
	s_cselect_b32 s57, s14, s16
	s_add_u32 s18, s18, 0x40080
	s_addc_u32 s19, s19, 0
	s_add_u32 vcc_lo, s16, 0x100
	v_mov_b32_e32 v2, 0
	s_addc_u32 vcc_hi, s17, 0
	s_mov_b32 s50, -2
	v_mov_b32_e32 v3, v2
	v_mov_b32_e32 v4, v2
	v_mov_b32_e32 v5, v2
	v_mov_b32_e32 v6, v2
	v_mov_b32_e32 v7, v2
	v_mov_b32_e32 v8, v2
	v_mov_b32_e32 v9, v2
	v_mov_b32_e32 v10, v2
	v_mov_b32_e32 v11, v2
	v_mov_b32_e32 v12, v2
	v_mov_b32_e32 v13, v2
	v_mov_b32_e32 v18, v2
	v_mov_b32_e32 v19, v2
	v_mov_b32_e32 v20, v2
	v_mov_b32_e32 v21, v2
	v_mov_b32_e32 v26, v2
	v_mov_b32_e32 v27, v2
	v_mov_b32_e32 v28, v2
	v_mov_b32_e32 v29, v2
	v_mov_b32_e32 v34, v2
	v_mov_b32_e32 v35, v2
	v_mov_b32_e32 v36, v2
	v_mov_b32_e32 v37, v2
	v_mov_b32_e32 v42, v2
	v_mov_b32_e32 v43, v2
	v_mov_b32_e32 v44, v2
	v_mov_b32_e32 v45, v2
	v_mov_b32_e32 v50, v2
	v_mov_b32_e32 v51, v2
	v_mov_b32_e32 v52, v2
	v_mov_b32_e32 v53, v2
	v_mov_b32_e32 v14, v2
	v_mov_b32_e32 v15, v2
	v_mov_b32_e32 v16, v2
	v_mov_b32_e32 v17, v2
	v_mov_b32_e32 v22, v2
	v_mov_b32_e32 v23, v2
	v_mov_b32_e32 v24, v2
	v_mov_b32_e32 v25, v2
	v_mov_b32_e32 v30, v2
	v_mov_b32_e32 v31, v2
	v_mov_b32_e32 v32, v2
	v_mov_b32_e32 v33, v2
	v_mov_b32_e32 v38, v2
	v_mov_b32_e32 v39, v2
	v_mov_b32_e32 v40, v2
	v_mov_b32_e32 v41, v2
	v_mov_b32_e32 v46, v2
	v_mov_b32_e32 v47, v2
	v_mov_b32_e32 v48, v2
	v_mov_b32_e32 v49, v2
	v_mov_b32_e32 v54, v2
	v_mov_b32_e32 v55, v2
	v_mov_b32_e32 v56, v2
	v_mov_b32_e32 v57, v2
	v_mov_b32_e32 v58, v2
	v_mov_b32_e32 v59, v2
	v_mov_b32_e32 v60, v2
	v_mov_b32_e32 v61, v2
	v_mov_b32_e32 v62, v2
	v_mov_b32_e32 v63, v2
	v_mov_b32_e32 v64, v2
	v_mov_b32_e32 v65, v2
	v_mov_b32_e32 v66, v2
	v_mov_b32_e32 v67, v2
	v_mov_b32_e32 v68, v2
	v_mov_b32_e32 v69, v2
	v_mov_b32_e32 v70, v2
	v_mov_b32_e32 v71, v2
	v_mov_b32_e32 v72, v2
	v_mov_b32_e32 v73, v2
	v_mov_b32_e32 v74, v2
	v_mov_b32_e32 v75, v2
	v_mov_b32_e32 v76, v2
	v_mov_b32_e32 v77, v2
	v_mov_b32_e32 v82, v2
	v_mov_b32_e32 v83, v2
	v_mov_b32_e32 v84, v2
	v_mov_b32_e32 v85, v2
	v_mov_b32_e32 v90, v2
	v_mov_b32_e32 v91, v2
	v_mov_b32_e32 v92, v2
	v_mov_b32_e32 v93, v2
	v_mov_b32_e32 v98, v2
	v_mov_b32_e32 v99, v2
	v_mov_b32_e32 v100, v2
	v_mov_b32_e32 v101, v2
	v_mov_b32_e32 v106, v2
	v_mov_b32_e32 v107, v2
	v_mov_b32_e32 v108, v2
	v_mov_b32_e32 v109, v2
	v_mov_b32_e32 v114, v2
	v_mov_b32_e32 v115, v2
	v_mov_b32_e32 v116, v2
	v_mov_b32_e32 v117, v2
	v_mov_b32_e32 v78, v2
	v_mov_b32_e32 v79, v2
	v_mov_b32_e32 v80, v2
	v_mov_b32_e32 v81, v2
	v_mov_b32_e32 v86, v2
	v_mov_b32_e32 v87, v2
	v_mov_b32_e32 v88, v2
	v_mov_b32_e32 v89, v2
	v_mov_b32_e32 v94, v2
	v_mov_b32_e32 v95, v2
	v_mov_b32_e32 v96, v2
	v_mov_b32_e32 v97, v2
	v_mov_b32_e32 v102, v2
	v_mov_b32_e32 v103, v2
	v_mov_b32_e32 v104, v2
	v_mov_b32_e32 v105, v2
	v_mov_b32_e32 v110, v2
	v_mov_b32_e32 v111, v2
	v_mov_b32_e32 v112, v2
	v_mov_b32_e32 v113, v2
	v_mov_b32_e32 v118, v2
	v_mov_b32_e32 v119, v2
	v_mov_b32_e32 v120, v2
	v_mov_b32_e32 v121, v2
	v_mov_b32_e32 v122, v2
	v_mov_b32_e32 v123, v2
	v_mov_b32_e32 v124, v2
	v_mov_b32_e32 v125, v2
	v_mov_b32_e32 v126, v2
	v_mov_b32_e32 v127, v2
	v_mov_b32_e32 v128, v2
	v_mov_b32_e32 v129, v2
	s_cmp_eq_u64 s[0:1], 0
	s_cbranch_scc1 .Lboff_skip_B
	s_barrier
.Lboff_skip_B:
.LBB0_247:
	s_add_u32 s16, s18, 0xfffc0080
	s_addc_u32 s17, s19, -1
	s_add_i32 s52, 0, 0x10000
	s_cmp_eq_u32 s50, 12
	s_cselect_b32 s21, s11, s17
	s_cselect_b32 s20, s46, s16
	v_add_u32_e32 v0, s52, v147
	s_cselect_b32 s17, s9, vcc_hi
	s_cselect_b32 s16, s57, vcc_lo
	s_add_i32 s63, 0, 0x14000
	ds_read_b128 v[158:161], v0
	ds_read_b128 v[162:165], v0 offset:1024
	ds_read_b128 v[166:169], v0 offset:2048
	ds_read_b128 v[170:173], v0 offset:3072
	v_add_u32_e32 v0, s63, v147
	ds_read_b128 v[174:177], v0
	ds_read_b128 v[178:181], v0 offset:1024
	ds_read_b128 v[182:185], v0 offset:2048
	ds_read_b128 v[186:189], v0 offset:3072
	v_lshl_add_u64 v[210:211], s[18:19], 0, v[142:143]
	s_add_i32 m0, s27, 0xc000
	ds_read_b128 v[190:193], v156
	ds_read_b128 v[194:197], v156 offset:1024
	ds_read_b128 v[198:201], v156 offset:2048
	ds_read_b128 v[202:205], v156 offset:3072
	ds_read_b128 v[206:209], v156 offset:4096
	ds_read_b128 v[220:223], v156 offset:5120
	ds_read_b128 v[224:227], v156 offset:6144
	ds_read_b128 v[228:231], v156 offset:7168
	global_load_lds_dwordx4 v[210:211], off
	v_lshl_add_u64 v[210:211], s[18:19], 0, v[144:145]
	s_add_i32 m0, s27, 0xe000
	s_nop 0
	global_load_lds_dwordx4 v[210:211], off
	s_waitcnt vmcnt(8)
	s_waitcnt lgkmcnt(0)
	s_barrier
; #define PG8_STAGE(bufoff, gbase, voff) do { _Pragma("unroll") for (int _i = 0; _i < 2; ++_i) \
;         __builtin_amdgcn_global_load_lds((const unsigned*)((const char*)(gbase) + (voff)[_i]), (PG8_LAS unsigned*)(lds + (bufoff) + ldsw + _i * 8192), 16, 0, 0); } while (0)
; #define PG8_LDA(dst, b, h) do { _Pragma("unroll") for (int m = 0; m < 4; ++m) _Pragma("unroll") for (int k = 0; k < 2; ++k) dst[m][k] = *(const PG8_LAS bf16x8*)(lds + PG8_SA(b, h) + aoff + m * 2048 + k * 1024); } while (0)
; #define PG8_MMA(ai, bj, At, Bt) do { __builtin_amdgcn_s_setprio(1); _Pragma("unroll") for (int m = 0; m < 4; ++m) _Pragma("unroll") for (int n = 0; n < 2; ++n) _Pragma("unroll") for (int k = 0; k < 2; ++k) \
;         acc[ai][bj][m][n] = __builtin_amdgcn_mfma_f32_16x16x32_bf16(Bt[n][k], At[m][k], acc[ai][bj][m][n], 0, 0, 0); __builtin_amdgcn_s_setprio(0); } while (0)
; #define PG8_WAIT_V(n) asm volatile("s_waitcnt vmcnt(" #n ")" ::: "memory")
; #define PG8_WAIT_L(n) asm volatile("s_waitcnt lgkmcnt(" #n ")" ::: "memory")
; #define PG8_BAR __builtin_amdgcn_s_barrier()
; #define PG8_SCHED __builtin_amdgcn_sched_barrier(0)
; template <class Epi, class Sched, bool ALIGN_EPI = false, bool SP2 = false>
; __device__ __forceinline__ void gemm_phase(PG8_LAS unsigned char* lds, const Gemm g, const Sched& S, const Epi& E) {
;     ...
;             PG8_WAIT_V(8); PG8_WAIT_L(0); PG8_BAR; PG8_MMA(0, 0, At, B0); PG8_MMA(0, 1, At, B1); PG8_BAR; PG8_SCHED;
;             PG8_LDA(At, 0, 1); PG8_STAGE(PG8_SB(0, 0), b2, voffB); PG8_STAGE(PG8_SB(0, 1), b2 + hstep, voffB); PG8_STAGE(PG8_SA(0, 0), a2, voffA);
;             PG8_WAIT_V(8); PG8_WAIT_L(0); PG8_BAR; PG8_MMA(1, 0, At, B0); PG8_MMA(1, 1, At, B1); PG8_BAR; PG8_SCHED;
	s_setprio 1
	s_waitcnt lgkmcnt(0)
	v_mfma_f32_16x16x32_bf16 v[126:129], v[158:161], v[190:193], v[126:129]
	v_mfma_f32_16x16x32_bf16 v[122:125], v[166:169], v[190:193], v[122:125]
	v_mfma_f32_16x16x32_bf16 v[118:121], v[158:161], v[198:201], v[118:121]
	v_mfma_f32_16x16x32_bf16 v[110:113], v[166:169], v[198:201], v[110:113]
	v_mfma_f32_16x16x32_bf16 v[102:105], v[158:161], v[206:209], v[102:105]
	v_mfma_f32_16x16x32_bf16 v[94:97], v[166:169], v[206:209], v[94:97]
	v_mfma_f32_16x16x32_bf16 v[86:89], v[158:161], v[224:227], v[86:89]
	v_mfma_f32_16x16x32_bf16 v[78:81], v[166:169], v[224:227], v[78:81]
	v_mfma_f32_16x16x32_bf16 v[126:129], v[162:165], v[194:197], v[126:129]
	v_mfma_f32_16x16x32_bf16 v[122:125], v[170:173], v[194:197], v[122:125]
	v_mfma_f32_16x16x32_bf16 v[118:121], v[162:165], v[202:205], v[118:121]
	v_mfma_f32_16x16x32_bf16 v[110:113], v[170:173], v[202:205], v[110:113]
	v_mfma_f32_16x16x32_bf16 v[102:105], v[162:165], v[220:223], v[102:105]
	v_mfma_f32_16x16x32_bf16 v[94:97], v[170:173], v[220:223], v[94:97]
	v_mfma_f32_16x16x32_bf16 v[86:89], v[162:165], v[228:231], v[86:89]
	v_mfma_f32_16x16x32_bf16 v[78:81], v[170:173], v[228:231], v[78:81]
	s_setprio 0
	s_setprio 1
	v_mfma_f32_16x16x32_bf16 v[114:117], v[174:177], v[190:193], v[114:117]
	v_mfma_f32_16x16x32_bf16 v[106:109], v[182:185], v[190:193], v[106:109]
	v_mfma_f32_16x16x32_bf16 v[98:101], v[174:177], v[198:201], v[98:101]
	v_mfma_f32_16x16x32_bf16 v[90:93], v[182:185], v[198:201], v[90:93]
	v_mfma_f32_16x16x32_bf16 v[82:85], v[174:177], v[206:209], v[82:85]
	v_mfma_f32_16x16x32_bf16 v[74:77], v[182:185], v[206:209], v[74:77]
	v_mfma_f32_16x16x32_bf16 v[70:73], v[174:177], v[224:227], v[70:73]
	v_mfma_f32_16x16x32_bf16 v[66:69], v[182:185], v[224:227], v[66:69]
	v_mfma_f32_16x16x32_bf16 v[114:117], v[178:181], v[194:197], v[114:117]
	v_mfma_f32_16x16x32_bf16 v[106:109], v[186:189], v[194:197], v[106:109]
	v_mfma_f32_16x16x32_bf16 v[98:101], v[178:181], v[202:205], v[98:101]
	v_mfma_f32_16x16x32_bf16 v[90:93], v[186:189], v[202:205], v[90:93]
	v_mfma_f32_16x16x32_bf16 v[82:85], v[178:181], v[220:223], v[82:85]
	v_mfma_f32_16x16x32_bf16 v[74:77], v[186:189], v[220:223], v[74:77]
	v_mfma_f32_16x16x32_bf16 v[70:73], v[178:181], v[228:231], v[70:73]
	v_mfma_f32_16x16x32_bf16 v[66:69], v[186:189], v[228:231], v[66:69]
	s_setprio 0
	s_barrier
	s_add_i32 s52, s52, s26
	v_lshl_add_u64 v[210:211], s[16:17], 0, v[134:135]
	s_mov_b32 m0, s52
	ds_read_b128 v[190:193], v156 offset:16384
	ds_read_b128 v[194:197], v156 offset:17408
	ds_read_b128 v[198:201], v156 offset:18432
	ds_read_b128 v[202:205], v156 offset:19456
	ds_read_b128 v[206:209], v156 offset:20480
	ds_read_b128 v[220:223], v156 offset:21504
	ds_read_b128 v[224:227], v156 offset:22528
	ds_read_b128 v[228:231], v156 offset:23552
	global_load_lds_dwordx4 v[210:211], off
	s_add_i32 m0, s52, 0x2000
	s_add_u32 s52, s16, 0x40000
	v_lshl_add_u64 v[212:213], s[16:17], 0, v[130:131]
	s_addc_u32 s53, s17, 0
	s_add_i32 s63, s63, s26
	global_load_lds_dwordx4 v[212:213], off
	v_lshl_add_u64 v[214:215], s[52:53], 0, v[134:135]
	s_mov_b32 m0, s63
	v_lshl_add_u64 v[216:217], s[20:21], 0, v[132:133]
	global_load_lds_dwordx4 v[214:215], off
	v_lshl_add_u64 v[214:215], s[52:53], 0, v[130:131]
	s_add_i32 m0, s63, 0x2000
	s_nop 0
	global_load_lds_dwordx4 v[214:215], off
	v_lshl_add_u64 v[214:215], s[20:21], 0, v[136:137]
	s_mov_b32 m0, s27
	s_nop 0
	global_load_lds_dwordx4 v[214:215], off
	s_mov_b32 m0, s28
	s_nop 0
	global_load_lds_dwordx4 v[216:217], off
	s_waitcnt vmcnt(8)
	s_waitcnt lgkmcnt(0)
	s_barrier
	s_setprio 1
	s_waitcnt lgkmcnt(0)
	v_mfma_f32_16x16x32_bf16 v[62:65], v[158:161], v[190:193], v[62:65]
	v_mfma_f32_16x16x32_bf16 v[58:61], v[166:169], v[190:193], v[58:61]
	v_mfma_f32_16x16x32_bf16 v[54:57], v[158:161], v[198:201], v[54:57]
	v_mfma_f32_16x16x32_bf16 v[46:49], v[166:169], v[198:201], v[46:49]
	v_mfma_f32_16x16x32_bf16 v[38:41], v[158:161], v[206:209], v[38:41]
	v_mfma_f32_16x16x32_bf16 v[30:33], v[166:169], v[206:209], v[30:33]
	v_mfma_f32_16x16x32_bf16 v[22:25], v[158:161], v[224:227], v[22:25]
	v_mfma_f32_16x16x32_bf16 v[14:17], v[166:169], v[224:227], v[14:17]
	v_mfma_f32_16x16x32_bf16 v[62:65], v[162:165], v[194:197], v[62:65]
	v_mfma_f32_16x16x32_bf16 v[58:61], v[170:173], v[194:197], v[58:61]
	v_mfma_f32_16x16x32_bf16 v[54:57], v[162:165], v[202:205], v[54:57]
	v_mfma_f32_16x16x32_bf16 v[46:49], v[170:173], v[202:205], v[46:49]
	v_mfma_f32_16x16x32_bf16 v[38:41], v[162:165], v[220:223], v[38:41]
	v_mfma_f32_16x16x32_bf16 v[30:33], v[170:173], v[220:223], v[30:33]
	v_mfma_f32_16x16x32_bf16 v[22:25], v[162:165], v[228:231], v[22:25]
	v_mfma_f32_16x16x32_bf16 v[14:17], v[170:173], v[228:231], v[14:17]
	s_setprio 0
	s_setprio 1
	v_mfma_f32_16x16x32_bf16 v[50:53], v[174:177], v[190:193], v[50:53]
	v_mfma_f32_16x16x32_bf16 v[42:45], v[182:185], v[190:193], v[42:45]
	v_mfma_f32_16x16x32_bf16 v[34:37], v[174:177], v[198:201], v[34:37]
	v_mfma_f32_16x16x32_bf16 v[26:29], v[182:185], v[198:201], v[26:29]
	v_mfma_f32_16x16x32_bf16 v[18:21], v[174:177], v[206:209], v[18:21]
	v_mfma_f32_16x16x32_bf16 v[10:13], v[182:185], v[206:209], v[10:13]
	v_mfma_f32_16x16x32_bf16 v[6:9], v[174:177], v[224:227], v[6:9]
	v_mfma_f32_16x16x32_bf16 v[2:5], v[182:185], v[224:227], v[2:5]
	v_mfma_f32_16x16x32_bf16 v[50:53], v[178:181], v[194:197], v[50:53]
	v_mfma_f32_16x16x32_bf16 v[42:45], v[186:189], v[194:197], v[42:45]
	v_mfma_f32_16x16x32_bf16 v[34:37], v[178:181], v[202:205], v[34:37]
	v_mfma_f32_16x16x32_bf16 v[26:29], v[186:189], v[202:205], v[26:29]
	v_mfma_f32_16x16x32_bf16 v[18:21], v[178:181], v[220:223], v[18:21]
	v_mfma_f32_16x16x32_bf16 v[10:13], v[186:189], v[220:223], v[10:13]
	v_mfma_f32_16x16x32_bf16 v[6:9], v[178:181], v[228:231], v[6:9]
	v_mfma_f32_16x16x32_bf16 v[2:5], v[186:189], v[228:231], v[2:5]
	s_setprio 0
	s_barrier
; #define PG8_STAGE(bufoff, gbase, voff) do { _Pragma("unroll") for (int _i = 0; _i < 2; ++_i) \
;         __builtin_amdgcn_global_load_lds((const unsigned*)((const char*)(gbase) + (voff)[_i]), (PG8_LAS unsigned*)(lds + (bufoff) + ldsw + _i * 8192), 16, 0, 0); } while (0)
; #define PG8_LDA(dst, b, h) do { _Pragma("unroll") for (int m = 0; m < 4; ++m) _Pragma("unroll") for (int k = 0; k < 2; ++k) dst[m][k] = *(const PG8_LAS bf16x8*)(lds + PG8_SA(b, h) + aoff + m * 2048 + k * 1024); } while (0)
; #define PG8_LDB(dst, b, h) do { _Pragma("unroll") for (int n = 0; n < 2; ++n) _Pragma("unroll") for (int k = 0; k < 2; ++k) dst[n][k] = *(const PG8_LAS bf16x8*)(lds + PG8_SB(b, h) + boff + n * 2048 + k * 1024); } while (0)
; #define PG8_MMA(ai, bj, At, Bt) do { __builtin_amdgcn_s_setprio(1); _Pragma("unroll") for (int m = 0; m < 4; ++m) _Pragma("unroll") for (int n = 0; n < 2; ++n) _Pragma("unroll") for (int k = 0; k < 2; ++k) \
;         acc[ai][bj][m][n] = __builtin_amdgcn_mfma_f32_16x16x32_bf16(Bt[n][k], At[m][k], acc[ai][bj][m][n], 0, 0, 0); __builtin_amdgcn_s_setprio(0); } while (0)
; #define PG8_WAIT_V(n) asm volatile("s_waitcnt vmcnt(" #n ")" ::: "memory")
; #define PG8_WAIT_L(n) asm volatile("s_waitcnt lgkmcnt(" #n ")" ::: "memory")
; #define PG8_BAR __builtin_amdgcn_s_barrier()
; #define PG8_SCHED __builtin_amdgcn_sched_barrier(0)
; template <class Epi, class Sched, bool ALIGN_EPI = false, bool SP2 = false>
; __device__ __forceinline__ void gemm_phase(PG8_LAS unsigned char* lds, const Gemm g, const Sched& S, const Epi& E) {
;     ...
;             PG8_LDB(B0, 1, 0); PG8_LDB(B1, 1, 1); PG8_SCHED; PG8_LDA(At, 1, 0); PG8_STAGE(PG8_SA(0, 1), a2 + hstep, voffA);
;             PG8_WAIT_V(8); PG8_WAIT_L(0); PG8_BAR; PG8_MMA(0, 0, At, B0); PG8_MMA(0, 1, At, B1); PG8_BAR; PG8_SCHED;
;             PG8_LDA(At, 1, 1); PG8_STAGE(PG8_SB(1, 0), b3, voffB); PG8_STAGE(PG8_SB(1, 1), b3 + hstep, voffB); PG8_STAGE(PG8_SA(1, 0), a3, voffA);
;             PG8_WAIT_V(8); PG8_WAIT_L(0); PG8_BAR; PG8_MMA(1, 0, At, B0); PG8_MMA(1, 1, At, B1); PG8_BAR; PG8_SCHED;
	s_add_i32 s52, 0, 0x18000
	v_add_u32_e32 v0, s52, v147
	s_add_i32 s53, 0, 0x1c000
	ds_read_b128 v[158:161], v0
	ds_read_b128 v[162:165], v0 offset:1024
	ds_read_b128 v[166:169], v0 offset:2048
	ds_read_b128 v[170:173], v0 offset:3072
	v_add_u32_e32 v0, s53, v147
	ds_read_b128 v[174:177], v0
	ds_read_b128 v[178:181], v0 offset:1024
	ds_read_b128 v[182:185], v0 offset:2048
	ds_read_b128 v[186:189], v0 offset:3072
	s_add_u32 s20, s20, 0x40000
	s_addc_u32 s21, s21, 0
	s_mov_b32 m0, s29
	v_lshl_add_u64 v[232:233], s[20:21], 0, v[136:137]
	ds_read_b128 v[190:193], v156 offset:32768
	ds_read_b128 v[194:197], v156 offset:33792
	ds_read_b128 v[198:201], v156 offset:34816
	ds_read_b128 v[202:205], v156 offset:35840
	ds_read_b128 v[206:209], v156 offset:36864
	ds_read_b128 v[220:223], v156 offset:37888
	ds_read_b128 v[224:227], v156 offset:38912
	ds_read_b128 v[228:231], v156 offset:39936
	global_load_lds_dwordx4 v[232:233], off
	v_lshl_add_u64 v[232:233], s[20:21], 0, v[132:133]
	s_mov_b32 m0, s30
	s_nop 0
	global_load_lds_dwordx4 v[232:233], off
	s_waitcnt vmcnt(8)
	s_waitcnt lgkmcnt(0)
	s_barrier
	s_setprio 1
	s_waitcnt lgkmcnt(0)
	v_mfma_f32_16x16x32_bf16 v[126:129], v[158:161], v[190:193], v[126:129]
	v_mfma_f32_16x16x32_bf16 v[122:125], v[166:169], v[190:193], v[122:125]
	v_mfma_f32_16x16x32_bf16 v[118:121], v[158:161], v[198:201], v[118:121]
	v_mfma_f32_16x16x32_bf16 v[110:113], v[166:169], v[198:201], v[110:113]
	v_mfma_f32_16x16x32_bf16 v[102:105], v[158:161], v[206:209], v[102:105]
	v_mfma_f32_16x16x32_bf16 v[94:97], v[166:169], v[206:209], v[94:97]
	v_mfma_f32_16x16x32_bf16 v[86:89], v[158:161], v[224:227], v[86:89]
	v_mfma_f32_16x16x32_bf16 v[78:81], v[166:169], v[224:227], v[78:81]
	v_mfma_f32_16x16x32_bf16 v[126:129], v[162:165], v[194:197], v[126:129]
	v_mfma_f32_16x16x32_bf16 v[122:125], v[170:173], v[194:197], v[122:125]
	v_mfma_f32_16x16x32_bf16 v[118:121], v[162:165], v[202:205], v[118:121]
	v_mfma_f32_16x16x32_bf16 v[110:113], v[170:173], v[202:205], v[110:113]
	v_mfma_f32_16x16x32_bf16 v[102:105], v[162:165], v[220:223], v[102:105]
	v_mfma_f32_16x16x32_bf16 v[94:97], v[170:173], v[220:223], v[94:97]
	v_mfma_f32_16x16x32_bf16 v[86:89], v[162:165], v[228:231], v[86:89]
	v_mfma_f32_16x16x32_bf16 v[78:81], v[170:173], v[228:231], v[78:81]
	s_setprio 0
	s_setprio 1
	v_mfma_f32_16x16x32_bf16 v[114:117], v[174:177], v[190:193], v[114:117]
	v_mfma_f32_16x16x32_bf16 v[106:109], v[182:185], v[190:193], v[106:109]
	v_mfma_f32_16x16x32_bf16 v[98:101], v[174:177], v[198:201], v[98:101]
	v_mfma_f32_16x16x32_bf16 v[90:93], v[182:185], v[198:201], v[90:93]
	v_mfma_f32_16x16x32_bf16 v[82:85], v[174:177], v[206:209], v[82:85]
	v_mfma_f32_16x16x32_bf16 v[74:77], v[182:185], v[206:209], v[74:77]
	v_mfma_f32_16x16x32_bf16 v[70:73], v[174:177], v[224:227], v[70:73]
	v_mfma_f32_16x16x32_bf16 v[66:69], v[182:185], v[224:227], v[66:69]
	v_mfma_f32_16x16x32_bf16 v[114:117], v[178:181], v[194:197], v[114:117]
	v_mfma_f32_16x16x32_bf16 v[106:109], v[186:189], v[194:197], v[106:109]
	v_mfma_f32_16x16x32_bf16 v[98:101], v[178:181], v[202:205], v[98:101]
	v_mfma_f32_16x16x32_bf16 v[90:93], v[186:189], v[202:205], v[90:93]
	v_mfma_f32_16x16x32_bf16 v[82:85], v[178:181], v[220:223], v[82:85]
	v_mfma_f32_16x16x32_bf16 v[74:77], v[186:189], v[220:223], v[74:77]
	v_mfma_f32_16x16x32_bf16 v[70:73], v[178:181], v[228:231], v[70:73]
	v_mfma_f32_16x16x32_bf16 v[66:69], v[186:189], v[228:231], v[66:69]
	s_setprio 0
	s_barrier
; #define PG8_STAGE(bufoff, gbase, voff) do { _Pragma("unroll") for (int _i = 0; _i < 2; ++_i) \
;         __builtin_amdgcn_global_load_lds((const unsigned*)((const char*)(gbase) + (voff)[_i]), (PG8_LAS unsigned*)(lds + (bufoff) + ldsw + _i * 8192), 16, 0, 0); } while (0)
; #define PG8_LDA(dst, b, h) do { _Pragma("unroll") for (int m = 0; m < 4; ++m) _Pragma("unroll") for (int k = 0; k < 2; ++k) dst[m][k] = *(const PG8_LAS bf16x8*)(lds + PG8_SA(b, h) + aoff + m * 2048 + k * 1024); } while (0)
; #define PG8_WAIT_V(n) asm volatile("s_waitcnt vmcnt(" #n ")" ::: "memory")
; template <class Epi, class Sched, bool ALIGN_EPI = false, bool SP2 = false>
; __device__ __forceinline__ void gemm_phase(PG8_LAS unsigned char* lds, const Gemm g, const Sched& S, const Epi& E) {
;     ...
;             PG8_LDA(At, 1, 1); PG8_STAGE(PG8_SB(1, 0), b3, voffB); PG8_STAGE(PG8_SB(1, 1), b3 + hstep, voffB); PG8_STAGE(PG8_SA(1, 0), a3, voffA);
;             PG8_WAIT_V(8); PG8_WAIT_L(0); PG8_BAR; PG8_MMA(1, 0, At, B0); PG8_MMA(1, 1, At, B1); PG8_BAR; PG8_SCHED;
;             } else {
;             PG8_LDB(B0, 0, 0); PG8_SCHED; PG8_LDA(At, 0, 0); PG8_STAGE(PG8_SA(1, 1), a1 + hstep, voffA);
;             PG8_WAIT_L(8); PG8_BAR; PG8_WAIT_L(0); PG8_MMA(0, 0, At, B0); PG8_BAR; PG8_SCHED;
;             PG8_LDB(B1, 0, 1); PG8_STAGE(PG8_SB(0, 0), b2, voffB);
;             PG8_BAR; PG8_WAIT_L(0); PG8_MMA(0, 1, At, B1); PG8_BAR;
;             PG8_LDA(At, 0, 1); PG8_STAGE(PG8_SA(0, 0), a2, voffA);
;             PG8_BAR; PG8_WAIT_L(0); PG8_MMA(1, 0, At, B0); PG8_BAR; PG8_SCHED;
;             PG8_STAGE(PG8_SB(0, 1), b2 + hstep, voffB);
;             PG8_WAIT_V(6); PG8_BAR; PG8_MMA(1, 1, At, B1); PG8_BAR;
;             PG8_LDB(B0, 1, 0); PG8_SCHED; PG8_LDA(At, 1, 0); PG8_STAGE(PG8_SA(0, 1), a2 + hstep, voffA);
;             PG8_WAIT_L(8); PG8_BAR; PG8_WAIT_L(0); PG8_MMA(0, 0, At, B0); PG8_BAR; PG8_SCHED;
;             PG8_LDB(B1, 1, 1); PG8_STAGE(PG8_SB(1, 0), b3, voffB);
;             PG8_BAR; PG8_WAIT_L(0); PG8_MMA(0, 1, At, B1); PG8_BAR;
;             PG8_LDA(At, 1, 1); PG8_STAGE(PG8_SA(1, 0), a3, voffA);
;             PG8_BAR; PG8_WAIT_L(0); PG8_MMA(1, 0, At, B0); PG8_BAR; PG8_SCHED;
;             PG8_STAGE(PG8_SB(1, 1), b3 + hstep, voffB);
;             PG8_WAIT_V(6); PG8_BAR; PG8_MMA(1, 1, At, B1); PG8_BAR;
;             }
;         }
;         if constexpr (ALIGN_EPI) { if (wr == 0) PG8_BAR; }
	s_add_i32 s20, s52, s26
	v_lshl_add_u64 v[210:211], v[210:211], 0, s[94:95]
	s_mov_b32 m0, s20
	ds_read_b128 v[190:193], v156 offset:49152
	ds_read_b128 v[194:197], v156 offset:50176
	ds_read_b128 v[198:201], v156 offset:51200
	ds_read_b128 v[202:205], v156 offset:52224
	ds_read_b128 v[206:209], v156 offset:53248
	ds_read_b128 v[220:223], v156 offset:54272
	ds_read_b128 v[224:227], v156 offset:55296
	ds_read_b128 v[228:231], v156 offset:56320
	global_load_lds_dwordx4 v[210:211], off
	s_add_i32 m0, s20, 0x2000
	s_add_u32 s16, s16, 0x40080
	v_lshl_add_u64 v[210:211], v[212:213], 0, s[94:95]
	s_addc_u32 s17, s17, 0
	s_add_i32 s20, s53, s26
	global_load_lds_dwordx4 v[210:211], off
	v_lshl_add_u64 v[210:211], s[16:17], 0, v[134:135]
	s_mov_b32 m0, s20
	s_nop 0
	global_load_lds_dwordx4 v[210:211], off
	v_lshl_add_u64 v[210:211], s[16:17], 0, v[130:131]
	s_add_i32 m0, s20, 0x2000
	s_nop 0
	global_load_lds_dwordx4 v[210:211], off
	v_lshl_add_u64 v[210:211], v[214:215], 0, s[94:95]
	s_mov_b32 m0, s38
	s_nop 0
	global_load_lds_dwordx4 v[210:211], off
	v_lshl_add_u64 v[210:211], v[216:217], 0, s[94:95]
	s_mov_b32 m0, s39
	s_nop 0
	global_load_lds_dwordx4 v[210:211], off
	s_waitcnt vmcnt(8)
	s_waitcnt lgkmcnt(0)
	s_barrier
	s_setprio 1
	s_waitcnt lgkmcnt(0)
	v_mfma_f32_16x16x32_bf16 v[62:65], v[158:161], v[190:193], v[62:65]
	v_mfma_f32_16x16x32_bf16 v[58:61], v[166:169], v[190:193], v[58:61]
	v_mfma_f32_16x16x32_bf16 v[54:57], v[158:161], v[198:201], v[54:57]
	v_mfma_f32_16x16x32_bf16 v[46:49], v[166:169], v[198:201], v[46:49]
	v_mfma_f32_16x16x32_bf16 v[38:41], v[158:161], v[206:209], v[38:41]
	v_mfma_f32_16x16x32_bf16 v[30:33], v[166:169], v[206:209], v[30:33]
	v_mfma_f32_16x16x32_bf16 v[22:25], v[158:161], v[224:227], v[22:25]
	v_mfma_f32_16x16x32_bf16 v[14:17], v[166:169], v[224:227], v[14:17]
	v_mfma_f32_16x16x32_bf16 v[62:65], v[162:165], v[194:197], v[62:65]
	v_mfma_f32_16x16x32_bf16 v[58:61], v[170:173], v[194:197], v[58:61]
	v_mfma_f32_16x16x32_bf16 v[54:57], v[162:165], v[202:205], v[54:57]
	v_mfma_f32_16x16x32_bf16 v[46:49], v[170:173], v[202:205], v[46:49]
	v_mfma_f32_16x16x32_bf16 v[38:41], v[162:165], v[220:223], v[38:41]
	v_mfma_f32_16x16x32_bf16 v[30:33], v[170:173], v[220:223], v[30:33]
	v_mfma_f32_16x16x32_bf16 v[22:25], v[162:165], v[228:231], v[22:25]
	v_mfma_f32_16x16x32_bf16 v[14:17], v[170:173], v[228:231], v[14:17]
	s_setprio 0
	s_setprio 1
	v_mfma_f32_16x16x32_bf16 v[50:53], v[174:177], v[190:193], v[50:53]
	v_mfma_f32_16x16x32_bf16 v[42:45], v[182:185], v[190:193], v[42:45]
	v_mfma_f32_16x16x32_bf16 v[34:37], v[174:177], v[198:201], v[34:37]
	v_mfma_f32_16x16x32_bf16 v[26:29], v[182:185], v[198:201], v[26:29]
	v_mfma_f32_16x16x32_bf16 v[18:21], v[174:177], v[206:209], v[18:21]
	v_mfma_f32_16x16x32_bf16 v[10:13], v[182:185], v[206:209], v[10:13]
	v_mfma_f32_16x16x32_bf16 v[6:9], v[174:177], v[224:227], v[6:9]
	v_mfma_f32_16x16x32_bf16 v[2:5], v[182:185], v[224:227], v[2:5]
	v_mfma_f32_16x16x32_bf16 v[50:53], v[178:181], v[194:197], v[50:53]
	v_mfma_f32_16x16x32_bf16 v[42:45], v[186:189], v[194:197], v[42:45]
	v_mfma_f32_16x16x32_bf16 v[34:37], v[178:181], v[202:205], v[34:37]
	v_mfma_f32_16x16x32_bf16 v[26:29], v[186:189], v[202:205], v[26:29]
	v_mfma_f32_16x16x32_bf16 v[18:21], v[178:181], v[220:223], v[18:21]
	v_mfma_f32_16x16x32_bf16 v[10:13], v[186:189], v[220:223], v[10:13]
	v_mfma_f32_16x16x32_bf16 v[6:9], v[178:181], v[228:231], v[6:9]
	v_mfma_f32_16x16x32_bf16 v[2:5], v[186:189], v[228:231], v[2:5]
	s_setprio 0
	s_barrier
	s_add_i32 s50, s50, 2
	s_add_u32 s18, s18, 0x100
	s_addc_u32 s19, s19, 0
	s_add_u32 vcc_lo, vcc_lo, 0x100
	s_addc_u32 vcc_hi, vcc_hi, 0
	s_cmp_gt_u32 s50, 13
	s_cbranch_scc0 .LBB0_247
	s_and_b64 vcc, exec, s[6:7]
	s_cbranch_vccz .LBB0_252
	s_barrier
	s_cmp_gt_i32 s56, 5
	s_mov_b64 s[16:17], -1
	s_cbranch_scc1 .LBB0_253

; #define PG8_BAR __builtin_amdgcn_s_barrier()
; template <class Epi, class Sched, bool ALIGN_EPI = false, bool SP2 = false>
; __device__ __forceinline__ void gemm_phase(PG8_LAS unsigned char* lds, const Gemm g, const Sched& S, const Epi& E) {
;     ...
;         if (!has_next) break;
; #pragma unroll
;         for (int a = 0; a < 2; ++a)
; #pragma unroll
;             for (int b = 0; b < 2; ++b)
; #pragma unroll
;                 for (int m = 0; m < 4; ++m)
; #pragma unroll
;                     for (int n = 0; n < 2; ++n) acc[a][b][m][n] = (f32x4){0.f, 0.f, 0.f, 0.f};
;         cur = nxt; cA = nA; cB = nB; ++ui;
;         if constexpr (ALIGN_EPI) { if (wr == 1) PG8_BAR; }
;     }
.LBB0_259:
	s_andn2_b64 vcc, exec, s[0:1]
	s_cbranch_vccnz .LBB0_238
	s_branch .LBB0_238

; #define PG8_WAIT_V(n) asm volatile("s_waitcnt vmcnt(" #n ")" ::: "memory")
; template <class Epi, class Sched, bool ALIGN_EPI = false, bool SP2 = false>
; __device__ __forceinline__ void gemm_phase(PG8_LAS unsigned char* lds, const Gemm g, const Sched& S, const Epi& E) {
;     int tid_ = threadIdx.x; asm volatile("" : "+v"(tid_));
;     const int tid = tid_, wid = __builtin_amdgcn_readfirstlane(tid >> 6), lane = tid & 63, wr = wid >> 2, wc = wid & 3, fr = lane & 15, fq = lane >> 4;
;     const int K = g.K, nt = K / BK, LD = g.ld ? g.ld : g.K;
;     unsigned voffA[2], voffB[2];
; #pragma unroll
;     for (int i = 0; i < 2; ++i) { int R, C; stage_rc(tid * 16 + i * 8192, R, C); const int Rb = Epi::PERM ? ((R & ~31) + perm32(R & 31)) : R;
;         voffA[i] = (unsigned)(R * LD + C) * 2u; voffB[i] = (unsigned)(Rb * LD + C) * 2u; }
;     const size_t kstep = (size_t)(BK * 2);
;     const size_t hstep = (size_t)HALF * LD * 2;
;     const size_t tstep = 2 * hstep;
;     const unsigned ldsw = (unsigned)wid * 1024u;
;     const int aoff = lds_byte(wr * 64 + fr, fq * 8), boff = lds_byte(wc * 32 + fr, fq * 8);
;     ...
;     Unit cur, nxt; int ui = 0;
;     if (!S.next(0, cur)) return;
;     f32x4 acc[2][2][4][2];
; #pragma unroll
;     for (int a = 0; a < 2; ++a)
; #pragma unroll
;         for (int b = 0; b < 2; ++b)
; #pragma unroll
;             for (int m = 0; m < 4; ++m)
; #pragma unroll
;                 for (int n = 0; n < 2; ++n) acc[a][b][m][n] = (f32x4){0.f, 0.f, 0.f, 0.f};
;     bf16x8 At[4][2], B0[2][2], B1[2][2];
;     const char* cA = (const char*)g.A + (size_t)cur.pm * tstep; const char* cB = (const char*)g.Bt + (size_t)cur.pn * tstep;
;     S.a_ready(cur);
;     if constexpr (SP2) {
;         PG8_STAGE(PG8_SB(0, 0), cB, voffB); PG8_STAGE(PG8_SB(0, 1), cB + hstep, voffB); PG8_STAGE(PG8_SA(0, 0), cA, voffA); PG8_STAGE(PG8_SA(0, 1), cA + hstep, voffA);
;         if (wr == 1) PG8_BAR;
;         PG8_WAIT_V(2); PG8_BAR;
;         PG8_STAGE(PG8_SB(1, 0), cB + kstep, voffB); PG8_STAGE(PG8_SA(1, 0), cA + kstep, voffA); PG8_STAGE(PG8_SB(1, 1), cB + hstep + kstep, voffB);
;         PG8_WAIT_V(6); PG8_BAR;
;     } else {
;         PG8_STAGE(PG8_SB(0, 0), cB, voffB); PG8_STAGE(PG8_SA(0, 0), cA, voffA); PG8_STAGE(PG8_SB(0, 1), cB + hstep, voffB); PG8_STAGE(PG8_SA(0, 1), cA + hstep, voffA);
;         if (wr == 1) PG8_BAR;
;         PG8_WAIT_V(4); PG8_BAR;
.LBB0_534:
	s_or_b64 exec, exec, s[36:37]
	s_mov_b64 s[4:5], s[72:73]
	v_mov_b32_e32 v15, v242
	s_waitcnt lgkmcnt(0)
	s_barrier
	s_and_b64 vcc, exec, s[86:87]
	v_readfirstlane_b32 s10, v15
	s_cbranch_vccz .LBB0_554
	v_lshlrev_b32_e32 v2, 4, v15
	v_add_u32_e32 v3, 0x2000, v2
	v_ashrrev_i32_e32 v0, 31, v3
	v_lshrrev_b32_e32 v0, 22, v0
	v_add_u32_e32 v0, v3, v0
	v_ashrrev_i32_e32 v0, 10, v0
	v_mul_i32_i24_e32 v4, 0x400, v0
	v_sub_u32_e32 v3, v3, v4
	v_lshrrev_b32_e32 v4, 4, v3
	v_bitop3_b32 v3, v4, v3, 32 bitop3:0x6c
	v_ashrrev_i32_e32 v4, 31, v3
	v_lshrrev_b32_e32 v4, 26, v4
	v_add_u32_e32 v4, v3, v4
	v_lshlrev_b32_e32 v5, 3, v0
	v_ashrrev_i32_e32 v10, 6, v4
	v_and_b32_e32 v5, -16, v5
	v_add_u32_e32 v5, v10, v5
	v_and_b32_e32 v6, 3, v10
	s_mov_b32 s0, 0x3fffe0
	v_lshrrev_b32_e32 v7, 2, v5
	v_lshlrev_b32_e32 v8, 1, v5
	v_and_b32_e32 v4, 0xc0, v4
	v_and_or_b32 v6, v5, s0, v6
	v_and_b32_e32 v7, 4, v7
	v_and_b32_e32 v8, 24, v8
	v_sub_u32_e32 v3, v3, v4
	v_or3_b32 v6, v6, v7, v8
	v_lshlrev_b32_e32 v7, 5, v0
	v_ashrrev_i16_sdwa v3, v241, sext(v3) dst_sel:DWORD dst_unused:UNUSED_PAD src0_sel:DWORD src1_sel:BYTE_0
	v_and_b32_e32 v7, 32, v7
	v_bfe_i32 v11, v3, 0, 16
	v_add_lshl_u32 v3, v7, v11, 1
	v_lshl_add_u32 v202, v6, 10, v3
	v_lshl_add_u32 v204, v5, 10, v3
	v_bfe_i32 v3, v15, 27, 1
	v_lshrrev_b32_e32 v3, 22, v3
	v_add_u32_e32 v3, v2, v3
	v_and_b32_e32 v3, 0xfffffc00, v3
	v_sub_u32_e32 v2, v2, v3
	v_lshrrev_b32_e32 v3, 4, v2
	v_ashrrev_i32_e32 v4, 31, v15
	v_bitop3_b32 v2, v3, v2, 32 bitop3:0x6c
	v_lshrrev_b32_e32 v4, 26, v4
	v_ashrrev_i32_e32 v3, 31, v2
	v_add_u32_e32 v4, v15, v4
	v_lshrrev_b32_e32 v3, 26, v3
	v_ashrrev_i32_e32 v13, 6, v4
	v_add_u32_e32 v3, v2, v3
	v_lshlrev_b32_e32 v4, 3, v13
	s_add_u32 s26, s4, 0x1f400000
	v_ashrrev_i32_e32 v12, 6, v3
	v_and_b32_e32 v4, -16, v4
	s_addc_u32 s27, s5, 0
	v_add_u32_e32 v4, v12, v4
	s_add_u32 s28, s4, 0x1d00000
	v_and_b32_e32 v5, 3, v12
	v_lshrrev_b32_e32 v6, 2, v4
	v_lshlrev_b32_e32 v7, 1, v4
	v_and_b32_e32 v3, 0xc0, v3
	s_addc_u32 s29, s5, 0
	s_ashr_i32 s11, s10, 6
	v_and_or_b32 v5, v4, s0, v5
	v_and_b32_e32 v6, 4, v6
	v_and_b32_e32 v7, 24, v7
	v_sub_u32_e32 v2, v2, v3
	s_ashr_i32 s12, s10, 8
	s_lshl_b32 s30, s11, 10
	v_or3_b32 v5, v5, v6, v7
	v_lshlrev_b32_e32 v6, 5, v13
	v_ashrrev_i16_sdwa v2, v241, sext(v2) dst_sel:DWORD dst_unused:UNUSED_PAD src0_sel:DWORD src1_sel:BYTE_0
	v_readlane_b32 s0, v255, 7
	v_and_b32_e32 v6, 32, v6
	v_bfe_i32 v14, v2, 0, 16
	v_readlane_b32 s1, v255, 8
	s_add_u32 s16, s28, s0
	v_add_lshl_u32 v2, v6, v14, 1
	s_addc_u32 s17, s29, s1
	s_add_i32 s31, s30, 0
	v_lshl_add_u32 v206, v5, 10, v2
	s_add_i32 m0, s31, 0x10000
	v_lshl_add_u32 v208, v4, 10, v2
	global_load_lds_dwordx4 v206, s[16:17]
	s_add_i32 m0, s31, 0x12000
	s_add_u32 s0, s16, 0x20000
	global_load_lds_dwordx4 v202, s[16:17]
	s_addc_u32 s1, s17, 0
	s_add_i32 m0, s31, 0x14000
	v_mov_b32_e32 v207, v1
	global_load_lds_dwordx4 v206, s[0:1]
	s_add_i32 m0, s31, 0x16000
	v_mov_b32_e32 v203, v1
	global_load_lds_dwordx4 v202, s[0:1]
	v_readlane_b32 s0, v255, 5
	v_readlane_b32 s1, v255, 6
	s_add_u32 s22, s26, s0
	s_addc_u32 s23, s27, s1
	s_add_i32 s34, s31, 0x2000
	s_mov_b32 m0, s31
	s_add_u32 s0, s22, 0x20000
	global_load_lds_dwordx4 v208, s[22:23]
	s_mov_b32 m0, s34
	s_addc_u32 s1, s23, 0
	s_add_i32 s35, s31, 0x4000
	global_load_lds_dwordx4 v204, s[22:23]
	s_mov_b32 m0, s35
	s_add_i32 s36, s31, 0x6000
	global_load_lds_dwordx4 v208, s[0:1]
	s_mov_b32 m0, s36
	v_mov_b32_e32 v209, v1
	global_load_lds_dwordx4 v204, s[0:1]
	v_mov_b32_e32 v205, v1
	s_cmp_eq_u32 s12, 1
	s_mov_b32 s20, s62
	s_mov_b32 s15, s54
	s_mov_b64 s[18:19], s[58:59]
	s_mov_b32 s13, s48
	v_lshl_add_u64 v[8:9], s[16:17], 0, v[206:207]
	v_lshl_add_u64 v[6:7], s[16:17], 0, v[202:203]
	v_lshl_add_u64 v[2:3], s[22:23], 0, v[208:209]
	s_cselect_b64 s[0:1], -1, 0
	s_cmp_lg_u32 s12, 1
	v_lshl_add_u64 v[4:5], s[22:23], 0, v[204:205]
	s_cbranch_scc1 .LBB0_537
.LBB0_537:
	s_lshl_b64 s[6:7], s[60:61], 11
	v_readlane_b32 s48, v254, 29
	v_readlane_b32 s58, v254, 39
	v_readlane_b32 s59, v254, 40
	s_add_u32 s6, s58, s6
	v_lshrrev_b32_e32 v17, 1, v15
	s_addc_u32 s7, s59, s7
	v_and_b32_e32 v17, 24, v17
	s_add_u32 s8, s4, 0xd400000
	v_and_b32_e32 v16, 15, v15
	v_lshlrev_b32_e32 v18, 1, v17
	v_lshlrev_b32_e32 v15, 2, v15
	s_addc_u32 s9, s5, 0
	v_lshl_or_b32 v211, s12, 6, v16
	v_lshl_or_b32 v16, v16, 6, v18
	s_lshl_b32 s4, s12, 13
	v_and_b32_e32 v15, 32, v15
	v_bitop3_b32 v18, v16, s4, v15 bitop3:0xde
	s_lshl_b32 s4, s11, 5
	s_and_b32 s12, s4, 0x60
	s_add_i32 m0, s31, 0x18000
	v_lshl_add_u64 v[8:9], v[8:9], 0, s[94:95]
	s_lshl_b32 s4, s12, 7
	s_waitcnt vmcnt(2)
	s_barrier
	global_load_lds_dwordx4 v[8:9], off
	v_lshl_add_u64 v[6:7], v[6:7], 0, s[94:95]
	s_add_i32 m0, s31, 0x1a000
	s_add_i32 s37, s31, 0x8000
	s_add_i32 s38, s31, 0xa000
	v_bitop3_b32 v244, v16, s4, v15 bitop3:0xde
	global_load_lds_dwordx4 v[6:7], off
	v_lshl_add_u64 v[2:3], v[2:3], 0, s[94:95]
	s_mov_b32 m0, s37
	s_add_u32 s4, s16, 0x20080
	global_load_lds_dwordx4 v[2:3], off
	v_lshl_add_u64 v[2:3], v[4:5], 0, s[94:95]
	s_mov_b32 m0, s38
	s_addc_u32 s5, s17, 0
	global_load_lds_dwordx4 v[2:3], off
	s_add_i32 m0, s31, 0x1c000
	v_lshl_add_u64 v[2:3], s[4:5], 0, v[206:207]
	global_load_lds_dwordx4 v[2:3], off
	v_lshl_add_u64 v[2:3], s[4:5], 0, v[202:203]
	s_add_i32 m0, s31, 0x1e000
	v_readlane_b32 s49, v254, 30
	global_load_lds_dwordx4 v[2:3], off
	v_lshlrev_b32_e32 v2, 13, v13
	v_and_b32_e32 v2, 0xffffc000, v2
	v_lshl_add_u32 v2, v12, 10, v2
	v_and_b32_e32 v3, 1, v13
	v_lshl_or_b32 v2, v3, 6, v2
	v_lshl_add_u32 v220, v14, 1, v2
	v_lshlrev_b32_e32 v2, 13, v0
	v_and_b32_e32 v2, 0xffffc000, v2
	s_waitcnt vmcnt(6)
	v_lshl_add_u32 v2, v10, 10, v2
	v_and_b32_e32 v0, 1, v0
	v_readlane_b32 s54, v254, 35
	v_readlane_b32 s62, v254, 43
	s_cmpk_lt_u32 s10, 0x100
	v_lshl_or_b32 v0, v0, 6, v2
	v_readlane_b32 s4, v255, 3
	v_readlane_b32 s51, v254, 32
	s_cselect_b64 s[10:11], -1, 0
	v_or_b32_e32 v210, s12, v17
	v_mov_b32_e32 v221, v1
	v_lshl_add_u32 v222, v11, 1, v0
	v_mov_b32_e32 v223, v1
	s_mov_b32 s39, 0
	v_add_u32_e32 v245, 0, v18
	v_readlane_b32 s46, v255, 2
	s_mov_b32 s33, s4
	s_mov_b32 s48, s13
	s_mov_b64 s[58:59], s[18:19]
	s_mov_b32 s49, 0x30000
	s_mov_b32 s54, s15
	s_mov_b32 s62, s20
	v_readlane_b32 s50, v254, 31
	v_readlane_b32 s52, v254, 33
	v_readlane_b32 s53, v254, 34
	v_readlane_b32 s55, v254, 36
	v_readlane_b32 s56, v254, 37
	v_readlane_b32 s57, v254, 38
	v_readlane_b32 s60, v254, 41
	v_readlane_b32 s61, v254, 42
	v_readlane_b32 s63, v254, 44
	s_barrier
	v_readlane_b32 s5, v255, 4
	v_readlane_b32 s51, v255, 32
	s_branch .LBB0_540

;     __device__ __forceinline__ bool next(int i, Unit& u) const { const int L = i * G + c; if (L >= 512) return false; u.pm = L; u.pn = L >> 4; return true; }
; #define PG8_STAGE(bufoff, gbase, voff) do { _Pragma("unroll") for (int _i = 0; _i < 2; ++_i) \
;         __builtin_amdgcn_global_load_lds((const unsigned*)((const char*)(gbase) + (voff)[_i]), (PG8_LAS unsigned*)(lds + (bufoff) + ldsw + _i * 8192), 16, 0, 0); } while (0)
; #define PG8_LDA(dst, b, h) do { _Pragma("unroll") for (int m = 0; m < 4; ++m) _Pragma("unroll") for (int k = 0; k < 2; ++k) dst[m][k] = *(const PG8_LAS bf16x8*)(lds + PG8_SA(b, h) + aoff + m * 2048 + k * 1024); } while (0)
; #define PG8_LDB(dst, b, h) do { _Pragma("unroll") for (int n = 0; n < 2; ++n) _Pragma("unroll") for (int k = 0; k < 2; ++k) dst[n][k] = *(const PG8_LAS bf16x8*)(lds + PG8_SB(b, h) + boff + n * 2048 + k * 1024); } while (0)
; template <class Epi, class Sched, bool ALIGN_EPI = false, bool SP2 = false>
; __device__ __forceinline__ void gemm_phase(PG8_LAS unsigned char* lds, const Gemm g, const Sched& S, const Epi& E) {
;     ...
;         const bool has_next = S.next(ui + 1, nxt);
;         const char* nA = has_next ? (const char*)g.A + (size_t)nxt.pm * tstep : cA; const char* nB = has_next ? (const char*)g.Bt + (size_t)nxt.pn * tstep : cB;
;         for (int t = 0; t < nt; t += 2) {
;             const bool last = (t == nt - 2);
;             const char* a1 = cA + (size_t)(t + 1) * kstep;
;             const char* a2 = last ? nA : cA + (size_t)(t + 2) * kstep; const char* b2 = last ? nB : cB + (size_t)(t + 2) * kstep;
;             const char* a3 = a2 + kstep; const char* b3 = b2 + kstep;
;             if (last && has_next) S.a_ready(nxt);
;             if constexpr (SP2) {
;             PG8_LDB(B0, 0, 0); PG8_LDB(B1, 0, 1); PG8_SCHED; PG8_LDA(At, 0, 0); PG8_STAGE(PG8_SA(1, 1), a1 + hstep, voffA);
;             PG8_WAIT_V(8); PG8_WAIT_L(0); PG8_BAR; PG8_MMA(0, 0, At, B0); PG8_MMA(0, 1, At, B1); PG8_BAR; PG8_SCHED;
;     ...
;         for (int a = 0; a < 2; ++a)
; #pragma unroll
;             for (int b = 0; b < 2; ++b)
; #pragma unroll
;                 for (int m = 0; m < 4; ++m)
; #pragma unroll
;                     for (int n = 0; n < 2; ++n) acc[a][b][m][n] = (f32x4){0.f, 0.f, 0.f, 0.f};
;         cur = nxt; cA = nA; cB = nB; ++ui;
;         if constexpr (ALIGN_EPI) { if (wr == 1) PG8_BAR; }
.LBB0_546:
	s_ashr_i32 s15, s14, 31
	s_lshl_b64 s[18:19], s[14:15], 18
	s_add_u32 s18, s26, s18
	s_addc_u32 s19, s27, s19
	s_and_b64 s[20:21], s[4:5], exec
	s_cselect_b32 s15, s19, s23
	s_cselect_b32 s55, s18, s22
	s_ashr_i32 s13, s12, 31
	s_lshl_b64 s[20:21], s[12:13], 18
	s_add_u32 s20, s28, s20
	s_addc_u32 s21, s29, s21
	s_and_b64 s[24:25], s[4:5], exec
	s_cselect_b32 s13, s21, s17
	s_cselect_b32 s56, s20, s16
	s_add_u32 s22, s22, 0x20080
	s_addc_u32 s23, s23, 0
	s_add_u32 s57, s16, 0x100
	v_mov_b32_e32 v2, 0
	s_addc_u32 s60, s17, 0
	s_mov_b32 s50, -2
	v_mov_b32_e32 v3, v2
	v_mov_b32_e32 v4, v2
	v_mov_b32_e32 v5, v2
	v_mov_b32_e32 v6, v2
	v_mov_b32_e32 v7, v2
	v_mov_b32_e32 v8, v2
	v_mov_b32_e32 v9, v2
	v_mov_b32_e32 v18, v2
	v_mov_b32_e32 v19, v2
	v_mov_b32_e32 v20, v2
	v_mov_b32_e32 v21, v2
	v_mov_b32_e32 v22, v2
	v_mov_b32_e32 v23, v2
	v_mov_b32_e32 v24, v2
	v_mov_b32_e32 v25, v2
	v_mov_b32_e32 v34, v2
	v_mov_b32_e32 v35, v2
	v_mov_b32_e32 v36, v2
	v_mov_b32_e32 v37, v2
	v_mov_b32_e32 v38, v2
	v_mov_b32_e32 v39, v2
	v_mov_b32_e32 v40, v2
	v_mov_b32_e32 v41, v2
	v_mov_b32_e32 v50, v2
	v_mov_b32_e32 v51, v2
	v_mov_b32_e32 v52, v2
	v_mov_b32_e32 v53, v2
	v_mov_b32_e32 v54, v2
	v_mov_b32_e32 v55, v2
	v_mov_b32_e32 v56, v2
	v_mov_b32_e32 v57, v2
	v_mov_b32_e32 v10, v2
	v_mov_b32_e32 v11, v2
	v_mov_b32_e32 v12, v2
	v_mov_b32_e32 v13, v2
	v_mov_b32_e32 v14, v2
	v_mov_b32_e32 v15, v2
	v_mov_b32_e32 v16, v2
	v_mov_b32_e32 v17, v2
	v_mov_b32_e32 v26, v2
	v_mov_b32_e32 v27, v2
	v_mov_b32_e32 v28, v2
	v_mov_b32_e32 v29, v2
	v_mov_b32_e32 v30, v2
	v_mov_b32_e32 v31, v2
	v_mov_b32_e32 v32, v2
	v_mov_b32_e32 v33, v2
	v_mov_b32_e32 v42, v2
	v_mov_b32_e32 v43, v2
	v_mov_b32_e32 v44, v2
	v_mov_b32_e32 v45, v2
	v_mov_b32_e32 v46, v2
	v_mov_b32_e32 v47, v2
	v_mov_b32_e32 v48, v2
	v_mov_b32_e32 v49, v2
	v_mov_b32_e32 v58, v2
	v_mov_b32_e32 v59, v2
	v_mov_b32_e32 v60, v2
	v_mov_b32_e32 v61, v2
	v_mov_b32_e32 v62, v2
	v_mov_b32_e32 v63, v2
	v_mov_b32_e32 v64, v2
	v_mov_b32_e32 v65, v2
	v_mov_b32_e32 v66, v2
	v_mov_b32_e32 v67, v2
	v_mov_b32_e32 v68, v2
	v_mov_b32_e32 v69, v2
	v_mov_b32_e32 v70, v2
	v_mov_b32_e32 v71, v2
	v_mov_b32_e32 v72, v2
	v_mov_b32_e32 v73, v2
	v_mov_b32_e32 v102, v2
	v_mov_b32_e32 v103, v2
	v_mov_b32_e32 v104, v2
	v_mov_b32_e32 v105, v2
	v_mov_b32_e32 v106, v2
	v_mov_b32_e32 v107, v2
	v_mov_b32_e32 v108, v2
	v_mov_b32_e32 v109, v2
	v_mov_b32_e32 v126, v2
	v_mov_b32_e32 v127, v2
	v_mov_b32_e32 v128, v2
	v_mov_b32_e32 v129, v2
	v_mov_b32_e32 v134, v2
	v_mov_b32_e32 v135, v2
	v_mov_b32_e32 v136, v2
	v_mov_b32_e32 v137, v2
	v_mov_b32_e32 v154, v2
	v_mov_b32_e32 v155, v2
	v_mov_b32_e32 v156, v2
	v_mov_b32_e32 v157, v2
	v_mov_b32_e32 v158, v2
	v_mov_b32_e32 v159, v2
	v_mov_b32_e32 v160, v2
	v_mov_b32_e32 v161, v2
	v_mov_b32_e32 v78, v2
	v_mov_b32_e32 v79, v2
	v_mov_b32_e32 v80, v2
	v_mov_b32_e32 v81, v2
	v_mov_b32_e32 v86, v2
	v_mov_b32_e32 v87, v2
	v_mov_b32_e32 v88, v2
	v_mov_b32_e32 v89, v2
	v_mov_b32_e32 v118, v2
	v_mov_b32_e32 v119, v2
	v_mov_b32_e32 v120, v2
	v_mov_b32_e32 v121, v2
	v_mov_b32_e32 v122, v2
	v_mov_b32_e32 v123, v2
	v_mov_b32_e32 v124, v2
	v_mov_b32_e32 v125, v2
	v_mov_b32_e32 v142, v2
	v_mov_b32_e32 v143, v2
	v_mov_b32_e32 v144, v2
	v_mov_b32_e32 v145, v2
	v_mov_b32_e32 v146, v2
	v_mov_b32_e32 v147, v2
	v_mov_b32_e32 v148, v2
	v_mov_b32_e32 v149, v2
	v_mov_b32_e32 v166, v2
	v_mov_b32_e32 v167, v2
	v_mov_b32_e32 v168, v2
	v_mov_b32_e32 v169, v2
	v_mov_b32_e32 v170, v2
	v_mov_b32_e32 v171, v2
	v_mov_b32_e32 v172, v2
	v_mov_b32_e32 v173, v2
	s_cmp_eq_u64 s[0:1], 0
	s_cbranch_scc1 .Lboff_skip_F
	s_barrier
.Lboff_skip_F:
.LBB0_547:
	s_add_u32 s16, s22, 0xfffe0080
	s_addc_u32 s17, s23, -1
	s_add_i32 s52, 0, 0x10000
	s_cmp_eq_u32 s50, 4
	s_cselect_b32 s25, s15, s17
	s_cselect_b32 s24, s55, s16
	v_add_u32_e32 v0, s52, v244
	s_cselect_b32 s17, s13, s60
	s_cselect_b32 s16, s56, s57
	s_add_i32 s61, 0, 0x14000
	ds_read_b128 v[74:77], v0
	ds_read_b128 v[82:85], v0 offset:1024
	ds_read_b128 v[90:93], v0 offset:2048
	ds_read_b128 v[94:97], v0 offset:3072
	v_add_u32_e32 v0, s61, v244
	ds_read_b128 v[98:101], v0
	ds_read_b128 v[110:113], v0 offset:1024
	ds_read_b128 v[114:117], v0 offset:2048
	ds_read_b128 v[130:133], v0 offset:3072
	v_lshl_add_u64 v[194:195], s[22:23], 0, v[220:221]
	s_add_i32 m0, s31, 0xc000
	ds_read_b128 v[138:141], v245
	ds_read_b128 v[150:153], v245 offset:1024
	ds_read_b128 v[162:165], v245 offset:2048
	ds_read_b128 v[174:177], v245 offset:3072
	ds_read_b128 v[178:181], v245 offset:4096
	ds_read_b128 v[182:185], v245 offset:5120
	ds_read_b128 v[186:189], v245 offset:6144
	ds_read_b128 v[190:193], v245 offset:7168
	global_load_lds_dwordx4 v[194:195], off
	v_lshl_add_u64 v[194:195], s[22:23], 0, v[222:223]
	s_add_i32 m0, s31, 0xe000
	s_nop 0
	global_load_lds_dwordx4 v[194:195], off
	s_waitcnt vmcnt(8)
	s_waitcnt lgkmcnt(0)
	s_barrier
; #define PG8_STAGE(bufoff, gbase, voff) do { _Pragma("unroll") for (int _i = 0; _i < 2; ++_i) \
;         __builtin_amdgcn_global_load_lds((const unsigned*)((const char*)(gbase) + (voff)[_i]), (PG8_LAS unsigned*)(lds + (bufoff) + ldsw + _i * 8192), 16, 0, 0); } while (0)
; #define PG8_LDA(dst, b, h) do { _Pragma("unroll") for (int m = 0; m < 4; ++m) _Pragma("unroll") for (int k = 0; k < 2; ++k) dst[m][k] = *(const PG8_LAS bf16x8*)(lds + PG8_SA(b, h) + aoff + m * 2048 + k * 1024); } while (0)
; #define PG8_MMA(ai, bj, At, Bt) do { __builtin_amdgcn_s_setprio(1); _Pragma("unroll") for (int m = 0; m < 4; ++m) _Pragma("unroll") for (int n = 0; n < 2; ++n) _Pragma("unroll") for (int k = 0; k < 2; ++k) \
;         acc[ai][bj][m][n] = __builtin_amdgcn_mfma_f32_16x16x32_bf16(Bt[n][k], At[m][k], acc[ai][bj][m][n], 0, 0, 0); __builtin_amdgcn_s_setprio(0); } while (0)
; #define PG8_WAIT_V(n) asm volatile("s_waitcnt vmcnt(" #n ")" ::: "memory")
; #define PG8_WAIT_L(n) asm volatile("s_waitcnt lgkmcnt(" #n ")" ::: "memory")
; #define PG8_BAR __builtin_amdgcn_s_barrier()
; #define PG8_SCHED __builtin_amdgcn_sched_barrier(0)
; template <class Epi, class Sched, bool ALIGN_EPI = false, bool SP2 = false>
; __device__ __forceinline__ void gemm_phase(PG8_LAS unsigned char* lds, const Gemm g, const Sched& S, const Epi& E) {
;     ...
;             PG8_WAIT_V(8); PG8_WAIT_L(0); PG8_BAR; PG8_MMA(0, 0, At, B0); PG8_MMA(0, 1, At, B1); PG8_BAR; PG8_SCHED;
;             PG8_LDA(At, 0, 1); PG8_STAGE(PG8_SB(0, 0), b2, voffB); PG8_STAGE(PG8_SB(0, 1), b2 + hstep, voffB); PG8_STAGE(PG8_SA(0, 0), a2, voffA);
;             PG8_WAIT_V(8); PG8_WAIT_L(0); PG8_BAR; PG8_MMA(1, 0, At, B0); PG8_MMA(1, 1, At, B1); PG8_BAR; PG8_SCHED;
	s_setprio 1
	s_waitcnt lgkmcnt(0)
	v_mfma_f32_16x16x32_bf16 v[170:173], v[74:77], v[138:141], v[170:173]
	v_mfma_f32_16x16x32_bf16 v[166:169], v[90:93], v[138:141], v[166:169]
	v_mfma_f32_16x16x32_bf16 v[146:149], v[74:77], v[162:165], v[146:149]
	v_mfma_f32_16x16x32_bf16 v[142:145], v[90:93], v[162:165], v[142:145]
	v_mfma_f32_16x16x32_bf16 v[122:125], v[74:77], v[178:181], v[122:125]
	v_mfma_f32_16x16x32_bf16 v[118:121], v[90:93], v[178:181], v[118:121]
	v_mfma_f32_16x16x32_bf16 v[86:89], v[74:77], v[186:189], v[86:89]
	v_mfma_f32_16x16x32_bf16 v[78:81], v[90:93], v[186:189], v[78:81]
	v_mfma_f32_16x16x32_bf16 v[170:173], v[82:85], v[150:153], v[170:173]
	v_mfma_f32_16x16x32_bf16 v[166:169], v[94:97], v[150:153], v[166:169]
	v_mfma_f32_16x16x32_bf16 v[146:149], v[82:85], v[174:177], v[146:149]
	v_mfma_f32_16x16x32_bf16 v[142:145], v[94:97], v[174:177], v[142:145]
	v_mfma_f32_16x16x32_bf16 v[122:125], v[82:85], v[182:185], v[122:125]
	v_mfma_f32_16x16x32_bf16 v[118:121], v[94:97], v[182:185], v[118:121]
	v_mfma_f32_16x16x32_bf16 v[86:89], v[82:85], v[190:193], v[86:89]
	v_mfma_f32_16x16x32_bf16 v[78:81], v[94:97], v[190:193], v[78:81]
	s_setprio 0
	s_setprio 1
	v_mfma_f32_16x16x32_bf16 v[158:161], v[98:101], v[138:141], v[158:161]
	v_mfma_f32_16x16x32_bf16 v[134:137], v[98:101], v[162:165], v[134:137]
	v_mfma_f32_16x16x32_bf16 v[126:129], v[114:117], v[162:165], v[126:129]
	v_mfma_f32_16x16x32_bf16 v[106:109], v[98:101], v[178:181], v[106:109]
	v_mfma_f32_16x16x32_bf16 v[102:105], v[114:117], v[178:181], v[102:105]
	v_mfma_f32_16x16x32_bf16 v[70:73], v[98:101], v[186:189], v[70:73]
	v_mfma_f32_16x16x32_bf16 v[66:69], v[114:117], v[186:189], v[66:69]
	v_mfma_f32_16x16x32_bf16 v[158:161], v[110:113], v[150:153], v[158:161]
	v_mfma_f32_16x16x32_bf16 v[138:141], v[114:117], v[138:141], v[154:157]
	v_mfma_f32_16x16x32_bf16 v[134:137], v[110:113], v[174:177], v[134:137]
	v_mfma_f32_16x16x32_bf16 v[126:129], v[130:133], v[174:177], v[126:129]
	v_mfma_f32_16x16x32_bf16 v[106:109], v[110:113], v[182:185], v[106:109]
	v_mfma_f32_16x16x32_bf16 v[102:105], v[130:133], v[182:185], v[102:105]
	v_mfma_f32_16x16x32_bf16 v[70:73], v[110:113], v[190:193], v[70:73]
	v_mfma_f32_16x16x32_bf16 v[66:69], v[130:133], v[190:193], v[66:69]
	v_mfma_f32_16x16x32_bf16 v[138:141], v[130:133], v[150:153], v[138:141]
	s_setprio 0
	s_barrier
	s_add_i32 s52, s52, s30
	v_lshl_add_u64 v[194:195], s[16:17], 0, v[206:207]
	s_mov_b32 m0, s52
	ds_read_b128 v[150:153], v245 offset:16384
	ds_read_b128 v[154:157], v245 offset:17408
	ds_read_b128 v[162:165], v245 offset:18432
	ds_read_b128 v[174:177], v245 offset:19456
	ds_read_b128 v[178:181], v245 offset:20480
	ds_read_b128 v[182:185], v245 offset:21504
	ds_read_b128 v[186:189], v245 offset:22528
	ds_read_b128 v[190:193], v245 offset:23552
	global_load_lds_dwordx4 v[194:195], off
	s_add_i32 m0, s52, 0x2000
	s_add_u32 s52, s16, 0x20000
	v_lshl_add_u64 v[196:197], s[16:17], 0, v[202:203]
	s_addc_u32 s53, s17, 0
	s_add_i32 s61, s61, s30
	global_load_lds_dwordx4 v[196:197], off
	v_lshl_add_u64 v[198:199], s[52:53], 0, v[206:207]
	s_mov_b32 m0, s61
	v_lshl_add_u64 v[200:201], s[24:25], 0, v[204:205]
	global_load_lds_dwordx4 v[198:199], off
	v_lshl_add_u64 v[198:199], s[52:53], 0, v[202:203]
	s_add_i32 m0, s61, 0x2000
	s_nop 0
	global_load_lds_dwordx4 v[198:199], off
	v_lshl_add_u64 v[198:199], s[24:25], 0, v[208:209]
	s_mov_b32 m0, s31
	s_nop 0
	global_load_lds_dwordx4 v[198:199], off
	s_mov_b32 m0, s34
	s_nop 0
	global_load_lds_dwordx4 v[200:201], off
	s_waitcnt vmcnt(8)
	s_waitcnt lgkmcnt(0)
	s_barrier
	s_setprio 1
	s_waitcnt lgkmcnt(0)
	v_mfma_f32_16x16x32_bf16 v[62:65], v[74:77], v[150:153], v[62:65]
	v_mfma_f32_16x16x32_bf16 v[58:61], v[90:93], v[150:153], v[58:61]
	v_mfma_f32_16x16x32_bf16 v[46:49], v[74:77], v[162:165], v[46:49]
	v_mfma_f32_16x16x32_bf16 v[42:45], v[90:93], v[162:165], v[42:45]
	v_mfma_f32_16x16x32_bf16 v[30:33], v[74:77], v[178:181], v[30:33]
	v_mfma_f32_16x16x32_bf16 v[26:29], v[90:93], v[178:181], v[26:29]
	v_mfma_f32_16x16x32_bf16 v[14:17], v[74:77], v[186:189], v[14:17]
	v_mfma_f32_16x16x32_bf16 v[10:13], v[90:93], v[186:189], v[10:13]
	v_mfma_f32_16x16x32_bf16 v[62:65], v[82:85], v[154:157], v[62:65]
	v_mfma_f32_16x16x32_bf16 v[58:61], v[94:97], v[154:157], v[58:61]
	v_mfma_f32_16x16x32_bf16 v[46:49], v[82:85], v[174:177], v[46:49]
	v_mfma_f32_16x16x32_bf16 v[42:45], v[94:97], v[174:177], v[42:45]
	v_mfma_f32_16x16x32_bf16 v[30:33], v[82:85], v[182:185], v[30:33]
	v_mfma_f32_16x16x32_bf16 v[26:29], v[94:97], v[182:185], v[26:29]
	v_mfma_f32_16x16x32_bf16 v[14:17], v[82:85], v[190:193], v[14:17]
	v_mfma_f32_16x16x32_bf16 v[10:13], v[94:97], v[190:193], v[10:13]
	s_setprio 0
	s_setprio 1
	v_mfma_f32_16x16x32_bf16 v[54:57], v[98:101], v[150:153], v[54:57]
	v_mfma_f32_16x16x32_bf16 v[50:53], v[114:117], v[150:153], v[50:53]
	v_mfma_f32_16x16x32_bf16 v[38:41], v[98:101], v[162:165], v[38:41]
	v_mfma_f32_16x16x32_bf16 v[34:37], v[114:117], v[162:165], v[34:37]
	v_mfma_f32_16x16x32_bf16 v[22:25], v[98:101], v[178:181], v[22:25]
	v_mfma_f32_16x16x32_bf16 v[18:21], v[114:117], v[178:181], v[18:21]
	v_mfma_f32_16x16x32_bf16 v[6:9], v[98:101], v[186:189], v[6:9]
	v_mfma_f32_16x16x32_bf16 v[2:5], v[114:117], v[186:189], v[2:5]
	v_mfma_f32_16x16x32_bf16 v[54:57], v[110:113], v[154:157], v[54:57]
	v_mfma_f32_16x16x32_bf16 v[50:53], v[130:133], v[154:157], v[50:53]
	v_mfma_f32_16x16x32_bf16 v[38:41], v[110:113], v[174:177], v[38:41]
	v_mfma_f32_16x16x32_bf16 v[34:37], v[130:133], v[174:177], v[34:37]
	v_mfma_f32_16x16x32_bf16 v[22:25], v[110:113], v[182:185], v[22:25]
	v_mfma_f32_16x16x32_bf16 v[18:21], v[130:133], v[182:185], v[18:21]
	v_mfma_f32_16x16x32_bf16 v[6:9], v[110:113], v[190:193], v[6:9]
	v_mfma_f32_16x16x32_bf16 v[2:5], v[130:133], v[190:193], v[2:5]
	s_setprio 0
	s_barrier
; #define PG8_STAGE(bufoff, gbase, voff) do { _Pragma("unroll") for (int _i = 0; _i < 2; ++_i) \
;         __builtin_amdgcn_global_load_lds((const unsigned*)((const char*)(gbase) + (voff)[_i]), (PG8_LAS unsigned*)(lds + (bufoff) + ldsw + _i * 8192), 16, 0, 0); } while (0)
; #define PG8_LDA(dst, b, h) do { _Pragma("unroll") for (int m = 0; m < 4; ++m) _Pragma("unroll") for (int k = 0; k < 2; ++k) dst[m][k] = *(const PG8_LAS bf16x8*)(lds + PG8_SA(b, h) + aoff + m * 2048 + k * 1024); } while (0)
; #define PG8_LDB(dst, b, h) do { _Pragma("unroll") for (int n = 0; n < 2; ++n) _Pragma("unroll") for (int k = 0; k < 2; ++k) dst[n][k] = *(const PG8_LAS bf16x8*)(lds + PG8_SB(b, h) + boff + n * 2048 + k * 1024); } while (0)
; #define PG8_MMA(ai, bj, At, Bt) do { __builtin_amdgcn_s_setprio(1); _Pragma("unroll") for (int m = 0; m < 4; ++m) _Pragma("unroll") for (int n = 0; n < 2; ++n) _Pragma("unroll") for (int k = 0; k < 2; ++k) \
;         acc[ai][bj][m][n] = __builtin_amdgcn_mfma_f32_16x16x32_bf16(Bt[n][k], At[m][k], acc[ai][bj][m][n], 0, 0, 0); __builtin_amdgcn_s_setprio(0); } while (0)
; #define PG8_WAIT_V(n) asm volatile("s_waitcnt vmcnt(" #n ")" ::: "memory")
; #define PG8_WAIT_L(n) asm volatile("s_waitcnt lgkmcnt(" #n ")" ::: "memory")
; #define PG8_BAR __builtin_amdgcn_s_barrier()
; #define PG8_SCHED __builtin_amdgcn_sched_barrier(0)
; template <class Epi, class Sched, bool ALIGN_EPI = false, bool SP2 = false>
; __device__ __forceinline__ void gemm_phase(PG8_LAS unsigned char* lds, const Gemm g, const Sched& S, const Epi& E) {
;     ...
;             PG8_LDB(B0, 1, 0); PG8_LDB(B1, 1, 1); PG8_SCHED; PG8_LDA(At, 1, 0); PG8_STAGE(PG8_SA(0, 1), a2 + hstep, voffA);
;             PG8_WAIT_V(8); PG8_WAIT_L(0); PG8_BAR; PG8_MMA(0, 0, At, B0); PG8_MMA(0, 1, At, B1); PG8_BAR; PG8_SCHED;
;             PG8_LDA(At, 1, 1); PG8_STAGE(PG8_SB(1, 0), b3, voffB); PG8_STAGE(PG8_SB(1, 1), b3 + hstep, voffB); PG8_STAGE(PG8_SA(1, 0), a3, voffA);
;             PG8_WAIT_V(8); PG8_WAIT_L(0); PG8_BAR; PG8_MMA(1, 0, At, B0); PG8_MMA(1, 1, At, B1); PG8_BAR; PG8_SCHED;
	s_add_i32 s52, 0, 0x18000
	v_add_u32_e32 v0, s52, v244
	s_add_i32 s53, 0, 0x1c000
	ds_read_b128 v[74:77], v0
	ds_read_b128 v[82:85], v0 offset:1024
	ds_read_b128 v[90:93], v0 offset:2048
	ds_read_b128 v[94:97], v0 offset:3072
	v_add_u32_e32 v0, s53, v244
	ds_read_b128 v[98:101], v0
	ds_read_b128 v[110:113], v0 offset:1024
	ds_read_b128 v[114:117], v0 offset:2048
	ds_read_b128 v[130:133], v0 offset:3072
	s_add_u32 s24, s24, 0x20000
	s_addc_u32 s25, s25, 0
	s_mov_b32 m0, s35
	v_lshl_add_u64 v[212:213], s[24:25], 0, v[208:209]
	ds_read_b128 v[150:153], v245 offset:32768
	ds_read_b128 v[154:157], v245 offset:33792
	ds_read_b128 v[162:165], v245 offset:34816
	ds_read_b128 v[174:177], v245 offset:35840
	ds_read_b128 v[178:181], v245 offset:36864
	ds_read_b128 v[182:185], v245 offset:37888
	ds_read_b128 v[186:189], v245 offset:38912
	ds_read_b128 v[190:193], v245 offset:39936
	global_load_lds_dwordx4 v[212:213], off
	v_lshl_add_u64 v[212:213], s[24:25], 0, v[204:205]
	s_mov_b32 m0, s36
	s_nop 0
	global_load_lds_dwordx4 v[212:213], off
	s_waitcnt vmcnt(8)
	s_waitcnt lgkmcnt(0)
	s_barrier
	s_setprio 1
	s_waitcnt lgkmcnt(0)
	v_mfma_f32_16x16x32_bf16 v[170:173], v[74:77], v[150:153], v[170:173]
	v_mfma_f32_16x16x32_bf16 v[166:169], v[90:93], v[150:153], v[166:169]
	v_mfma_f32_16x16x32_bf16 v[146:149], v[74:77], v[162:165], v[146:149]
	v_mfma_f32_16x16x32_bf16 v[142:145], v[90:93], v[162:165], v[142:145]
	v_mfma_f32_16x16x32_bf16 v[122:125], v[74:77], v[178:181], v[122:125]
	v_mfma_f32_16x16x32_bf16 v[118:121], v[90:93], v[178:181], v[118:121]
	v_mfma_f32_16x16x32_bf16 v[86:89], v[74:77], v[186:189], v[86:89]
	v_mfma_f32_16x16x32_bf16 v[78:81], v[90:93], v[186:189], v[78:81]
	v_mfma_f32_16x16x32_bf16 v[170:173], v[82:85], v[154:157], v[170:173]
	v_mfma_f32_16x16x32_bf16 v[166:169], v[94:97], v[154:157], v[166:169]
	v_mfma_f32_16x16x32_bf16 v[146:149], v[82:85], v[174:177], v[146:149]
	v_mfma_f32_16x16x32_bf16 v[142:145], v[94:97], v[174:177], v[142:145]
	v_mfma_f32_16x16x32_bf16 v[122:125], v[82:85], v[182:185], v[122:125]
	v_mfma_f32_16x16x32_bf16 v[118:121], v[94:97], v[182:185], v[118:121]
	v_mfma_f32_16x16x32_bf16 v[86:89], v[82:85], v[190:193], v[86:89]
	v_mfma_f32_16x16x32_bf16 v[78:81], v[94:97], v[190:193], v[78:81]
	s_setprio 0
	s_setprio 1
	v_mfma_f32_16x16x32_bf16 v[158:161], v[98:101], v[150:153], v[158:161]
	v_mfma_f32_16x16x32_bf16 v[138:141], v[114:117], v[150:153], v[138:141]
	v_mfma_f32_16x16x32_bf16 v[134:137], v[98:101], v[162:165], v[134:137]
	v_mfma_f32_16x16x32_bf16 v[126:129], v[114:117], v[162:165], v[126:129]
	v_mfma_f32_16x16x32_bf16 v[106:109], v[98:101], v[178:181], v[106:109]
	v_mfma_f32_16x16x32_bf16 v[102:105], v[114:117], v[178:181], v[102:105]
	v_mfma_f32_16x16x32_bf16 v[70:73], v[98:101], v[186:189], v[70:73]
	v_mfma_f32_16x16x32_bf16 v[66:69], v[114:117], v[186:189], v[66:69]
	v_mfma_f32_16x16x32_bf16 v[158:161], v[110:113], v[154:157], v[158:161]
	v_mfma_f32_16x16x32_bf16 v[154:157], v[130:133], v[154:157], v[138:141]
	v_mfma_f32_16x16x32_bf16 v[134:137], v[110:113], v[174:177], v[134:137]
	v_mfma_f32_16x16x32_bf16 v[126:129], v[130:133], v[174:177], v[126:129]
	v_mfma_f32_16x16x32_bf16 v[106:109], v[110:113], v[182:185], v[106:109]
	v_mfma_f32_16x16x32_bf16 v[102:105], v[130:133], v[182:185], v[102:105]
	v_mfma_f32_16x16x32_bf16 v[70:73], v[110:113], v[190:193], v[70:73]
	v_mfma_f32_16x16x32_bf16 v[66:69], v[130:133], v[190:193], v[66:69]
	s_setprio 0
	s_barrier
	s_add_i32 s24, s52, s30
	v_lshl_add_u64 v[194:195], v[194:195], 0, s[94:95]
	s_mov_b32 m0, s24
	ds_read_b128 v[138:141], v245 offset:49152
	ds_read_b128 v[150:153], v245 offset:50176
	ds_read_b128 v[162:165], v245 offset:51200
	ds_read_b128 v[174:177], v245 offset:52224
	ds_read_b128 v[178:181], v245 offset:53248
	ds_read_b128 v[182:185], v245 offset:54272
	ds_read_b128 v[186:189], v245 offset:55296
	ds_read_b128 v[190:193], v245 offset:56320
	global_load_lds_dwordx4 v[194:195], off
	s_add_i32 m0, s24, 0x2000
	s_add_u32 s16, s16, 0x20080
	v_lshl_add_u64 v[194:195], v[196:197], 0, s[94:95]
	s_addc_u32 s17, s17, 0
	s_add_i32 s24, s53, s30
	global_load_lds_dwordx4 v[194:195], off
	v_lshl_add_u64 v[194:195], s[16:17], 0, v[206:207]
	s_mov_b32 m0, s24
	s_nop 0
	global_load_lds_dwordx4 v[194:195], off
	v_lshl_add_u64 v[194:195], s[16:17], 0, v[202:203]
	s_add_i32 m0, s24, 0x2000
	s_nop 0
	global_load_lds_dwordx4 v[194:195], off
	v_lshl_add_u64 v[194:195], v[198:199], 0, s[94:95]
	s_mov_b32 m0, s37
	s_nop 0
	global_load_lds_dwordx4 v[194:195], off
	v_lshl_add_u64 v[194:195], v[200:201], 0, s[94:95]
	s_mov_b32 m0, s38
	s_nop 0
	global_load_lds_dwordx4 v[194:195], off
	s_waitcnt vmcnt(8)
	s_waitcnt lgkmcnt(0)
	s_barrier
;     __device__ __forceinline__ void operator()(const f32x4 (&acc)[2][2][4][2], const Unit& u, int wr, int wc, int fr, int fq) const {
;         u32x4 y[2][4][2]; f32x4 bb[2][2];
;         _Pragma("unroll") for (int bj = 0; bj < 2; ++bj) { const int col = u.pn * BM + EPI_CT(bj); bb[bj][0] = *(const f32x4*)(bias + col); bb[bj][1] = *(const f32x4*)(bias + col + 4); }
;         _Pragma("unroll") for (int ai = 0; ai < 2; ++ai) _Pragma("unroll") for (int m = 0; m < 4; ++m) _Pragma("unroll") for (int bj = 0; bj < 2; ++bj)
;             y[ai][m][bj] = *(const u32x4*)(YB + (size_t)EPI_ROW(ai, m) * 512 + u.pn * BM + EPI_CT(bj));
;         _Pragma("unroll") for (int ai = 0; ai < 2; ++ai) _Pragma("unroll") for (int m = 0; m < 4; ++m) _Pragma("unroll") for (int bj = 0; bj < 2; ++bj) {
;             f32x4 v0 = acc[ai][bj][m][0] + bb[bj][0], v1 = acc[ai][bj][m][1] + bb[bj][1]; const u32x4 yy = y[ai][m][bj]; EPI_SIG(v0, v1);
;             v0[0] *= bf_lo(yy.x); v0[1] *= bf_hi(yy.x); v0[2] *= bf_lo(yy.y); v0[3] *= bf_hi(yy.y); v1[0] *= bf_lo(yy.z); v1[1] *= bf_hi(yy.z); v1[2] *= bf_lo(yy.w); v1[3] *= bf_hi(yy.w);
;             *(u32x4*)(O + (size_t)EPI_ROW(ai, m) * 512 + u.pn * BM + EPI_CT(bj)) = pack8(v0, v1); }
; template <class Epi, class Sched, bool ALIGN_EPI = false, bool SP2 = false>
; __device__ __forceinline__ void gemm_phase(PG8_LAS unsigned char* lds, const Gemm g, const Sched& S, const Epi& E) {
;     ...
;             PG8_WAIT_V(8); PG8_WAIT_L(0); PG8_BAR; PG8_MMA(1, 0, At, B0); PG8_MMA(1, 1, At, B1); PG8_BAR; PG8_SCHED;
;             } else {
;             PG8_LDB(B0, 0, 0); PG8_SCHED; PG8_LDA(At, 0, 0); PG8_STAGE(PG8_SA(1, 1), a1 + hstep, voffA);
;             PG8_WAIT_L(8); PG8_BAR; PG8_WAIT_L(0); PG8_MMA(0, 0, At, B0); PG8_BAR; PG8_SCHED;
;             PG8_LDB(B1, 0, 1); PG8_STAGE(PG8_SB(0, 0), b2, voffB);
;             PG8_BAR; PG8_WAIT_L(0); PG8_MMA(0, 1, At, B1); PG8_BAR;
;             PG8_LDA(At, 0, 1); PG8_STAGE(PG8_SA(0, 0), a2, voffA);
;             PG8_BAR; PG8_WAIT_L(0); PG8_MMA(1, 0, At, B0); PG8_BAR; PG8_SCHED;
;             PG8_STAGE(PG8_SB(0, 1), b2 + hstep, voffB);
;             PG8_WAIT_V(6); PG8_BAR; PG8_MMA(1, 1, At, B1); PG8_BAR;
;             PG8_LDB(B0, 1, 0); PG8_SCHED; PG8_LDA(At, 1, 0); PG8_STAGE(PG8_SA(0, 1), a2 + hstep, voffA);
;             PG8_WAIT_L(8); PG8_BAR; PG8_WAIT_L(0); PG8_MMA(0, 0, At, B0); PG8_BAR; PG8_SCHED;
	s_setprio 1
	s_waitcnt lgkmcnt(0)
	v_mfma_f32_16x16x32_bf16 v[62:65], v[74:77], v[138:141], v[62:65]
	v_mfma_f32_16x16x32_bf16 v[58:61], v[90:93], v[138:141], v[58:61]
	v_mfma_f32_16x16x32_bf16 v[46:49], v[74:77], v[162:165], v[46:49]
	v_mfma_f32_16x16x32_bf16 v[42:45], v[90:93], v[162:165], v[42:45]
	v_mfma_f32_16x16x32_bf16 v[30:33], v[74:77], v[178:181], v[30:33]
	v_mfma_f32_16x16x32_bf16 v[26:29], v[90:93], v[178:181], v[26:29]
	v_mfma_f32_16x16x32_bf16 v[14:17], v[74:77], v[186:189], v[14:17]
	v_mfma_f32_16x16x32_bf16 v[10:13], v[90:93], v[186:189], v[10:13]
	v_mfma_f32_16x16x32_bf16 v[62:65], v[82:85], v[150:153], v[62:65]
	v_mfma_f32_16x16x32_bf16 v[58:61], v[94:97], v[150:153], v[58:61]
	v_mfma_f32_16x16x32_bf16 v[46:49], v[82:85], v[174:177], v[46:49]
	v_mfma_f32_16x16x32_bf16 v[42:45], v[94:97], v[174:177], v[42:45]
	v_mfma_f32_16x16x32_bf16 v[30:33], v[82:85], v[182:185], v[30:33]
	v_mfma_f32_16x16x32_bf16 v[26:29], v[94:97], v[182:185], v[26:29]
	v_mfma_f32_16x16x32_bf16 v[14:17], v[82:85], v[190:193], v[14:17]
	v_mfma_f32_16x16x32_bf16 v[10:13], v[94:97], v[190:193], v[10:13]
	s_setprio 0
	s_setprio 1
	v_mfma_f32_16x16x32_bf16 v[54:57], v[98:101], v[138:141], v[54:57]
	v_mfma_f32_16x16x32_bf16 v[50:53], v[114:117], v[138:141], v[50:53]
	v_mfma_f32_16x16x32_bf16 v[38:41], v[98:101], v[162:165], v[38:41]
	v_mfma_f32_16x16x32_bf16 v[34:37], v[114:117], v[162:165], v[34:37]
	v_mfma_f32_16x16x32_bf16 v[22:25], v[98:101], v[178:181], v[22:25]
	v_mfma_f32_16x16x32_bf16 v[18:21], v[114:117], v[178:181], v[18:21]
	v_mfma_f32_16x16x32_bf16 v[6:9], v[98:101], v[186:189], v[6:9]
	v_mfma_f32_16x16x32_bf16 v[2:5], v[114:117], v[186:189], v[2:5]
	v_mfma_f32_16x16x32_bf16 v[54:57], v[110:113], v[150:153], v[54:57]
	v_mfma_f32_16x16x32_bf16 v[50:53], v[130:133], v[150:153], v[50:53]
	v_mfma_f32_16x16x32_bf16 v[38:41], v[110:113], v[174:177], v[38:41]
	v_mfma_f32_16x16x32_bf16 v[34:37], v[130:133], v[174:177], v[34:37]
	v_mfma_f32_16x16x32_bf16 v[22:25], v[110:113], v[182:185], v[22:25]
	v_mfma_f32_16x16x32_bf16 v[18:21], v[130:133], v[182:185], v[18:21]
	v_mfma_f32_16x16x32_bf16 v[6:9], v[110:113], v[190:193], v[6:9]
	v_mfma_f32_16x16x32_bf16 v[2:5], v[130:133], v[190:193], v[2:5]
	s_setprio 0
	s_barrier
	s_add_i32 s50, s50, 2
	s_add_u32 s22, s22, 0x100
	s_addc_u32 s23, s23, 0
	s_add_u32 s57, s57, 0x100
	s_addc_u32 s60, s60, 0
	s_cmp_gt_u32 s50, 5
	s_cbranch_scc0 .LBB0_547
	s_and_b64 vcc, exec, s[10:11]
	s_cbranch_vccz .LBB0_550
	s_barrier
.LBB0_550:
	s_lshl_b32 s16, s46, 8
	v_or_b32_e32 v74, s16, v210
	v_ashrrev_i32_e32 v75, 31, v74
	v_lshl_add_u64 v[74:75], v[74:75], 2, s[6:7]
	global_load_dwordx4 v[90:93], v[74:75], off
	global_load_dwordx4 v[82:85], v[74:75], off offset:16
	s_ashr_i32 s17, s16, 31
	v_lshl_add_u32 v76, s33, 8, v211
	s_lshl_b64 s[22:23], s[16:17], 1
	v_ashrrev_i32_e32 v77, 31, v76
	s_add_u32 s16, s26, s22
	v_lshlrev_b64 v[216:217], 10, v[76:77]
	s_addc_u32 s17, s27, s23
	v_lshlrev_b32_e32 v0, 1, v210
	v_or_b32_e32 v94, 16, v76
	v_or_b32_e32 v96, 32, v76
	v_or_b32_e32 v98, 48, v76
	v_add_u32_e32 v100, 0x80, v76
	v_add_u32_e32 v110, 0x90, v76
	v_add_u32_e32 v112, 0xa0, v76
	v_add_u32_e32 v114, 0xb0, v76
	v_lshl_add_u64 v[76:77], s[16:17], 0, v[216:217]
	v_lshl_add_u64 v[76:77], v[76:77], 0, v[0:1]
	global_load_dwordx4 v[212:215], v[76:77], off
	v_ashrrev_i32_e32 v95, 31, v94
	v_ashrrev_i32_e32 v97, 31, v96
	v_ashrrev_i32_e32 v99, 31, v98
	v_ashrrev_i32_e32 v101, 31, v100
	v_lshlrev_b64 v[236:237], 10, v[94:95]
	v_lshlrev_b64 v[234:235], 10, v[96:97]
	v_lshlrev_b64 v[232:233], 10, v[98:99]
	v_lshlrev_b64 v[230:231], 10, v[100:101]
	global_load_dwordx4 v[94:97], v[74:75], off offset:528
	global_load_dwordx4 v[98:101], v[74:75], off offset:512
	v_ashrrev_i32_e32 v111, 31, v110
	v_ashrrev_i32_e32 v113, 31, v112
	v_ashrrev_i32_e32 v115, 31, v114
	v_lshlrev_b64 v[228:229], 10, v[110:111]
	v_lshlrev_b64 v[226:227], 10, v[112:113]
	v_lshlrev_b64 v[224:225], 10, v[114:115]
	v_lshl_add_u64 v[74:75], s[16:17], 0, v[236:237]
	v_lshl_add_u64 v[110:111], s[16:17], 0, v[234:235]
	v_lshl_add_u64 v[112:113], s[16:17], 0, v[232:233]
	v_lshl_add_u64 v[114:115], s[16:17], 0, v[230:231]
	v_lshl_add_u64 v[116:117], s[16:17], 0, v[228:229]
	v_lshl_add_u64 v[130:131], s[16:17], 0, v[226:227]
	v_lshl_add_u64 v[132:133], s[16:17], 0, v[224:225]
	v_lshl_add_u64 v[74:75], v[74:75], 0, v[0:1]
	v_lshl_add_u64 v[110:111], v[110:111], 0, v[0:1]
	v_lshl_add_u64 v[112:113], v[112:113], 0, v[0:1]
	v_lshl_add_u64 v[114:115], v[114:115], 0, v[0:1]
	v_lshl_add_u64 v[116:117], v[116:117], 0, v[0:1]
	v_lshl_add_u64 v[218:219], v[130:131], 0, v[0:1]
	v_lshl_add_u64 v[238:239], v[132:133], 0, v[0:1]
	global_load_dwordx4 v[246:249], v[76:77], off offset:256
	global_load_dwordx4 v[198:201], v[74:75], off
	global_load_dwordx4 v[194:197], v[74:75], off offset:256
	global_load_dwordx4 v[190:193], v[110:111], off
	global_load_dwordx4 v[186:189], v[110:111], off offset:256
	global_load_dwordx4 v[182:185], v[112:113], off
	global_load_dwordx4 v[178:181], v[112:113], off offset:256
	global_load_dwordx4 v[174:177], v[114:115], off
	global_load_dwordx4 v[162:165], v[114:115], off offset:256
	global_load_dwordx4 v[150:153], v[116:117], off
	global_load_dwordx4 v[138:141], v[116:117], off offset:256
	global_load_dwordx4 v[130:133], v[218:219], off
	s_nop 0
	global_load_dwordx4 v[114:117], v[218:219], off offset:256
	global_load_dwordx4 v[110:113], v[238:239], off
	global_load_dwordx4 v[74:77], v[238:239], off offset:256
	s_andn2_b64 vcc, exec, s[4:5]
	s_mov_b64 s[4:5], -1
	s_waitcnt vmcnt(0)
; __device__ __forceinline__ u32x4 pack8(const f32x4 v0, const f32x4 v1) { u32x4 w; w.x = cvt_pk_bf16(v0[0], v0[1]); w.y = cvt_pk_bf16(v0[2], v0[3]); w.z = cvt_pk_bf16(v1[0], v1[1]); w.w = cvt_pk_bf16(v1[2], v1[3]); return w; }
; __device__ __forceinline__ float bf_lo(unsigned w) { return __uint_as_float(w << 16); }
; __device__ __forceinline__ float bf_hi(unsigned w) { return __uint_as_float(w & 0xffff0000u); }
; #define EPI_SIG(v0, v1) do { _Pragma("unroll") for (int e_ = 0; e_ < 4; ++e_) { v0[e_] = sigm(v0[e_]); v1[e_] = sigm(v1[e_]); } } while (0)
;     __device__ __forceinline__ void operator()(const f32x4 (&acc)[2][2][4][2], const Unit& u, int wr, int wc, int fr, int fq) const {
;     ...
;         _Pragma("unroll") for (int ai = 0; ai < 2; ++ai) _Pragma("unroll") for (int m = 0; m < 4; ++m) _Pragma("unroll") for (int bj = 0; bj < 2; ++bj) {
;             f32x4 v0 = acc[ai][bj][m][0] + bb[bj][0], v1 = acc[ai][bj][m][1] + bb[bj][1]; const u32x4 yy = y[ai][m][bj]; EPI_SIG(v0, v1);
;             v0[0] *= bf_lo(yy.x); v0[1] *= bf_hi(yy.x); v0[2] *= bf_lo(yy.y); v0[3] *= bf_hi(yy.y); v1[0] *= bf_lo(yy.z); v1[1] *= bf_hi(yy.z); v1[2] *= bf_lo(yy.w); v1[3] *= bf_hi(yy.w);
;             *(u32x4*)(O + (size_t)EPI_ROW(ai, m) * 512 + u.pn * BM + EPI_CT(bj)) = pack8(v0, v1); }
	v_pk_add_f32 v[170:171], v[170:171], v[90:91]
	v_pk_add_f32 v[172:173], v[172:173], v[92:93]
	v_pk_add_f32 v[168:169], v[168:169], v[84:85]
	v_pk_add_f32 v[166:167], v[166:167], v[82:83]
	v_mul_f32_e32 v170, 0xbfb8aa3b, v170
	v_mul_f32_e32 v166, 0xbfb8aa3b, v166
	v_mul_f32_e32 v172, 0xbfb8aa3b, v172
	v_mul_f32_e32 v168, 0xbfb8aa3b, v168
	v_exp_f32_e32 v170, v170
	v_exp_f32_e32 v166, v166
	v_exp_f32_e32 v172, v172
	v_exp_f32_e32 v218, v168
	v_mul_f32_e32 v173, 0xbfb8aa3b, v173
	v_mul_f32_e32 v171, 0xbfb8aa3b, v171
	v_mul_f32_e32 v167, 0xbfb8aa3b, v167
	v_exp_f32_e32 v173, v173
	v_exp_f32_e32 v171, v171
	v_exp_f32_e32 v167, v167
	v_add_f32_e32 v168, 1.0, v170
	v_mul_f32_e32 v169, 0xbfb8aa3b, v169
	v_add_f32_e32 v170, 1.0, v166
	v_rcp_f32_e32 v166, v168
	v_add_f32_e32 v168, 1.0, v172
	v_add_f32_e32 v172, 1.0, v218
	v_exp_f32_e32 v218, v169
	v_add_f32_e32 v169, 1.0, v173
	v_add_f32_e32 v171, 1.0, v171
	v_add_f32_e32 v219, 1.0, v167
	v_rcp_f32_e32 v168, v168
	v_rcp_f32_e32 v169, v169
	v_rcp_f32_e32 v170, v170
	v_rcp_f32_e32 v167, v171
	v_rcp_f32_e32 v171, v219
	v_add_f32_e32 v173, 1.0, v218
	v_rcp_f32_e32 v172, v172
	v_rcp_f32_e32 v173, v173
	v_lshlrev_b32_e32 v218, 16, v212
	v_and_b32_e32 v219, 0xffff0000, v212
	v_lshlrev_b32_e32 v212, 16, v213
	v_and_b32_e32 v213, 0xffff0000, v213
	v_pk_mul_f32 v[168:169], v[168:169], v[212:213]
	v_lshlrev_b32_e32 v212, 16, v214
	v_and_b32_e32 v213, 0xffff0000, v214
	v_pk_mul_f32 v[166:167], v[166:167], v[218:219]
	v_pk_mul_f32 v[170:171], v[170:171], v[212:213]
	v_lshlrev_b32_e32 v212, 16, v215
	v_and_b32_e32 v213, 0xffff0000, v215
	v_cvt_pk_bf16_f32 v166, v166, v167
	v_cvt_pk_bf16_f32 v167, v168, v169
	v_cvt_pk_bf16_f32 v168, v170, v171
	v_lshl_add_u64 v[170:171], s[8:9], 0, v[216:217]
	v_pk_mul_f32 v[172:173], v[172:173], v[212:213]
	v_lshl_add_u64 v[170:171], v[170:171], 0, s[22:23]
	v_pk_add_f32 v[158:159], v[158:159], v[98:99]
	v_pk_add_f32 v[154:155], v[154:155], v[94:95]
	v_cvt_pk_bf16_f32 v169, v172, v173
	v_lshl_add_u64 v[170:171], v[170:171], 0, v[0:1]
	v_mul_f32_e32 v158, 0xbfb8aa3b, v158
	v_mul_f32_e32 v154, 0xbfb8aa3b, v154
	global_store_dwordx4 v[170:171], v[166:169], off
	v_exp_f32_e32 v158, v158
	v_mul_f32_e32 v159, 0xbfb8aa3b, v159
	v_exp_f32_e32 v166, v154
	v_mul_f32_e32 v155, 0xbfb8aa3b, v155
	v_add_f32_e32 v154, 1.0, v158
	v_exp_f32_e32 v159, v159
	v_add_f32_e32 v158, 1.0, v166
	v_exp_f32_e32 v166, v155
	v_pk_add_f32 v[160:161], v[160:161], v[100:101]
	v_pk_add_f32 v[156:157], v[156:157], v[96:97]
	v_mul_f32_e32 v160, 0xbfb8aa3b, v160
	v_mul_f32_e32 v156, 0xbfb8aa3b, v156
	v_add_f32_e32 v155, 1.0, v159
	v_add_f32_e32 v159, 1.0, v166
	v_exp_f32_e32 v160, v160
	v_exp_f32_e32 v166, v156
	v_mul_f32_e32 v161, 0xbfb8aa3b, v161
	v_exp_f32_e32 v161, v161
	v_mul_f32_e32 v157, 0xbfb8aa3b, v157
	v_add_f32_e32 v156, 1.0, v160
	v_add_f32_e32 v160, 1.0, v166
	v_exp_f32_e32 v166, v157
	v_rcp_f32_e32 v154, v154
	v_rcp_f32_e32 v155, v155
	v_add_f32_e32 v157, 1.0, v161
	v_rcp_f32_e32 v156, v156
	v_rcp_f32_e32 v157, v157
	v_rcp_f32_e32 v158, v158
	v_rcp_f32_e32 v159, v159
	v_add_f32_e32 v161, 1.0, v166
	v_rcp_f32_e32 v160, v160
	v_rcp_f32_e32 v161, v161
	v_lshlrev_b32_e32 v166, 16, v246
	v_and_b32_e32 v167, 0xffff0000, v246
	v_pk_mul_f32 v[154:155], v[154:155], v[166:167]
	v_lshlrev_b32_e32 v166, 16, v247
	v_and_b32_e32 v167, 0xffff0000, v247
	v_pk_mul_f32 v[156:157], v[156:157], v[166:167]
	v_lshlrev_b32_e32 v166, 16, v248
	v_and_b32_e32 v167, 0xffff0000, v248
	v_pk_mul_f32 v[158:159], v[158:159], v[166:167]
	v_lshlrev_b32_e32 v166, 16, v249
	v_and_b32_e32 v167, 0xffff0000, v249
	v_pk_mul_f32 v[160:161], v[160:161], v[166:167]
	v_pk_add_f32 v[146:147], v[146:147], v[90:91]
	v_pk_add_f32 v[142:143], v[142:143], v[82:83]
	v_cvt_pk_bf16_f32 v154, v154, v155
	v_cvt_pk_bf16_f32 v155, v156, v157
	v_cvt_pk_bf16_f32 v156, v158, v159
	v_cvt_pk_bf16_f32 v157, v160, v161
	v_mul_f32_e32 v146, 0xbfb8aa3b, v146
	v_mul_f32_e32 v142, 0xbfb8aa3b, v142
	global_store_dwordx4 v[170:171], v[154:157], off offset:256
	v_exp_f32_e32 v146, v146
	v_mul_f32_e32 v147, 0xbfb8aa3b, v147
	v_exp_f32_e32 v154, v142
	v_mul_f32_e32 v143, 0xbfb8aa3b, v143
	v_add_f32_e32 v142, 1.0, v146
	v_exp_f32_e32 v147, v147
	v_add_f32_e32 v146, 1.0, v154
	v_exp_f32_e32 v154, v143
	v_pk_add_f32 v[148:149], v[148:149], v[92:93]
	v_pk_add_f32 v[144:145], v[144:145], v[84:85]
	v_mul_f32_e32 v148, 0xbfb8aa3b, v148
	v_mul_f32_e32 v144, 0xbfb8aa3b, v144
	v_add_f32_e32 v143, 1.0, v147
	v_add_f32_e32 v147, 1.0, v154
	v_exp_f32_e32 v148, v148
	v_exp_f32_e32 v154, v144
	v_mul_f32_e32 v149, 0xbfb8aa3b, v149
	v_exp_f32_e32 v149, v149
	v_mul_f32_e32 v145, 0xbfb8aa3b, v145
	v_add_f32_e32 v144, 1.0, v148
	v_add_f32_e32 v148, 1.0, v154
	v_exp_f32_e32 v154, v145
	v_rcp_f32_e32 v142, v142
	v_rcp_f32_e32 v143, v143
	v_add_f32_e32 v145, 1.0, v149
	v_rcp_f32_e32 v144, v144
	v_rcp_f32_e32 v145, v145
	v_rcp_f32_e32 v146, v146
	v_rcp_f32_e32 v147, v147
	v_add_f32_e32 v149, 1.0, v154
	v_lshlrev_b32_e32 v154, 16, v198
	v_and_b32_e32 v155, 0xffff0000, v198
	v_rcp_f32_e32 v148, v148
	v_rcp_f32_e32 v149, v149
	v_pk_mul_f32 v[142:143], v[142:143], v[154:155]
	v_lshlrev_b32_e32 v154, 16, v199
	v_and_b32_e32 v155, 0xffff0000, v199
	v_pk_mul_f32 v[144:145], v[144:145], v[154:155]
	v_lshlrev_b32_e32 v154, 16, v200
	v_and_b32_e32 v155, 0xffff0000, v200
	v_pk_mul_f32 v[146:147], v[146:147], v[154:155]
	v_lshlrev_b32_e32 v154, 16, v201
	v_and_b32_e32 v155, 0xffff0000, v201
	v_cvt_pk_bf16_f32 v142, v142, v143
	v_cvt_pk_bf16_f32 v143, v144, v145
	v_cvt_pk_bf16_f32 v144, v146, v147
	v_lshl_add_u64 v[146:147], s[8:9], 0, v[236:237]
	v_pk_mul_f32 v[148:149], v[148:149], v[154:155]
; __device__ __forceinline__ u32x4 pack8(const f32x4 v0, const f32x4 v1) { u32x4 w; w.x = cvt_pk_bf16(v0[0], v0[1]); w.y = cvt_pk_bf16(v0[2], v0[3]); w.z = cvt_pk_bf16(v1[0], v1[1]); w.w = cvt_pk_bf16(v1[2], v1[3]); return w; }
; __device__ __forceinline__ float bf_lo(unsigned w) { return __uint_as_float(w << 16); }
; __device__ __forceinline__ float bf_hi(unsigned w) { return __uint_as_float(w & 0xffff0000u); }
; #define EPI_SIG(v0, v1) do { _Pragma("unroll") for (int e_ = 0; e_ < 4; ++e_) { v0[e_] = sigm(v0[e_]); v1[e_] = sigm(v1[e_]); } } while (0)
;     __device__ __forceinline__ void operator()(const f32x4 (&acc)[2][2][4][2], const Unit& u, int wr, int wc, int fr, int fq) const {
;     ...
;         _Pragma("unroll") for (int ai = 0; ai < 2; ++ai) _Pragma("unroll") for (int m = 0; m < 4; ++m) _Pragma("unroll") for (int bj = 0; bj < 2; ++bj) {
;             f32x4 v0 = acc[ai][bj][m][0] + bb[bj][0], v1 = acc[ai][bj][m][1] + bb[bj][1]; const u32x4 yy = y[ai][m][bj]; EPI_SIG(v0, v1);
;             v0[0] *= bf_lo(yy.x); v0[1] *= bf_hi(yy.x); v0[2] *= bf_lo(yy.y); v0[3] *= bf_hi(yy.y); v1[0] *= bf_lo(yy.z); v1[1] *= bf_hi(yy.z); v1[2] *= bf_lo(yy.w); v1[3] *= bf_hi(yy.w);
;             *(u32x4*)(O + (size_t)EPI_ROW(ai, m) * 512 + u.pn * BM + EPI_CT(bj)) = pack8(v0, v1); }
	v_lshl_add_u64 v[146:147], v[146:147], 0, s[22:23]
	v_pk_add_f32 v[134:135], v[134:135], v[98:99]
	v_pk_add_f32 v[126:127], v[126:127], v[94:95]
	v_cvt_pk_bf16_f32 v145, v148, v149
	v_lshl_add_u64 v[146:147], v[146:147], 0, v[0:1]
	v_mul_f32_e32 v134, 0xbfb8aa3b, v134
	v_mul_f32_e32 v126, 0xbfb8aa3b, v126
	global_store_dwordx4 v[146:147], v[142:145], off
	v_exp_f32_e32 v134, v134
	v_mul_f32_e32 v135, 0xbfb8aa3b, v135
	v_exp_f32_e32 v142, v126
	v_mul_f32_e32 v127, 0xbfb8aa3b, v127
	v_add_f32_e32 v126, 1.0, v134
	v_exp_f32_e32 v135, v135
	v_add_f32_e32 v134, 1.0, v142
	v_exp_f32_e32 v142, v127
	v_pk_add_f32 v[136:137], v[136:137], v[100:101]
	v_pk_add_f32 v[128:129], v[128:129], v[96:97]
	v_mul_f32_e32 v136, 0xbfb8aa3b, v136
	v_mul_f32_e32 v128, 0xbfb8aa3b, v128
	v_add_f32_e32 v127, 1.0, v135
	v_add_f32_e32 v135, 1.0, v142
	v_exp_f32_e32 v136, v136
	v_exp_f32_e32 v142, v128
	v_mul_f32_e32 v137, 0xbfb8aa3b, v137
	v_exp_f32_e32 v137, v137
	v_mul_f32_e32 v129, 0xbfb8aa3b, v129
	v_add_f32_e32 v128, 1.0, v136
	v_add_f32_e32 v136, 1.0, v142
	v_exp_f32_e32 v142, v129
	v_rcp_f32_e32 v126, v126
	v_rcp_f32_e32 v127, v127
	v_add_f32_e32 v129, 1.0, v137
	v_rcp_f32_e32 v128, v128
	v_rcp_f32_e32 v129, v129
	v_rcp_f32_e32 v134, v134
	v_rcp_f32_e32 v135, v135
	v_add_f32_e32 v137, 1.0, v142
	v_rcp_f32_e32 v136, v136
	v_rcp_f32_e32 v137, v137
	v_lshlrev_b32_e32 v142, 16, v194
	v_and_b32_e32 v143, 0xffff0000, v194
	v_pk_mul_f32 v[126:127], v[126:127], v[142:143]
	v_lshlrev_b32_e32 v142, 16, v195
	v_and_b32_e32 v143, 0xffff0000, v195
	v_pk_mul_f32 v[128:129], v[128:129], v[142:143]
	v_lshlrev_b32_e32 v142, 16, v196
	v_and_b32_e32 v143, 0xffff0000, v196
	v_pk_mul_f32 v[134:135], v[134:135], v[142:143]
	v_lshlrev_b32_e32 v142, 16, v197
	v_and_b32_e32 v143, 0xffff0000, v197
	v_pk_mul_f32 v[136:137], v[136:137], v[142:143]
	v_pk_add_f32 v[122:123], v[122:123], v[90:91]
	v_pk_add_f32 v[118:119], v[118:119], v[82:83]
	v_cvt_pk_bf16_f32 v126, v126, v127
	v_cvt_pk_bf16_f32 v127, v128, v129
	v_cvt_pk_bf16_f32 v128, v134, v135
	v_cvt_pk_bf16_f32 v129, v136, v137
	v_mul_f32_e32 v122, 0xbfb8aa3b, v122
	v_mul_f32_e32 v118, 0xbfb8aa3b, v118
	global_store_dwordx4 v[146:147], v[126:129], off offset:256
	v_exp_f32_e32 v122, v122
	v_mul_f32_e32 v123, 0xbfb8aa3b, v123
	v_exp_f32_e32 v126, v118
	v_mul_f32_e32 v119, 0xbfb8aa3b, v119
	v_add_f32_e32 v118, 1.0, v122
	v_exp_f32_e32 v123, v123
	v_add_f32_e32 v122, 1.0, v126
	v_exp_f32_e32 v126, v119
	v_pk_add_f32 v[124:125], v[124:125], v[92:93]
	v_pk_add_f32 v[120:121], v[120:121], v[84:85]
	v_mul_f32_e32 v124, 0xbfb8aa3b, v124
	v_mul_f32_e32 v120, 0xbfb8aa3b, v120
	v_add_f32_e32 v119, 1.0, v123
	v_add_f32_e32 v123, 1.0, v126
	v_exp_f32_e32 v124, v124
	v_exp_f32_e32 v126, v120
	v_mul_f32_e32 v125, 0xbfb8aa3b, v125
	v_exp_f32_e32 v125, v125
	v_mul_f32_e32 v121, 0xbfb8aa3b, v121
	v_add_f32_e32 v120, 1.0, v124
	v_add_f32_e32 v124, 1.0, v126
	v_exp_f32_e32 v126, v121
	v_rcp_f32_e32 v118, v118
	v_rcp_f32_e32 v119, v119
	v_add_f32_e32 v121, 1.0, v125
	v_rcp_f32_e32 v120, v120
	v_rcp_f32_e32 v121, v121
	v_rcp_f32_e32 v122, v122
	v_rcp_f32_e32 v123, v123
	v_add_f32_e32 v125, 1.0, v126
	v_lshlrev_b32_e32 v126, 16, v190
	v_and_b32_e32 v127, 0xffff0000, v190
	v_rcp_f32_e32 v124, v124
	v_rcp_f32_e32 v125, v125
	v_pk_mul_f32 v[118:119], v[118:119], v[126:127]
	v_lshlrev_b32_e32 v126, 16, v191
	v_and_b32_e32 v127, 0xffff0000, v191
	v_pk_mul_f32 v[120:121], v[120:121], v[126:127]
	v_lshlrev_b32_e32 v126, 16, v192
	v_and_b32_e32 v127, 0xffff0000, v192
	v_pk_mul_f32 v[122:123], v[122:123], v[126:127]
	v_lshlrev_b32_e32 v126, 16, v193
	v_and_b32_e32 v127, 0xffff0000, v193
	v_cvt_pk_bf16_f32 v118, v118, v119
	v_cvt_pk_bf16_f32 v119, v120, v121
	v_cvt_pk_bf16_f32 v120, v122, v123
	v_lshl_add_u64 v[122:123], s[8:9], 0, v[234:235]
	v_pk_mul_f32 v[124:125], v[124:125], v[126:127]
	v_lshl_add_u64 v[122:123], v[122:123], 0, s[22:23]
	v_pk_add_f32 v[106:107], v[106:107], v[98:99]
	v_pk_add_f32 v[102:103], v[102:103], v[94:95]
	v_cvt_pk_bf16_f32 v121, v124, v125
	v_lshl_add_u64 v[122:123], v[122:123], 0, v[0:1]
	v_mul_f32_e32 v106, 0xbfb8aa3b, v106
	v_mul_f32_e32 v102, 0xbfb8aa3b, v102
	global_store_dwordx4 v[122:123], v[118:121], off
	v_exp_f32_e32 v106, v106
	v_mul_f32_e32 v107, 0xbfb8aa3b, v107
	v_exp_f32_e32 v118, v102
	v_mul_f32_e32 v103, 0xbfb8aa3b, v103
	v_add_f32_e32 v102, 1.0, v106
	v_exp_f32_e32 v107, v107
	v_add_f32_e32 v106, 1.0, v118
	v_exp_f32_e32 v118, v103
	v_pk_add_f32 v[108:109], v[108:109], v[100:101]
	v_pk_add_f32 v[104:105], v[104:105], v[96:97]
	v_mul_f32_e32 v108, 0xbfb8aa3b, v108
	v_mul_f32_e32 v104, 0xbfb8aa3b, v104
	v_add_f32_e32 v103, 1.0, v107
	v_add_f32_e32 v107, 1.0, v118
	v_exp_f32_e32 v108, v108
	v_exp_f32_e32 v118, v104
	v_mul_f32_e32 v109, 0xbfb8aa3b, v109
	v_exp_f32_e32 v109, v109
	v_mul_f32_e32 v105, 0xbfb8aa3b, v105
	v_add_f32_e32 v104, 1.0, v108
	v_add_f32_e32 v108, 1.0, v118
	v_exp_f32_e32 v118, v105
	v_rcp_f32_e32 v102, v102
	v_rcp_f32_e32 v103, v103
	v_add_f32_e32 v105, 1.0, v109
	v_rcp_f32_e32 v104, v104
	v_rcp_f32_e32 v105, v105
	v_rcp_f32_e32 v106, v106
	v_rcp_f32_e32 v107, v107
	v_add_f32_e32 v109, 1.0, v118
	v_rcp_f32_e32 v108, v108
	v_rcp_f32_e32 v109, v109
	v_lshlrev_b32_e32 v118, 16, v186
	v_and_b32_e32 v119, 0xffff0000, v186
	v_pk_mul_f32 v[102:103], v[102:103], v[118:119]
	v_lshlrev_b32_e32 v118, 16, v187
	v_and_b32_e32 v119, 0xffff0000, v187
	v_pk_mul_f32 v[104:105], v[104:105], v[118:119]
	v_lshlrev_b32_e32 v118, 16, v188
	v_and_b32_e32 v119, 0xffff0000, v188
	v_pk_mul_f32 v[106:107], v[106:107], v[118:119]
	v_lshlrev_b32_e32 v118, 16, v189
	v_and_b32_e32 v119, 0xffff0000, v189
	v_pk_mul_f32 v[108:109], v[108:109], v[118:119]
; __device__ __forceinline__ u32x4 pack8(const f32x4 v0, const f32x4 v1) { u32x4 w; w.x = cvt_pk_bf16(v0[0], v0[1]); w.y = cvt_pk_bf16(v0[2], v0[3]); w.z = cvt_pk_bf16(v1[0], v1[1]); w.w = cvt_pk_bf16(v1[2], v1[3]); return w; }
; __device__ __forceinline__ float bf_lo(unsigned w) { return __uint_as_float(w << 16); }
; __device__ __forceinline__ float bf_hi(unsigned w) { return __uint_as_float(w & 0xffff0000u); }
; #define EPI_SIG(v0, v1) do { _Pragma("unroll") for (int e_ = 0; e_ < 4; ++e_) { v0[e_] = sigm(v0[e_]); v1[e_] = sigm(v1[e_]); } } while (0)
;     __device__ __forceinline__ void operator()(const f32x4 (&acc)[2][2][4][2], const Unit& u, int wr, int wc, int fr, int fq) const {
;     ...
;         _Pragma("unroll") for (int ai = 0; ai < 2; ++ai) _Pragma("unroll") for (int m = 0; m < 4; ++m) _Pragma("unroll") for (int bj = 0; bj < 2; ++bj) {
;             f32x4 v0 = acc[ai][bj][m][0] + bb[bj][0], v1 = acc[ai][bj][m][1] + bb[bj][1]; const u32x4 yy = y[ai][m][bj]; EPI_SIG(v0, v1);
;             v0[0] *= bf_lo(yy.x); v0[1] *= bf_hi(yy.x); v0[2] *= bf_lo(yy.y); v0[3] *= bf_hi(yy.y); v1[0] *= bf_lo(yy.z); v1[1] *= bf_hi(yy.z); v1[2] *= bf_lo(yy.w); v1[3] *= bf_hi(yy.w);
;             *(u32x4*)(O + (size_t)EPI_ROW(ai, m) * 512 + u.pn * BM + EPI_CT(bj)) = pack8(v0, v1); }
	v_pk_add_f32 v[86:87], v[86:87], v[90:91]
	v_pk_add_f32 v[78:79], v[78:79], v[82:83]
	v_cvt_pk_bf16_f32 v102, v102, v103
	v_cvt_pk_bf16_f32 v103, v104, v105
	v_cvt_pk_bf16_f32 v104, v106, v107
	v_cvt_pk_bf16_f32 v105, v108, v109
	v_mul_f32_e32 v86, 0xbfb8aa3b, v86
	v_mul_f32_e32 v78, 0xbfb8aa3b, v78
	global_store_dwordx4 v[122:123], v[102:105], off offset:256
	v_exp_f32_e32 v86, v86
	v_mul_f32_e32 v87, 0xbfb8aa3b, v87
	v_exp_f32_e32 v102, v78
	v_mul_f32_e32 v79, 0xbfb8aa3b, v79
	v_add_f32_e32 v78, 1.0, v86
	v_exp_f32_e32 v87, v87
	v_add_f32_e32 v86, 1.0, v102
	v_exp_f32_e32 v102, v79
	v_pk_add_f32 v[88:89], v[88:89], v[92:93]
	v_pk_add_f32 v[80:81], v[80:81], v[84:85]
	v_mul_f32_e32 v88, 0xbfb8aa3b, v88
	v_mul_f32_e32 v80, 0xbfb8aa3b, v80
	v_add_f32_e32 v79, 1.0, v87
	v_add_f32_e32 v87, 1.0, v102
	v_exp_f32_e32 v88, v88
	v_exp_f32_e32 v102, v80
	v_mul_f32_e32 v89, 0xbfb8aa3b, v89
	v_exp_f32_e32 v89, v89
	v_mul_f32_e32 v81, 0xbfb8aa3b, v81
	v_add_f32_e32 v80, 1.0, v88
	v_add_f32_e32 v88, 1.0, v102
	v_exp_f32_e32 v102, v81
	v_rcp_f32_e32 v78, v78
	v_rcp_f32_e32 v79, v79
	v_add_f32_e32 v81, 1.0, v89
	v_rcp_f32_e32 v80, v80
	v_rcp_f32_e32 v81, v81
	v_rcp_f32_e32 v86, v86
	v_rcp_f32_e32 v87, v87
	v_add_f32_e32 v89, 1.0, v102
	v_lshlrev_b32_e32 v102, 16, v182
	v_and_b32_e32 v103, 0xffff0000, v182
	v_rcp_f32_e32 v88, v88
	v_rcp_f32_e32 v89, v89
	v_pk_mul_f32 v[78:79], v[78:79], v[102:103]
	v_lshlrev_b32_e32 v102, 16, v183
	v_and_b32_e32 v103, 0xffff0000, v183
	v_pk_mul_f32 v[80:81], v[80:81], v[102:103]
	v_lshlrev_b32_e32 v102, 16, v184
	v_and_b32_e32 v103, 0xffff0000, v184
	v_pk_mul_f32 v[86:87], v[86:87], v[102:103]
	v_lshlrev_b32_e32 v102, 16, v185
	v_and_b32_e32 v103, 0xffff0000, v185
	v_cvt_pk_bf16_f32 v78, v78, v79
	v_cvt_pk_bf16_f32 v79, v80, v81
	v_cvt_pk_bf16_f32 v80, v86, v87
	v_lshl_add_u64 v[86:87], s[8:9], 0, v[232:233]
	v_pk_mul_f32 v[88:89], v[88:89], v[102:103]
	v_lshl_add_u64 v[86:87], v[86:87], 0, s[22:23]
	v_pk_add_f32 v[70:71], v[70:71], v[98:99]
	v_pk_add_f32 v[66:67], v[66:67], v[94:95]
	v_cvt_pk_bf16_f32 v81, v88, v89
	v_lshl_add_u64 v[86:87], v[86:87], 0, v[0:1]
	v_mul_f32_e32 v70, 0xbfb8aa3b, v70
	v_mul_f32_e32 v66, 0xbfb8aa3b, v66
	global_store_dwordx4 v[86:87], v[78:81], off
	v_exp_f32_e32 v70, v70
	v_mul_f32_e32 v71, 0xbfb8aa3b, v71
	v_exp_f32_e32 v78, v66
	v_mul_f32_e32 v67, 0xbfb8aa3b, v67
	v_add_f32_e32 v66, 1.0, v70
	v_exp_f32_e32 v71, v71
	v_add_f32_e32 v70, 1.0, v78
	v_exp_f32_e32 v78, v67
	v_pk_add_f32 v[72:73], v[72:73], v[100:101]
	v_pk_add_f32 v[68:69], v[68:69], v[96:97]
	v_mul_f32_e32 v72, 0xbfb8aa3b, v72
	v_mul_f32_e32 v68, 0xbfb8aa3b, v68
	v_add_f32_e32 v67, 1.0, v71
	v_add_f32_e32 v71, 1.0, v78
	v_exp_f32_e32 v72, v72
	v_exp_f32_e32 v78, v68
	v_mul_f32_e32 v73, 0xbfb8aa3b, v73
	v_exp_f32_e32 v73, v73
	v_mul_f32_e32 v69, 0xbfb8aa3b, v69
	v_add_f32_e32 v68, 1.0, v72
	v_add_f32_e32 v72, 1.0, v78
	v_exp_f32_e32 v78, v69
	v_rcp_f32_e32 v66, v66
	v_rcp_f32_e32 v67, v67
	v_add_f32_e32 v69, 1.0, v73
	v_rcp_f32_e32 v68, v68
	v_rcp_f32_e32 v69, v69
	v_rcp_f32_e32 v70, v70
	v_rcp_f32_e32 v71, v71
	v_add_f32_e32 v73, 1.0, v78
	v_rcp_f32_e32 v72, v72
	v_rcp_f32_e32 v73, v73
	v_lshlrev_b32_e32 v78, 16, v178
	v_and_b32_e32 v79, 0xffff0000, v178
	v_pk_mul_f32 v[66:67], v[66:67], v[78:79]
	v_lshlrev_b32_e32 v78, 16, v179
	v_and_b32_e32 v79, 0xffff0000, v179
	v_pk_mul_f32 v[68:69], v[68:69], v[78:79]
	v_lshlrev_b32_e32 v78, 16, v180
	v_and_b32_e32 v79, 0xffff0000, v180
	v_pk_mul_f32 v[70:71], v[70:71], v[78:79]
	v_lshlrev_b32_e32 v78, 16, v181
	v_and_b32_e32 v79, 0xffff0000, v181
	v_pk_mul_f32 v[72:73], v[72:73], v[78:79]
	v_pk_add_f32 v[62:63], v[62:63], v[90:91]
	v_pk_add_f32 v[58:59], v[58:59], v[82:83]
	v_cvt_pk_bf16_f32 v66, v66, v67
	v_cvt_pk_bf16_f32 v67, v68, v69
	v_cvt_pk_bf16_f32 v68, v70, v71
	v_cvt_pk_bf16_f32 v69, v72, v73
	v_mul_f32_e32 v62, 0xbfb8aa3b, v62
	v_mul_f32_e32 v58, 0xbfb8aa3b, v58
	global_store_dwordx4 v[86:87], v[66:69], off offset:256
	v_exp_f32_e32 v62, v62
	v_mul_f32_e32 v63, 0xbfb8aa3b, v63
	v_exp_f32_e32 v66, v58
	v_mul_f32_e32 v59, 0xbfb8aa3b, v59
	v_add_f32_e32 v58, 1.0, v62
	v_exp_f32_e32 v63, v63
	v_add_f32_e32 v62, 1.0, v66
	v_exp_f32_e32 v66, v59
	v_pk_add_f32 v[64:65], v[64:65], v[92:93]
	v_pk_add_f32 v[60:61], v[60:61], v[84:85]
	v_mul_f32_e32 v64, 0xbfb8aa3b, v64
	v_mul_f32_e32 v60, 0xbfb8aa3b, v60
	v_add_f32_e32 v59, 1.0, v63
	v_add_f32_e32 v63, 1.0, v66
	v_exp_f32_e32 v64, v64
	v_exp_f32_e32 v66, v60
	v_mul_f32_e32 v65, 0xbfb8aa3b, v65
	v_exp_f32_e32 v65, v65
	v_mul_f32_e32 v61, 0xbfb8aa3b, v61
	v_add_f32_e32 v60, 1.0, v64
	v_add_f32_e32 v64, 1.0, v66
	v_exp_f32_e32 v66, v61
	v_rcp_f32_e32 v58, v58
	v_rcp_f32_e32 v59, v59
	v_add_f32_e32 v61, 1.0, v65
	v_rcp_f32_e32 v60, v60
	v_rcp_f32_e32 v61, v61
	v_rcp_f32_e32 v62, v62
	v_rcp_f32_e32 v63, v63
	v_add_f32_e32 v65, 1.0, v66
	v_lshlrev_b32_e32 v66, 16, v174
	v_and_b32_e32 v67, 0xffff0000, v174
	v_rcp_f32_e32 v64, v64
	v_rcp_f32_e32 v65, v65
	v_pk_mul_f32 v[58:59], v[58:59], v[66:67]
	v_lshlrev_b32_e32 v66, 16, v175
	v_and_b32_e32 v67, 0xffff0000, v175
	v_pk_mul_f32 v[60:61], v[60:61], v[66:67]
	v_lshlrev_b32_e32 v66, 16, v176
	v_and_b32_e32 v67, 0xffff0000, v176
	v_pk_mul_f32 v[62:63], v[62:63], v[66:67]
	v_lshlrev_b32_e32 v66, 16, v177
	v_and_b32_e32 v67, 0xffff0000, v177
	v_cvt_pk_bf16_f32 v58, v58, v59
	v_cvt_pk_bf16_f32 v59, v60, v61
	v_cvt_pk_bf16_f32 v60, v62, v63
	v_lshl_add_u64 v[62:63], s[8:9], 0, v[230:231]
	v_pk_mul_f32 v[64:65], v[64:65], v[66:67]
	v_lshl_add_u64 v[62:63], v[62:63], 0, s[22:23]
	v_pk_add_f32 v[54:55], v[54:55], v[98:99]
	v_pk_add_f32 v[50:51], v[50:51], v[94:95]
	v_cvt_pk_bf16_f32 v61, v64, v65
; __device__ __forceinline__ u32x4 pack8(const f32x4 v0, const f32x4 v1) { u32x4 w; w.x = cvt_pk_bf16(v0[0], v0[1]); w.y = cvt_pk_bf16(v0[2], v0[3]); w.z = cvt_pk_bf16(v1[0], v1[1]); w.w = cvt_pk_bf16(v1[2], v1[3]); return w; }
; __device__ __forceinline__ float bf_lo(unsigned w) { return __uint_as_float(w << 16); }
; __device__ __forceinline__ float bf_hi(unsigned w) { return __uint_as_float(w & 0xffff0000u); }
; #define EPI_SIG(v0, v1) do { _Pragma("unroll") for (int e_ = 0; e_ < 4; ++e_) { v0[e_] = sigm(v0[e_]); v1[e_] = sigm(v1[e_]); } } while (0)
;     __device__ __forceinline__ void operator()(const f32x4 (&acc)[2][2][4][2], const Unit& u, int wr, int wc, int fr, int fq) const {
;     ...
;         _Pragma("unroll") for (int ai = 0; ai < 2; ++ai) _Pragma("unroll") for (int m = 0; m < 4; ++m) _Pragma("unroll") for (int bj = 0; bj < 2; ++bj) {
;             f32x4 v0 = acc[ai][bj][m][0] + bb[bj][0], v1 = acc[ai][bj][m][1] + bb[bj][1]; const u32x4 yy = y[ai][m][bj]; EPI_SIG(v0, v1);
;             v0[0] *= bf_lo(yy.x); v0[1] *= bf_hi(yy.x); v0[2] *= bf_lo(yy.y); v0[3] *= bf_hi(yy.y); v1[0] *= bf_lo(yy.z); v1[1] *= bf_hi(yy.z); v1[2] *= bf_lo(yy.w); v1[3] *= bf_hi(yy.w);
;             *(u32x4*)(O + (size_t)EPI_ROW(ai, m) * 512 + u.pn * BM + EPI_CT(bj)) = pack8(v0, v1); }
	v_lshl_add_u64 v[62:63], v[62:63], 0, v[0:1]
	v_mul_f32_e32 v54, 0xbfb8aa3b, v54
	v_mul_f32_e32 v50, 0xbfb8aa3b, v50
	global_store_dwordx4 v[62:63], v[58:61], off
	v_exp_f32_e32 v54, v54
	v_mul_f32_e32 v55, 0xbfb8aa3b, v55
	v_exp_f32_e32 v58, v50
	v_mul_f32_e32 v51, 0xbfb8aa3b, v51
	v_add_f32_e32 v50, 1.0, v54
	v_exp_f32_e32 v55, v55
	v_add_f32_e32 v54, 1.0, v58
	v_exp_f32_e32 v58, v51
	v_pk_add_f32 v[56:57], v[56:57], v[100:101]
	v_pk_add_f32 v[52:53], v[52:53], v[96:97]
	v_mul_f32_e32 v56, 0xbfb8aa3b, v56
	v_mul_f32_e32 v52, 0xbfb8aa3b, v52
	v_add_f32_e32 v51, 1.0, v55
	v_add_f32_e32 v55, 1.0, v58
	v_exp_f32_e32 v56, v56
	v_exp_f32_e32 v58, v52
	v_mul_f32_e32 v57, 0xbfb8aa3b, v57
	v_exp_f32_e32 v57, v57
	v_mul_f32_e32 v53, 0xbfb8aa3b, v53
	v_add_f32_e32 v52, 1.0, v56
	v_add_f32_e32 v56, 1.0, v58
	v_exp_f32_e32 v58, v53
	v_rcp_f32_e32 v50, v50
	v_rcp_f32_e32 v51, v51
	v_add_f32_e32 v53, 1.0, v57
	v_rcp_f32_e32 v52, v52
	v_rcp_f32_e32 v53, v53
	v_rcp_f32_e32 v54, v54
	v_rcp_f32_e32 v55, v55
	v_add_f32_e32 v57, 1.0, v58
	v_rcp_f32_e32 v56, v56
	v_rcp_f32_e32 v57, v57
	v_lshlrev_b32_e32 v58, 16, v162
	v_and_b32_e32 v59, 0xffff0000, v162
	v_pk_mul_f32 v[50:51], v[50:51], v[58:59]
	v_lshlrev_b32_e32 v58, 16, v163
	v_and_b32_e32 v59, 0xffff0000, v163
	v_pk_mul_f32 v[52:53], v[52:53], v[58:59]
	v_lshlrev_b32_e32 v58, 16, v164
	v_and_b32_e32 v59, 0xffff0000, v164
	v_pk_mul_f32 v[54:55], v[54:55], v[58:59]
	v_lshlrev_b32_e32 v58, 16, v165
	v_and_b32_e32 v59, 0xffff0000, v165
	v_pk_mul_f32 v[56:57], v[56:57], v[58:59]
	v_pk_add_f32 v[46:47], v[46:47], v[90:91]
	v_pk_add_f32 v[42:43], v[42:43], v[82:83]
	v_cvt_pk_bf16_f32 v50, v50, v51
	v_cvt_pk_bf16_f32 v51, v52, v53
	v_cvt_pk_bf16_f32 v52, v54, v55
	v_cvt_pk_bf16_f32 v53, v56, v57
	v_mul_f32_e32 v46, 0xbfb8aa3b, v46
	v_mul_f32_e32 v42, 0xbfb8aa3b, v42
	global_store_dwordx4 v[62:63], v[50:53], off offset:256
	v_exp_f32_e32 v46, v46
	v_mul_f32_e32 v47, 0xbfb8aa3b, v47
	v_exp_f32_e32 v50, v42
	v_mul_f32_e32 v43, 0xbfb8aa3b, v43
	v_add_f32_e32 v42, 1.0, v46
	v_exp_f32_e32 v47, v47
	v_add_f32_e32 v46, 1.0, v50
	v_exp_f32_e32 v50, v43
	v_pk_add_f32 v[48:49], v[48:49], v[92:93]
	v_pk_add_f32 v[44:45], v[44:45], v[84:85]
	v_mul_f32_e32 v48, 0xbfb8aa3b, v48
	v_mul_f32_e32 v44, 0xbfb8aa3b, v44
	v_add_f32_e32 v43, 1.0, v47
	v_add_f32_e32 v47, 1.0, v50
	v_exp_f32_e32 v48, v48
	v_exp_f32_e32 v50, v44
	v_mul_f32_e32 v49, 0xbfb8aa3b, v49
	v_exp_f32_e32 v49, v49
	v_mul_f32_e32 v45, 0xbfb8aa3b, v45
	v_add_f32_e32 v44, 1.0, v48
	v_add_f32_e32 v48, 1.0, v50
	v_exp_f32_e32 v50, v45
	v_rcp_f32_e32 v42, v42
	v_rcp_f32_e32 v43, v43
	v_add_f32_e32 v45, 1.0, v49
	v_rcp_f32_e32 v44, v44
	v_rcp_f32_e32 v45, v45
	v_rcp_f32_e32 v46, v46
	v_rcp_f32_e32 v47, v47
	v_add_f32_e32 v49, 1.0, v50
	v_lshlrev_b32_e32 v50, 16, v150
	v_and_b32_e32 v51, 0xffff0000, v150
	v_rcp_f32_e32 v48, v48
	v_rcp_f32_e32 v49, v49
	v_pk_mul_f32 v[42:43], v[42:43], v[50:51]
	v_lshlrev_b32_e32 v50, 16, v151
	v_and_b32_e32 v51, 0xffff0000, v151
	v_pk_mul_f32 v[44:45], v[44:45], v[50:51]
	v_lshlrev_b32_e32 v50, 16, v152
	v_and_b32_e32 v51, 0xffff0000, v152
	v_pk_mul_f32 v[46:47], v[46:47], v[50:51]
	v_lshlrev_b32_e32 v50, 16, v153
	v_and_b32_e32 v51, 0xffff0000, v153
	v_cvt_pk_bf16_f32 v42, v42, v43
	v_cvt_pk_bf16_f32 v43, v44, v45
	v_cvt_pk_bf16_f32 v44, v46, v47
	v_lshl_add_u64 v[46:47], s[8:9], 0, v[228:229]
	v_pk_mul_f32 v[48:49], v[48:49], v[50:51]
	v_lshl_add_u64 v[46:47], v[46:47], 0, s[22:23]
	v_pk_add_f32 v[38:39], v[38:39], v[98:99]
	v_pk_add_f32 v[34:35], v[34:35], v[94:95]
	v_cvt_pk_bf16_f32 v45, v48, v49
	v_lshl_add_u64 v[46:47], v[46:47], 0, v[0:1]
	v_mul_f32_e32 v38, 0xbfb8aa3b, v38
	v_mul_f32_e32 v34, 0xbfb8aa3b, v34
	global_store_dwordx4 v[46:47], v[42:45], off
	v_exp_f32_e32 v38, v38
	v_mul_f32_e32 v39, 0xbfb8aa3b, v39
	v_exp_f32_e32 v42, v34
	v_mul_f32_e32 v35, 0xbfb8aa3b, v35
	v_add_f32_e32 v34, 1.0, v38
	v_exp_f32_e32 v39, v39
	v_add_f32_e32 v38, 1.0, v42
	v_exp_f32_e32 v42, v35
	v_pk_add_f32 v[40:41], v[40:41], v[100:101]
	v_pk_add_f32 v[36:37], v[36:37], v[96:97]
	v_mul_f32_e32 v40, 0xbfb8aa3b, v40
	v_mul_f32_e32 v36, 0xbfb8aa3b, v36
	v_add_f32_e32 v35, 1.0, v39
	v_add_f32_e32 v39, 1.0, v42
	v_exp_f32_e32 v40, v40
	v_exp_f32_e32 v42, v36
	v_mul_f32_e32 v41, 0xbfb8aa3b, v41
	v_exp_f32_e32 v41, v41
	v_mul_f32_e32 v37, 0xbfb8aa3b, v37
	v_add_f32_e32 v36, 1.0, v40
	v_add_f32_e32 v40, 1.0, v42
	v_exp_f32_e32 v42, v37
	v_rcp_f32_e32 v34, v34
	v_rcp_f32_e32 v35, v35
	v_add_f32_e32 v37, 1.0, v41
	v_rcp_f32_e32 v36, v36
	v_rcp_f32_e32 v37, v37
	v_rcp_f32_e32 v38, v38
	v_rcp_f32_e32 v39, v39
	v_add_f32_e32 v41, 1.0, v42
	v_rcp_f32_e32 v40, v40
	v_rcp_f32_e32 v41, v41
	v_lshlrev_b32_e32 v42, 16, v138
	v_and_b32_e32 v43, 0xffff0000, v138
	v_pk_mul_f32 v[34:35], v[34:35], v[42:43]
	v_lshlrev_b32_e32 v42, 16, v139
	v_and_b32_e32 v43, 0xffff0000, v139
	v_pk_mul_f32 v[36:37], v[36:37], v[42:43]
	v_lshlrev_b32_e32 v42, 16, v140
	v_and_b32_e32 v43, 0xffff0000, v140
	v_pk_mul_f32 v[38:39], v[38:39], v[42:43]
	v_lshlrev_b32_e32 v42, 16, v141
	v_and_b32_e32 v43, 0xffff0000, v141
	v_pk_mul_f32 v[40:41], v[40:41], v[42:43]
	v_pk_add_f32 v[30:31], v[30:31], v[90:91]
	v_pk_add_f32 v[26:27], v[26:27], v[82:83]
	v_cvt_pk_bf16_f32 v34, v34, v35
	v_cvt_pk_bf16_f32 v35, v36, v37
	v_cvt_pk_bf16_f32 v36, v38, v39
	v_cvt_pk_bf16_f32 v37, v40, v41
	v_mul_f32_e32 v30, 0xbfb8aa3b, v30
	v_mul_f32_e32 v26, 0xbfb8aa3b, v26
	global_store_dwordx4 v[46:47], v[34:37], off offset:256
	v_exp_f32_e32 v30, v30
	v_mul_f32_e32 v31, 0xbfb8aa3b, v31
	v_exp_f32_e32 v34, v26
	v_mul_f32_e32 v27, 0xbfb8aa3b, v27
	v_add_f32_e32 v26, 1.0, v30
	v_exp_f32_e32 v31, v31
	v_add_f32_e32 v30, 1.0, v34
; __device__ __forceinline__ u32x4 pack8(const f32x4 v0, const f32x4 v1) { u32x4 w; w.x = cvt_pk_bf16(v0[0], v0[1]); w.y = cvt_pk_bf16(v0[2], v0[3]); w.z = cvt_pk_bf16(v1[0], v1[1]); w.w = cvt_pk_bf16(v1[2], v1[3]); return w; }
; __device__ __forceinline__ float bf_lo(unsigned w) { return __uint_as_float(w << 16); }
; __device__ __forceinline__ float bf_hi(unsigned w) { return __uint_as_float(w & 0xffff0000u); }
; #define EPI_SIG(v0, v1) do { _Pragma("unroll") for (int e_ = 0; e_ < 4; ++e_) { v0[e_] = sigm(v0[e_]); v1[e_] = sigm(v1[e_]); } } while (0)
; #define PG8_BAR __builtin_amdgcn_s_barrier()
;     __device__ __forceinline__ void operator()(const f32x4 (&acc)[2][2][4][2], const Unit& u, int wr, int wc, int fr, int fq) const {
;     ...
;         _Pragma("unroll") for (int ai = 0; ai < 2; ++ai) _Pragma("unroll") for (int m = 0; m < 4; ++m) _Pragma("unroll") for (int bj = 0; bj < 2; ++bj) {
;             f32x4 v0 = acc[ai][bj][m][0] + bb[bj][0], v1 = acc[ai][bj][m][1] + bb[bj][1]; const u32x4 yy = y[ai][m][bj]; EPI_SIG(v0, v1);
;             v0[0] *= bf_lo(yy.x); v0[1] *= bf_hi(yy.x); v0[2] *= bf_lo(yy.y); v0[3] *= bf_hi(yy.y); v1[0] *= bf_lo(yy.z); v1[1] *= bf_hi(yy.z); v1[2] *= bf_lo(yy.w); v1[3] *= bf_hi(yy.w);
;             *(u32x4*)(O + (size_t)EPI_ROW(ai, m) * 512 + u.pn * BM + EPI_CT(bj)) = pack8(v0, v1); }
; template <class Epi, class Sched, bool ALIGN_EPI = false, bool SP2 = false>
; __device__ __forceinline__ void gemm_phase(PG8_LAS unsigned char* lds, const Gemm g, const Sched& S, const Epi& E) {
;     ...
;         if constexpr (!Epi::AFTER_DRAIN) { E(acc, cur, wr, wc, fr, fq); S.done(cur); }
;         if (!has_next) break;
; #pragma unroll
;         for (int a = 0; a < 2; ++a)
; #pragma unroll
;             for (int b = 0; b < 2; ++b)
; #pragma unroll
;                 for (int m = 0; m < 4; ++m)
; #pragma unroll
;                     for (int n = 0; n < 2; ++n) acc[a][b][m][n] = (f32x4){0.f, 0.f, 0.f, 0.f};
;         cur = nxt; cA = nA; cB = nB; ++ui;
;         if constexpr (ALIGN_EPI) { if (wr == 1) PG8_BAR; }
	v_exp_f32_e32 v34, v27
	v_pk_add_f32 v[32:33], v[32:33], v[92:93]
	v_pk_add_f32 v[28:29], v[28:29], v[84:85]
	v_mul_f32_e32 v32, 0xbfb8aa3b, v32
	v_mul_f32_e32 v28, 0xbfb8aa3b, v28
	v_add_f32_e32 v27, 1.0, v31
	v_add_f32_e32 v31, 1.0, v34
	v_exp_f32_e32 v32, v32
	v_exp_f32_e32 v34, v28
	v_mul_f32_e32 v33, 0xbfb8aa3b, v33
	v_exp_f32_e32 v33, v33
	v_mul_f32_e32 v29, 0xbfb8aa3b, v29
	v_add_f32_e32 v28, 1.0, v32
	v_add_f32_e32 v32, 1.0, v34
	v_exp_f32_e32 v34, v29
	v_rcp_f32_e32 v26, v26
	v_rcp_f32_e32 v27, v27
	v_add_f32_e32 v29, 1.0, v33
	v_rcp_f32_e32 v28, v28
	v_rcp_f32_e32 v29, v29
	v_rcp_f32_e32 v30, v30
	v_rcp_f32_e32 v31, v31
	v_add_f32_e32 v33, 1.0, v34
	v_lshlrev_b32_e32 v34, 16, v130
	v_and_b32_e32 v35, 0xffff0000, v130
	v_rcp_f32_e32 v32, v32
	v_rcp_f32_e32 v33, v33
	v_pk_mul_f32 v[26:27], v[26:27], v[34:35]
	v_lshlrev_b32_e32 v34, 16, v131
	v_and_b32_e32 v35, 0xffff0000, v131
	v_pk_mul_f32 v[28:29], v[28:29], v[34:35]
	v_lshlrev_b32_e32 v34, 16, v132
	v_and_b32_e32 v35, 0xffff0000, v132
	v_pk_mul_f32 v[30:31], v[30:31], v[34:35]
	v_lshlrev_b32_e32 v34, 16, v133
	v_and_b32_e32 v35, 0xffff0000, v133
	v_cvt_pk_bf16_f32 v26, v26, v27
	v_cvt_pk_bf16_f32 v27, v28, v29
	v_cvt_pk_bf16_f32 v28, v30, v31
	v_lshl_add_u64 v[30:31], s[8:9], 0, v[226:227]
	v_pk_mul_f32 v[32:33], v[32:33], v[34:35]
	v_lshl_add_u64 v[30:31], v[30:31], 0, s[22:23]
	v_pk_add_f32 v[22:23], v[22:23], v[98:99]
	v_pk_add_f32 v[18:19], v[18:19], v[94:95]
	v_cvt_pk_bf16_f32 v29, v32, v33
	v_lshl_add_u64 v[30:31], v[30:31], 0, v[0:1]
	v_mul_f32_e32 v22, 0xbfb8aa3b, v22
	v_mul_f32_e32 v18, 0xbfb8aa3b, v18
	global_store_dwordx4 v[30:31], v[26:29], off
	v_exp_f32_e32 v22, v22
	v_mul_f32_e32 v23, 0xbfb8aa3b, v23
	v_exp_f32_e32 v26, v18
	v_mul_f32_e32 v19, 0xbfb8aa3b, v19
	v_add_f32_e32 v18, 1.0, v22
	v_exp_f32_e32 v23, v23
	v_add_f32_e32 v22, 1.0, v26
	v_exp_f32_e32 v26, v19
	v_pk_add_f32 v[24:25], v[24:25], v[100:101]
	v_pk_add_f32 v[20:21], v[20:21], v[96:97]
	v_mul_f32_e32 v24, 0xbfb8aa3b, v24
	v_mul_f32_e32 v20, 0xbfb8aa3b, v20
	v_add_f32_e32 v19, 1.0, v23
	v_add_f32_e32 v23, 1.0, v26
	v_exp_f32_e32 v24, v24
	v_exp_f32_e32 v26, v20
	v_mul_f32_e32 v25, 0xbfb8aa3b, v25
	v_exp_f32_e32 v25, v25
	v_mul_f32_e32 v21, 0xbfb8aa3b, v21
	v_add_f32_e32 v20, 1.0, v24
	v_add_f32_e32 v24, 1.0, v26
	v_exp_f32_e32 v26, v21
	v_rcp_f32_e32 v18, v18
	v_rcp_f32_e32 v19, v19
	v_add_f32_e32 v21, 1.0, v25
	v_rcp_f32_e32 v20, v20
	v_rcp_f32_e32 v21, v21
	v_rcp_f32_e32 v22, v22
	v_rcp_f32_e32 v23, v23
	v_add_f32_e32 v25, 1.0, v26
	v_rcp_f32_e32 v24, v24
	v_rcp_f32_e32 v25, v25
	v_lshlrev_b32_e32 v26, 16, v114
	v_and_b32_e32 v27, 0xffff0000, v114
	v_pk_mul_f32 v[18:19], v[18:19], v[26:27]
	v_lshlrev_b32_e32 v26, 16, v115
	v_and_b32_e32 v27, 0xffff0000, v115
	v_pk_mul_f32 v[20:21], v[20:21], v[26:27]
	v_lshlrev_b32_e32 v26, 16, v116
	v_and_b32_e32 v27, 0xffff0000, v116
	v_pk_mul_f32 v[22:23], v[22:23], v[26:27]
	v_lshlrev_b32_e32 v26, 16, v117
	v_and_b32_e32 v27, 0xffff0000, v117
	v_pk_mul_f32 v[24:25], v[24:25], v[26:27]
	v_pk_add_f32 v[14:15], v[14:15], v[90:91]
	v_pk_add_f32 v[10:11], v[10:11], v[82:83]
	v_cvt_pk_bf16_f32 v18, v18, v19
	v_cvt_pk_bf16_f32 v19, v20, v21
	v_cvt_pk_bf16_f32 v20, v22, v23
	v_cvt_pk_bf16_f32 v21, v24, v25
	v_mul_f32_e32 v14, 0xbfb8aa3b, v14
	v_mul_f32_e32 v10, 0xbfb8aa3b, v10
	global_store_dwordx4 v[30:31], v[18:21], off offset:256
	v_exp_f32_e32 v14, v14
	v_mul_f32_e32 v15, 0xbfb8aa3b, v15
	v_exp_f32_e32 v18, v10
	v_mul_f32_e32 v11, 0xbfb8aa3b, v11
	v_add_f32_e32 v10, 1.0, v14
	v_exp_f32_e32 v15, v15
	v_add_f32_e32 v14, 1.0, v18
	v_exp_f32_e32 v18, v11
	v_pk_add_f32 v[16:17], v[16:17], v[92:93]
	v_pk_add_f32 v[12:13], v[12:13], v[84:85]
	v_mul_f32_e32 v16, 0xbfb8aa3b, v16
	v_mul_f32_e32 v12, 0xbfb8aa3b, v12
	v_add_f32_e32 v11, 1.0, v15
	v_add_f32_e32 v15, 1.0, v18
	v_exp_f32_e32 v16, v16
	v_exp_f32_e32 v18, v12
	v_mul_f32_e32 v17, 0xbfb8aa3b, v17
	v_exp_f32_e32 v17, v17
	v_mul_f32_e32 v13, 0xbfb8aa3b, v13
	v_add_f32_e32 v12, 1.0, v16
	v_add_f32_e32 v16, 1.0, v18
	v_exp_f32_e32 v18, v13
	v_rcp_f32_e32 v10, v10
	v_rcp_f32_e32 v11, v11
	v_add_f32_e32 v13, 1.0, v17
	v_rcp_f32_e32 v12, v12
	v_rcp_f32_e32 v13, v13
	v_rcp_f32_e32 v14, v14
	v_rcp_f32_e32 v15, v15
	v_add_f32_e32 v17, 1.0, v18
	v_lshlrev_b32_e32 v18, 16, v110
	v_and_b32_e32 v19, 0xffff0000, v110
	v_pk_mul_f32 v[10:11], v[10:11], v[18:19]
	v_lshlrev_b32_e32 v18, 16, v111
	v_and_b32_e32 v19, 0xffff0000, v111
	v_pk_mul_f32 v[12:13], v[12:13], v[18:19]
	v_lshlrev_b32_e32 v18, 16, v112
	v_and_b32_e32 v19, 0xffff0000, v112
	v_pk_mul_f32 v[14:15], v[14:15], v[18:19]
	v_cvt_pk_bf16_f32 v10, v10, v11
	v_cvt_pk_bf16_f32 v11, v12, v13
	v_cvt_pk_bf16_f32 v12, v14, v15
	v_lshl_add_u64 v[14:15], s[8:9], 0, v[224:225]
	v_lshl_add_u64 v[14:15], v[14:15], 0, s[22:23]
	v_pk_add_f32 v[6:7], v[6:7], v[98:99]
	v_lshl_add_u64 v[14:15], v[14:15], 0, v[0:1]
	v_pk_add_f32 v[2:3], v[2:3], v[94:95]
	v_mul_f32_e32 v0, 0xbfb8aa3b, v6
	v_exp_f32_e32 v0, v0
	v_mul_f32_e32 v2, 0xbfb8aa3b, v2
	v_exp_f32_e32 v6, v2
	v_rcp_f32_e32 v16, v16
	v_rcp_f32_e32 v17, v17
	v_add_f32_e32 v0, 1.0, v0
	v_rcp_f32_e32 v2, v0
	v_add_f32_e32 v0, 1.0, v6
	v_mul_f32_e32 v6, 0xbfb8aa3b, v7
	v_exp_f32_e32 v7, v6
	v_lshlrev_b32_e32 v18, 16, v113
	v_and_b32_e32 v19, 0xffff0000, v113
	v_pk_mul_f32 v[16:17], v[16:17], v[18:19]
	v_pk_add_f32 v[8:9], v[8:9], v[100:101]
	v_cvt_pk_bf16_f32 v13, v16, v17
	v_mul_f32_e32 v3, 0xbfb8aa3b, v3
	global_store_dwordx4 v[14:15], v[10:13], off
	v_rcp_f32_e32 v6, v0
	v_add_f32_e32 v0, 1.0, v7
	v_exp_f32_e32 v10, v3
	v_mul_f32_e32 v7, 0xbfb8aa3b, v8
	v_exp_f32_e32 v8, v7
	v_pk_add_f32 v[4:5], v[4:5], v[96:97]
	v_rcp_f32_e32 v3, v0
	v_mul_f32_e32 v4, 0xbfb8aa3b, v4
	v_add_f32_e32 v0, 1.0, v10
	v_exp_f32_e32 v10, v4
	v_rcp_f32_e32 v7, v0
	v_add_f32_e32 v0, 1.0, v8
	v_mul_f32_e32 v8, 0xbfb8aa3b, v9
	v_exp_f32_e32 v9, v8
	v_mul_f32_e32 v5, 0xbfb8aa3b, v5
	v_rcp_f32_e32 v4, v0
	v_add_f32_e32 v0, 1.0, v10
	v_exp_f32_e32 v10, v5
	v_rcp_f32_e32 v8, v0
	v_add_f32_e32 v0, 1.0, v9
	v_rcp_f32_e32 v5, v0
	v_add_f32_e32 v0, 1.0, v10
	v_rcp_f32_e32 v9, v0
	v_lshlrev_b32_e32 v10, 16, v74
	v_and_b32_e32 v11, 0xffff0000, v74
	v_pk_mul_f32 v[2:3], v[2:3], v[10:11]
	v_lshlrev_b32_e32 v10, 16, v75
	v_and_b32_e32 v11, 0xffff0000, v75
	v_pk_mul_f32 v[4:5], v[4:5], v[10:11]
	v_lshlrev_b32_e32 v10, 16, v76
	v_and_b32_e32 v11, 0xffff0000, v76
	v_pk_mul_f32 v[6:7], v[6:7], v[10:11]
	v_lshlrev_b32_e32 v10, 16, v77
	v_and_b32_e32 v11, 0xffff0000, v77
	v_pk_mul_f32 v[8:9], v[8:9], v[10:11]
	v_cvt_pk_bf16_f32 v2, v2, v3
	v_cvt_pk_bf16_f32 v3, v4, v5
	v_cvt_pk_bf16_f32 v4, v6, v7
	v_cvt_pk_bf16_f32 v5, v8, v9
	global_store_dwordx4 v[14:15], v[2:5], off offset:256
	s_cbranch_vccnz .LBB0_539
	s_andn2_b64 vcc, exec, s[0:1]
	s_cbranch_vccnz .LBB0_538
	s_branch .LBB0_538

; #define PG8_WAIT_V(n) asm volatile("s_waitcnt vmcnt(" #n ")" ::: "memory")
; template <class Epi, class Sched, bool ALIGN_EPI = false, bool SP2 = false>
; __device__ __forceinline__ void gemm_phase(PG8_LAS unsigned char* lds, const Gemm g, const Sched& S, const Epi& E) {
;     int tid_ = threadIdx.x; asm volatile("" : "+v"(tid_));
;     const int tid = tid_, wid = __builtin_amdgcn_readfirstlane(tid >> 6), lane = tid & 63, wr = wid >> 2, wc = wid & 3, fr = lane & 15, fq = lane >> 4;
;     const int K = g.K, nt = K / BK, LD = g.ld ? g.ld : g.K;
;     unsigned voffA[2], voffB[2];
; #pragma unroll
;     for (int i = 0; i < 2; ++i) { int R, C; stage_rc(tid * 16 + i * 8192, R, C); const int Rb = Epi::PERM ? ((R & ~31) + perm32(R & 31)) : R;
;         voffA[i] = (unsigned)(R * LD + C) * 2u; voffB[i] = (unsigned)(Rb * LD + C) * 2u; }
;     const size_t kstep = (size_t)(BK * 2);
;     const size_t hstep = (size_t)HALF * LD * 2;
;     const size_t tstep = 2 * hstep;
;     const unsigned ldsw = (unsigned)wid * 1024u;
;     const int aoff = lds_byte(wr * 64 + fr, fq * 8), boff = lds_byte(wc * 32 + fr, fq * 8);
;     ...
;     Unit cur, nxt; int ui = 0;
;     if (!S.next(0, cur)) return;
;     f32x4 acc[2][2][4][2];
; #pragma unroll
;     for (int a = 0; a < 2; ++a)
; #pragma unroll
;         for (int b = 0; b < 2; ++b)
; #pragma unroll
;             for (int m = 0; m < 4; ++m)
; #pragma unroll
;                 for (int n = 0; n < 2; ++n) acc[a][b][m][n] = (f32x4){0.f, 0.f, 0.f, 0.f};
;     bf16x8 At[4][2], B0[2][2], B1[2][2];
;     const char* cA = (const char*)g.A + (size_t)cur.pm * tstep; const char* cB = (const char*)g.Bt + (size_t)cur.pn * tstep;
;     S.a_ready(cur);
;     if constexpr (SP2) {
;         PG8_STAGE(PG8_SB(0, 0), cB, voffB); PG8_STAGE(PG8_SB(0, 1), cB + hstep, voffB); PG8_STAGE(PG8_SA(0, 0), cA, voffA); PG8_STAGE(PG8_SA(0, 1), cA + hstep, voffA);
;         if (wr == 1) PG8_BAR;
;         PG8_WAIT_V(2); PG8_BAR;
;         PG8_STAGE(PG8_SB(1, 0), cB + kstep, voffB); PG8_STAGE(PG8_SA(1, 0), cA + kstep, voffA); PG8_STAGE(PG8_SB(1, 1), cB + hstep + kstep, voffB);
;         PG8_WAIT_V(6); PG8_BAR;
;     } else {
;         PG8_STAGE(PG8_SB(0, 0), cB, voffB); PG8_STAGE(PG8_SA(0, 0), cA, voffA); PG8_STAGE(PG8_SB(0, 1), cB + hstep, voffB); PG8_STAGE(PG8_SA(0, 1), cA + hstep, voffA);
;         if (wr == 1) PG8_BAR;
;         PG8_WAIT_V(4); PG8_BAR;
.LBB0_554:
	v_readlane_b32 s0, v254, 56
	s_mov_b64 s[4:5], s[72:73]
	v_mov_b32_e32 v15, v242
	v_readlane_b32 s1, v254, 57
	s_andn2_b64 vcc, exec, s[0:1]
	v_readfirstlane_b32 s8, v15
	s_cbranch_vccnz .LBB0_574
	v_lshlrev_b32_e32 v2, 4, v15
	v_add_u32_e32 v3, 0x2000, v2
	v_ashrrev_i32_e32 v0, 31, v3
	v_lshrrev_b32_e32 v0, 22, v0
	v_add_u32_e32 v0, v3, v0
	v_ashrrev_i32_e32 v0, 10, v0
	v_mul_i32_i24_e32 v4, 0x400, v0
	v_sub_u32_e32 v3, v3, v4
	v_lshrrev_b32_e32 v4, 4, v3
	v_bitop3_b32 v3, v4, v3, 32 bitop3:0x6c
	v_ashrrev_i32_e32 v4, 31, v3
	v_lshrrev_b32_e32 v4, 26, v4
	v_add_u32_e32 v4, v3, v4
	v_lshlrev_b32_e32 v5, 3, v0
	v_ashrrev_i32_e32 v10, 6, v4
	v_and_b32_e32 v5, -16, v5
	v_add_u32_e32 v5, v10, v5
	v_and_b32_e32 v6, 3, v10
	s_mov_b32 s0, 0x3fffe0
	v_lshrrev_b32_e32 v7, 2, v5
	v_lshlrev_b32_e32 v8, 1, v5
	v_and_b32_e32 v4, 0xc0, v4
	v_and_or_b32 v6, v5, s0, v6
	v_and_b32_e32 v7, 4, v7
	v_and_b32_e32 v8, 24, v8
	v_sub_u32_e32 v3, v3, v4
	v_or3_b32 v6, v6, v7, v8
	v_lshlrev_b32_e32 v7, 5, v0
	v_ashrrev_i16_sdwa v3, v241, sext(v3) dst_sel:DWORD dst_unused:UNUSED_PAD src0_sel:DWORD src1_sel:BYTE_0
	v_and_b32_e32 v7, 32, v7
	v_bfe_i32 v11, v3, 0, 16
	v_add_lshl_u32 v3, v7, v11, 1
	v_lshl_add_u32 v150, v6, 10, v3
	v_lshl_add_u32 v152, v5, 10, v3
	v_bfe_i32 v3, v15, 27, 1
	v_lshrrev_b32_e32 v3, 22, v3
	v_add_u32_e32 v3, v2, v3
	v_and_b32_e32 v3, 0xfffffc00, v3
	v_sub_u32_e32 v2, v2, v3
	v_lshrrev_b32_e32 v3, 4, v2
	v_ashrrev_i32_e32 v4, 31, v15
	v_bitop3_b32 v2, v3, v2, 32 bitop3:0x6c
	v_lshrrev_b32_e32 v4, 26, v4
	v_ashrrev_i32_e32 v3, 31, v2
	v_add_u32_e32 v4, v15, v4
	v_lshrrev_b32_e32 v3, 26, v3
	v_ashrrev_i32_e32 v13, 6, v4
	v_add_u32_e32 v3, v2, v3
	v_lshlrev_b32_e32 v4, 3, v13
	s_add_u32 s24, s4, 0x5400000
	v_ashrrev_i32_e32 v12, 6, v3
	v_and_b32_e32 v4, -16, v4
	s_addc_u32 s25, s5, 0
	v_add_u32_e32 v4, v12, v4
	s_add_u32 s26, s4, 0x1b00000
	v_and_b32_e32 v5, 3, v12
	v_lshrrev_b32_e32 v6, 2, v4
	v_lshlrev_b32_e32 v7, 1, v4
	v_and_b32_e32 v3, 0xc0, v3
	s_addc_u32 s27, s5, 0
	s_ashr_i32 s9, s8, 6
	v_and_or_b32 v5, v4, s0, v5
	v_and_b32_e32 v6, 4, v6
	v_and_b32_e32 v7, 24, v7
	v_sub_u32_e32 v2, v2, v3
	s_ashr_i32 s10, s8, 8
	s_lshl_b32 s28, s9, 10
	v_or3_b32 v5, v5, v6, v7
	v_lshlrev_b32_e32 v6, 5, v13
	v_ashrrev_i16_sdwa v2, v241, sext(v2) dst_sel:DWORD dst_unused:UNUSED_PAD src0_sel:DWORD src1_sel:BYTE_0
	v_readlane_b32 s0, v255, 12
	v_and_b32_e32 v6, 32, v6
	v_bfe_i32 v14, v2, 0, 16
	v_readlane_b32 s1, v255, 13
	s_add_u32 s16, s26, s0
	v_add_lshl_u32 v2, v6, v14, 1
	s_addc_u32 s17, s27, s1
	s_add_i32 s29, s28, 0
	v_lshl_add_u32 v154, v5, 10, v2
	s_add_i32 m0, s29, 0x10000
	v_lshl_add_u32 v156, v4, 10, v2
	global_load_lds_dwordx4 v154, s[16:17]
	s_add_i32 m0, s29, 0x12000
	s_add_u32 s0, s16, 0x20000
	global_load_lds_dwordx4 v150, s[16:17]
	s_addc_u32 s1, s17, 0
	s_add_i32 m0, s29, 0x14000
	v_mov_b32_e32 v155, v1
	global_load_lds_dwordx4 v154, s[0:1]
	s_add_i32 m0, s29, 0x16000
	v_mov_b32_e32 v151, v1
	global_load_lds_dwordx4 v150, s[0:1]
	v_readlane_b32 s0, v255, 10
	v_readlane_b32 s1, v255, 11
	s_add_u32 s20, s24, s0
	s_addc_u32 s21, s25, s1
	s_add_i32 s30, s29, 0x2000
	s_mov_b32 m0, s29
	s_add_u32 s0, s20, 0x20000
	global_load_lds_dwordx4 v156, s[20:21]
	s_mov_b32 m0, s30
	s_addc_u32 s1, s21, 0
	s_add_i32 s31, s29, 0x4000
	global_load_lds_dwordx4 v152, s[20:21]
	s_mov_b32 m0, s31
	s_add_i32 s34, s29, 0x6000
	global_load_lds_dwordx4 v156, s[0:1]
	s_mov_b32 m0, s34
	v_mov_b32_e32 v157, v1
	global_load_lds_dwordx4 v152, s[0:1]
	v_mov_b32_e32 v153, v1
	s_cmp_eq_u32 s10, 1
	v_lshl_add_u64 v[8:9], s[16:17], 0, v[154:155]
	v_lshl_add_u64 v[6:7], s[16:17], 0, v[150:151]
	v_lshl_add_u64 v[2:3], s[20:21], 0, v[156:157]
	s_cselect_b64 s[0:1], -1, 0
	s_cmp_lg_u32 s10, 1
	v_lshl_add_u64 v[4:5], s[20:21], 0, v[152:153]
	s_cbranch_scc1 .LBB0_557
.LBB0_557:
	s_add_u32 s35, s4, 0x23400000
	v_lshrrev_b32_e32 v17, 1, v15
	s_addc_u32 s36, s5, 0
	v_and_b32_e32 v17, 24, v17
	s_add_u32 s6, s4, 0x11400000
	v_and_b32_e32 v16, 15, v15
	v_lshlrev_b32_e32 v18, 1, v17
	v_lshlrev_b32_e32 v15, 2, v15
	s_addc_u32 s7, s5, 0
	v_lshl_or_b32 v170, s10, 6, v16
	v_lshl_or_b32 v16, v16, 6, v18
	s_lshl_b32 s4, s10, 13
	v_and_b32_e32 v15, 32, v15
	v_bitop3_b32 v18, v16, s4, v15 bitop3:0xde
	s_lshl_b32 s4, s9, 5
	s_and_b32 s10, s4, 0x60
	s_add_i32 m0, s29, 0x18000
	v_lshl_add_u64 v[8:9], v[8:9], 0, s[94:95]
	s_lshl_b32 s4, s10, 7
	s_waitcnt vmcnt(2)
	s_barrier
	global_load_lds_dwordx4 v[8:9], off
	v_lshl_add_u64 v[6:7], v[6:7], 0, s[94:95]
	s_add_i32 m0, s29, 0x1a000
	s_add_i32 s33, s29, 0x8000
	s_add_i32 s37, s29, 0xa000
	v_bitop3_b32 v171, v16, s4, v15 bitop3:0xde
	global_load_lds_dwordx4 v[6:7], off
	v_lshl_add_u64 v[2:3], v[2:3], 0, s[94:95]
	s_mov_b32 m0, s33
	s_add_u32 s4, s16, 0x20080
	global_load_lds_dwordx4 v[2:3], off
	v_lshl_add_u64 v[2:3], v[4:5], 0, s[94:95]
	s_mov_b32 m0, s37
	s_addc_u32 s5, s17, 0
	global_load_lds_dwordx4 v[2:3], off
	s_add_i32 m0, s29, 0x1c000
	v_lshl_add_u64 v[2:3], s[4:5], 0, v[154:155]
	global_load_lds_dwordx4 v[2:3], off
	v_lshl_add_u64 v[2:3], s[4:5], 0, v[150:151]
	s_add_i32 m0, s29, 0x1e000
	v_and_b32_e32 v4, 1, v13
	global_load_lds_dwordx4 v[2:3], off
	v_lshlrev_b32_e32 v3, 13, v13
	v_and_b32_e32 v3, 0xffffc000, v3
	v_lshl_add_u32 v3, v12, 10, v3
	v_lshl_or_b32 v3, v4, 6, v3
	v_lshl_add_u32 v158, v14, 1, v3
	v_lshlrev_b32_e32 v3, 13, v0
	v_and_b32_e32 v3, 0xffffc000, v3
	s_waitcnt vmcnt(6)
	v_lshl_add_u32 v3, v10, 10, v3
	v_and_b32_e32 v0, 1, v0
	s_cmpk_lt_u32 s8, 0x100
	v_or_b32_e32 v2, s10, v17
	v_lshl_or_b32 v0, v0, 6, v3
	v_readlane_b32 s4, v255, 18
	s_cselect_b64 s[8:9], -1, 0
	v_mov_b32_e32 v159, v1
	v_lshl_add_u32 v160, v11, 1, v0
	v_mov_b32_e32 v161, v1
	s_mov_b32 s38, 0
	v_add_u32_e32 v172, 0, v18
	v_lshlrev_b32_e32 v0, 1, v2
	v_readlane_b32 s39, v255, 9
	s_mov_b32 s46, s4
	s_barrier
	v_readlane_b32 s5, v255, 19
	s_branch .LBB0_560

;     __device__ __forceinline__ bool next(int i, Unit& u) const { const int L = i * G + c; if (L >= 512) return false; u.pm = L; u.pn = L >> 4; return true; }
; #define PG8_STAGE(bufoff, gbase, voff) do { _Pragma("unroll") for (int _i = 0; _i < 2; ++_i) \
;         __builtin_amdgcn_global_load_lds((const unsigned*)((const char*)(gbase) + (voff)[_i]), (PG8_LAS unsigned*)(lds + (bufoff) + ldsw + _i * 8192), 16, 0, 0); } while (0)
; #define PG8_LDA(dst, b, h) do { _Pragma("unroll") for (int m = 0; m < 4; ++m) _Pragma("unroll") for (int k = 0; k < 2; ++k) dst[m][k] = *(const PG8_LAS bf16x8*)(lds + PG8_SA(b, h) + aoff + m * 2048 + k * 1024); } while (0)
; #define PG8_LDB(dst, b, h) do { _Pragma("unroll") for (int n = 0; n < 2; ++n) _Pragma("unroll") for (int k = 0; k < 2; ++k) dst[n][k] = *(const PG8_LAS bf16x8*)(lds + PG8_SB(b, h) + boff + n * 2048 + k * 1024); } while (0)
; template <class Epi, class Sched, bool ALIGN_EPI = false, bool SP2 = false>
; __device__ __forceinline__ void gemm_phase(PG8_LAS unsigned char* lds, const Gemm g, const Sched& S, const Epi& E) {
;     ...
;         const bool has_next = S.next(ui + 1, nxt);
;         const char* nA = has_next ? (const char*)g.A + (size_t)nxt.pm * tstep : cA; const char* nB = has_next ? (const char*)g.Bt + (size_t)nxt.pn * tstep : cB;
;         for (int t = 0; t < nt; t += 2) {
;             const bool last = (t == nt - 2);
;             const char* a1 = cA + (size_t)(t + 1) * kstep;
;             const char* a2 = last ? nA : cA + (size_t)(t + 2) * kstep; const char* b2 = last ? nB : cB + (size_t)(t + 2) * kstep;
;             const char* a3 = a2 + kstep; const char* b3 = b2 + kstep;
;             if (last && has_next) S.a_ready(nxt);
;             if constexpr (SP2) {
;             PG8_LDB(B0, 0, 0); PG8_LDB(B1, 0, 1); PG8_SCHED; PG8_LDA(At, 0, 0); PG8_STAGE(PG8_SA(1, 1), a1 + hstep, voffA);
;             PG8_WAIT_V(8); PG8_WAIT_L(0); PG8_BAR; PG8_MMA(0, 0, At, B0); PG8_MMA(0, 1, At, B1); PG8_BAR; PG8_SCHED;
;     ...
;         for (int a = 0; a < 2; ++a)
; #pragma unroll
;             for (int b = 0; b < 2; ++b)
; #pragma unroll
;                 for (int m = 0; m < 4; ++m)
; #pragma unroll
;                     for (int n = 0; n < 2; ++n) acc[a][b][m][n] = (f32x4){0.f, 0.f, 0.f, 0.f};
;         cur = nxt; cA = nA; cB = nB; ++ui;
;         if constexpr (ALIGN_EPI) { if (wr == 1) PG8_BAR; }
.LBB0_566:
	s_ashr_i32 s13, s12, 31
	s_lshl_b64 s[14:15], s[12:13], 18
	s_add_u32 s14, s24, s14
	s_addc_u32 s15, s25, s15
	s_and_b64 s[18:19], s[4:5], exec
	s_cselect_b32 s13, s15, s21
	s_cselect_b32 s55, s14, s20
	s_ashr_i32 s11, s10, 31
	s_lshl_b64 s[18:19], s[10:11], 18
	s_add_u32 s18, s26, s18
	s_addc_u32 s19, s27, s19
	s_and_b64 s[22:23], s[4:5], exec
	s_cselect_b32 s11, s19, s17
	s_cselect_b32 s56, s18, s16
	s_add_u32 s20, s20, 0x20080
	s_addc_u32 s21, s21, 0
	s_add_u32 s57, s16, 0x100
	v_mov_b32_e32 v2, 0
	s_addc_u32 s60, s17, 0
	s_mov_b32 s50, -2
	v_mov_b32_e32 v3, v2
	v_mov_b32_e32 v4, v2
	v_mov_b32_e32 v5, v2
	v_mov_b32_e32 v6, v2
	v_mov_b32_e32 v7, v2
	v_mov_b32_e32 v8, v2
	v_mov_b32_e32 v9, v2
	v_mov_b32_e32 v14, v2
	v_mov_b32_e32 v15, v2
	v_mov_b32_e32 v16, v2
	v_mov_b32_e32 v17, v2
	v_mov_b32_e32 v22, v2
	v_mov_b32_e32 v23, v2
	v_mov_b32_e32 v24, v2
	v_mov_b32_e32 v25, v2
	v_mov_b32_e32 v30, v2
	v_mov_b32_e32 v31, v2
	v_mov_b32_e32 v32, v2
	v_mov_b32_e32 v33, v2
	v_mov_b32_e32 v38, v2
	v_mov_b32_e32 v39, v2
	v_mov_b32_e32 v40, v2
	v_mov_b32_e32 v41, v2
	v_mov_b32_e32 v46, v2
	v_mov_b32_e32 v47, v2
	v_mov_b32_e32 v48, v2
	v_mov_b32_e32 v49, v2
	v_mov_b32_e32 v54, v2
	v_mov_b32_e32 v55, v2
	v_mov_b32_e32 v56, v2
	v_mov_b32_e32 v57, v2
	v_mov_b32_e32 v10, v2
	v_mov_b32_e32 v11, v2
	v_mov_b32_e32 v12, v2
	v_mov_b32_e32 v13, v2
	v_mov_b32_e32 v18, v2
	v_mov_b32_e32 v19, v2
	v_mov_b32_e32 v20, v2
	v_mov_b32_e32 v21, v2
	v_mov_b32_e32 v26, v2
	v_mov_b32_e32 v27, v2
	v_mov_b32_e32 v28, v2
	v_mov_b32_e32 v29, v2
	v_mov_b32_e32 v34, v2
	v_mov_b32_e32 v35, v2
	v_mov_b32_e32 v36, v2
	v_mov_b32_e32 v37, v2
	v_mov_b32_e32 v42, v2
	v_mov_b32_e32 v43, v2
	v_mov_b32_e32 v44, v2
	v_mov_b32_e32 v45, v2
	v_mov_b32_e32 v50, v2
	v_mov_b32_e32 v51, v2
	v_mov_b32_e32 v52, v2
	v_mov_b32_e32 v53, v2
	v_mov_b32_e32 v58, v2
	v_mov_b32_e32 v59, v2
	v_mov_b32_e32 v60, v2
	v_mov_b32_e32 v61, v2
	v_mov_b32_e32 v62, v2
	v_mov_b32_e32 v63, v2
	v_mov_b32_e32 v64, v2
	v_mov_b32_e32 v65, v2
	v_mov_b32_e32 v66, v2
	v_mov_b32_e32 v67, v2
	v_mov_b32_e32 v68, v2
	v_mov_b32_e32 v69, v2
	v_mov_b32_e32 v70, v2
	v_mov_b32_e32 v71, v2
	v_mov_b32_e32 v72, v2
	v_mov_b32_e32 v73, v2
	v_mov_b32_e32 v78, v2
	v_mov_b32_e32 v79, v2
	v_mov_b32_e32 v80, v2
	v_mov_b32_e32 v81, v2
	v_mov_b32_e32 v86, v2
	v_mov_b32_e32 v87, v2
	v_mov_b32_e32 v88, v2
	v_mov_b32_e32 v89, v2
	v_mov_b32_e32 v94, v2
	v_mov_b32_e32 v95, v2
	v_mov_b32_e32 v96, v2
	v_mov_b32_e32 v97, v2
	v_mov_b32_e32 v102, v2
	v_mov_b32_e32 v103, v2
	v_mov_b32_e32 v104, v2
	v_mov_b32_e32 v105, v2
	v_mov_b32_e32 v106, v2
	v_mov_b32_e32 v107, v2
	v_mov_b32_e32 v108, v2
	v_mov_b32_e32 v109, v2
	v_mov_b32_e32 v114, v2
	v_mov_b32_e32 v115, v2
	v_mov_b32_e32 v116, v2
	v_mov_b32_e32 v117, v2
	v_mov_b32_e32 v74, v2
	v_mov_b32_e32 v75, v2
	v_mov_b32_e32 v76, v2
	v_mov_b32_e32 v77, v2
	v_mov_b32_e32 v82, v2
	v_mov_b32_e32 v83, v2
	v_mov_b32_e32 v84, v2
	v_mov_b32_e32 v85, v2
	v_mov_b32_e32 v90, v2
	v_mov_b32_e32 v91, v2
	v_mov_b32_e32 v92, v2
	v_mov_b32_e32 v93, v2
	v_mov_b32_e32 v98, v2
	v_mov_b32_e32 v99, v2
	v_mov_b32_e32 v100, v2
	v_mov_b32_e32 v101, v2
	v_mov_b32_e32 v110, v2
	v_mov_b32_e32 v111, v2
	v_mov_b32_e32 v112, v2
	v_mov_b32_e32 v113, v2
	v_mov_b32_e32 v118, v2
	v_mov_b32_e32 v119, v2
	v_mov_b32_e32 v120, v2
	v_mov_b32_e32 v121, v2
	v_mov_b32_e32 v122, v2
	v_mov_b32_e32 v123, v2
	v_mov_b32_e32 v124, v2
	v_mov_b32_e32 v125, v2
	v_mov_b32_e32 v126, v2
	v_mov_b32_e32 v127, v2
	v_mov_b32_e32 v128, v2
	v_mov_b32_e32 v129, v2
	s_cmp_eq_u64 s[0:1], 0
	s_cbranch_scc1 .Lboff_skip_G
	s_barrier
.Lboff_skip_G:
.LBB0_567:
	s_add_u32 s16, s20, 0xfffe0080
	s_addc_u32 s17, s21, -1
	s_add_i32 s52, 0, 0x10000
	s_cmp_eq_u32 s50, 4
	s_cselect_b32 s23, s13, s17
	s_cselect_b32 s22, s55, s16
	s_cselect_b32 s17, s11, s60
	s_cselect_b32 s16, s56, s57
	s_add_i32 s61, 0, 0x14000
	v_add_u32_e32 v142, s52, v171
	v_add_u32_e32 v173, s61, v171
	ds_read_b128 v[130:133], v142
	ds_read_b128 v[134:137], v142 offset:1024
	ds_read_b128 v[138:141], v142 offset:2048
	ds_read_b128 v[142:145], v142 offset:3072
	ds_read_b128 v[146:149], v173
	ds_read_b128 v[162:165], v173 offset:1024
	ds_read_b128 v[166:169], v173 offset:2048
	ds_read_b128 v[174:177], v173 offset:3072
	v_lshl_add_u64 v[210:211], s[20:21], 0, v[158:159]
	s_add_i32 m0, s29, 0xc000
	ds_read_b128 v[178:181], v172
	ds_read_b128 v[182:185], v172 offset:1024
	ds_read_b128 v[186:189], v172 offset:2048
	ds_read_b128 v[190:193], v172 offset:3072
	ds_read_b128 v[194:197], v172 offset:4096
	ds_read_b128 v[198:201], v172 offset:5120
	ds_read_b128 v[202:205], v172 offset:6144
	ds_read_b128 v[206:209], v172 offset:7168
	global_load_lds_dwordx4 v[210:211], off
	v_lshl_add_u64 v[210:211], s[20:21], 0, v[160:161]
	s_add_i32 m0, s29, 0xe000
	s_nop 0
	global_load_lds_dwordx4 v[210:211], off
	s_waitcnt vmcnt(8)
	s_waitcnt lgkmcnt(0)
	s_barrier
; #define PG8_STAGE(bufoff, gbase, voff) do { _Pragma("unroll") for (int _i = 0; _i < 2; ++_i) \
;         __builtin_amdgcn_global_load_lds((const unsigned*)((const char*)(gbase) + (voff)[_i]), (PG8_LAS unsigned*)(lds + (bufoff) + ldsw + _i * 8192), 16, 0, 0); } while (0)
; #define PG8_LDA(dst, b, h) do { _Pragma("unroll") for (int m = 0; m < 4; ++m) _Pragma("unroll") for (int k = 0; k < 2; ++k) dst[m][k] = *(const PG8_LAS bf16x8*)(lds + PG8_SA(b, h) + aoff + m * 2048 + k * 1024); } while (0)
; #define PG8_MMA(ai, bj, At, Bt) do { __builtin_amdgcn_s_setprio(1); _Pragma("unroll") for (int m = 0; m < 4; ++m) _Pragma("unroll") for (int n = 0; n < 2; ++n) _Pragma("unroll") for (int k = 0; k < 2; ++k) \
;         acc[ai][bj][m][n] = __builtin_amdgcn_mfma_f32_16x16x32_bf16(Bt[n][k], At[m][k], acc[ai][bj][m][n], 0, 0, 0); __builtin_amdgcn_s_setprio(0); } while (0)
; #define PG8_WAIT_V(n) asm volatile("s_waitcnt vmcnt(" #n ")" ::: "memory")
; #define PG8_WAIT_L(n) asm volatile("s_waitcnt lgkmcnt(" #n ")" ::: "memory")
; #define PG8_BAR __builtin_amdgcn_s_barrier()
; #define PG8_SCHED __builtin_amdgcn_sched_barrier(0)
; template <class Epi, class Sched, bool ALIGN_EPI = false, bool SP2 = false>
; __device__ __forceinline__ void gemm_phase(PG8_LAS unsigned char* lds, const Gemm g, const Sched& S, const Epi& E) {
;     ...
;             PG8_WAIT_V(8); PG8_WAIT_L(0); PG8_BAR; PG8_MMA(0, 0, At, B0); PG8_MMA(0, 1, At, B1); PG8_BAR; PG8_SCHED;
;             PG8_LDA(At, 0, 1); PG8_STAGE(PG8_SB(0, 0), b2, voffB); PG8_STAGE(PG8_SB(0, 1), b2 + hstep, voffB); PG8_STAGE(PG8_SA(0, 0), a2, voffA);
;             PG8_WAIT_V(8); PG8_WAIT_L(0); PG8_BAR; PG8_MMA(1, 0, At, B0); PG8_MMA(1, 1, At, B1); PG8_BAR; PG8_SCHED;
	s_setprio 1
	s_waitcnt lgkmcnt(0)
	v_mfma_f32_16x16x32_bf16 v[126:129], v[130:133], v[178:181], v[126:129]
	v_mfma_f32_16x16x32_bf16 v[122:125], v[138:141], v[178:181], v[122:125]
	v_mfma_f32_16x16x32_bf16 v[118:121], v[130:133], v[186:189], v[118:121]
	v_mfma_f32_16x16x32_bf16 v[110:113], v[138:141], v[186:189], v[110:113]
	v_mfma_f32_16x16x32_bf16 v[98:101], v[130:133], v[194:197], v[98:101]
	v_mfma_f32_16x16x32_bf16 v[90:93], v[138:141], v[194:197], v[90:93]
	v_mfma_f32_16x16x32_bf16 v[82:85], v[130:133], v[202:205], v[82:85]
	v_mfma_f32_16x16x32_bf16 v[74:77], v[138:141], v[202:205], v[74:77]
	v_mfma_f32_16x16x32_bf16 v[126:129], v[134:137], v[182:185], v[126:129]
	v_mfma_f32_16x16x32_bf16 v[122:125], v[142:145], v[182:185], v[122:125]
	v_mfma_f32_16x16x32_bf16 v[118:121], v[134:137], v[190:193], v[118:121]
	v_mfma_f32_16x16x32_bf16 v[110:113], v[142:145], v[190:193], v[110:113]
	v_mfma_f32_16x16x32_bf16 v[98:101], v[134:137], v[198:201], v[98:101]
	v_mfma_f32_16x16x32_bf16 v[90:93], v[142:145], v[198:201], v[90:93]
	v_mfma_f32_16x16x32_bf16 v[82:85], v[134:137], v[206:209], v[82:85]
	v_mfma_f32_16x16x32_bf16 v[74:77], v[142:145], v[206:209], v[74:77]
	s_setprio 0
	s_setprio 1
	v_mfma_f32_16x16x32_bf16 v[114:117], v[146:149], v[178:181], v[114:117]
	v_mfma_f32_16x16x32_bf16 v[106:109], v[166:169], v[178:181], v[106:109]
	v_mfma_f32_16x16x32_bf16 v[102:105], v[146:149], v[186:189], v[102:105]
	v_mfma_f32_16x16x32_bf16 v[94:97], v[166:169], v[186:189], v[94:97]
	v_mfma_f32_16x16x32_bf16 v[86:89], v[146:149], v[194:197], v[86:89]
	v_mfma_f32_16x16x32_bf16 v[78:81], v[166:169], v[194:197], v[78:81]
	v_mfma_f32_16x16x32_bf16 v[70:73], v[146:149], v[202:205], v[70:73]
	v_mfma_f32_16x16x32_bf16 v[66:69], v[166:169], v[202:205], v[66:69]
	v_mfma_f32_16x16x32_bf16 v[114:117], v[162:165], v[182:185], v[114:117]
	v_mfma_f32_16x16x32_bf16 v[106:109], v[174:177], v[182:185], v[106:109]
	v_mfma_f32_16x16x32_bf16 v[102:105], v[162:165], v[190:193], v[102:105]
	v_mfma_f32_16x16x32_bf16 v[94:97], v[174:177], v[190:193], v[94:97]
	v_mfma_f32_16x16x32_bf16 v[86:89], v[162:165], v[198:201], v[86:89]
	v_mfma_f32_16x16x32_bf16 v[78:81], v[174:177], v[198:201], v[78:81]
	v_mfma_f32_16x16x32_bf16 v[70:73], v[162:165], v[206:209], v[70:73]
	v_mfma_f32_16x16x32_bf16 v[66:69], v[174:177], v[206:209], v[66:69]
	s_setprio 0
	s_barrier
	s_add_i32 s52, s52, s28
	v_lshl_add_u64 v[210:211], s[16:17], 0, v[154:155]
	s_mov_b32 m0, s52
	ds_read_b128 v[178:181], v172 offset:16384
	ds_read_b128 v[182:185], v172 offset:17408
	ds_read_b128 v[186:189], v172 offset:18432
	ds_read_b128 v[190:193], v172 offset:19456
	ds_read_b128 v[194:197], v172 offset:20480
	ds_read_b128 v[198:201], v172 offset:21504
	ds_read_b128 v[202:205], v172 offset:22528
	ds_read_b128 v[206:209], v172 offset:23552
	global_load_lds_dwordx4 v[210:211], off
	s_add_i32 m0, s52, 0x2000
	s_add_u32 s52, s16, 0x20000
	v_lshl_add_u64 v[212:213], s[16:17], 0, v[150:151]
	s_addc_u32 s53, s17, 0
	s_add_i32 s61, s61, s28
	global_load_lds_dwordx4 v[212:213], off
	v_lshl_add_u64 v[214:215], s[52:53], 0, v[154:155]
	s_mov_b32 m0, s61
	v_lshl_add_u64 v[216:217], s[22:23], 0, v[152:153]
	global_load_lds_dwordx4 v[214:215], off
	v_lshl_add_u64 v[214:215], s[52:53], 0, v[150:151]
	s_add_i32 m0, s61, 0x2000
	s_nop 0
	global_load_lds_dwordx4 v[214:215], off
	v_lshl_add_u64 v[214:215], s[22:23], 0, v[156:157]
	s_mov_b32 m0, s29
	s_nop 0
	global_load_lds_dwordx4 v[214:215], off
	s_mov_b32 m0, s30
	s_nop 0
	global_load_lds_dwordx4 v[216:217], off
	s_waitcnt vmcnt(8)
	s_waitcnt lgkmcnt(0)
	s_barrier
	s_setprio 1
	s_waitcnt lgkmcnt(0)
	v_mfma_f32_16x16x32_bf16 v[62:65], v[130:133], v[178:181], v[62:65]
	v_mfma_f32_16x16x32_bf16 v[58:61], v[138:141], v[178:181], v[58:61]
	v_mfma_f32_16x16x32_bf16 v[50:53], v[130:133], v[186:189], v[50:53]
	v_mfma_f32_16x16x32_bf16 v[42:45], v[138:141], v[186:189], v[42:45]
	v_mfma_f32_16x16x32_bf16 v[34:37], v[130:133], v[194:197], v[34:37]
	v_mfma_f32_16x16x32_bf16 v[26:29], v[138:141], v[194:197], v[26:29]
	v_mfma_f32_16x16x32_bf16 v[18:21], v[130:133], v[202:205], v[18:21]
	v_mfma_f32_16x16x32_bf16 v[10:13], v[138:141], v[202:205], v[10:13]
	v_mfma_f32_16x16x32_bf16 v[62:65], v[134:137], v[182:185], v[62:65]
	v_mfma_f32_16x16x32_bf16 v[58:61], v[142:145], v[182:185], v[58:61]
	v_mfma_f32_16x16x32_bf16 v[50:53], v[134:137], v[190:193], v[50:53]
	v_mfma_f32_16x16x32_bf16 v[42:45], v[142:145], v[190:193], v[42:45]
	v_mfma_f32_16x16x32_bf16 v[34:37], v[134:137], v[198:201], v[34:37]
	v_mfma_f32_16x16x32_bf16 v[26:29], v[142:145], v[198:201], v[26:29]
	v_mfma_f32_16x16x32_bf16 v[18:21], v[134:137], v[206:209], v[18:21]
	v_mfma_f32_16x16x32_bf16 v[10:13], v[142:145], v[206:209], v[10:13]
	s_setprio 0
	s_setprio 1
	v_mfma_f32_16x16x32_bf16 v[54:57], v[146:149], v[178:181], v[54:57]
	v_mfma_f32_16x16x32_bf16 v[46:49], v[166:169], v[178:181], v[46:49]
	v_mfma_f32_16x16x32_bf16 v[38:41], v[146:149], v[186:189], v[38:41]
	v_mfma_f32_16x16x32_bf16 v[30:33], v[166:169], v[186:189], v[30:33]
	v_mfma_f32_16x16x32_bf16 v[22:25], v[146:149], v[194:197], v[22:25]
	v_mfma_f32_16x16x32_bf16 v[14:17], v[166:169], v[194:197], v[14:17]
	v_mfma_f32_16x16x32_bf16 v[6:9], v[146:149], v[202:205], v[6:9]
	v_mfma_f32_16x16x32_bf16 v[2:5], v[166:169], v[202:205], v[2:5]
	v_mfma_f32_16x16x32_bf16 v[54:57], v[162:165], v[182:185], v[54:57]
	v_mfma_f32_16x16x32_bf16 v[46:49], v[174:177], v[182:185], v[46:49]
	v_mfma_f32_16x16x32_bf16 v[38:41], v[162:165], v[190:193], v[38:41]
	v_mfma_f32_16x16x32_bf16 v[30:33], v[174:177], v[190:193], v[30:33]
	v_mfma_f32_16x16x32_bf16 v[22:25], v[162:165], v[198:201], v[22:25]
	v_mfma_f32_16x16x32_bf16 v[14:17], v[174:177], v[198:201], v[14:17]
	v_mfma_f32_16x16x32_bf16 v[6:9], v[162:165], v[206:209], v[6:9]
	v_mfma_f32_16x16x32_bf16 v[2:5], v[174:177], v[206:209], v[2:5]
	s_setprio 0
	s_barrier
; #define PG8_STAGE(bufoff, gbase, voff) do { _Pragma("unroll") for (int _i = 0; _i < 2; ++_i) \
;         __builtin_amdgcn_global_load_lds((const unsigned*)((const char*)(gbase) + (voff)[_i]), (PG8_LAS unsigned*)(lds + (bufoff) + ldsw + _i * 8192), 16, 0, 0); } while (0)
; #define PG8_LDA(dst, b, h) do { _Pragma("unroll") for (int m = 0; m < 4; ++m) _Pragma("unroll") for (int k = 0; k < 2; ++k) dst[m][k] = *(const PG8_LAS bf16x8*)(lds + PG8_SA(b, h) + aoff + m * 2048 + k * 1024); } while (0)
; #define PG8_LDB(dst, b, h) do { _Pragma("unroll") for (int n = 0; n < 2; ++n) _Pragma("unroll") for (int k = 0; k < 2; ++k) dst[n][k] = *(const PG8_LAS bf16x8*)(lds + PG8_SB(b, h) + boff + n * 2048 + k * 1024); } while (0)
; #define PG8_MMA(ai, bj, At, Bt) do { __builtin_amdgcn_s_setprio(1); _Pragma("unroll") for (int m = 0; m < 4; ++m) _Pragma("unroll") for (int n = 0; n < 2; ++n) _Pragma("unroll") for (int k = 0; k < 2; ++k) \
;         acc[ai][bj][m][n] = __builtin_amdgcn_mfma_f32_16x16x32_bf16(Bt[n][k], At[m][k], acc[ai][bj][m][n], 0, 0, 0); __builtin_amdgcn_s_setprio(0); } while (0)
; #define PG8_WAIT_V(n) asm volatile("s_waitcnt vmcnt(" #n ")" ::: "memory")
; #define PG8_WAIT_L(n) asm volatile("s_waitcnt lgkmcnt(" #n ")" ::: "memory")
; #define PG8_BAR __builtin_amdgcn_s_barrier()
; #define PG8_SCHED __builtin_amdgcn_sched_barrier(0)
; template <class Epi, class Sched, bool ALIGN_EPI = false, bool SP2 = false>
; __device__ __forceinline__ void gemm_phase(PG8_LAS unsigned char* lds, const Gemm g, const Sched& S, const Epi& E) {
;     ...
;             PG8_LDB(B0, 1, 0); PG8_LDB(B1, 1, 1); PG8_SCHED; PG8_LDA(At, 1, 0); PG8_STAGE(PG8_SA(0, 1), a2 + hstep, voffA);
;             PG8_WAIT_V(8); PG8_WAIT_L(0); PG8_BAR; PG8_MMA(0, 0, At, B0); PG8_MMA(0, 1, At, B1); PG8_BAR; PG8_SCHED;
;             PG8_LDA(At, 1, 1); PG8_STAGE(PG8_SB(1, 0), b3, voffB); PG8_STAGE(PG8_SB(1, 1), b3 + hstep, voffB); PG8_STAGE(PG8_SA(1, 0), a3, voffA);
;             PG8_WAIT_V(8); PG8_WAIT_L(0); PG8_BAR; PG8_MMA(1, 0, At, B0); PG8_MMA(1, 1, At, B1); PG8_BAR; PG8_SCHED;
	s_add_i32 s52, 0, 0x18000
	s_add_i32 s53, 0, 0x1c000
	v_add_u32_e32 v142, s52, v171
	v_add_u32_e32 v173, s53, v171
	ds_read_b128 v[130:133], v142
	ds_read_b128 v[134:137], v142 offset:1024
	ds_read_b128 v[138:141], v142 offset:2048
	ds_read_b128 v[142:145], v142 offset:3072
	ds_read_b128 v[146:149], v173
	ds_read_b128 v[162:165], v173 offset:1024
	ds_read_b128 v[166:169], v173 offset:2048
	ds_read_b128 v[174:177], v173 offset:3072
	s_add_u32 s22, s22, 0x20000
	s_addc_u32 s23, s23, 0
	s_mov_b32 m0, s31
	v_lshl_add_u64 v[218:219], s[22:23], 0, v[156:157]
	ds_read_b128 v[178:181], v172 offset:32768
	ds_read_b128 v[182:185], v172 offset:33792
	ds_read_b128 v[186:189], v172 offset:34816
	ds_read_b128 v[190:193], v172 offset:35840
	ds_read_b128 v[194:197], v172 offset:36864
	ds_read_b128 v[198:201], v172 offset:37888
	ds_read_b128 v[202:205], v172 offset:38912
	ds_read_b128 v[206:209], v172 offset:39936
	global_load_lds_dwordx4 v[218:219], off
	v_lshl_add_u64 v[218:219], s[22:23], 0, v[152:153]
	s_mov_b32 m0, s34
	s_nop 0
	global_load_lds_dwordx4 v[218:219], off
	s_waitcnt vmcnt(8)
	s_waitcnt lgkmcnt(0)
	s_barrier
	s_setprio 1
	s_waitcnt lgkmcnt(0)
	v_mfma_f32_16x16x32_bf16 v[126:129], v[130:133], v[178:181], v[126:129]
	v_mfma_f32_16x16x32_bf16 v[122:125], v[138:141], v[178:181], v[122:125]
	v_mfma_f32_16x16x32_bf16 v[118:121], v[130:133], v[186:189], v[118:121]
	v_mfma_f32_16x16x32_bf16 v[110:113], v[138:141], v[186:189], v[110:113]
	v_mfma_f32_16x16x32_bf16 v[98:101], v[130:133], v[194:197], v[98:101]
	v_mfma_f32_16x16x32_bf16 v[90:93], v[138:141], v[194:197], v[90:93]
	v_mfma_f32_16x16x32_bf16 v[82:85], v[130:133], v[202:205], v[82:85]
	v_mfma_f32_16x16x32_bf16 v[74:77], v[138:141], v[202:205], v[74:77]
	v_mfma_f32_16x16x32_bf16 v[126:129], v[134:137], v[182:185], v[126:129]
	v_mfma_f32_16x16x32_bf16 v[122:125], v[142:145], v[182:185], v[122:125]
	v_mfma_f32_16x16x32_bf16 v[118:121], v[134:137], v[190:193], v[118:121]
	v_mfma_f32_16x16x32_bf16 v[110:113], v[142:145], v[190:193], v[110:113]
	v_mfma_f32_16x16x32_bf16 v[98:101], v[134:137], v[198:201], v[98:101]
	v_mfma_f32_16x16x32_bf16 v[90:93], v[142:145], v[198:201], v[90:93]
	v_mfma_f32_16x16x32_bf16 v[82:85], v[134:137], v[206:209], v[82:85]
	v_mfma_f32_16x16x32_bf16 v[74:77], v[142:145], v[206:209], v[74:77]
	s_setprio 0
	s_setprio 1
	v_mfma_f32_16x16x32_bf16 v[114:117], v[146:149], v[178:181], v[114:117]
	v_mfma_f32_16x16x32_bf16 v[106:109], v[166:169], v[178:181], v[106:109]
	v_mfma_f32_16x16x32_bf16 v[102:105], v[146:149], v[186:189], v[102:105]
	v_mfma_f32_16x16x32_bf16 v[94:97], v[166:169], v[186:189], v[94:97]
	v_mfma_f32_16x16x32_bf16 v[86:89], v[146:149], v[194:197], v[86:89]
	v_mfma_f32_16x16x32_bf16 v[78:81], v[166:169], v[194:197], v[78:81]
	v_mfma_f32_16x16x32_bf16 v[70:73], v[146:149], v[202:205], v[70:73]
	v_mfma_f32_16x16x32_bf16 v[66:69], v[166:169], v[202:205], v[66:69]
	v_mfma_f32_16x16x32_bf16 v[114:117], v[162:165], v[182:185], v[114:117]
	v_mfma_f32_16x16x32_bf16 v[106:109], v[174:177], v[182:185], v[106:109]
	v_mfma_f32_16x16x32_bf16 v[102:105], v[162:165], v[190:193], v[102:105]
	v_mfma_f32_16x16x32_bf16 v[94:97], v[174:177], v[190:193], v[94:97]
	v_mfma_f32_16x16x32_bf16 v[86:89], v[162:165], v[198:201], v[86:89]
	v_mfma_f32_16x16x32_bf16 v[78:81], v[174:177], v[198:201], v[78:81]
	v_mfma_f32_16x16x32_bf16 v[70:73], v[162:165], v[206:209], v[70:73]
	v_mfma_f32_16x16x32_bf16 v[66:69], v[174:177], v[206:209], v[66:69]
	s_setprio 0
	s_barrier
	s_add_i32 s22, s52, s28
	v_lshl_add_u64 v[210:211], v[210:211], 0, s[94:95]
	s_mov_b32 m0, s22
	ds_read_b128 v[178:181], v172 offset:49152
	ds_read_b128 v[182:185], v172 offset:50176
	ds_read_b128 v[186:189], v172 offset:51200
	ds_read_b128 v[190:193], v172 offset:52224
	ds_read_b128 v[194:197], v172 offset:53248
	ds_read_b128 v[198:201], v172 offset:54272
	ds_read_b128 v[202:205], v172 offset:55296
	ds_read_b128 v[206:209], v172 offset:56320
	global_load_lds_dwordx4 v[210:211], off
	s_add_i32 m0, s22, 0x2000
	s_add_u32 s16, s16, 0x20080
	v_lshl_add_u64 v[210:211], v[212:213], 0, s[94:95]
	s_addc_u32 s17, s17, 0
	s_add_i32 s22, s53, s28
	global_load_lds_dwordx4 v[210:211], off
	v_lshl_add_u64 v[210:211], s[16:17], 0, v[154:155]
	s_mov_b32 m0, s22
	s_nop 0
	global_load_lds_dwordx4 v[210:211], off
	v_lshl_add_u64 v[210:211], s[16:17], 0, v[150:151]
	s_add_i32 m0, s22, 0x2000
	s_nop 0
	global_load_lds_dwordx4 v[210:211], off
	v_lshl_add_u64 v[210:211], v[214:215], 0, s[94:95]
	s_mov_b32 m0, s33
	s_nop 0
	global_load_lds_dwordx4 v[210:211], off
	v_lshl_add_u64 v[210:211], v[216:217], 0, s[94:95]
	s_mov_b32 m0, s37
	s_nop 0
	global_load_lds_dwordx4 v[210:211], off
	s_waitcnt vmcnt(8)
	s_waitcnt lgkmcnt(0)
	s_barrier
; #define PG8_WAIT_V(n) asm volatile("s_waitcnt vmcnt(" #n ")" ::: "memory")
;     __device__ __forceinline__ void operator()(const f32x4 (&acc)[2][2][4][2], const Unit& u, int wr, int wc, int fr, int fq) const {
;         _Pragma("unroll") for (int ai = 0; ai < 2; ++ai) {
;             u32x4 gt[4][2], oo[4][2];
;             _Pragma("unroll") for (int m = 0; m < 4; ++m) _Pragma("unroll") for (int bj = 0; bj < 2; ++bj) { const size_t off = (size_t)EPI_ROW(ai, m) * 1024 + u.pn * BM + EPI_CT(bj);
;                 gt[m][bj] = *(const u32x4*)(G + off); if (ADD) oo[m][bj] = *(const u32x4*)(O + off); }
;             _Pragma("unroll") for (int m = 0; m < 4; ++m) _Pragma("unroll") for (int bj = 0; bj < 2; ++bj) { const size_t off = (size_t)EPI_ROW(ai, m) * 1024 + u.pn * BM + EPI_CT(bj);
;                 f32x4 v0 = acc[ai][bj][m][0], v1 = acc[ai][bj][m][1]; const u32x4 g4 = gt[m][bj];
;                 v0[0] *= bf_lo(g4.x); v0[1] *= bf_hi(g4.x); v0[2] *= bf_lo(g4.y); v0[3] *= bf_hi(g4.y); v1[0] *= bf_lo(g4.z); v1[1] *= bf_hi(g4.z); v1[2] *= bf_lo(g4.w); v1[3] *= bf_hi(g4.w);
;                 if (ADD) { const u32x4 o = oo[m][bj];
;                     v0[0] += bf_lo(o.x); v0[1] += bf_hi(o.x); v0[2] += bf_lo(o.y); v0[3] += bf_hi(o.y); v1[0] += bf_lo(o.z); v1[1] += bf_hi(o.z); v1[2] += bf_lo(o.w); v1[3] += bf_hi(o.w); }
;                 *(u32x4*)(O + off) = pack8(v0, v1); }
;             asm volatile("" ::: "memory");
; template <class Epi, class Sched, bool ALIGN_EPI = false, bool SP2 = false>
; __device__ __forceinline__ void gemm_phase(PG8_LAS unsigned char* lds, const Gemm g, const Sched& S, const Epi& E) {
;     ...
;             PG8_WAIT_V(8); PG8_WAIT_L(0); PG8_BAR; PG8_MMA(1, 0, At, B0); PG8_MMA(1, 1, At, B1); PG8_BAR; PG8_SCHED;
;             } else {
;             PG8_LDB(B0, 0, 0); PG8_SCHED; PG8_LDA(At, 0, 0); PG8_STAGE(PG8_SA(1, 1), a1 + hstep, voffA);
;             PG8_WAIT_L(8); PG8_BAR; PG8_WAIT_L(0); PG8_MMA(0, 0, At, B0); PG8_BAR; PG8_SCHED;
;             PG8_LDB(B1, 0, 1); PG8_STAGE(PG8_SB(0, 0), b2, voffB);
;             PG8_BAR; PG8_WAIT_L(0); PG8_MMA(0, 1, At, B1); PG8_BAR;
;             PG8_LDA(At, 0, 1); PG8_STAGE(PG8_SA(0, 0), a2, voffA);
;             PG8_BAR; PG8_WAIT_L(0); PG8_MMA(1, 0, At, B0); PG8_BAR; PG8_SCHED;
;             PG8_STAGE(PG8_SB(0, 1), b2 + hstep, voffB);
;             PG8_WAIT_V(6); PG8_BAR; PG8_MMA(1, 1, At, B1); PG8_BAR;
	s_setprio 1
	s_waitcnt lgkmcnt(0)
	v_mfma_f32_16x16x32_bf16 v[62:65], v[130:133], v[178:181], v[62:65]
	v_mfma_f32_16x16x32_bf16 v[58:61], v[138:141], v[178:181], v[58:61]
	v_mfma_f32_16x16x32_bf16 v[50:53], v[130:133], v[186:189], v[50:53]
	v_mfma_f32_16x16x32_bf16 v[42:45], v[138:141], v[186:189], v[42:45]
	v_mfma_f32_16x16x32_bf16 v[34:37], v[130:133], v[194:197], v[34:37]
	v_mfma_f32_16x16x32_bf16 v[26:29], v[138:141], v[194:197], v[26:29]
	v_mfma_f32_16x16x32_bf16 v[18:21], v[130:133], v[202:205], v[18:21]
	v_mfma_f32_16x16x32_bf16 v[10:13], v[138:141], v[202:205], v[10:13]
	v_mfma_f32_16x16x32_bf16 v[62:65], v[134:137], v[182:185], v[62:65]
	v_mfma_f32_16x16x32_bf16 v[58:61], v[142:145], v[182:185], v[58:61]
	v_mfma_f32_16x16x32_bf16 v[50:53], v[134:137], v[190:193], v[50:53]
	v_mfma_f32_16x16x32_bf16 v[42:45], v[142:145], v[190:193], v[42:45]
	v_mfma_f32_16x16x32_bf16 v[34:37], v[134:137], v[198:201], v[34:37]
	v_mfma_f32_16x16x32_bf16 v[26:29], v[142:145], v[198:201], v[26:29]
	v_mfma_f32_16x16x32_bf16 v[18:21], v[134:137], v[206:209], v[18:21]
	v_mfma_f32_16x16x32_bf16 v[10:13], v[142:145], v[206:209], v[10:13]
	s_setprio 0
	s_setprio 1
	v_mfma_f32_16x16x32_bf16 v[54:57], v[146:149], v[178:181], v[54:57]
	v_mfma_f32_16x16x32_bf16 v[46:49], v[166:169], v[178:181], v[46:49]
	v_mfma_f32_16x16x32_bf16 v[38:41], v[146:149], v[186:189], v[38:41]
	v_mfma_f32_16x16x32_bf16 v[30:33], v[166:169], v[186:189], v[30:33]
	v_mfma_f32_16x16x32_bf16 v[22:25], v[146:149], v[194:197], v[22:25]
	v_mfma_f32_16x16x32_bf16 v[14:17], v[166:169], v[194:197], v[14:17]
	v_mfma_f32_16x16x32_bf16 v[6:9], v[146:149], v[202:205], v[6:9]
	v_mfma_f32_16x16x32_bf16 v[2:5], v[166:169], v[202:205], v[2:5]
	v_mfma_f32_16x16x32_bf16 v[54:57], v[162:165], v[182:185], v[54:57]
	v_mfma_f32_16x16x32_bf16 v[46:49], v[174:177], v[182:185], v[46:49]
	v_mfma_f32_16x16x32_bf16 v[38:41], v[162:165], v[190:193], v[38:41]
	v_mfma_f32_16x16x32_bf16 v[30:33], v[174:177], v[190:193], v[30:33]
	v_mfma_f32_16x16x32_bf16 v[22:25], v[162:165], v[198:201], v[22:25]
	v_mfma_f32_16x16x32_bf16 v[14:17], v[174:177], v[198:201], v[14:17]
	v_mfma_f32_16x16x32_bf16 v[6:9], v[162:165], v[206:209], v[6:9]
	v_mfma_f32_16x16x32_bf16 v[2:5], v[174:177], v[206:209], v[2:5]
	s_setprio 0
	s_barrier
	s_add_i32 s50, s50, 2
	s_add_u32 s20, s20, 0x100
	s_addc_u32 s21, s21, 0
	s_add_u32 s57, s57, 0x100
	s_addc_u32 s60, s60, 0
	s_cmp_gt_u32 s50, 5
	s_cbranch_scc0 .LBB0_567
	s_and_b64 vcc, exec, s[8:9]
	s_cbranch_vccz .LBB0_570
	s_barrier
.LBB0_570:
	s_lshl_b32 s16, s39, 8
	s_ashr_i32 s17, s16, 31
	v_lshl_add_u32 v162, s46, 8, v170
	s_lshl_b64 s[20:21], s[16:17], 1
	s_add_u32 s22, s35, s20
	v_ashrrev_i32_e32 v163, 31, v162
	s_addc_u32 s23, s36, s21
	v_lshlrev_b64 v[186:187], 11, v[162:163]
	v_lshl_add_u64 v[130:131], s[22:23], 0, v[186:187]
	v_lshl_add_u64 v[130:131], v[130:131], 0, v[0:1]
	global_load_dwordx4 v[174:177], v[130:131], off
	global_load_dwordx4 v[178:181], v[130:131], off offset:256
	v_or_b32_e32 v130, 16, v162
	v_ashrrev_i32_e32 v131, 31, v130
	v_lshlrev_b64 v[168:169], 11, v[130:131]
	v_lshl_add_u64 v[130:131], s[22:23], 0, v[168:169]
	v_lshl_add_u64 v[130:131], v[130:131], 0, v[0:1]
	global_load_dwordx4 v[182:185], v[130:131], off
	global_load_dwordx4 v[146:149], v[130:131], off offset:256
	v_or_b32_e32 v130, 32, v162
	v_ashrrev_i32_e32 v131, 31, v130
	v_lshlrev_b64 v[166:167], 11, v[130:131]
	v_lshl_add_u64 v[130:131], s[22:23], 0, v[166:167]
	v_lshl_add_u64 v[130:131], v[130:131], 0, v[0:1]
	global_load_dwordx4 v[142:145], v[130:131], off
	global_load_dwordx4 v[134:137], v[130:131], off offset:256
	v_or_b32_e32 v130, 48, v162
	v_ashrrev_i32_e32 v131, 31, v130
	v_lshlrev_b64 v[164:165], 11, v[130:131]
	v_lshl_add_u64 v[130:131], s[22:23], 0, v[164:165]
	v_lshl_add_u64 v[130:131], v[130:131], 0, v[0:1]
	global_load_dwordx4 v[138:141], v[130:131], off
	s_nop 0
	global_load_dwordx4 v[130:133], v[130:131], off offset:256
	s_mov_b64 s[16:17], -1
	s_andn2_b64 vcc, exec, s[4:5]
	s_waitcnt vmcnt(0)
	v_lshlrev_b32_e32 v188, 16, v174
	v_and_b32_e32 v189, 0xffff0000, v174
	v_lshlrev_b32_e32 v174, 16, v175
	v_and_b32_e32 v175, 0xffff0000, v175
	v_pk_mul_f32 v[128:129], v[128:129], v[174:175]
	v_lshlrev_b32_e32 v174, 16, v176
	v_and_b32_e32 v175, 0xffff0000, v176
	v_pk_mul_f32 v[126:127], v[126:127], v[188:189]
	v_pk_mul_f32 v[174:175], v[122:123], v[174:175]
	v_lshlrev_b32_e32 v122, 16, v177
	v_and_b32_e32 v123, 0xffff0000, v177
	v_pk_mul_f32 v[176:177], v[124:125], v[122:123]
	v_cvt_pk_bf16_f32 v122, v126, v127
	v_lshl_add_u64 v[126:127], s[6:7], 0, v[186:187]
	v_lshl_add_u64 v[126:127], v[126:127], 0, s[20:21]
	v_cvt_pk_bf16_f32 v123, v128, v129
	v_cvt_pk_bf16_f32 v124, v174, v175
	v_cvt_pk_bf16_f32 v125, v176, v177
	v_lshl_add_u64 v[126:127], v[126:127], 0, v[0:1]
	global_store_dwordx4 v[126:127], v[122:125], off
	s_nop 1
	v_lshlrev_b32_e32 v122, 16, v178
	v_and_b32_e32 v123, 0xffff0000, v178
	v_pk_mul_f32 v[114:115], v[114:115], v[122:123]
	v_lshlrev_b32_e32 v122, 16, v179
	v_and_b32_e32 v123, 0xffff0000, v179
	v_pk_mul_f32 v[116:117], v[116:117], v[122:123]
	v_lshlrev_b32_e32 v122, 16, v180
	v_and_b32_e32 v123, 0xffff0000, v180
	v_pk_mul_f32 v[122:123], v[106:107], v[122:123]
	v_lshlrev_b32_e32 v106, 16, v181
	v_and_b32_e32 v107, 0xffff0000, v181
	v_pk_mul_f32 v[124:125], v[108:109], v[106:107]
	v_cvt_pk_bf16_f32 v106, v114, v115
	v_cvt_pk_bf16_f32 v107, v116, v117
	v_cvt_pk_bf16_f32 v108, v122, v123
	v_cvt_pk_bf16_f32 v109, v124, v125
	global_store_dwordx4 v[126:127], v[106:109], off offset:256
	v_lshlrev_b32_e32 v114, 16, v184
	v_and_b32_e32 v115, 0xffff0000, v184
	v_lshlrev_b32_e32 v106, 16, v182
; __device__ __forceinline__ u32x4 pack8(const f32x4 v0, const f32x4 v1) { u32x4 w; w.x = cvt_pk_bf16(v0[0], v0[1]); w.y = cvt_pk_bf16(v0[2], v0[3]); w.z = cvt_pk_bf16(v1[0], v1[1]); w.w = cvt_pk_bf16(v1[2], v1[3]); return w; }
; __device__ __forceinline__ float bf_lo(unsigned w) { return __uint_as_float(w << 16); }
; __device__ __forceinline__ float bf_hi(unsigned w) { return __uint_as_float(w & 0xffff0000u); }
;     __device__ __forceinline__ void operator()(const f32x4 (&acc)[2][2][4][2], const Unit& u, int wr, int wc, int fr, int fq) const {
;         _Pragma("unroll") for (int ai = 0; ai < 2; ++ai) {
;             u32x4 gt[4][2], oo[4][2];
;             _Pragma("unroll") for (int m = 0; m < 4; ++m) _Pragma("unroll") for (int bj = 0; bj < 2; ++bj) { const size_t off = (size_t)EPI_ROW(ai, m) * 1024 + u.pn * BM + EPI_CT(bj);
;                 gt[m][bj] = *(const u32x4*)(G + off); if (ADD) oo[m][bj] = *(const u32x4*)(O + off); }
;             _Pragma("unroll") for (int m = 0; m < 4; ++m) _Pragma("unroll") for (int bj = 0; bj < 2; ++bj) { const size_t off = (size_t)EPI_ROW(ai, m) * 1024 + u.pn * BM + EPI_CT(bj);
;                 f32x4 v0 = acc[ai][bj][m][0], v1 = acc[ai][bj][m][1]; const u32x4 g4 = gt[m][bj];
;                 v0[0] *= bf_lo(g4.x); v0[1] *= bf_hi(g4.x); v0[2] *= bf_lo(g4.y); v0[3] *= bf_hi(g4.y); v1[0] *= bf_lo(g4.z); v1[1] *= bf_hi(g4.z); v1[2] *= bf_lo(g4.w); v1[3] *= bf_hi(g4.w);
;                 if (ADD) { const u32x4 o = oo[m][bj];
;                     v0[0] += bf_lo(o.x); v0[1] += bf_hi(o.x); v0[2] += bf_lo(o.y); v0[3] += bf_hi(o.y); v1[0] += bf_lo(o.z); v1[1] += bf_hi(o.z); v1[2] += bf_lo(o.w); v1[3] += bf_hi(o.w); }
;                 *(u32x4*)(O + off) = pack8(v0, v1); }
;             asm volatile("" ::: "memory");
	v_and_b32_e32 v107, 0xffff0000, v182
	v_lshlrev_b32_e32 v108, 16, v183
	v_and_b32_e32 v109, 0xffff0000, v183
	v_pk_mul_f32 v[106:107], v[118:119], v[106:107]
	v_pk_mul_f32 v[108:109], v[120:121], v[108:109]
	v_pk_mul_f32 v[110:111], v[110:111], v[114:115]
	v_lshlrev_b32_e32 v114, 16, v185
	v_and_b32_e32 v115, 0xffff0000, v185
	v_cvt_pk_bf16_f32 v106, v106, v107
	v_cvt_pk_bf16_f32 v107, v108, v109
	v_cvt_pk_bf16_f32 v108, v110, v111
	v_lshl_add_u64 v[110:111], s[6:7], 0, v[168:169]
	v_pk_mul_f32 v[112:113], v[112:113], v[114:115]
	v_lshl_add_u64 v[110:111], v[110:111], 0, s[20:21]
	v_cvt_pk_bf16_f32 v109, v112, v113
	v_lshl_add_u64 v[110:111], v[110:111], 0, v[0:1]
	global_store_dwordx4 v[110:111], v[106:109], off
	s_nop 1
	v_lshlrev_b32_e32 v106, 16, v146
	v_and_b32_e32 v107, 0xffff0000, v146
	v_pk_mul_f32 v[102:103], v[102:103], v[106:107]
	v_lshlrev_b32_e32 v106, 16, v147
	v_and_b32_e32 v107, 0xffff0000, v147
	v_pk_mul_f32 v[104:105], v[104:105], v[106:107]
	v_lshlrev_b32_e32 v106, 16, v148
	v_and_b32_e32 v107, 0xffff0000, v148
	v_pk_mul_f32 v[106:107], v[94:95], v[106:107]
	v_lshlrev_b32_e32 v94, 16, v149
	v_and_b32_e32 v95, 0xffff0000, v149
	v_pk_mul_f32 v[108:109], v[96:97], v[94:95]
	v_cvt_pk_bf16_f32 v94, v102, v103
	v_cvt_pk_bf16_f32 v95, v104, v105
	v_cvt_pk_bf16_f32 v96, v106, v107
	v_cvt_pk_bf16_f32 v97, v108, v109
	global_store_dwordx4 v[110:111], v[94:97], off offset:256
	s_nop 1
	v_lshlrev_b32_e32 v94, 16, v142
	v_and_b32_e32 v95, 0xffff0000, v142
	v_pk_mul_f32 v[94:95], v[98:99], v[94:95]
	v_lshlrev_b32_e32 v98, 16, v144
	v_and_b32_e32 v99, 0xffff0000, v144
	v_lshlrev_b32_e32 v96, 16, v143
	v_and_b32_e32 v97, 0xffff0000, v143
	v_pk_mul_f32 v[98:99], v[90:91], v[98:99]
	v_lshlrev_b32_e32 v90, 16, v145
	v_and_b32_e32 v91, 0xffff0000, v145
	v_pk_mul_f32 v[96:97], v[100:101], v[96:97]
	v_pk_mul_f32 v[100:101], v[92:93], v[90:91]
	v_cvt_pk_bf16_f32 v90, v94, v95
	v_lshl_add_u64 v[94:95], s[6:7], 0, v[166:167]
	v_lshl_add_u64 v[94:95], v[94:95], 0, s[20:21]
	v_cvt_pk_bf16_f32 v91, v96, v97
	v_cvt_pk_bf16_f32 v92, v98, v99
	v_cvt_pk_bf16_f32 v93, v100, v101
	v_lshl_add_u64 v[94:95], v[94:95], 0, v[0:1]
	global_store_dwordx4 v[94:95], v[90:93], off
	s_nop 1
	v_lshlrev_b32_e32 v90, 16, v134
	v_and_b32_e32 v91, 0xffff0000, v134
	v_pk_mul_f32 v[86:87], v[86:87], v[90:91]
	v_lshlrev_b32_e32 v90, 16, v135
	v_and_b32_e32 v91, 0xffff0000, v135
	v_pk_mul_f32 v[88:89], v[88:89], v[90:91]
	v_lshlrev_b32_e32 v90, 16, v136
	v_and_b32_e32 v91, 0xffff0000, v136
	v_pk_mul_f32 v[90:91], v[78:79], v[90:91]
	v_lshlrev_b32_e32 v78, 16, v137
	v_and_b32_e32 v79, 0xffff0000, v137
	v_pk_mul_f32 v[92:93], v[80:81], v[78:79]
	v_cvt_pk_bf16_f32 v78, v86, v87
	v_cvt_pk_bf16_f32 v79, v88, v89
	v_cvt_pk_bf16_f32 v80, v90, v91
	v_cvt_pk_bf16_f32 v81, v92, v93
	global_store_dwordx4 v[94:95], v[78:81], off offset:256
	s_nop 1
	v_lshlrev_b32_e32 v78, 16, v138
	v_and_b32_e32 v79, 0xffff0000, v138
	v_pk_mul_f32 v[78:79], v[82:83], v[78:79]
	v_lshlrev_b32_e32 v82, 16, v140
	v_and_b32_e32 v83, 0xffff0000, v140
	v_lshlrev_b32_e32 v80, 16, v139
	v_and_b32_e32 v81, 0xffff0000, v139
	v_pk_mul_f32 v[82:83], v[74:75], v[82:83]
	v_lshlrev_b32_e32 v74, 16, v141
	v_and_b32_e32 v75, 0xffff0000, v141
	v_pk_mul_f32 v[80:81], v[84:85], v[80:81]
	v_pk_mul_f32 v[84:85], v[76:77], v[74:75]
	v_cvt_pk_bf16_f32 v74, v78, v79
	v_lshl_add_u64 v[78:79], s[6:7], 0, v[164:165]
	v_lshl_add_u64 v[78:79], v[78:79], 0, s[20:21]
	v_cvt_pk_bf16_f32 v75, v80, v81
	v_cvt_pk_bf16_f32 v76, v82, v83
	v_cvt_pk_bf16_f32 v77, v84, v85
	v_lshl_add_u64 v[78:79], v[78:79], 0, v[0:1]
	global_store_dwordx4 v[78:79], v[74:77], off
	s_nop 1
	v_lshlrev_b32_e32 v74, 16, v130
	v_and_b32_e32 v75, 0xffff0000, v130
	v_pk_mul_f32 v[70:71], v[70:71], v[74:75]
	v_lshlrev_b32_e32 v74, 16, v131
	v_and_b32_e32 v75, 0xffff0000, v131
	v_pk_mul_f32 v[72:73], v[72:73], v[74:75]
	v_lshlrev_b32_e32 v74, 16, v132
	v_and_b32_e32 v75, 0xffff0000, v132
	v_pk_mul_f32 v[74:75], v[66:67], v[74:75]
	v_lshlrev_b32_e32 v66, 16, v133
	v_and_b32_e32 v67, 0xffff0000, v133
	v_pk_mul_f32 v[76:77], v[68:69], v[66:67]
	v_cvt_pk_bf16_f32 v66, v70, v71
	v_cvt_pk_bf16_f32 v67, v72, v73
	v_cvt_pk_bf16_f32 v68, v74, v75
	v_cvt_pk_bf16_f32 v69, v76, v77
	global_store_dwordx4 v[78:79], v[66:69], off offset:256
	s_nop 1
	v_add_u32_e32 v66, 0x80, v162
	v_ashrrev_i32_e32 v67, 31, v66
	v_lshlrev_b64 v[98:99], 11, v[66:67]
	v_lshl_add_u64 v[66:67], s[22:23], 0, v[98:99]
	v_lshl_add_u64 v[66:67], v[66:67], 0, v[0:1]
	global_load_dwordx4 v[70:73], v[66:67], off
	global_load_dwordx4 v[74:77], v[66:67], off offset:256
	v_add_u32_e32 v66, 0x90, v162
	v_ashrrev_i32_e32 v67, 31, v66
	v_lshlrev_b64 v[100:101], 11, v[66:67]
	v_lshl_add_u64 v[66:67], s[22:23], 0, v[100:101]
	v_lshl_add_u64 v[66:67], v[66:67], 0, v[0:1]
	global_load_dwordx4 v[78:81], v[66:67], off
	global_load_dwordx4 v[82:85], v[66:67], off offset:256
	v_add_u32_e32 v66, 0xa0, v162
	v_ashrrev_i32_e32 v67, 31, v66
	v_lshlrev_b64 v[102:103], 11, v[66:67]
	v_lshl_add_u64 v[66:67], s[22:23], 0, v[102:103]
	v_lshl_add_u64 v[66:67], v[66:67], 0, v[0:1]
	global_load_dwordx4 v[86:89], v[66:67], off
	global_load_dwordx4 v[90:93], v[66:67], off offset:256
	v_add_u32_e32 v66, 0xb0, v162
	v_ashrrev_i32_e32 v67, 31, v66
	v_lshlrev_b64 v[104:105], 11, v[66:67]
	v_lshl_add_u64 v[66:67], s[22:23], 0, v[104:105]
	v_lshl_add_u64 v[66:67], v[66:67], 0, v[0:1]
	global_load_dwordx4 v[94:97], v[66:67], off
	s_nop 0
	global_load_dwordx4 v[66:69], v[66:67], off offset:256
	s_waitcnt vmcnt(7)
; __device__ __forceinline__ u32x4 pack8(const f32x4 v0, const f32x4 v1) { u32x4 w; w.x = cvt_pk_bf16(v0[0], v0[1]); w.y = cvt_pk_bf16(v0[2], v0[3]); w.z = cvt_pk_bf16(v1[0], v1[1]); w.w = cvt_pk_bf16(v1[2], v1[3]); return w; }
; __device__ __forceinline__ float bf_lo(unsigned w) { return __uint_as_float(w << 16); }
;     __device__ __forceinline__ void operator()(const f32x4 (&acc)[2][2][4][2], const Unit& u, int wr, int wc, int fr, int fq) const {
;         _Pragma("unroll") for (int ai = 0; ai < 2; ++ai) {
;             u32x4 gt[4][2], oo[4][2];
;             _Pragma("unroll") for (int m = 0; m < 4; ++m) _Pragma("unroll") for (int bj = 0; bj < 2; ++bj) { const size_t off = (size_t)EPI_ROW(ai, m) * 1024 + u.pn * BM + EPI_CT(bj);
;                 gt[m][bj] = *(const u32x4*)(G + off); if (ADD) oo[m][bj] = *(const u32x4*)(O + off); }
;             _Pragma("unroll") for (int m = 0; m < 4; ++m) _Pragma("unroll") for (int bj = 0; bj < 2; ++bj) { const size_t off = (size_t)EPI_ROW(ai, m) * 1024 + u.pn * BM + EPI_CT(bj);
;                 f32x4 v0 = acc[ai][bj][m][0], v1 = acc[ai][bj][m][1]; const u32x4 g4 = gt[m][bj];
;                 v0[0] *= bf_lo(g4.x); v0[1] *= bf_hi(g4.x); v0[2] *= bf_lo(g4.y); v0[3] *= bf_hi(g4.y); v1[0] *= bf_lo(g4.z); v1[1] *= bf_hi(g4.z); v1[2] *= bf_lo(g4.w); v1[3] *= bf_hi(g4.w);
;                 if (ADD) { const u32x4 o = oo[m][bj];
;                     v0[0] += bf_lo(o.x); v0[1] += bf_hi(o.x); v0[2] += bf_lo(o.y); v0[3] += bf_hi(o.y); v1[0] += bf_lo(o.z); v1[1] += bf_hi(o.z); v1[2] += bf_lo(o.w); v1[3] += bf_hi(o.w); }
;                 *(u32x4*)(O + off) = pack8(v0, v1); }
;             asm volatile("" ::: "memory");
; template <class Epi, class Sched, bool ALIGN_EPI = false, bool SP2 = false>
; __device__ __forceinline__ void gemm_phase(PG8_LAS unsigned char* lds, const Gemm g, const Sched& S, const Epi& E) {
;     ...
;         if constexpr (!Epi::AFTER_DRAIN) { E(acc, cur, wr, wc, fr, fq); S.done(cur); }
;         if (!has_next) break;
; #pragma unroll
;         for (int a = 0; a < 2; ++a)
; #pragma unroll
;             for (int b = 0; b < 2; ++b)
; #pragma unroll
;                 for (int m = 0; m < 4; ++m)
; #pragma unroll
;                     for (int n = 0; n < 2; ++n) acc[a][b][m][n] = (f32x4){0.f, 0.f, 0.f, 0.f};
;         cur = nxt; cA = nA; cB = nB; ++ui;
;         if constexpr (ALIGN_EPI) { if (wr == 1) PG8_BAR; }
	v_lshlrev_b32_e32 v106, 16, v70
	v_and_b32_e32 v107, 0xffff0000, v70
	v_lshlrev_b32_e32 v70, 16, v71
	v_and_b32_e32 v71, 0xffff0000, v71
	v_pk_mul_f32 v[64:65], v[64:65], v[70:71]
	v_lshlrev_b32_e32 v70, 16, v72
	v_and_b32_e32 v71, 0xffff0000, v72
	v_pk_mul_f32 v[62:63], v[62:63], v[106:107]
	v_pk_mul_f32 v[70:71], v[58:59], v[70:71]
	v_lshlrev_b32_e32 v58, 16, v73
	v_and_b32_e32 v59, 0xffff0000, v73
	v_pk_mul_f32 v[72:73], v[60:61], v[58:59]
	v_cvt_pk_bf16_f32 v58, v62, v63
	v_lshl_add_u64 v[62:63], s[6:7], 0, v[98:99]
	v_lshl_add_u64 v[62:63], v[62:63], 0, s[20:21]
	v_cvt_pk_bf16_f32 v59, v64, v65
	v_cvt_pk_bf16_f32 v60, v70, v71
	v_cvt_pk_bf16_f32 v61, v72, v73
	v_lshl_add_u64 v[62:63], v[62:63], 0, v[0:1]
	global_store_dwordx4 v[62:63], v[58:61], off
	s_waitcnt vmcnt(7)
	s_nop 0
	v_lshlrev_b32_e32 v58, 16, v74
	v_and_b32_e32 v59, 0xffff0000, v74
	v_pk_mul_f32 v[54:55], v[54:55], v[58:59]
	v_lshlrev_b32_e32 v58, 16, v75
	v_and_b32_e32 v59, 0xffff0000, v75
	v_pk_mul_f32 v[56:57], v[56:57], v[58:59]
	v_lshlrev_b32_e32 v58, 16, v76
	v_and_b32_e32 v59, 0xffff0000, v76
	v_pk_mul_f32 v[58:59], v[46:47], v[58:59]
	v_lshlrev_b32_e32 v46, 16, v77
	v_and_b32_e32 v47, 0xffff0000, v77
	v_pk_mul_f32 v[60:61], v[48:49], v[46:47]
	v_cvt_pk_bf16_f32 v46, v54, v55
	v_cvt_pk_bf16_f32 v47, v56, v57
	v_cvt_pk_bf16_f32 v48, v58, v59
	v_cvt_pk_bf16_f32 v49, v60, v61
	global_store_dwordx4 v[62:63], v[46:49], off offset:256
	s_waitcnt vmcnt(7)
	s_nop 0
	v_lshlrev_b32_e32 v46, 16, v78
	v_and_b32_e32 v47, 0xffff0000, v78
	v_pk_mul_f32 v[46:47], v[50:51], v[46:47]
	v_lshlrev_b32_e32 v50, 16, v80
	v_and_b32_e32 v51, 0xffff0000, v80
	v_lshlrev_b32_e32 v48, 16, v79
	v_and_b32_e32 v49, 0xffff0000, v79
	v_pk_mul_f32 v[50:51], v[42:43], v[50:51]
	v_lshlrev_b32_e32 v42, 16, v81
	v_and_b32_e32 v43, 0xffff0000, v81
	v_pk_mul_f32 v[48:49], v[52:53], v[48:49]
	v_pk_mul_f32 v[52:53], v[44:45], v[42:43]
	v_cvt_pk_bf16_f32 v42, v46, v47
	v_lshl_add_u64 v[46:47], s[6:7], 0, v[100:101]
	v_lshl_add_u64 v[46:47], v[46:47], 0, s[20:21]
	v_cvt_pk_bf16_f32 v43, v48, v49
	v_cvt_pk_bf16_f32 v44, v50, v51
	v_cvt_pk_bf16_f32 v45, v52, v53
	v_lshl_add_u64 v[46:47], v[46:47], 0, v[0:1]
	global_store_dwordx4 v[46:47], v[42:45], off
	s_waitcnt vmcnt(7)
	s_nop 0
	v_lshlrev_b32_e32 v42, 16, v82
	v_and_b32_e32 v43, 0xffff0000, v82
	v_pk_mul_f32 v[38:39], v[38:39], v[42:43]
	v_lshlrev_b32_e32 v42, 16, v83
	v_and_b32_e32 v43, 0xffff0000, v83
	v_pk_mul_f32 v[40:41], v[40:41], v[42:43]
	v_lshlrev_b32_e32 v42, 16, v84
	v_and_b32_e32 v43, 0xffff0000, v84
	v_pk_mul_f32 v[42:43], v[30:31], v[42:43]
	v_lshlrev_b32_e32 v30, 16, v85
	v_and_b32_e32 v31, 0xffff0000, v85
	v_pk_mul_f32 v[44:45], v[32:33], v[30:31]
	v_cvt_pk_bf16_f32 v30, v38, v39
	v_cvt_pk_bf16_f32 v31, v40, v41
	v_cvt_pk_bf16_f32 v32, v42, v43
	v_cvt_pk_bf16_f32 v33, v44, v45
	global_store_dwordx4 v[46:47], v[30:33], off offset:256
	s_waitcnt vmcnt(7)
	s_nop 0
	v_lshlrev_b32_e32 v30, 16, v86
	v_and_b32_e32 v31, 0xffff0000, v86
	v_pk_mul_f32 v[30:31], v[34:35], v[30:31]
	v_lshlrev_b32_e32 v34, 16, v88
	v_and_b32_e32 v35, 0xffff0000, v88
	v_lshlrev_b32_e32 v32, 16, v87
	v_and_b32_e32 v33, 0xffff0000, v87
	v_pk_mul_f32 v[34:35], v[26:27], v[34:35]
	v_lshlrev_b32_e32 v26, 16, v89
	v_and_b32_e32 v27, 0xffff0000, v89
	v_pk_mul_f32 v[32:33], v[36:37], v[32:33]
	v_pk_mul_f32 v[36:37], v[28:29], v[26:27]
	v_cvt_pk_bf16_f32 v26, v30, v31
	v_lshl_add_u64 v[30:31], s[6:7], 0, v[102:103]
	v_lshl_add_u64 v[30:31], v[30:31], 0, s[20:21]
	v_cvt_pk_bf16_f32 v27, v32, v33
	v_cvt_pk_bf16_f32 v28, v34, v35
	v_cvt_pk_bf16_f32 v29, v36, v37
	v_lshl_add_u64 v[30:31], v[30:31], 0, v[0:1]
	global_store_dwordx4 v[30:31], v[26:29], off
	s_waitcnt vmcnt(7)
	s_nop 0
	v_lshlrev_b32_e32 v26, 16, v90
	v_and_b32_e32 v27, 0xffff0000, v90
	v_pk_mul_f32 v[22:23], v[22:23], v[26:27]
	v_lshlrev_b32_e32 v26, 16, v91
	v_and_b32_e32 v27, 0xffff0000, v91
	v_pk_mul_f32 v[24:25], v[24:25], v[26:27]
	v_lshlrev_b32_e32 v26, 16, v92
	v_and_b32_e32 v27, 0xffff0000, v92
	v_pk_mul_f32 v[26:27], v[14:15], v[26:27]
	v_lshlrev_b32_e32 v14, 16, v93
	v_and_b32_e32 v15, 0xffff0000, v93
	v_pk_mul_f32 v[28:29], v[16:17], v[14:15]
	v_cvt_pk_bf16_f32 v14, v22, v23
	v_cvt_pk_bf16_f32 v15, v24, v25
	v_cvt_pk_bf16_f32 v16, v26, v27
	v_cvt_pk_bf16_f32 v17, v28, v29
	global_store_dwordx4 v[30:31], v[14:17], off offset:256
	s_waitcnt vmcnt(7)
	s_nop 0
	v_lshlrev_b32_e32 v14, 16, v94
	v_and_b32_e32 v15, 0xffff0000, v94
	v_pk_mul_f32 v[14:15], v[18:19], v[14:15]
	v_lshlrev_b32_e32 v18, 16, v96
	v_and_b32_e32 v19, 0xffff0000, v96
	v_lshlrev_b32_e32 v16, 16, v95
	v_and_b32_e32 v17, 0xffff0000, v95
	v_pk_mul_f32 v[18:19], v[10:11], v[18:19]
	v_lshlrev_b32_e32 v10, 16, v97
	v_and_b32_e32 v11, 0xffff0000, v97
	v_pk_mul_f32 v[16:17], v[20:21], v[16:17]
	v_pk_mul_f32 v[20:21], v[12:13], v[10:11]
	v_cvt_pk_bf16_f32 v10, v14, v15
	v_lshl_add_u64 v[14:15], s[6:7], 0, v[104:105]
	v_lshl_add_u64 v[14:15], v[14:15], 0, s[20:21]
	v_cvt_pk_bf16_f32 v11, v16, v17
	v_cvt_pk_bf16_f32 v12, v18, v19
	v_cvt_pk_bf16_f32 v13, v20, v21
	v_lshl_add_u64 v[14:15], v[14:15], 0, v[0:1]
	global_store_dwordx4 v[14:15], v[10:13], off
	s_waitcnt vmcnt(7)
	s_nop 0
	v_lshlrev_b32_e32 v10, 16, v66
	v_and_b32_e32 v11, 0xffff0000, v66
	v_pk_mul_f32 v[6:7], v[6:7], v[10:11]
	v_lshlrev_b32_e32 v10, 16, v67
	v_and_b32_e32 v11, 0xffff0000, v67
	v_pk_mul_f32 v[8:9], v[8:9], v[10:11]
	v_lshlrev_b32_e32 v10, 16, v68
	v_and_b32_e32 v11, 0xffff0000, v68
	v_pk_mul_f32 v[10:11], v[2:3], v[10:11]
	v_lshlrev_b32_e32 v2, 16, v69
	v_and_b32_e32 v3, 0xffff0000, v69
	v_pk_mul_f32 v[12:13], v[4:5], v[2:3]
	v_cvt_pk_bf16_f32 v2, v6, v7
	v_cvt_pk_bf16_f32 v3, v8, v9
	v_cvt_pk_bf16_f32 v4, v10, v11
	v_cvt_pk_bf16_f32 v5, v12, v13
	global_store_dwordx4 v[14:15], v[2:5], off offset:256
	s_cbranch_vccnz .LBB0_559
	s_andn2_b64 vcc, exec, s[0:1]
	s_cbranch_vccnz .LBB0_558
	s_branch .LBB0_558

;     __device__ __forceinline__ bool next(int i, Unit& u) const { const int L = i * G + c; if (L >= 512) return false; u.pm = L; u.pn = L >> 4; return true; }
; #define PG8_WAIT_V(n) asm volatile("s_waitcnt vmcnt(" #n ")" ::: "memory")
; #define PG8_BAR __builtin_amdgcn_s_barrier()
; template <class Epi, class Sched, bool ALIGN_EPI = false, bool SP2 = false>
; __device__ __forceinline__ void gemm_phase(PG8_LAS unsigned char* lds, const Gemm g, const Sched& S, const Epi& E) {
;     int tid_ = threadIdx.x; asm volatile("" : "+v"(tid_));
;     const int tid = tid_, wid = __builtin_amdgcn_readfirstlane(tid >> 6), lane = tid & 63, wr = wid >> 2, wc = wid & 3, fr = lane & 15, fq = lane >> 4;
;     const int K = g.K, nt = K / BK, LD = g.ld ? g.ld : g.K;
;     unsigned voffA[2], voffB[2];
; #pragma unroll
;     for (int i = 0; i < 2; ++i) { int R, C; stage_rc(tid * 16 + i * 8192, R, C); const int Rb = Epi::PERM ? ((R & ~31) + perm32(R & 31)) : R;
;         voffA[i] = (unsigned)(R * LD + C) * 2u; voffB[i] = (unsigned)(Rb * LD + C) * 2u; }
;     const size_t kstep = (size_t)(BK * 2);
;     const size_t hstep = (size_t)HALF * LD * 2;
;     const size_t tstep = 2 * hstep;
;     const unsigned ldsw = (unsigned)wid * 1024u;
;     const int aoff = lds_byte(wr * 64 + fr, fq * 8), boff = lds_byte(wc * 32 + fr, fq * 8);
;     ...
;     Unit cur, nxt; int ui = 0;
;     if (!S.next(0, cur)) return;
;     f32x4 acc[2][2][4][2];
; #pragma unroll
;     for (int a = 0; a < 2; ++a)
; #pragma unroll
;         for (int b = 0; b < 2; ++b)
; #pragma unroll
;             for (int m = 0; m < 4; ++m)
; #pragma unroll
;                 for (int n = 0; n < 2; ++n) acc[a][b][m][n] = (f32x4){0.f, 0.f, 0.f, 0.f};
;     bf16x8 At[4][2], B0[2][2], B1[2][2];
;     const char* cA = (const char*)g.A + (size_t)cur.pm * tstep; const char* cB = (const char*)g.Bt + (size_t)cur.pn * tstep;
;     S.a_ready(cur);
;     if constexpr (SP2) {
;         PG8_STAGE(PG8_SB(0, 0), cB, voffB); PG8_STAGE(PG8_SB(0, 1), cB + hstep, voffB); PG8_STAGE(PG8_SA(0, 0), cA, voffA); PG8_STAGE(PG8_SA(0, 1), cA + hstep, voffA);
;         if (wr == 1) PG8_BAR;
;         PG8_WAIT_V(2); PG8_BAR;
;         PG8_STAGE(PG8_SB(1, 0), cB + kstep, voffB); PG8_STAGE(PG8_SA(1, 0), cA + kstep, voffA); PG8_STAGE(PG8_SB(1, 1), cB + hstep + kstep, voffB);
;         PG8_WAIT_V(6); PG8_BAR;
.LBB0_619:
	s_or_b64 exec, exec, s[36:37]
	v_readlane_b32 s0, v254, 56
	s_mov_b64 s[4:5], s[72:73]
	v_mov_b32_e32 v15, v242
	v_readlane_b32 s1, v254, 57
	s_waitcnt lgkmcnt(0)
	s_barrier
	s_and_b64 vcc, exec, s[0:1]
	v_readfirstlane_b32 s10, v15
	s_cbranch_vccz .LBB0_639
	v_lshlrev_b32_e32 v2, 4, v15
	v_add_u32_e32 v3, 0x2000, v2
	v_ashrrev_i32_e32 v0, 31, v3
	v_lshrrev_b32_e32 v0, 22, v0
	v_add_u32_e32 v0, v3, v0
	v_ashrrev_i32_e32 v0, 10, v0
	v_mul_i32_i24_e32 v4, 0x400, v0
	v_sub_u32_e32 v3, v3, v4
	v_lshrrev_b32_e32 v4, 4, v3
	v_bitop3_b32 v3, v4, v3, 32 bitop3:0x6c
	v_ashrrev_i32_e32 v4, 31, v3
	v_lshrrev_b32_e32 v4, 26, v4
	v_add_u32_e32 v4, v3, v4
	v_lshlrev_b32_e32 v5, 3, v0
	v_ashrrev_i32_e32 v10, 6, v4
	v_and_b32_e32 v5, -16, v5
	v_add_u32_e32 v5, v10, v5
	v_and_b32_e32 v6, 3, v10
	s_mov_b32 s0, 0x3fffe0
	v_lshrrev_b32_e32 v7, 2, v5
	v_lshlrev_b32_e32 v8, 1, v5
	v_and_b32_e32 v4, 0xc0, v4
	v_and_or_b32 v6, v5, s0, v6
	v_and_b32_e32 v7, 4, v7
	v_and_b32_e32 v8, 24, v8
	v_sub_u32_e32 v3, v3, v4
	v_or3_b32 v6, v6, v7, v8
	v_lshlrev_b32_e32 v7, 5, v0
	v_ashrrev_i16_sdwa v3, v241, sext(v3) dst_sel:DWORD dst_unused:UNUSED_PAD src0_sel:DWORD src1_sel:BYTE_0
	v_and_b32_e32 v7, 32, v7
	v_bfe_i32 v11, v3, 0, 16
	v_add_lshl_u32 v3, v7, v11, 1
	v_lshl_add_u32 v194, v6, 10, v3
	v_lshl_add_u32 v196, v5, 10, v3
	v_bfe_i32 v3, v15, 27, 1
	v_lshrrev_b32_e32 v3, 22, v3
	v_add_u32_e32 v3, v2, v3
	v_and_b32_e32 v3, 0xfffffc00, v3
	v_sub_u32_e32 v2, v2, v3
	v_lshrrev_b32_e32 v3, 4, v2
	v_ashrrev_i32_e32 v4, 31, v15
	v_bitop3_b32 v2, v3, v2, 32 bitop3:0x6c
	v_lshrrev_b32_e32 v4, 26, v4
	v_ashrrev_i32_e32 v3, 31, v2
	v_add_u32_e32 v4, v15, v4
	v_lshrrev_b32_e32 v3, 26, v3
	v_ashrrev_i32_e32 v13, 6, v4
	v_add_u32_e32 v3, v2, v3
	v_lshlrev_b32_e32 v4, 3, v13
	s_add_u32 s26, s4, 0xd400000
	v_ashrrev_i32_e32 v12, 6, v3
	v_and_b32_e32 v4, -16, v4
	s_addc_u32 s27, s5, 0
	v_add_u32_e32 v4, v12, v4
	s_add_u32 s28, s4, 0x1c00000
	v_and_b32_e32 v5, 3, v12
	v_lshrrev_b32_e32 v6, 2, v4
	v_lshlrev_b32_e32 v7, 1, v4
	v_and_b32_e32 v3, 0xc0, v3
	s_addc_u32 s29, s5, 0
	s_ashr_i32 s11, s10, 6
	v_and_or_b32 v5, v4, s0, v5
	v_and_b32_e32 v6, 4, v6
	v_and_b32_e32 v7, 24, v7
	v_sub_u32_e32 v2, v2, v3
	s_ashr_i32 s12, s10, 8
	s_lshl_b32 s30, s11, 10
	v_or3_b32 v5, v5, v6, v7
	v_lshlrev_b32_e32 v6, 5, v13
	v_ashrrev_i16_sdwa v2, v241, sext(v2) dst_sel:DWORD dst_unused:UNUSED_PAD src0_sel:DWORD src1_sel:BYTE_0
	v_readlane_b32 s0, v255, 12
	v_and_b32_e32 v6, 32, v6
	v_bfe_i32 v14, v2, 0, 16
	v_readlane_b32 s1, v255, 13
	s_add_u32 s16, s28, s0
	v_add_lshl_u32 v2, v6, v14, 1
	s_addc_u32 s17, s29, s1
	s_add_i32 s31, s30, 0
	v_lshl_add_u32 v198, v5, 10, v2
	s_add_i32 m0, s31, 0x10000
	v_lshl_add_u32 v200, v4, 10, v2
	global_load_lds_dwordx4 v198, s[16:17]
	s_add_i32 m0, s31, 0x12000
	s_add_u32 s0, s16, 0x20000
	global_load_lds_dwordx4 v194, s[16:17]
	s_addc_u32 s1, s17, 0
	s_add_i32 m0, s31, 0x14000
	v_mov_b32_e32 v199, v1
	global_load_lds_dwordx4 v198, s[0:1]
	s_add_i32 m0, s31, 0x16000
	v_mov_b32_e32 v195, v1
	global_load_lds_dwordx4 v194, s[0:1]
	v_readlane_b32 s0, v255, 10
	v_readlane_b32 s1, v255, 11
	s_add_u32 s22, s26, s0
	s_addc_u32 s23, s27, s1
	s_add_i32 s34, s31, 0x2000
	s_mov_b32 m0, s31
	s_add_u32 s0, s22, 0x20000
	global_load_lds_dwordx4 v200, s[22:23]
	s_mov_b32 m0, s34
	s_addc_u32 s1, s23, 0
	s_add_i32 s35, s31, 0x4000
	global_load_lds_dwordx4 v196, s[22:23]
	s_mov_b32 m0, s35
	s_add_i32 s36, s31, 0x6000
	global_load_lds_dwordx4 v200, s[0:1]
	s_mov_b32 m0, s36
	v_mov_b32_e32 v201, v1
	global_load_lds_dwordx4 v196, s[0:1]
	v_mov_b32_e32 v197, v1
	s_cmp_eq_u32 s12, 1
	v_lshl_add_u64 v[8:9], s[16:17], 0, v[198:199]
	v_lshl_add_u64 v[6:7], s[16:17], 0, v[194:195]
	v_lshl_add_u64 v[2:3], s[22:23], 0, v[200:201]
	s_cselect_b64 s[0:1], -1, 0
	s_cmp_lg_u32 s12, 1
	v_lshl_add_u64 v[4:5], s[22:23], 0, v[196:197]
	s_cbranch_scc1 .LBB0_622
.LBB0_622:
	s_add_u32 s6, s4, 0x2b400000
	v_lshrrev_b32_e32 v17, 1, v15
	s_addc_u32 s7, s5, 0
	v_and_b32_e32 v17, 24, v17
	s_add_u32 s8, s4, 0x11400000
	v_and_b32_e32 v16, 15, v15
	v_lshlrev_b32_e32 v18, 1, v17
	v_lshlrev_b32_e32 v15, 2, v15
	s_addc_u32 s9, s5, 0
	v_lshl_or_b32 v203, s12, 6, v16
	v_lshl_or_b32 v16, v16, 6, v18
	s_lshl_b32 s4, s12, 13
	v_and_b32_e32 v15, 32, v15
	v_bitop3_b32 v18, v16, s4, v15 bitop3:0xde
	s_lshl_b32 s4, s11, 5
	s_and_b32 s12, s4, 0x60
	s_add_i32 m0, s31, 0x18000
	v_lshl_add_u64 v[8:9], v[8:9], 0, s[94:95]
	s_lshl_b32 s4, s12, 7
	s_waitcnt vmcnt(2)
	s_barrier
	global_load_lds_dwordx4 v[8:9], off
	v_lshl_add_u64 v[6:7], v[6:7], 0, s[94:95]
	s_add_i32 m0, s31, 0x1a000
	s_add_i32 s37, s31, 0x8000
	s_add_i32 s38, s31, 0xa000
	v_bitop3_b32 v205, v16, s4, v15 bitop3:0xde
	global_load_lds_dwordx4 v[6:7], off
	v_lshl_add_u64 v[2:3], v[2:3], 0, s[94:95]
	s_mov_b32 m0, s37
	s_add_u32 s4, s16, 0x20080
	global_load_lds_dwordx4 v[2:3], off
	v_lshl_add_u64 v[2:3], v[4:5], 0, s[94:95]
	s_mov_b32 m0, s38
	s_addc_u32 s5, s17, 0
	global_load_lds_dwordx4 v[2:3], off
	s_add_i32 m0, s31, 0x1c000
	v_lshl_add_u64 v[2:3], s[4:5], 0, v[198:199]
	global_load_lds_dwordx4 v[2:3], off
	v_lshl_add_u64 v[2:3], s[4:5], 0, v[194:195]
	s_add_i32 m0, s31, 0x1e000
	s_cmpk_lt_u32 s10, 0x100
	global_load_lds_dwordx4 v[2:3], off
	v_lshlrev_b32_e32 v2, 13, v13
	v_and_b32_e32 v2, 0xffffc000, v2
	v_lshl_add_u32 v2, v12, 10, v2
	v_and_b32_e32 v3, 1, v13
	v_lshl_or_b32 v2, v3, 6, v2
	v_lshl_add_u32 v206, v14, 1, v2
	v_lshlrev_b32_e32 v2, 13, v0
	v_and_b32_e32 v2, 0xffffc000, v2
	s_waitcnt vmcnt(6)
	v_lshl_add_u32 v2, v10, 10, v2
	v_and_b32_e32 v0, 1, v0
	v_or_b32_e32 v202, s12, v17
	v_lshl_or_b32 v0, v0, 6, v2
	v_readlane_b32 s4, v255, 18
	s_cselect_b64 s[10:11], -1, 0
	v_or_b32_e32 v204, 0x80, v202
	v_mov_b32_e32 v207, v1
	v_lshl_add_u32 v208, v11, 1, v0
	v_mov_b32_e32 v209, v1
	s_mov_b32 s39, 0
	v_add_u32_e32 v226, 0, v18
	v_readlane_b32 s33, v255, 9
	s_mov_b32 s46, s4
	s_barrier
	v_readlane_b32 s5, v255, 19
	s_branch .LBB0_625

;     __device__ __forceinline__ bool next(int i, Unit& u) const { const int L = i * G + c; if (L >= 512) return false; u.pm = L; u.pn = L >> 4; return true; }
; #define PG8_STAGE(bufoff, gbase, voff) do { _Pragma("unroll") for (int _i = 0; _i < 2; ++_i) \
;         __builtin_amdgcn_global_load_lds((const unsigned*)((const char*)(gbase) + (voff)[_i]), (PG8_LAS unsigned*)(lds + (bufoff) + ldsw + _i * 8192), 16, 0, 0); } while (0)
; #define PG8_LDA(dst, b, h) do { _Pragma("unroll") for (int m = 0; m < 4; ++m) _Pragma("unroll") for (int k = 0; k < 2; ++k) dst[m][k] = *(const PG8_LAS bf16x8*)(lds + PG8_SA(b, h) + aoff + m * 2048 + k * 1024); } while (0)
; #define PG8_LDB(dst, b, h) do { _Pragma("unroll") for (int n = 0; n < 2; ++n) _Pragma("unroll") for (int k = 0; k < 2; ++k) dst[n][k] = *(const PG8_LAS bf16x8*)(lds + PG8_SB(b, h) + boff + n * 2048 + k * 1024); } while (0)
; #define PG8_WAIT_V(n) asm volatile("s_waitcnt vmcnt(" #n ")" ::: "memory")
; template <class Epi, class Sched, bool ALIGN_EPI = false, bool SP2 = false>
; __device__ __forceinline__ void gemm_phase(PG8_LAS unsigned char* lds, const Gemm g, const Sched& S, const Epi& E) {
;     ...
;         const bool has_next = S.next(ui + 1, nxt);
;         const char* nA = has_next ? (const char*)g.A + (size_t)nxt.pm * tstep : cA; const char* nB = has_next ? (const char*)g.Bt + (size_t)nxt.pn * tstep : cB;
;         for (int t = 0; t < nt; t += 2) {
;             const bool last = (t == nt - 2);
;             const char* a1 = cA + (size_t)(t + 1) * kstep;
;             const char* a2 = last ? nA : cA + (size_t)(t + 2) * kstep; const char* b2 = last ? nB : cB + (size_t)(t + 2) * kstep;
;             const char* a3 = a2 + kstep; const char* b3 = b2 + kstep;
;             if (last && has_next) S.a_ready(nxt);
;             if constexpr (SP2) {
;             PG8_LDB(B0, 0, 0); PG8_LDB(B1, 0, 1); PG8_SCHED; PG8_LDA(At, 0, 0); PG8_STAGE(PG8_SA(1, 1), a1 + hstep, voffA);
;             PG8_WAIT_V(8); PG8_WAIT_L(0); PG8_BAR; PG8_MMA(0, 0, At, B0); PG8_MMA(0, 1, At, B1); PG8_BAR; PG8_SCHED;
;     ...
;         for (int a = 0; a < 2; ++a)
; #pragma unroll
;             for (int b = 0; b < 2; ++b)
; #pragma unroll
;                 for (int m = 0; m < 4; ++m)
; #pragma unroll
;                     for (int n = 0; n < 2; ++n) acc[a][b][m][n] = (f32x4){0.f, 0.f, 0.f, 0.f};
;         cur = nxt; cA = nA; cB = nB; ++ui;
.LBB0_631:
	s_ashr_i32 s15, s14, 31
	s_lshl_b64 s[18:19], s[14:15], 18
	s_add_u32 s18, s26, s18
	s_addc_u32 s19, s27, s19
	s_and_b64 s[20:21], s[4:5], exec
	s_cselect_b32 s15, s19, s23
	s_cselect_b32 s55, s18, s22
	s_ashr_i32 s13, s12, 31
	s_lshl_b64 s[20:21], s[12:13], 18
	s_add_u32 s20, s28, s20
	s_addc_u32 s21, s29, s21
	s_and_b64 s[24:25], s[4:5], exec
	s_cselect_b32 s13, s21, s17
	s_cselect_b32 s56, s20, s16
	s_add_u32 s22, s22, 0x20080
	s_addc_u32 s23, s23, 0
	s_add_u32 s57, s16, 0x100
	v_mov_b32_e32 v2, 0
	s_addc_u32 s60, s17, 0
	s_mov_b32 s50, -2
	v_mov_b32_e32 v3, v2
	v_mov_b32_e32 v4, v2
	v_mov_b32_e32 v5, v2
	v_mov_b32_e32 v6, v2
	v_mov_b32_e32 v7, v2
	v_mov_b32_e32 v8, v2
	v_mov_b32_e32 v9, v2
	v_mov_b32_e32 v18, v2
	v_mov_b32_e32 v19, v2
	v_mov_b32_e32 v20, v2
	v_mov_b32_e32 v21, v2
	v_mov_b32_e32 v22, v2
	v_mov_b32_e32 v23, v2
	v_mov_b32_e32 v24, v2
	v_mov_b32_e32 v25, v2
	v_mov_b32_e32 v34, v2
	v_mov_b32_e32 v35, v2
	v_mov_b32_e32 v36, v2
	v_mov_b32_e32 v37, v2
	v_mov_b32_e32 v38, v2
	v_mov_b32_e32 v39, v2
	v_mov_b32_e32 v40, v2
	v_mov_b32_e32 v41, v2
	v_mov_b32_e32 v50, v2
	v_mov_b32_e32 v51, v2
	v_mov_b32_e32 v52, v2
	v_mov_b32_e32 v53, v2
	v_mov_b32_e32 v54, v2
	v_mov_b32_e32 v55, v2
	v_mov_b32_e32 v56, v2
	v_mov_b32_e32 v57, v2
	v_mov_b32_e32 v10, v2
	v_mov_b32_e32 v11, v2
	v_mov_b32_e32 v12, v2
	v_mov_b32_e32 v13, v2
	v_mov_b32_e32 v14, v2
	v_mov_b32_e32 v15, v2
	v_mov_b32_e32 v16, v2
	v_mov_b32_e32 v17, v2
	v_mov_b32_e32 v26, v2
	v_mov_b32_e32 v27, v2
	v_mov_b32_e32 v28, v2
	v_mov_b32_e32 v29, v2
	v_mov_b32_e32 v30, v2
	v_mov_b32_e32 v31, v2
	v_mov_b32_e32 v32, v2
	v_mov_b32_e32 v33, v2
	v_mov_b32_e32 v42, v2
	v_mov_b32_e32 v43, v2
	v_mov_b32_e32 v44, v2
	v_mov_b32_e32 v45, v2
	v_mov_b32_e32 v46, v2
	v_mov_b32_e32 v47, v2
	v_mov_b32_e32 v48, v2
	v_mov_b32_e32 v49, v2
	v_mov_b32_e32 v58, v2
	v_mov_b32_e32 v59, v2
	v_mov_b32_e32 v60, v2
	v_mov_b32_e32 v61, v2
	v_mov_b32_e32 v62, v2
	v_mov_b32_e32 v63, v2
	v_mov_b32_e32 v64, v2
	v_mov_b32_e32 v65, v2
	v_mov_b32_e32 v66, v2
	v_mov_b32_e32 v67, v2
	v_mov_b32_e32 v68, v2
	v_mov_b32_e32 v69, v2
	v_mov_b32_e32 v70, v2
	v_mov_b32_e32 v71, v2
	v_mov_b32_e32 v72, v2
	v_mov_b32_e32 v73, v2
	v_mov_b32_e32 v82, v2
	v_mov_b32_e32 v83, v2
	v_mov_b32_e32 v84, v2
	v_mov_b32_e32 v85, v2
	v_mov_b32_e32 v86, v2
	v_mov_b32_e32 v87, v2
	v_mov_b32_e32 v88, v2
	v_mov_b32_e32 v89, v2
	v_mov_b32_e32 v98, v2
	v_mov_b32_e32 v99, v2
	v_mov_b32_e32 v100, v2
	v_mov_b32_e32 v101, v2
	v_mov_b32_e32 v102, v2
	v_mov_b32_e32 v103, v2
	v_mov_b32_e32 v104, v2
	v_mov_b32_e32 v105, v2
	v_mov_b32_e32 v114, v2
	v_mov_b32_e32 v115, v2
	v_mov_b32_e32 v116, v2
	v_mov_b32_e32 v117, v2
	v_mov_b32_e32 v118, v2
	v_mov_b32_e32 v119, v2
	v_mov_b32_e32 v120, v2
	v_mov_b32_e32 v121, v2
	v_mov_b32_e32 v74, v2
	v_mov_b32_e32 v75, v2
	v_mov_b32_e32 v76, v2
	v_mov_b32_e32 v77, v2
	v_mov_b32_e32 v78, v2
	v_mov_b32_e32 v79, v2
	v_mov_b32_e32 v80, v2
	v_mov_b32_e32 v81, v2
	v_mov_b32_e32 v90, v2
	v_mov_b32_e32 v91, v2
	v_mov_b32_e32 v92, v2
	v_mov_b32_e32 v93, v2
	v_mov_b32_e32 v94, v2
	v_mov_b32_e32 v95, v2
	v_mov_b32_e32 v96, v2
	v_mov_b32_e32 v97, v2
	v_mov_b32_e32 v106, v2
	v_mov_b32_e32 v107, v2
	v_mov_b32_e32 v108, v2
	v_mov_b32_e32 v109, v2
	v_mov_b32_e32 v110, v2
	v_mov_b32_e32 v111, v2
	v_mov_b32_e32 v112, v2
	v_mov_b32_e32 v113, v2
	v_mov_b32_e32 v122, v2
	v_mov_b32_e32 v123, v2
	v_mov_b32_e32 v124, v2
	v_mov_b32_e32 v125, v2
	v_mov_b32_e32 v126, v2
	v_mov_b32_e32 v127, v2
	v_mov_b32_e32 v128, v2
	v_mov_b32_e32 v129, v2
	s_cmp_eq_u64 s[0:1], 0
	s_cbranch_scc1 .Lboff_skip_H
	s_barrier
.Lboff_skip_H:
.LBB0_632:
	s_add_u32 s16, s22, 0xfffe0080
	s_addc_u32 s17, s23, -1
	s_add_i32 s52, 0, 0x10000
	s_cmp_eq_u32 s50, 4
	s_cselect_b32 s25, s15, s17
	s_cselect_b32 s24, s55, s16
	v_add_u32_e32 v0, s52, v205
	s_cselect_b32 s17, s13, s60
	s_cselect_b32 s16, s56, s57
	s_add_i32 s61, 0, 0x14000
	ds_read_b128 v[130:133], v0
	ds_read_b128 v[134:137], v0 offset:1024
	ds_read_b128 v[138:141], v0 offset:2048
	ds_read_b128 v[142:145], v0 offset:3072
	v_add_u32_e32 v0, s61, v205
	ds_read_b128 v[146:149], v0
	ds_read_b128 v[150:153], v0 offset:1024
	ds_read_b128 v[154:157], v0 offset:2048
	ds_read_b128 v[158:161], v0 offset:3072
	v_lshl_add_u64 v[210:211], s[22:23], 0, v[206:207]
	s_add_i32 m0, s31, 0xc000
	ds_read_b128 v[162:165], v226
	ds_read_b128 v[166:169], v226 offset:1024
	ds_read_b128 v[170:173], v226 offset:2048
	ds_read_b128 v[174:177], v226 offset:3072
	ds_read_b128 v[178:181], v226 offset:4096
	ds_read_b128 v[182:185], v226 offset:5120
	ds_read_b128 v[186:189], v226 offset:6144
	ds_read_b128 v[190:193], v226 offset:7168
	global_load_lds_dwordx4 v[210:211], off
	v_lshl_add_u64 v[210:211], s[22:23], 0, v[208:209]
	s_add_i32 m0, s31, 0xe000
	s_nop 0
	global_load_lds_dwordx4 v[210:211], off
	s_waitcnt vmcnt(8)
	s_waitcnt lgkmcnt(0)
	s_barrier
; #define PG8_STAGE(bufoff, gbase, voff) do { _Pragma("unroll") for (int _i = 0; _i < 2; ++_i) \
;         __builtin_amdgcn_global_load_lds((const unsigned*)((const char*)(gbase) + (voff)[_i]), (PG8_LAS unsigned*)(lds + (bufoff) + ldsw + _i * 8192), 16, 0, 0); } while (0)
; #define PG8_LDA(dst, b, h) do { _Pragma("unroll") for (int m = 0; m < 4; ++m) _Pragma("unroll") for (int k = 0; k < 2; ++k) dst[m][k] = *(const PG8_LAS bf16x8*)(lds + PG8_SA(b, h) + aoff + m * 2048 + k * 1024); } while (0)
; #define PG8_MMA(ai, bj, At, Bt) do { __builtin_amdgcn_s_setprio(1); _Pragma("unroll") for (int m = 0; m < 4; ++m) _Pragma("unroll") for (int n = 0; n < 2; ++n) _Pragma("unroll") for (int k = 0; k < 2; ++k) \
;         acc[ai][bj][m][n] = __builtin_amdgcn_mfma_f32_16x16x32_bf16(Bt[n][k], At[m][k], acc[ai][bj][m][n], 0, 0, 0); __builtin_amdgcn_s_setprio(0); } while (0)
; #define PG8_WAIT_V(n) asm volatile("s_waitcnt vmcnt(" #n ")" ::: "memory")
; #define PG8_WAIT_L(n) asm volatile("s_waitcnt lgkmcnt(" #n ")" ::: "memory")
; #define PG8_BAR __builtin_amdgcn_s_barrier()
; #define PG8_SCHED __builtin_amdgcn_sched_barrier(0)
; template <class Epi, class Sched, bool ALIGN_EPI = false, bool SP2 = false>
; __device__ __forceinline__ void gemm_phase(PG8_LAS unsigned char* lds, const Gemm g, const Sched& S, const Epi& E) {
;     ...
;             PG8_WAIT_V(8); PG8_WAIT_L(0); PG8_BAR; PG8_MMA(0, 0, At, B0); PG8_MMA(0, 1, At, B1); PG8_BAR; PG8_SCHED;
;             PG8_LDA(At, 0, 1); PG8_STAGE(PG8_SB(0, 0), b2, voffB); PG8_STAGE(PG8_SB(0, 1), b2 + hstep, voffB); PG8_STAGE(PG8_SA(0, 0), a2, voffA);
;             PG8_WAIT_V(8); PG8_WAIT_L(0); PG8_BAR; PG8_MMA(1, 0, At, B0); PG8_MMA(1, 1, At, B1); PG8_BAR; PG8_SCHED;
	s_setprio 1
	s_waitcnt lgkmcnt(0)
	v_mfma_f32_16x16x32_bf16 v[126:129], v[130:133], v[162:165], v[126:129]
	v_mfma_f32_16x16x32_bf16 v[122:125], v[138:141], v[162:165], v[122:125]
	v_mfma_f32_16x16x32_bf16 v[110:113], v[130:133], v[170:173], v[110:113]
	v_mfma_f32_16x16x32_bf16 v[106:109], v[138:141], v[170:173], v[106:109]
	v_mfma_f32_16x16x32_bf16 v[94:97], v[130:133], v[178:181], v[94:97]
	v_mfma_f32_16x16x32_bf16 v[90:93], v[138:141], v[178:181], v[90:93]
	v_mfma_f32_16x16x32_bf16 v[78:81], v[130:133], v[186:189], v[78:81]
	v_mfma_f32_16x16x32_bf16 v[74:77], v[138:141], v[186:189], v[74:77]
	v_mfma_f32_16x16x32_bf16 v[126:129], v[134:137], v[166:169], v[126:129]
	v_mfma_f32_16x16x32_bf16 v[122:125], v[142:145], v[166:169], v[122:125]
	v_mfma_f32_16x16x32_bf16 v[110:113], v[134:137], v[174:177], v[110:113]
	v_mfma_f32_16x16x32_bf16 v[106:109], v[142:145], v[174:177], v[106:109]
	v_mfma_f32_16x16x32_bf16 v[94:97], v[134:137], v[182:185], v[94:97]
	v_mfma_f32_16x16x32_bf16 v[90:93], v[142:145], v[182:185], v[90:93]
	v_mfma_f32_16x16x32_bf16 v[78:81], v[134:137], v[190:193], v[78:81]
	v_mfma_f32_16x16x32_bf16 v[74:77], v[142:145], v[190:193], v[74:77]
	s_setprio 0
	s_setprio 1
	v_mfma_f32_16x16x32_bf16 v[118:121], v[146:149], v[162:165], v[118:121]
	v_mfma_f32_16x16x32_bf16 v[114:117], v[154:157], v[162:165], v[114:117]
	v_mfma_f32_16x16x32_bf16 v[102:105], v[146:149], v[170:173], v[102:105]
	v_mfma_f32_16x16x32_bf16 v[98:101], v[154:157], v[170:173], v[98:101]
	v_mfma_f32_16x16x32_bf16 v[86:89], v[146:149], v[178:181], v[86:89]
	v_mfma_f32_16x16x32_bf16 v[82:85], v[154:157], v[178:181], v[82:85]
	v_mfma_f32_16x16x32_bf16 v[70:73], v[146:149], v[186:189], v[70:73]
	v_mfma_f32_16x16x32_bf16 v[66:69], v[154:157], v[186:189], v[66:69]
	v_mfma_f32_16x16x32_bf16 v[118:121], v[150:153], v[166:169], v[118:121]
	v_mfma_f32_16x16x32_bf16 v[114:117], v[158:161], v[166:169], v[114:117]
	v_mfma_f32_16x16x32_bf16 v[102:105], v[150:153], v[174:177], v[102:105]
	v_mfma_f32_16x16x32_bf16 v[98:101], v[158:161], v[174:177], v[98:101]
	v_mfma_f32_16x16x32_bf16 v[86:89], v[150:153], v[182:185], v[86:89]
	v_mfma_f32_16x16x32_bf16 v[82:85], v[158:161], v[182:185], v[82:85]
	v_mfma_f32_16x16x32_bf16 v[70:73], v[150:153], v[190:193], v[70:73]
	v_mfma_f32_16x16x32_bf16 v[66:69], v[158:161], v[190:193], v[66:69]
	s_setprio 0
	s_barrier
	s_add_i32 s52, s52, s30
	v_lshl_add_u64 v[210:211], s[16:17], 0, v[198:199]
	s_mov_b32 m0, s52
	ds_read_b128 v[162:165], v226 offset:16384
	ds_read_b128 v[166:169], v226 offset:17408
	ds_read_b128 v[170:173], v226 offset:18432
	ds_read_b128 v[174:177], v226 offset:19456
	ds_read_b128 v[178:181], v226 offset:20480
	ds_read_b128 v[182:185], v226 offset:21504
	ds_read_b128 v[186:189], v226 offset:22528
	ds_read_b128 v[190:193], v226 offset:23552
	global_load_lds_dwordx4 v[210:211], off
	s_add_i32 m0, s52, 0x2000
	s_add_u32 s52, s16, 0x20000
	v_lshl_add_u64 v[212:213], s[16:17], 0, v[194:195]
	s_addc_u32 s53, s17, 0
	s_add_i32 s61, s61, s30
	global_load_lds_dwordx4 v[212:213], off
	v_lshl_add_u64 v[214:215], s[52:53], 0, v[198:199]
	s_mov_b32 m0, s61
	v_lshl_add_u64 v[216:217], s[24:25], 0, v[196:197]
	global_load_lds_dwordx4 v[214:215], off
	v_lshl_add_u64 v[214:215], s[52:53], 0, v[194:195]
	s_add_i32 m0, s61, 0x2000
	s_nop 0
	global_load_lds_dwordx4 v[214:215], off
	v_lshl_add_u64 v[214:215], s[24:25], 0, v[200:201]
	s_mov_b32 m0, s31
	s_nop 0
	global_load_lds_dwordx4 v[214:215], off
	s_mov_b32 m0, s34
	s_nop 0
	global_load_lds_dwordx4 v[216:217], off
	s_waitcnt vmcnt(8)
	s_waitcnt lgkmcnt(0)
	s_barrier
	s_setprio 1
	s_waitcnt lgkmcnt(0)
	v_mfma_f32_16x16x32_bf16 v[62:65], v[130:133], v[162:165], v[62:65]
	v_mfma_f32_16x16x32_bf16 v[58:61], v[138:141], v[162:165], v[58:61]
	v_mfma_f32_16x16x32_bf16 v[46:49], v[130:133], v[170:173], v[46:49]
	v_mfma_f32_16x16x32_bf16 v[42:45], v[138:141], v[170:173], v[42:45]
	v_mfma_f32_16x16x32_bf16 v[30:33], v[130:133], v[178:181], v[30:33]
	v_mfma_f32_16x16x32_bf16 v[26:29], v[138:141], v[178:181], v[26:29]
	v_mfma_f32_16x16x32_bf16 v[14:17], v[130:133], v[186:189], v[14:17]
	v_mfma_f32_16x16x32_bf16 v[10:13], v[138:141], v[186:189], v[10:13]
	v_mfma_f32_16x16x32_bf16 v[62:65], v[134:137], v[166:169], v[62:65]
	v_mfma_f32_16x16x32_bf16 v[58:61], v[142:145], v[166:169], v[58:61]
	v_mfma_f32_16x16x32_bf16 v[46:49], v[134:137], v[174:177], v[46:49]
	v_mfma_f32_16x16x32_bf16 v[42:45], v[142:145], v[174:177], v[42:45]
	v_mfma_f32_16x16x32_bf16 v[30:33], v[134:137], v[182:185], v[30:33]
	v_mfma_f32_16x16x32_bf16 v[26:29], v[142:145], v[182:185], v[26:29]
	v_mfma_f32_16x16x32_bf16 v[14:17], v[134:137], v[190:193], v[14:17]
	v_mfma_f32_16x16x32_bf16 v[10:13], v[142:145], v[190:193], v[10:13]
	s_setprio 0
	s_setprio 1
	v_mfma_f32_16x16x32_bf16 v[54:57], v[146:149], v[162:165], v[54:57]
	v_mfma_f32_16x16x32_bf16 v[50:53], v[154:157], v[162:165], v[50:53]
	v_mfma_f32_16x16x32_bf16 v[38:41], v[146:149], v[170:173], v[38:41]
	v_mfma_f32_16x16x32_bf16 v[34:37], v[154:157], v[170:173], v[34:37]
	v_mfma_f32_16x16x32_bf16 v[22:25], v[146:149], v[178:181], v[22:25]
	v_mfma_f32_16x16x32_bf16 v[18:21], v[154:157], v[178:181], v[18:21]
	v_mfma_f32_16x16x32_bf16 v[6:9], v[146:149], v[186:189], v[6:9]
	v_mfma_f32_16x16x32_bf16 v[2:5], v[154:157], v[186:189], v[2:5]
	v_mfma_f32_16x16x32_bf16 v[54:57], v[150:153], v[166:169], v[54:57]
	v_mfma_f32_16x16x32_bf16 v[50:53], v[158:161], v[166:169], v[50:53]
	v_mfma_f32_16x16x32_bf16 v[38:41], v[150:153], v[174:177], v[38:41]
	v_mfma_f32_16x16x32_bf16 v[34:37], v[158:161], v[174:177], v[34:37]
	v_mfma_f32_16x16x32_bf16 v[22:25], v[150:153], v[182:185], v[22:25]
	v_mfma_f32_16x16x32_bf16 v[18:21], v[158:161], v[182:185], v[18:21]
	v_mfma_f32_16x16x32_bf16 v[6:9], v[150:153], v[190:193], v[6:9]
	v_mfma_f32_16x16x32_bf16 v[2:5], v[158:161], v[190:193], v[2:5]
	s_setprio 0
	s_barrier
; #define PG8_STAGE(bufoff, gbase, voff) do { _Pragma("unroll") for (int _i = 0; _i < 2; ++_i) \
;         __builtin_amdgcn_global_load_lds((const unsigned*)((const char*)(gbase) + (voff)[_i]), (PG8_LAS unsigned*)(lds + (bufoff) + ldsw + _i * 8192), 16, 0, 0); } while (0)
; #define PG8_LDA(dst, b, h) do { _Pragma("unroll") for (int m = 0; m < 4; ++m) _Pragma("unroll") for (int k = 0; k < 2; ++k) dst[m][k] = *(const PG8_LAS bf16x8*)(lds + PG8_SA(b, h) + aoff + m * 2048 + k * 1024); } while (0)
; #define PG8_LDB(dst, b, h) do { _Pragma("unroll") for (int n = 0; n < 2; ++n) _Pragma("unroll") for (int k = 0; k < 2; ++k) dst[n][k] = *(const PG8_LAS bf16x8*)(lds + PG8_SB(b, h) + boff + n * 2048 + k * 1024); } while (0)
; #define PG8_MMA(ai, bj, At, Bt) do { __builtin_amdgcn_s_setprio(1); _Pragma("unroll") for (int m = 0; m < 4; ++m) _Pragma("unroll") for (int n = 0; n < 2; ++n) _Pragma("unroll") for (int k = 0; k < 2; ++k) \
;         acc[ai][bj][m][n] = __builtin_amdgcn_mfma_f32_16x16x32_bf16(Bt[n][k], At[m][k], acc[ai][bj][m][n], 0, 0, 0); __builtin_amdgcn_s_setprio(0); } while (0)
; #define PG8_WAIT_V(n) asm volatile("s_waitcnt vmcnt(" #n ")" ::: "memory")
; #define PG8_WAIT_L(n) asm volatile("s_waitcnt lgkmcnt(" #n ")" ::: "memory")
; #define PG8_BAR __builtin_amdgcn_s_barrier()
; #define PG8_SCHED __builtin_amdgcn_sched_barrier(0)
; template <class Epi, class Sched, bool ALIGN_EPI = false, bool SP2 = false>
; __device__ __forceinline__ void gemm_phase(PG8_LAS unsigned char* lds, const Gemm g, const Sched& S, const Epi& E) {
;     ...
;             PG8_LDB(B0, 1, 0); PG8_LDB(B1, 1, 1); PG8_SCHED; PG8_LDA(At, 1, 0); PG8_STAGE(PG8_SA(0, 1), a2 + hstep, voffA);
;             PG8_WAIT_V(8); PG8_WAIT_L(0); PG8_BAR; PG8_MMA(0, 0, At, B0); PG8_MMA(0, 1, At, B1); PG8_BAR; PG8_SCHED;
;             PG8_LDA(At, 1, 1); PG8_STAGE(PG8_SB(1, 0), b3, voffB); PG8_STAGE(PG8_SB(1, 1), b3 + hstep, voffB); PG8_STAGE(PG8_SA(1, 0), a3, voffA);
	s_add_i32 s52, 0, 0x18000
	v_add_u32_e32 v0, s52, v205
	s_add_i32 s53, 0, 0x1c000
	ds_read_b128 v[130:133], v0
	ds_read_b128 v[134:137], v0 offset:1024
	ds_read_b128 v[138:141], v0 offset:2048
	ds_read_b128 v[142:145], v0 offset:3072
	v_add_u32_e32 v0, s53, v205
	ds_read_b128 v[146:149], v0
	ds_read_b128 v[150:153], v0 offset:1024
	ds_read_b128 v[154:157], v0 offset:2048
	ds_read_b128 v[158:161], v0 offset:3072
	s_add_u32 s24, s24, 0x20000
	s_addc_u32 s25, s25, 0
	s_mov_b32 m0, s35
	v_lshl_add_u64 v[218:219], s[24:25], 0, v[200:201]
	ds_read_b128 v[162:165], v226 offset:32768
	ds_read_b128 v[166:169], v226 offset:33792
	ds_read_b128 v[170:173], v226 offset:34816
	ds_read_b128 v[174:177], v226 offset:35840
	ds_read_b128 v[178:181], v226 offset:36864
	ds_read_b128 v[182:185], v226 offset:37888
	ds_read_b128 v[186:189], v226 offset:38912
	ds_read_b128 v[190:193], v226 offset:39936
	global_load_lds_dwordx4 v[218:219], off
	v_lshl_add_u64 v[218:219], s[24:25], 0, v[196:197]
	s_mov_b32 m0, s36
	s_nop 0
	global_load_lds_dwordx4 v[218:219], off
	s_waitcnt vmcnt(8)
	s_waitcnt lgkmcnt(0)
	s_barrier
	s_setprio 1
	s_waitcnt lgkmcnt(0)
	v_mfma_f32_16x16x32_bf16 v[126:129], v[130:133], v[162:165], v[126:129]
	v_mfma_f32_16x16x32_bf16 v[122:125], v[138:141], v[162:165], v[122:125]
	v_mfma_f32_16x16x32_bf16 v[110:113], v[130:133], v[170:173], v[110:113]
	v_mfma_f32_16x16x32_bf16 v[106:109], v[138:141], v[170:173], v[106:109]
	v_mfma_f32_16x16x32_bf16 v[94:97], v[130:133], v[178:181], v[94:97]
	v_mfma_f32_16x16x32_bf16 v[90:93], v[138:141], v[178:181], v[90:93]
	v_mfma_f32_16x16x32_bf16 v[78:81], v[130:133], v[186:189], v[78:81]
	v_mfma_f32_16x16x32_bf16 v[74:77], v[138:141], v[186:189], v[74:77]
	v_mfma_f32_16x16x32_bf16 v[126:129], v[134:137], v[166:169], v[126:129]
	v_mfma_f32_16x16x32_bf16 v[122:125], v[142:145], v[166:169], v[122:125]
	v_mfma_f32_16x16x32_bf16 v[110:113], v[134:137], v[174:177], v[110:113]
	v_mfma_f32_16x16x32_bf16 v[106:109], v[142:145], v[174:177], v[106:109]
	v_mfma_f32_16x16x32_bf16 v[94:97], v[134:137], v[182:185], v[94:97]
	v_mfma_f32_16x16x32_bf16 v[90:93], v[142:145], v[182:185], v[90:93]
	v_mfma_f32_16x16x32_bf16 v[78:81], v[134:137], v[190:193], v[78:81]
	v_mfma_f32_16x16x32_bf16 v[74:77], v[142:145], v[190:193], v[74:77]
	s_setprio 0
	s_setprio 1
	v_mfma_f32_16x16x32_bf16 v[118:121], v[146:149], v[162:165], v[118:121]
	v_mfma_f32_16x16x32_bf16 v[114:117], v[154:157], v[162:165], v[114:117]
	v_mfma_f32_16x16x32_bf16 v[102:105], v[146:149], v[170:173], v[102:105]
	v_mfma_f32_16x16x32_bf16 v[98:101], v[154:157], v[170:173], v[98:101]
	v_mfma_f32_16x16x32_bf16 v[86:89], v[146:149], v[178:181], v[86:89]
	v_mfma_f32_16x16x32_bf16 v[82:85], v[154:157], v[178:181], v[82:85]
	v_mfma_f32_16x16x32_bf16 v[70:73], v[146:149], v[186:189], v[70:73]
	v_mfma_f32_16x16x32_bf16 v[66:69], v[154:157], v[186:189], v[66:69]
	v_mfma_f32_16x16x32_bf16 v[118:121], v[150:153], v[166:169], v[118:121]
	v_mfma_f32_16x16x32_bf16 v[114:117], v[158:161], v[166:169], v[114:117]
	v_mfma_f32_16x16x32_bf16 v[102:105], v[150:153], v[174:177], v[102:105]
	v_mfma_f32_16x16x32_bf16 v[98:101], v[158:161], v[174:177], v[98:101]
	v_mfma_f32_16x16x32_bf16 v[86:89], v[150:153], v[182:185], v[86:89]
	v_mfma_f32_16x16x32_bf16 v[82:85], v[158:161], v[182:185], v[82:85]
	v_mfma_f32_16x16x32_bf16 v[70:73], v[150:153], v[190:193], v[70:73]
	v_mfma_f32_16x16x32_bf16 v[66:69], v[158:161], v[190:193], v[66:69]
	s_setprio 0
	s_barrier
	s_add_i32 s24, s52, s30
	v_lshl_add_u64 v[210:211], v[210:211], 0, s[94:95]
	s_mov_b32 m0, s24
	ds_read_b128 v[162:165], v226 offset:49152
	ds_read_b128 v[166:169], v226 offset:50176
	ds_read_b128 v[170:173], v226 offset:51200
	ds_read_b128 v[174:177], v226 offset:52224
	ds_read_b128 v[178:181], v226 offset:53248
	ds_read_b128 v[182:185], v226 offset:54272
	ds_read_b128 v[186:189], v226 offset:55296
	ds_read_b128 v[190:193], v226 offset:56320
	global_load_lds_dwordx4 v[210:211], off
	s_add_i32 m0, s24, 0x2000
	s_add_u32 s16, s16, 0x20080
	v_lshl_add_u64 v[210:211], v[212:213], 0, s[94:95]
	s_addc_u32 s17, s17, 0
	s_add_i32 s24, s53, s30
	global_load_lds_dwordx4 v[210:211], off
	v_lshl_add_u64 v[210:211], s[16:17], 0, v[198:199]
	s_mov_b32 m0, s24
	s_nop 0
	global_load_lds_dwordx4 v[210:211], off
	v_lshl_add_u64 v[210:211], s[16:17], 0, v[194:195]
	s_add_i32 m0, s24, 0x2000
	s_nop 0
	global_load_lds_dwordx4 v[210:211], off
	v_lshl_add_u64 v[210:211], v[214:215], 0, s[94:95]
	s_mov_b32 m0, s37
	s_nop 0
	global_load_lds_dwordx4 v[210:211], off
	v_lshl_add_u64 v[210:211], v[216:217], 0, s[94:95]
	s_mov_b32 m0, s38
	s_nop 0
	global_load_lds_dwordx4 v[210:211], off
	s_waitcnt vmcnt(8)
	s_waitcnt lgkmcnt(0)
	s_barrier
; #define PG8_WAIT_V(n) asm volatile("s_waitcnt vmcnt(" #n ")" ::: "memory")
; #define PG8_WAIT_L(n) asm volatile("s_waitcnt lgkmcnt(" #n ")" ::: "memory")
; #define PG8_BAR __builtin_amdgcn_s_barrier()
;     __device__ __forceinline__ void operator()(const f32x4 (&acc)[2][2][4][2], const Unit& u, int wr, int wc, int fr, int fq) const {
;         _Pragma("unroll") for (int ai = 0; ai < 2; ++ai) {
;             u32x4 gt[4][2], oo[4][2];
;             _Pragma("unroll") for (int m = 0; m < 4; ++m) _Pragma("unroll") for (int bj = 0; bj < 2; ++bj) { const size_t off = (size_t)EPI_ROW(ai, m) * 1024 + u.pn * BM + EPI_CT(bj);
;                 gt[m][bj] = *(const u32x4*)(G + off); if (ADD) oo[m][bj] = *(const u32x4*)(O + off); }
; template <class Epi, class Sched, bool ALIGN_EPI = false, bool SP2 = false>
; __device__ __forceinline__ void gemm_phase(PG8_LAS unsigned char* lds, const Gemm g, const Sched& S, const Epi& E) {
;     ...
;             PG8_WAIT_V(8); PG8_WAIT_L(0); PG8_BAR; PG8_MMA(1, 0, At, B0); PG8_MMA(1, 1, At, B1); PG8_BAR; PG8_SCHED;
;             } else {
;             PG8_LDB(B0, 0, 0); PG8_SCHED; PG8_LDA(At, 0, 0); PG8_STAGE(PG8_SA(1, 1), a1 + hstep, voffA);
;             PG8_WAIT_L(8); PG8_BAR; PG8_WAIT_L(0); PG8_MMA(0, 0, At, B0); PG8_BAR; PG8_SCHED;
;             PG8_LDB(B1, 0, 1); PG8_STAGE(PG8_SB(0, 0), b2, voffB);
;             PG8_BAR; PG8_WAIT_L(0); PG8_MMA(0, 1, At, B1); PG8_BAR;
;             PG8_LDA(At, 0, 1); PG8_STAGE(PG8_SA(0, 0), a2, voffA);
;             PG8_BAR; PG8_WAIT_L(0); PG8_MMA(1, 0, At, B0); PG8_BAR; PG8_SCHED;
;             PG8_STAGE(PG8_SB(0, 1), b2 + hstep, voffB);
;             PG8_WAIT_V(6); PG8_BAR; PG8_MMA(1, 1, At, B1); PG8_BAR;
;             PG8_LDB(B0, 1, 0); PG8_SCHED; PG8_LDA(At, 1, 0); PG8_STAGE(PG8_SA(0, 1), a2 + hstep, voffA);
;             PG8_WAIT_L(8); PG8_BAR; PG8_WAIT_L(0); PG8_MMA(0, 0, At, B0); PG8_BAR; PG8_SCHED;
;             PG8_LDB(B1, 1, 1); PG8_STAGE(PG8_SB(1, 0), b3, voffB);
;             PG8_BAR; PG8_WAIT_L(0); PG8_MMA(0, 1, At, B1); PG8_BAR;
;             PG8_LDA(At, 1, 1); PG8_STAGE(PG8_SA(1, 0), a3, voffA);
;             PG8_BAR; PG8_WAIT_L(0); PG8_MMA(1, 0, At, B0); PG8_BAR; PG8_SCHED;
;             PG8_STAGE(PG8_SB(1, 1), b3 + hstep, voffB);
;             PG8_WAIT_V(6); PG8_BAR; PG8_MMA(1, 1, At, B1); PG8_BAR;
;             }
;         }
;         if constexpr (ALIGN_EPI) { if (wr == 0) PG8_BAR; }
	s_setprio 1
	s_waitcnt lgkmcnt(0)
	v_mfma_f32_16x16x32_bf16 v[62:65], v[130:133], v[162:165], v[62:65]
	v_mfma_f32_16x16x32_bf16 v[58:61], v[138:141], v[162:165], v[58:61]
	v_mfma_f32_16x16x32_bf16 v[46:49], v[130:133], v[170:173], v[46:49]
	v_mfma_f32_16x16x32_bf16 v[42:45], v[138:141], v[170:173], v[42:45]
	v_mfma_f32_16x16x32_bf16 v[30:33], v[130:133], v[178:181], v[30:33]
	v_mfma_f32_16x16x32_bf16 v[26:29], v[138:141], v[178:181], v[26:29]
	v_mfma_f32_16x16x32_bf16 v[14:17], v[130:133], v[186:189], v[14:17]
	v_mfma_f32_16x16x32_bf16 v[10:13], v[138:141], v[186:189], v[10:13]
	v_mfma_f32_16x16x32_bf16 v[62:65], v[134:137], v[166:169], v[62:65]
	v_mfma_f32_16x16x32_bf16 v[58:61], v[142:145], v[166:169], v[58:61]
	v_mfma_f32_16x16x32_bf16 v[46:49], v[134:137], v[174:177], v[46:49]
	v_mfma_f32_16x16x32_bf16 v[42:45], v[142:145], v[174:177], v[42:45]
	v_mfma_f32_16x16x32_bf16 v[30:33], v[134:137], v[182:185], v[30:33]
	v_mfma_f32_16x16x32_bf16 v[26:29], v[142:145], v[182:185], v[26:29]
	v_mfma_f32_16x16x32_bf16 v[14:17], v[134:137], v[190:193], v[14:17]
	v_mfma_f32_16x16x32_bf16 v[10:13], v[142:145], v[190:193], v[10:13]
	s_setprio 0
	s_setprio 1
	v_mfma_f32_16x16x32_bf16 v[54:57], v[146:149], v[162:165], v[54:57]
	v_mfma_f32_16x16x32_bf16 v[50:53], v[154:157], v[162:165], v[50:53]
	v_mfma_f32_16x16x32_bf16 v[38:41], v[146:149], v[170:173], v[38:41]
	v_mfma_f32_16x16x32_bf16 v[34:37], v[154:157], v[170:173], v[34:37]
	v_mfma_f32_16x16x32_bf16 v[22:25], v[146:149], v[178:181], v[22:25]
	v_mfma_f32_16x16x32_bf16 v[18:21], v[154:157], v[178:181], v[18:21]
	v_mfma_f32_16x16x32_bf16 v[6:9], v[146:149], v[186:189], v[6:9]
	v_mfma_f32_16x16x32_bf16 v[2:5], v[154:157], v[186:189], v[2:5]
	v_mfma_f32_16x16x32_bf16 v[54:57], v[150:153], v[166:169], v[54:57]
	v_mfma_f32_16x16x32_bf16 v[50:53], v[158:161], v[166:169], v[50:53]
	v_mfma_f32_16x16x32_bf16 v[38:41], v[150:153], v[174:177], v[38:41]
	v_mfma_f32_16x16x32_bf16 v[34:37], v[158:161], v[174:177], v[34:37]
	v_mfma_f32_16x16x32_bf16 v[22:25], v[150:153], v[182:185], v[22:25]
	v_mfma_f32_16x16x32_bf16 v[18:21], v[158:161], v[182:185], v[18:21]
	v_mfma_f32_16x16x32_bf16 v[6:9], v[150:153], v[190:193], v[6:9]
	v_mfma_f32_16x16x32_bf16 v[2:5], v[158:161], v[190:193], v[2:5]
	s_setprio 0
	s_barrier
	s_add_i32 s50, s50, 2
	s_add_u32 s22, s22, 0x100
	s_addc_u32 s23, s23, 0
	s_add_u32 s57, s57, 0x100
	s_addc_u32 s60, s60, 0
	s_cmp_gt_u32 s50, 5
	s_cbranch_scc0 .LBB0_632
	s_and_b64 vcc, exec, s[10:11]
	s_cbranch_vccz .LBB0_635
	s_barrier
.LBB0_635:
	v_lshl_add_u32 v210, s46, 8, v203
	s_lshl_b32 s22, s33, 8
	v_ashrrev_i32_e32 v211, 31, v210
	s_ashr_i32 s23, s22, 31
	v_lshlrev_b64 v[130:131], 10, v[210:211]
	v_lshl_add_u64 v[130:131], v[130:131], 0, s[22:23]
	v_or_b32_e32 v132, v130, v202
	v_mov_b32_e32 v133, v131
	v_lshlrev_b64 v[132:133], 1, v[132:133]
	v_lshl_add_u64 v[134:135], s[6:7], 0, v[132:133]
	v_lshl_add_u64 v[132:133], s[8:9], 0, v[132:133]
	global_load_dwordx4 v[190:193], v[134:135], off
	global_load_dwordx4 v[186:189], v[132:133], off
	v_or_b32_e32 v130, v130, v204
	v_lshlrev_b64 v[130:131], 1, v[130:131]
	v_lshl_add_u64 v[132:133], s[6:7], 0, v[130:131]
	v_lshl_add_u64 v[130:131], s[8:9], 0, v[130:131]
	v_or_b32_e32 v224, 16, v210
	global_load_dwordx4 v[182:185], v[132:133], off
	global_load_dwordx4 v[178:181], v[130:131], off
	v_ashrrev_i32_e32 v225, 31, v224
	v_lshlrev_b64 v[130:131], 10, v[224:225]
	v_lshl_add_u64 v[130:131], v[130:131], 0, s[22:23]
	v_or_b32_e32 v132, v130, v202
	v_mov_b32_e32 v133, v131
	v_lshlrev_b64 v[132:133], 1, v[132:133]
	v_lshl_add_u64 v[134:135], s[6:7], 0, v[132:133]
	v_lshl_add_u64 v[132:133], s[8:9], 0, v[132:133]
	global_load_dwordx4 v[166:169], v[134:135], off
	global_load_dwordx4 v[162:165], v[132:133], off
	v_or_b32_e32 v130, v130, v204
	v_lshlrev_b64 v[130:131], 1, v[130:131]
	v_lshl_add_u64 v[132:133], s[6:7], 0, v[130:131]
	v_lshl_add_u64 v[130:131], s[8:9], 0, v[130:131]
	v_or_b32_e32 v222, 32, v210
	global_load_dwordx4 v[142:145], v[132:133], off
	global_load_dwordx4 v[138:141], v[130:131], off
	v_ashrrev_i32_e32 v223, 31, v222
	v_lshlrev_b64 v[130:131], 10, v[222:223]
	v_lshl_add_u64 v[130:131], v[130:131], 0, s[22:23]
	v_or_b32_e32 v132, v130, v202
	v_mov_b32_e32 v133, v131
	v_lshlrev_b64 v[132:133], 1, v[132:133]
	v_lshl_add_u64 v[134:135], s[6:7], 0, v[132:133]
	v_lshl_add_u64 v[132:133], s[8:9], 0, v[132:133]
	global_load_dwordx4 v[158:161], v[134:135], off
	global_load_dwordx4 v[154:157], v[132:133], off
	v_or_b32_e32 v220, 48, v210
	v_ashrrev_i32_e32 v221, 31, v220
	v_lshlrev_b64 v[146:147], 10, v[220:221]
	v_lshl_add_u64 v[146:147], v[146:147], 0, s[22:23]
	v_or_b32_e32 v130, v130, v204
	v_or_b32_e32 v148, v146, v202
	v_mov_b32_e32 v149, v147
	v_lshlrev_b64 v[130:131], 1, v[130:131]
	v_lshlrev_b64 v[148:149], 1, v[148:149]
	v_lshl_add_u64 v[132:133], s[6:7], 0, v[130:131]
	v_lshl_add_u64 v[130:131], s[8:9], 0, v[130:131]
	v_lshl_add_u64 v[150:151], s[6:7], 0, v[148:149]
	v_lshl_add_u64 v[148:149], s[8:9], 0, v[148:149]
	global_load_dwordx4 v[134:137], v[132:133], off
	global_load_dwordx4 v[170:173], v[148:149], off
	global_load_dwordx4 v[174:177], v[150:151], off
	v_or_b32_e32 v146, v146, v204
	global_load_dwordx4 v[130:133], v[130:131], off
	v_lshlrev_b64 v[146:147], 1, v[146:147]
	v_lshl_add_u64 v[148:149], s[6:7], 0, v[146:147]
	v_lshl_add_u64 v[146:147], s[8:9], 0, v[146:147]
	global_load_dwordx4 v[150:153], v[148:149], off
	v_lshlrev_b64 v[212:213], 11, v[210:211]
	global_load_dwordx4 v[146:149], v[146:147], off
	s_lshl_b64 s[24:25], s[22:23], 1
	v_lshlrev_b32_e32 v0, 1, v202
	s_mov_b64 s[16:17], -1
	s_andn2_b64 vcc, exec, s[4:5]
	s_waitcnt vmcnt(0)
; __device__ __forceinline__ u32x4 pack8(const f32x4 v0, const f32x4 v1) { u32x4 w; w.x = cvt_pk_bf16(v0[0], v0[1]); w.y = cvt_pk_bf16(v0[2], v0[3]); w.z = cvt_pk_bf16(v1[0], v1[1]); w.w = cvt_pk_bf16(v1[2], v1[3]); return w; }
; __device__ __forceinline__ float bf_lo(unsigned w) { return __uint_as_float(w << 16); }
; __device__ __forceinline__ float bf_hi(unsigned w) { return __uint_as_float(w & 0xffff0000u); }
;     __device__ __forceinline__ void operator()(const f32x4 (&acc)[2][2][4][2], const Unit& u, int wr, int wc, int fr, int fq) const {
;     ...
;             _Pragma("unroll") for (int m = 0; m < 4; ++m) _Pragma("unroll") for (int bj = 0; bj < 2; ++bj) { const size_t off = (size_t)EPI_ROW(ai, m) * 1024 + u.pn * BM + EPI_CT(bj);
;                 f32x4 v0 = acc[ai][bj][m][0], v1 = acc[ai][bj][m][1]; const u32x4 g4 = gt[m][bj];
;                 v0[0] *= bf_lo(g4.x); v0[1] *= bf_hi(g4.x); v0[2] *= bf_lo(g4.y); v0[3] *= bf_hi(g4.y); v1[0] *= bf_lo(g4.z); v1[1] *= bf_hi(g4.z); v1[2] *= bf_lo(g4.w); v1[3] *= bf_hi(g4.w);
;                 if (ADD) { const u32x4 o = oo[m][bj];
;                     v0[0] += bf_lo(o.x); v0[1] += bf_hi(o.x); v0[2] += bf_lo(o.y); v0[3] += bf_hi(o.y); v1[0] += bf_lo(o.z); v1[1] += bf_hi(o.z); v1[2] += bf_lo(o.w); v1[3] += bf_hi(o.w); }
;                 *(u32x4*)(O + off) = pack8(v0, v1); }
	v_lshlrev_b32_e32 v214, 16, v190
	v_and_b32_e32 v215, 0xffff0000, v190
	v_lshlrev_b32_e32 v216, 16, v186
	v_and_b32_e32 v217, 0xffff0000, v186
	v_lshlrev_b32_e32 v190, 16, v191
	v_and_b32_e32 v191, 0xffff0000, v191
	v_lshlrev_b32_e32 v186, 16, v187
	v_and_b32_e32 v187, 0xffff0000, v187
	v_pk_fma_f32 v[128:129], v[128:129], v[190:191], v[186:187]
	v_lshlrev_b32_e32 v186, 16, v192
	v_and_b32_e32 v187, 0xffff0000, v192
	v_lshlrev_b32_e32 v190, 16, v188
	v_and_b32_e32 v191, 0xffff0000, v188
	v_pk_fma_f32 v[126:127], v[126:127], v[214:215], v[216:217]
	v_pk_fma_f32 v[186:187], v[122:123], v[186:187], v[190:191]
	v_lshlrev_b32_e32 v122, 16, v193
	v_and_b32_e32 v123, 0xffff0000, v193
	v_lshlrev_b32_e32 v188, 16, v189
	v_and_b32_e32 v189, 0xffff0000, v189
	v_pk_fma_f32 v[188:189], v[124:125], v[122:123], v[188:189]
	v_cvt_pk_bf16_f32 v122, v126, v127
	v_lshl_add_u64 v[126:127], s[8:9], 0, v[212:213]
	v_lshl_add_u64 v[126:127], v[126:127], 0, s[24:25]
	v_cvt_pk_bf16_f32 v123, v128, v129
	v_cvt_pk_bf16_f32 v124, v186, v187
	v_cvt_pk_bf16_f32 v125, v188, v189
	v_lshl_add_u64 v[126:127], v[126:127], 0, v[0:1]
	global_store_dwordx4 v[126:127], v[122:125], off
	s_nop 1
	v_lshlrev_b32_e32 v122, 16, v182
	v_and_b32_e32 v123, 0xffff0000, v182
	v_lshlrev_b32_e32 v124, 16, v178
	v_and_b32_e32 v125, 0xffff0000, v178
	v_pk_fma_f32 v[118:119], v[118:119], v[122:123], v[124:125]
	v_lshlrev_b32_e32 v122, 16, v183
	v_and_b32_e32 v123, 0xffff0000, v183
	v_lshlrev_b32_e32 v124, 16, v179
	v_and_b32_e32 v125, 0xffff0000, v179
	v_pk_fma_f32 v[120:121], v[120:121], v[122:123], v[124:125]
	v_lshlrev_b32_e32 v122, 16, v184
	v_and_b32_e32 v123, 0xffff0000, v184
	v_lshlrev_b32_e32 v124, 16, v180
	v_and_b32_e32 v125, 0xffff0000, v180
	v_pk_fma_f32 v[122:123], v[114:115], v[122:123], v[124:125]
	v_lshlrev_b32_e32 v114, 16, v185
	v_and_b32_e32 v115, 0xffff0000, v185
	v_lshlrev_b32_e32 v124, 16, v181
	v_and_b32_e32 v125, 0xffff0000, v181
	v_pk_fma_f32 v[124:125], v[116:117], v[114:115], v[124:125]
	v_cvt_pk_bf16_f32 v114, v118, v119
	v_cvt_pk_bf16_f32 v115, v120, v121
	v_cvt_pk_bf16_f32 v116, v122, v123
	v_cvt_pk_bf16_f32 v117, v124, v125
	global_store_dwordx4 v[126:127], v[114:117], off offset:256
	v_lshlrev_b32_e32 v118, 16, v162
	v_and_b32_e32 v119, 0xffff0000, v162
	v_lshlrev_b32_e32 v116, 16, v166
	v_and_b32_e32 v117, 0xffff0000, v166
	v_pk_fma_f32 v[110:111], v[110:111], v[116:117], v[118:119]
	v_lshlrev_b32_e32 v116, 16, v167
	v_and_b32_e32 v117, 0xffff0000, v167
	v_lshlrev_b32_e32 v118, 16, v163
	v_and_b32_e32 v119, 0xffff0000, v163
	v_pk_fma_f32 v[112:113], v[112:113], v[116:117], v[118:119]
	v_lshlrev_b32_e32 v116, 16, v168
	v_and_b32_e32 v117, 0xffff0000, v168
	v_lshlrev_b32_e32 v118, 16, v164
	v_and_b32_e32 v119, 0xffff0000, v164
	v_lshlrev_b64 v[114:115], 11, v[224:225]
	v_pk_fma_f32 v[116:117], v[106:107], v[116:117], v[118:119]
	v_lshlrev_b32_e32 v106, 16, v169
	v_and_b32_e32 v107, 0xffff0000, v169
	v_lshlrev_b32_e32 v118, 16, v165
	v_and_b32_e32 v119, 0xffff0000, v165
	v_pk_fma_f32 v[118:119], v[108:109], v[106:107], v[118:119]
	v_cvt_pk_bf16_f32 v106, v110, v111
	v_lshl_add_u64 v[110:111], s[8:9], 0, v[114:115]
	v_lshl_add_u64 v[110:111], v[110:111], 0, s[24:25]
	v_cvt_pk_bf16_f32 v107, v112, v113
	v_cvt_pk_bf16_f32 v108, v116, v117
	v_cvt_pk_bf16_f32 v109, v118, v119
	v_lshl_add_u64 v[110:111], v[110:111], 0, v[0:1]
	global_store_dwordx4 v[110:111], v[106:109], off
	s_nop 1
	v_lshlrev_b32_e32 v106, 16, v142
	v_and_b32_e32 v107, 0xffff0000, v142
	v_lshlrev_b32_e32 v108, 16, v138
	v_and_b32_e32 v109, 0xffff0000, v138
	v_pk_fma_f32 v[102:103], v[102:103], v[106:107], v[108:109]
	v_lshlrev_b32_e32 v106, 16, v143
	v_and_b32_e32 v107, 0xffff0000, v143
	v_lshlrev_b32_e32 v108, 16, v139
	v_and_b32_e32 v109, 0xffff0000, v139
	v_pk_fma_f32 v[104:105], v[104:105], v[106:107], v[108:109]
	v_lshlrev_b32_e32 v106, 16, v144
	v_and_b32_e32 v107, 0xffff0000, v144
	v_lshlrev_b32_e32 v108, 16, v140
	v_and_b32_e32 v109, 0xffff0000, v140
	v_pk_fma_f32 v[106:107], v[98:99], v[106:107], v[108:109]
	v_lshlrev_b32_e32 v98, 16, v145
	v_and_b32_e32 v99, 0xffff0000, v145
	v_lshlrev_b32_e32 v108, 16, v141
	v_and_b32_e32 v109, 0xffff0000, v141
	v_pk_fma_f32 v[108:109], v[100:101], v[98:99], v[108:109]
	v_cvt_pk_bf16_f32 v98, v102, v103
	v_cvt_pk_bf16_f32 v99, v104, v105
	v_cvt_pk_bf16_f32 v100, v106, v107
	v_cvt_pk_bf16_f32 v101, v108, v109
	global_store_dwordx4 v[110:111], v[98:101], off offset:256
	v_lshlrev_b32_e32 v102, 16, v154
	v_and_b32_e32 v103, 0xffff0000, v154
	v_lshlrev_b32_e32 v100, 16, v158
	v_and_b32_e32 v101, 0xffff0000, v158
	v_pk_fma_f32 v[94:95], v[94:95], v[100:101], v[102:103]
	v_lshlrev_b32_e32 v100, 16, v159
	v_and_b32_e32 v101, 0xffff0000, v159
	v_lshlrev_b32_e32 v102, 16, v155
	v_and_b32_e32 v103, 0xffff0000, v155
	v_pk_fma_f32 v[96:97], v[96:97], v[100:101], v[102:103]
	v_lshlrev_b32_e32 v100, 16, v160
	v_and_b32_e32 v101, 0xffff0000, v160
	v_lshlrev_b32_e32 v102, 16, v156
	v_and_b32_e32 v103, 0xffff0000, v156
	v_lshlrev_b64 v[98:99], 11, v[222:223]
	v_pk_fma_f32 v[100:101], v[90:91], v[100:101], v[102:103]
	v_lshlrev_b32_e32 v90, 16, v161
	v_and_b32_e32 v91, 0xffff0000, v161
	v_lshlrev_b32_e32 v102, 16, v157
	v_and_b32_e32 v103, 0xffff0000, v157
	v_pk_fma_f32 v[102:103], v[92:93], v[90:91], v[102:103]
	v_cvt_pk_bf16_f32 v90, v94, v95
	v_lshl_add_u64 v[94:95], s[8:9], 0, v[98:99]
	v_lshl_add_u64 v[94:95], v[94:95], 0, s[24:25]
	v_cvt_pk_bf16_f32 v91, v96, v97
	v_cvt_pk_bf16_f32 v92, v100, v101
	v_cvt_pk_bf16_f32 v93, v102, v103
	v_lshl_add_u64 v[94:95], v[94:95], 0, v[0:1]
	global_store_dwordx4 v[94:95], v[90:93], off
	v_add_u32_e32 v108, 0xa0, v210
; __device__ __forceinline__ u32x4 pack8(const f32x4 v0, const f32x4 v1) { u32x4 w; w.x = cvt_pk_bf16(v0[0], v0[1]); w.y = cvt_pk_bf16(v0[2], v0[3]); w.z = cvt_pk_bf16(v1[0], v1[1]); w.w = cvt_pk_bf16(v1[2], v1[3]); return w; }
; __device__ __forceinline__ float bf_lo(unsigned w) { return __uint_as_float(w << 16); }
; __device__ __forceinline__ float bf_hi(unsigned w) { return __uint_as_float(w & 0xffff0000u); }
;     __device__ __forceinline__ void operator()(const f32x4 (&acc)[2][2][4][2], const Unit& u, int wr, int wc, int fr, int fq) const {
;     ...
;             _Pragma("unroll") for (int m = 0; m < 4; ++m) _Pragma("unroll") for (int bj = 0; bj < 2; ++bj) { const size_t off = (size_t)EPI_ROW(ai, m) * 1024 + u.pn * BM + EPI_CT(bj);
;                 gt[m][bj] = *(const u32x4*)(G + off); if (ADD) oo[m][bj] = *(const u32x4*)(O + off); }
;             _Pragma("unroll") for (int m = 0; m < 4; ++m) _Pragma("unroll") for (int bj = 0; bj < 2; ++bj) { const size_t off = (size_t)EPI_ROW(ai, m) * 1024 + u.pn * BM + EPI_CT(bj);
;                 f32x4 v0 = acc[ai][bj][m][0], v1 = acc[ai][bj][m][1]; const u32x4 g4 = gt[m][bj];
;                 v0[0] *= bf_lo(g4.x); v0[1] *= bf_hi(g4.x); v0[2] *= bf_lo(g4.y); v0[3] *= bf_hi(g4.y); v1[0] *= bf_lo(g4.z); v1[1] *= bf_hi(g4.z); v1[2] *= bf_lo(g4.w); v1[3] *= bf_hi(g4.w);
;                 if (ADD) { const u32x4 o = oo[m][bj];
;                     v0[0] += bf_lo(o.x); v0[1] += bf_hi(o.x); v0[2] += bf_lo(o.y); v0[3] += bf_hi(o.y); v1[0] += bf_lo(o.z); v1[1] += bf_hi(o.z); v1[2] += bf_lo(o.w); v1[3] += bf_hi(o.w); }
;                 *(u32x4*)(O + off) = pack8(v0, v1); }
	v_ashrrev_i32_e32 v109, 31, v108
	v_lshlrev_b32_e32 v90, 16, v134
	v_and_b32_e32 v91, 0xffff0000, v134
	v_lshlrev_b32_e32 v92, 16, v130
	v_and_b32_e32 v93, 0xffff0000, v130
	v_pk_fma_f32 v[86:87], v[86:87], v[90:91], v[92:93]
	v_lshlrev_b32_e32 v90, 16, v135
	v_and_b32_e32 v91, 0xffff0000, v135
	v_lshlrev_b32_e32 v92, 16, v131
	v_and_b32_e32 v93, 0xffff0000, v131
	v_pk_fma_f32 v[88:89], v[88:89], v[90:91], v[92:93]
	v_lshlrev_b32_e32 v90, 16, v136
	v_and_b32_e32 v91, 0xffff0000, v136
	v_lshlrev_b32_e32 v92, 16, v132
	v_and_b32_e32 v93, 0xffff0000, v132
	v_pk_fma_f32 v[90:91], v[82:83], v[90:91], v[92:93]
	v_lshlrev_b32_e32 v82, 16, v137
	v_and_b32_e32 v83, 0xffff0000, v137
	v_lshlrev_b32_e32 v92, 16, v133
	v_and_b32_e32 v93, 0xffff0000, v133
	v_pk_fma_f32 v[92:93], v[84:85], v[82:83], v[92:93]
	v_cvt_pk_bf16_f32 v82, v86, v87
	v_cvt_pk_bf16_f32 v83, v88, v89
	v_cvt_pk_bf16_f32 v84, v90, v91
	v_cvt_pk_bf16_f32 v85, v92, v93
	global_store_dwordx4 v[94:95], v[82:85], off offset:256
	v_lshlrev_b32_e32 v86, 16, v170
	v_and_b32_e32 v87, 0xffff0000, v170
	v_lshlrev_b32_e32 v84, 16, v174
	v_and_b32_e32 v85, 0xffff0000, v174
	v_pk_fma_f32 v[78:79], v[78:79], v[84:85], v[86:87]
	v_lshlrev_b32_e32 v84, 16, v175
	v_and_b32_e32 v85, 0xffff0000, v175
	v_lshlrev_b32_e32 v86, 16, v171
	v_and_b32_e32 v87, 0xffff0000, v171
	v_pk_fma_f32 v[80:81], v[80:81], v[84:85], v[86:87]
	v_lshlrev_b32_e32 v84, 16, v176
	v_and_b32_e32 v85, 0xffff0000, v176
	v_lshlrev_b32_e32 v86, 16, v172
	v_and_b32_e32 v87, 0xffff0000, v172
	v_lshlrev_b64 v[82:83], 11, v[220:221]
	v_pk_fma_f32 v[84:85], v[74:75], v[84:85], v[86:87]
	v_lshlrev_b32_e32 v74, 16, v177
	v_and_b32_e32 v75, 0xffff0000, v177
	v_lshlrev_b32_e32 v86, 16, v173
	v_and_b32_e32 v87, 0xffff0000, v173
	v_pk_fma_f32 v[86:87], v[76:77], v[74:75], v[86:87]
	v_cvt_pk_bf16_f32 v74, v78, v79
	v_lshl_add_u64 v[78:79], s[8:9], 0, v[82:83]
	v_lshl_add_u64 v[78:79], v[78:79], 0, s[24:25]
	v_cvt_pk_bf16_f32 v75, v80, v81
	v_cvt_pk_bf16_f32 v76, v84, v85
	v_cvt_pk_bf16_f32 v77, v86, v87
	v_lshl_add_u64 v[78:79], v[78:79], 0, v[0:1]
	global_store_dwordx4 v[78:79], v[74:77], off
	v_add_u32_e32 v134, 0x80, v210
	v_ashrrev_i32_e32 v135, 31, v134
	v_lshlrev_b32_e32 v74, 16, v150
	v_and_b32_e32 v75, 0xffff0000, v150
	v_lshlrev_b32_e32 v76, 16, v146
	v_and_b32_e32 v77, 0xffff0000, v146
	v_pk_fma_f32 v[70:71], v[70:71], v[74:75], v[76:77]
	v_lshlrev_b32_e32 v74, 16, v151
	v_and_b32_e32 v75, 0xffff0000, v151
	v_lshlrev_b32_e32 v76, 16, v147
	v_and_b32_e32 v77, 0xffff0000, v147
	v_pk_fma_f32 v[72:73], v[72:73], v[74:75], v[76:77]
	v_lshlrev_b32_e32 v74, 16, v152
	v_and_b32_e32 v75, 0xffff0000, v152
	v_lshlrev_b32_e32 v76, 16, v148
	v_and_b32_e32 v77, 0xffff0000, v148
	v_pk_fma_f32 v[74:75], v[66:67], v[74:75], v[76:77]
	v_lshlrev_b32_e32 v66, 16, v153
	v_and_b32_e32 v67, 0xffff0000, v153
	v_lshlrev_b32_e32 v76, 16, v149
	v_and_b32_e32 v77, 0xffff0000, v149
	v_pk_fma_f32 v[76:77], v[68:69], v[66:67], v[76:77]
	v_cvt_pk_bf16_f32 v66, v70, v71
	v_cvt_pk_bf16_f32 v67, v72, v73
	v_cvt_pk_bf16_f32 v68, v74, v75
	v_cvt_pk_bf16_f32 v69, v76, v77
	global_store_dwordx4 v[78:79], v[66:69], off offset:256
	v_add_u32_e32 v136, 0x90, v210
	v_ashrrev_i32_e32 v137, 31, v136
	v_lshlrev_b64 v[66:67], 10, v[134:135]
	v_lshl_add_u64 v[66:67], v[66:67], 0, s[22:23]
	v_or_b32_e32 v68, v66, v202
	v_mov_b32_e32 v69, v67
	v_lshlrev_b64 v[68:69], 1, v[68:69]
	v_lshl_add_u64 v[70:71], s[6:7], 0, v[68:69]
	v_lshl_add_u64 v[68:69], s[8:9], 0, v[68:69]
	global_load_dwordx4 v[110:113], v[70:71], off
	global_load_dwordx4 v[114:117], v[68:69], off
	v_or_b32_e32 v66, v66, v204
	v_lshlrev_b64 v[66:67], 1, v[66:67]
	v_lshl_add_u64 v[68:69], s[6:7], 0, v[66:67]
	v_lshl_add_u64 v[66:67], s[8:9], 0, v[66:67]
	global_load_dwordx4 v[118:121], v[68:69], off
	global_load_dwordx4 v[122:125], v[66:67], off
	v_lshlrev_b64 v[66:67], 10, v[136:137]
	v_lshl_add_u64 v[66:67], v[66:67], 0, s[22:23]
	v_or_b32_e32 v68, v66, v202
	v_mov_b32_e32 v69, v67
	v_lshlrev_b64 v[68:69], 1, v[68:69]
	v_lshl_add_u64 v[70:71], s[6:7], 0, v[68:69]
	v_lshl_add_u64 v[68:69], s[8:9], 0, v[68:69]
	global_load_dwordx4 v[126:129], v[70:71], off
	global_load_dwordx4 v[130:133], v[68:69], off
	v_or_b32_e32 v66, v66, v204
	v_lshlrev_b64 v[66:67], 1, v[66:67]
	v_lshl_add_u64 v[68:69], s[6:7], 0, v[66:67]
	v_lshl_add_u64 v[66:67], s[8:9], 0, v[66:67]
	global_load_dwordx4 v[98:101], v[68:69], off
	global_load_dwordx4 v[102:105], v[66:67], off
	v_lshlrev_b64 v[66:67], 10, v[108:109]
	v_lshl_add_u64 v[66:67], v[66:67], 0, s[22:23]
	v_or_b32_e32 v68, v66, v202
	v_mov_b32_e32 v69, v67
	v_lshlrev_b64 v[68:69], 1, v[68:69]
	v_lshl_add_u64 v[70:71], s[6:7], 0, v[68:69]
	v_lshl_add_u64 v[68:69], s[8:9], 0, v[68:69]
	global_load_dwordx4 v[90:93], v[70:71], off
	global_load_dwordx4 v[94:97], v[68:69], off
	v_or_b32_e32 v66, v66, v204
	v_lshlrev_b64 v[66:67], 1, v[66:67]
	v_lshl_add_u64 v[68:69], s[6:7], 0, v[66:67]
	v_lshl_add_u64 v[66:67], s[8:9], 0, v[66:67]
	v_add_u32_e32 v106, 0xb0, v210
	global_load_dwordx4 v[82:85], v[68:69], off
	global_load_dwordx4 v[86:89], v[66:67], off
	v_ashrrev_i32_e32 v107, 31, v106
	v_lshlrev_b64 v[66:67], 10, v[106:107]
	v_lshl_add_u64 v[66:67], v[66:67], 0, s[22:23]
	v_or_b32_e32 v68, v66, v202
	v_mov_b32_e32 v69, v67
	v_lshlrev_b64 v[68:69], 1, v[68:69]
	v_lshl_add_u64 v[70:71], s[6:7], 0, v[68:69]
	v_lshl_add_u64 v[68:69], s[8:9], 0, v[68:69]
	global_load_dwordx4 v[74:77], v[70:71], off
	global_load_dwordx4 v[78:81], v[68:69], off
	v_or_b32_e32 v66, v66, v204
	v_lshlrev_b64 v[70:71], 1, v[66:67]
	v_lshl_add_u64 v[66:67], s[6:7], 0, v[70:71]
	v_lshl_add_u64 v[70:71], s[8:9], 0, v[70:71]
	global_load_dwordx4 v[66:69], v[66:67], off
	v_lshlrev_b64 v[134:135], 11, v[134:135]
	global_load_dwordx4 v[70:73], v[70:71], off
	s_waitcnt vmcnt(15)
; __device__ __forceinline__ u32x4 pack8(const f32x4 v0, const f32x4 v1) { u32x4 w; w.x = cvt_pk_bf16(v0[0], v0[1]); w.y = cvt_pk_bf16(v0[2], v0[3]); w.z = cvt_pk_bf16(v1[0], v1[1]); w.w = cvt_pk_bf16(v1[2], v1[3]); return w; }
; __device__ __forceinline__ float bf_lo(unsigned w) { return __uint_as_float(w << 16); }
; __device__ __forceinline__ float bf_hi(unsigned w) { return __uint_as_float(w & 0xffff0000u); }
;     __device__ __forceinline__ void operator()(const f32x4 (&acc)[2][2][4][2], const Unit& u, int wr, int wc, int fr, int fq) const {
;     ...
;             _Pragma("unroll") for (int m = 0; m < 4; ++m) _Pragma("unroll") for (int bj = 0; bj < 2; ++bj) { const size_t off = (size_t)EPI_ROW(ai, m) * 1024 + u.pn * BM + EPI_CT(bj);
;                 f32x4 v0 = acc[ai][bj][m][0], v1 = acc[ai][bj][m][1]; const u32x4 g4 = gt[m][bj];
;                 v0[0] *= bf_lo(g4.x); v0[1] *= bf_hi(g4.x); v0[2] *= bf_lo(g4.y); v0[3] *= bf_hi(g4.y); v1[0] *= bf_lo(g4.z); v1[1] *= bf_hi(g4.z); v1[2] *= bf_lo(g4.w); v1[3] *= bf_hi(g4.w);
;                 if (ADD) { const u32x4 o = oo[m][bj];
;                     v0[0] += bf_lo(o.x); v0[1] += bf_hi(o.x); v0[2] += bf_lo(o.y); v0[3] += bf_hi(o.y); v1[0] += bf_lo(o.z); v1[1] += bf_hi(o.z); v1[2] += bf_lo(o.w); v1[3] += bf_hi(o.w); }
;                 *(u32x4*)(O + off) = pack8(v0, v1); }
	v_lshlrev_b32_e32 v138, 16, v110
	v_and_b32_e32 v139, 0xffff0000, v110
	s_waitcnt vmcnt(14)
	v_lshlrev_b32_e32 v140, 16, v114
	v_and_b32_e32 v141, 0xffff0000, v114
	v_lshlrev_b32_e32 v110, 16, v111
	v_and_b32_e32 v111, 0xffff0000, v111
	v_lshlrev_b32_e32 v114, 16, v115
	v_and_b32_e32 v115, 0xffff0000, v115
	v_pk_fma_f32 v[64:65], v[64:65], v[110:111], v[114:115]
	v_lshlrev_b32_e32 v110, 16, v112
	v_and_b32_e32 v111, 0xffff0000, v112
	v_lshlrev_b32_e32 v114, 16, v116
	v_and_b32_e32 v115, 0xffff0000, v116
	v_pk_fma_f32 v[62:63], v[62:63], v[138:139], v[140:141]
	v_pk_fma_f32 v[110:111], v[58:59], v[110:111], v[114:115]
	v_lshlrev_b32_e32 v58, 16, v113
	v_and_b32_e32 v59, 0xffff0000, v113
	v_lshlrev_b32_e32 v112, 16, v117
	v_and_b32_e32 v113, 0xffff0000, v117
	v_pk_fma_f32 v[112:113], v[60:61], v[58:59], v[112:113]
	v_cvt_pk_bf16_f32 v58, v62, v63
	v_lshl_add_u64 v[62:63], s[8:9], 0, v[134:135]
	v_lshl_add_u64 v[62:63], v[62:63], 0, s[24:25]
	v_cvt_pk_bf16_f32 v59, v64, v65
	v_cvt_pk_bf16_f32 v60, v110, v111
	v_cvt_pk_bf16_f32 v61, v112, v113
	v_lshl_add_u64 v[62:63], v[62:63], 0, v[0:1]
	global_store_dwordx4 v[62:63], v[58:61], off
	s_waitcnt vmcnt(14)
	s_nop 0
	v_lshlrev_b32_e32 v58, 16, v118
	v_and_b32_e32 v59, 0xffff0000, v118
	s_waitcnt vmcnt(13)
	v_lshlrev_b32_e32 v60, 16, v122
	v_and_b32_e32 v61, 0xffff0000, v122
	v_pk_fma_f32 v[54:55], v[54:55], v[58:59], v[60:61]
	v_lshlrev_b32_e32 v58, 16, v119
	v_and_b32_e32 v59, 0xffff0000, v119
	v_lshlrev_b32_e32 v60, 16, v123
	v_and_b32_e32 v61, 0xffff0000, v123
	v_pk_fma_f32 v[56:57], v[56:57], v[58:59], v[60:61]
	v_lshlrev_b32_e32 v58, 16, v120
	v_and_b32_e32 v59, 0xffff0000, v120
	v_lshlrev_b32_e32 v60, 16, v124
	v_and_b32_e32 v61, 0xffff0000, v124
	v_pk_fma_f32 v[58:59], v[50:51], v[58:59], v[60:61]
	v_lshlrev_b32_e32 v50, 16, v121
	v_and_b32_e32 v51, 0xffff0000, v121
	v_lshlrev_b32_e32 v60, 16, v125
	v_and_b32_e32 v61, 0xffff0000, v125
	v_pk_fma_f32 v[60:61], v[52:53], v[50:51], v[60:61]
	v_cvt_pk_bf16_f32 v50, v54, v55
	v_cvt_pk_bf16_f32 v51, v56, v57
	v_cvt_pk_bf16_f32 v52, v58, v59
	v_cvt_pk_bf16_f32 v53, v60, v61
	global_store_dwordx4 v[62:63], v[50:53], off offset:256
	s_waitcnt vmcnt(12)
	v_lshlrev_b32_e32 v54, 16, v130
	v_and_b32_e32 v55, 0xffff0000, v130
	v_lshlrev_b32_e32 v52, 16, v126
	v_and_b32_e32 v53, 0xffff0000, v126
	v_pk_fma_f32 v[46:47], v[46:47], v[52:53], v[54:55]
	v_lshlrev_b32_e32 v52, 16, v127
	v_and_b32_e32 v53, 0xffff0000, v127
	v_lshlrev_b32_e32 v54, 16, v131
	v_and_b32_e32 v55, 0xffff0000, v131
	v_pk_fma_f32 v[48:49], v[48:49], v[52:53], v[54:55]
	v_lshlrev_b32_e32 v52, 16, v128
	v_and_b32_e32 v53, 0xffff0000, v128
	v_lshlrev_b32_e32 v54, 16, v132
	v_and_b32_e32 v55, 0xffff0000, v132
	v_lshlrev_b64 v[50:51], 11, v[136:137]
	v_pk_fma_f32 v[52:53], v[42:43], v[52:53], v[54:55]
	v_lshlrev_b32_e32 v42, 16, v129
	v_and_b32_e32 v43, 0xffff0000, v129
	v_lshlrev_b32_e32 v54, 16, v133
	v_and_b32_e32 v55, 0xffff0000, v133
	v_pk_fma_f32 v[54:55], v[44:45], v[42:43], v[54:55]
	v_cvt_pk_bf16_f32 v42, v46, v47
	v_lshl_add_u64 v[46:47], s[8:9], 0, v[50:51]
	v_lshl_add_u64 v[46:47], v[46:47], 0, s[24:25]
	v_cvt_pk_bf16_f32 v43, v48, v49
	v_cvt_pk_bf16_f32 v44, v52, v53
	v_cvt_pk_bf16_f32 v45, v54, v55
	v_lshl_add_u64 v[46:47], v[46:47], 0, v[0:1]
	global_store_dwordx4 v[46:47], v[42:45], off
	s_waitcnt vmcnt(12)
	s_nop 0
	v_lshlrev_b32_e32 v42, 16, v98
	v_and_b32_e32 v43, 0xffff0000, v98
	s_waitcnt vmcnt(11)
	v_lshlrev_b32_e32 v44, 16, v102
	v_and_b32_e32 v45, 0xffff0000, v102
	v_pk_fma_f32 v[38:39], v[38:39], v[42:43], v[44:45]
	v_lshlrev_b32_e32 v42, 16, v99
	v_and_b32_e32 v43, 0xffff0000, v99
	v_lshlrev_b32_e32 v44, 16, v103
	v_and_b32_e32 v45, 0xffff0000, v103
	v_pk_fma_f32 v[40:41], v[40:41], v[42:43], v[44:45]
	v_lshlrev_b32_e32 v42, 16, v100
	v_and_b32_e32 v43, 0xffff0000, v100
	v_lshlrev_b32_e32 v44, 16, v104
	v_and_b32_e32 v45, 0xffff0000, v104
	v_pk_fma_f32 v[42:43], v[34:35], v[42:43], v[44:45]
	v_lshlrev_b32_e32 v34, 16, v101
	v_and_b32_e32 v35, 0xffff0000, v101
	v_lshlrev_b32_e32 v44, 16, v105
	v_and_b32_e32 v45, 0xffff0000, v105
	v_pk_fma_f32 v[44:45], v[36:37], v[34:35], v[44:45]
	v_cvt_pk_bf16_f32 v34, v38, v39
	v_cvt_pk_bf16_f32 v35, v40, v41
	v_cvt_pk_bf16_f32 v36, v42, v43
	v_cvt_pk_bf16_f32 v37, v44, v45
	global_store_dwordx4 v[46:47], v[34:37], off offset:256
	s_waitcnt vmcnt(10)
; __device__ __forceinline__ u32x4 pack8(const f32x4 v0, const f32x4 v1) { u32x4 w; w.x = cvt_pk_bf16(v0[0], v0[1]); w.y = cvt_pk_bf16(v0[2], v0[3]); w.z = cvt_pk_bf16(v1[0], v1[1]); w.w = cvt_pk_bf16(v1[2], v1[3]); return w; }
; __device__ __forceinline__ float bf_lo(unsigned w) { return __uint_as_float(w << 16); }
; __device__ __forceinline__ float bf_hi(unsigned w) { return __uint_as_float(w & 0xffff0000u); }
; #define PG8_BAR __builtin_amdgcn_s_barrier()
;     __device__ __forceinline__ void operator()(const f32x4 (&acc)[2][2][4][2], const Unit& u, int wr, int wc, int fr, int fq) const {
;     ...
;             _Pragma("unroll") for (int m = 0; m < 4; ++m) _Pragma("unroll") for (int bj = 0; bj < 2; ++bj) { const size_t off = (size_t)EPI_ROW(ai, m) * 1024 + u.pn * BM + EPI_CT(bj);
;                 f32x4 v0 = acc[ai][bj][m][0], v1 = acc[ai][bj][m][1]; const u32x4 g4 = gt[m][bj];
;                 v0[0] *= bf_lo(g4.x); v0[1] *= bf_hi(g4.x); v0[2] *= bf_lo(g4.y); v0[3] *= bf_hi(g4.y); v1[0] *= bf_lo(g4.z); v1[1] *= bf_hi(g4.z); v1[2] *= bf_lo(g4.w); v1[3] *= bf_hi(g4.w);
;                 if (ADD) { const u32x4 o = oo[m][bj];
;                     v0[0] += bf_lo(o.x); v0[1] += bf_hi(o.x); v0[2] += bf_lo(o.y); v0[3] += bf_hi(o.y); v1[0] += bf_lo(o.z); v1[1] += bf_hi(o.z); v1[2] += bf_lo(o.w); v1[3] += bf_hi(o.w); }
;                 *(u32x4*)(O + off) = pack8(v0, v1); }
; template <class Epi, class Sched, bool ALIGN_EPI = false, bool SP2 = false>
; __device__ __forceinline__ void gemm_phase(PG8_LAS unsigned char* lds, const Gemm g, const Sched& S, const Epi& E) {
;     ...
;         if (!has_next) break;
; #pragma unroll
;         for (int a = 0; a < 2; ++a)
; #pragma unroll
;             for (int b = 0; b < 2; ++b)
; #pragma unroll
;                 for (int m = 0; m < 4; ++m)
; #pragma unroll
;                     for (int n = 0; n < 2; ++n) acc[a][b][m][n] = (f32x4){0.f, 0.f, 0.f, 0.f};
;         cur = nxt; cA = nA; cB = nB; ++ui;
;         if constexpr (ALIGN_EPI) { if (wr == 1) PG8_BAR; }
;     }
	v_lshlrev_b32_e32 v38, 16, v94
	v_and_b32_e32 v39, 0xffff0000, v94
	v_lshlrev_b32_e32 v36, 16, v90
	v_and_b32_e32 v37, 0xffff0000, v90
	v_pk_fma_f32 v[30:31], v[30:31], v[36:37], v[38:39]
	v_lshlrev_b32_e32 v36, 16, v91
	v_and_b32_e32 v37, 0xffff0000, v91
	v_lshlrev_b32_e32 v38, 16, v95
	v_and_b32_e32 v39, 0xffff0000, v95
	v_pk_fma_f32 v[32:33], v[32:33], v[36:37], v[38:39]
	v_lshlrev_b32_e32 v36, 16, v92
	v_and_b32_e32 v37, 0xffff0000, v92
	v_lshlrev_b32_e32 v38, 16, v96
	v_and_b32_e32 v39, 0xffff0000, v96
	v_lshlrev_b64 v[34:35], 11, v[108:109]
	v_pk_fma_f32 v[36:37], v[26:27], v[36:37], v[38:39]
	v_lshlrev_b32_e32 v26, 16, v93
	v_and_b32_e32 v27, 0xffff0000, v93
	v_lshlrev_b32_e32 v38, 16, v97
	v_and_b32_e32 v39, 0xffff0000, v97
	v_pk_fma_f32 v[38:39], v[28:29], v[26:27], v[38:39]
	v_cvt_pk_bf16_f32 v26, v30, v31
	v_lshl_add_u64 v[30:31], s[8:9], 0, v[34:35]
	v_lshl_add_u64 v[30:31], v[30:31], 0, s[24:25]
	v_cvt_pk_bf16_f32 v27, v32, v33
	v_cvt_pk_bf16_f32 v28, v36, v37
	v_cvt_pk_bf16_f32 v29, v38, v39
	v_lshl_add_u64 v[30:31], v[30:31], 0, v[0:1]
	global_store_dwordx4 v[30:31], v[26:29], off
	s_waitcnt vmcnt(10)
	s_nop 0
	v_lshlrev_b32_e32 v26, 16, v82
	v_and_b32_e32 v27, 0xffff0000, v82
	s_waitcnt vmcnt(9)
	v_lshlrev_b32_e32 v28, 16, v86
	v_and_b32_e32 v29, 0xffff0000, v86
	v_pk_fma_f32 v[22:23], v[22:23], v[26:27], v[28:29]
	v_lshlrev_b32_e32 v26, 16, v83
	v_and_b32_e32 v27, 0xffff0000, v83
	v_lshlrev_b32_e32 v28, 16, v87
	v_and_b32_e32 v29, 0xffff0000, v87
	v_pk_fma_f32 v[24:25], v[24:25], v[26:27], v[28:29]
	v_lshlrev_b32_e32 v26, 16, v84
	v_and_b32_e32 v27, 0xffff0000, v84
	v_lshlrev_b32_e32 v28, 16, v88
	v_and_b32_e32 v29, 0xffff0000, v88
	v_pk_fma_f32 v[26:27], v[18:19], v[26:27], v[28:29]
	v_lshlrev_b32_e32 v18, 16, v85
	v_and_b32_e32 v19, 0xffff0000, v85
	v_lshlrev_b32_e32 v28, 16, v89
	v_and_b32_e32 v29, 0xffff0000, v89
	v_pk_fma_f32 v[28:29], v[20:21], v[18:19], v[28:29]
	v_cvt_pk_bf16_f32 v18, v22, v23
	v_cvt_pk_bf16_f32 v19, v24, v25
	v_cvt_pk_bf16_f32 v20, v26, v27
	v_cvt_pk_bf16_f32 v21, v28, v29
	global_store_dwordx4 v[30:31], v[18:21], off offset:256
	s_waitcnt vmcnt(8)
	v_lshlrev_b32_e32 v22, 16, v78
	v_and_b32_e32 v23, 0xffff0000, v78
	v_lshlrev_b32_e32 v20, 16, v74
	v_and_b32_e32 v21, 0xffff0000, v74
	v_pk_fma_f32 v[14:15], v[14:15], v[20:21], v[22:23]
	v_lshlrev_b32_e32 v20, 16, v75
	v_and_b32_e32 v21, 0xffff0000, v75
	v_lshlrev_b32_e32 v22, 16, v79
	v_and_b32_e32 v23, 0xffff0000, v79
	v_pk_fma_f32 v[16:17], v[16:17], v[20:21], v[22:23]
	v_lshlrev_b32_e32 v20, 16, v76
	v_and_b32_e32 v21, 0xffff0000, v76
	v_lshlrev_b32_e32 v22, 16, v80
	v_and_b32_e32 v23, 0xffff0000, v80
	v_lshlrev_b64 v[18:19], 11, v[106:107]
	v_pk_fma_f32 v[20:21], v[10:11], v[20:21], v[22:23]
	v_lshlrev_b32_e32 v10, 16, v77
	v_and_b32_e32 v11, 0xffff0000, v77
	v_lshlrev_b32_e32 v22, 16, v81
	v_and_b32_e32 v23, 0xffff0000, v81
	v_pk_fma_f32 v[22:23], v[12:13], v[10:11], v[22:23]
	v_cvt_pk_bf16_f32 v10, v14, v15
	v_lshl_add_u64 v[14:15], s[8:9], 0, v[18:19]
	v_lshl_add_u64 v[14:15], v[14:15], 0, s[24:25]
	v_cvt_pk_bf16_f32 v11, v16, v17
	v_cvt_pk_bf16_f32 v12, v20, v21
	v_cvt_pk_bf16_f32 v13, v22, v23
	v_lshl_add_u64 v[14:15], v[14:15], 0, v[0:1]
	global_store_dwordx4 v[14:15], v[10:13], off
	s_waitcnt vmcnt(8)
	s_nop 0
	v_lshlrev_b32_e32 v10, 16, v66
	v_and_b32_e32 v11, 0xffff0000, v66
	s_waitcnt vmcnt(7)
	v_lshlrev_b32_e32 v12, 16, v70
	v_and_b32_e32 v13, 0xffff0000, v70
	v_pk_fma_f32 v[6:7], v[6:7], v[10:11], v[12:13]
	v_lshlrev_b32_e32 v10, 16, v67
	v_and_b32_e32 v11, 0xffff0000, v67
	v_lshlrev_b32_e32 v12, 16, v71
	v_and_b32_e32 v13, 0xffff0000, v71
	v_pk_fma_f32 v[8:9], v[8:9], v[10:11], v[12:13]
	v_lshlrev_b32_e32 v10, 16, v68
	v_and_b32_e32 v11, 0xffff0000, v68
	v_lshlrev_b32_e32 v12, 16, v72
	v_and_b32_e32 v13, 0xffff0000, v72
	v_pk_fma_f32 v[10:11], v[2:3], v[10:11], v[12:13]
	v_lshlrev_b32_e32 v2, 16, v69
	v_and_b32_e32 v3, 0xffff0000, v69
	v_lshlrev_b32_e32 v12, 16, v73
	v_and_b32_e32 v13, 0xffff0000, v73
	v_pk_fma_f32 v[12:13], v[4:5], v[2:3], v[12:13]
	v_cvt_pk_bf16_f32 v2, v6, v7
	v_cvt_pk_bf16_f32 v3, v8, v9
	v_cvt_pk_bf16_f32 v4, v10, v11
	v_cvt_pk_bf16_f32 v5, v12, v13
	global_store_dwordx4 v[14:15], v[2:5], off offset:256
	s_cbranch_vccnz .LBB0_624
	s_andn2_b64 vcc, exec, s[0:1]
	s_cbranch_vccnz .LBB0_623
	s_branch .LBB0_623

;     __device__ __forceinline__ bool next(int i, Unit& u) const { const int L = i * G + c; if (L >= 512) return false; u.pm = L; u.pn = L >> 4; return true; }
; #define PG8_WAIT_V(n) asm volatile("s_waitcnt vmcnt(" #n ")" ::: "memory")
; #define PG8_BAR __builtin_amdgcn_s_barrier()
; template <class Epi, class Sched, bool ALIGN_EPI = false, bool SP2 = false>
; __device__ __forceinline__ void gemm_phase(PG8_LAS unsigned char* lds, const Gemm g, const Sched& S, const Epi& E) {
;     int tid_ = threadIdx.x; asm volatile("" : "+v"(tid_));
;     const int tid = tid_, wid = __builtin_amdgcn_readfirstlane(tid >> 6), lane = tid & 63, wr = wid >> 2, wc = wid & 3, fr = lane & 15, fq = lane >> 4;
;     const int K = g.K, nt = K / BK, LD = g.ld ? g.ld : g.K;
;     unsigned voffA[2], voffB[2];
; #pragma unroll
;     for (int i = 0; i < 2; ++i) { int R, C; stage_rc(tid * 16 + i * 8192, R, C); const int Rb = Epi::PERM ? ((R & ~31) + perm32(R & 31)) : R;
;         voffA[i] = (unsigned)(R * LD + C) * 2u; voffB[i] = (unsigned)(Rb * LD + C) * 2u; }
;     const size_t kstep = (size_t)(BK * 2);
;     const size_t hstep = (size_t)HALF * LD * 2;
;     const size_t tstep = 2 * hstep;
;     const unsigned ldsw = (unsigned)wid * 1024u;
;     const int aoff = lds_byte(wr * 64 + fr, fq * 8), boff = lds_byte(wc * 32 + fr, fq * 8);
;     ...
;     Unit cur, nxt; int ui = 0;
;     if (!S.next(0, cur)) return;
;     f32x4 acc[2][2][4][2];
; #pragma unroll
;     for (int a = 0; a < 2; ++a)
; #pragma unroll
;         for (int b = 0; b < 2; ++b)
; #pragma unroll
;             for (int m = 0; m < 4; ++m)
; #pragma unroll
;                 for (int n = 0; n < 2; ++n) acc[a][b][m][n] = (f32x4){0.f, 0.f, 0.f, 0.f};
;     bf16x8 At[4][2], B0[2][2], B1[2][2];
;     const char* cA = (const char*)g.A + (size_t)cur.pm * tstep; const char* cB = (const char*)g.Bt + (size_t)cur.pn * tstep;
;     S.a_ready(cur);
;     if constexpr (SP2) {
;         PG8_STAGE(PG8_SB(0, 0), cB, voffB); PG8_STAGE(PG8_SB(0, 1), cB + hstep, voffB); PG8_STAGE(PG8_SA(0, 0), cA, voffA); PG8_STAGE(PG8_SA(0, 1), cA + hstep, voffA);
;         if (wr == 1) PG8_BAR;
;         PG8_WAIT_V(2); PG8_BAR;
;         PG8_STAGE(PG8_SB(1, 0), cB + kstep, voffB); PG8_STAGE(PG8_SA(1, 0), cA + kstep, voffA); PG8_STAGE(PG8_SB(1, 1), cB + hstep + kstep, voffB);
;         PG8_WAIT_V(6); PG8_BAR;
.LBB0_684:
	s_or_b64 exec, exec, s[36:37]
	v_readlane_b32 s0, v254, 56
	s_mov_b64 s[4:5], s[72:73]
	v_mov_b32_e32 v15, v242
	v_readlane_b32 s1, v254, 57
	s_waitcnt lgkmcnt(0)
	s_barrier
	s_and_b64 vcc, exec, s[0:1]
	v_readfirstlane_b32 s8, v15
	s_cbranch_vccz .LBB0_704
	v_lshlrev_b32_e32 v2, 4, v15
	v_add_u32_e32 v3, 0x2000, v2
	v_ashrrev_i32_e32 v0, 31, v3
	v_lshrrev_b32_e32 v0, 22, v0
	v_add_u32_e32 v0, v3, v0
	v_ashrrev_i32_e32 v0, 10, v0
	v_mul_i32_i24_e32 v4, 0x400, v0
	v_sub_u32_e32 v3, v3, v4
	v_lshrrev_b32_e32 v4, 4, v3
	v_bitop3_b32 v3, v4, v3, 32 bitop3:0x6c
	v_ashrrev_i32_e32 v4, 31, v3
	v_lshrrev_b32_e32 v4, 26, v4
	v_add_u32_e32 v4, v3, v4
	v_lshlrev_b32_e32 v5, 3, v0
	v_ashrrev_i32_e32 v10, 6, v4
	v_and_b32_e32 v5, -16, v5
	v_add_u32_e32 v5, v10, v5
	v_and_b32_e32 v6, 3, v10
	s_mov_b32 s0, 0x1fffe0
	v_lshrrev_b32_e32 v7, 2, v5
	v_lshlrev_b32_e32 v8, 1, v5
	v_and_b32_e32 v4, 0xc0, v4
	v_and_or_b32 v6, v5, s0, v6
	v_and_b32_e32 v7, 4, v7
	v_and_b32_e32 v8, 24, v8
	v_sub_u32_e32 v3, v3, v4
	v_or3_b32 v6, v6, v7, v8
	v_lshlrev_b32_e32 v7, 5, v0
	v_ashrrev_i16_sdwa v3, v241, sext(v3) dst_sel:DWORD dst_unused:UNUSED_PAD src0_sel:DWORD src1_sel:BYTE_0
	v_and_b32_e32 v7, 32, v7
	v_bfe_i32 v11, v3, 0, 16
	v_add_lshl_u32 v3, v7, v11, 1
	v_lshl_add_u32 v194, v6, 11, v3
	v_lshl_add_u32 v196, v5, 11, v3
	v_bfe_i32 v3, v15, 27, 1
	v_lshrrev_b32_e32 v3, 22, v3
	v_add_u32_e32 v3, v2, v3
	v_and_b32_e32 v3, 0xfffffc00, v3
	v_sub_u32_e32 v2, v2, v3
	v_lshrrev_b32_e32 v3, 4, v2
	v_ashrrev_i32_e32 v4, 31, v15
	v_bitop3_b32 v2, v3, v2, 32 bitop3:0x6c
	v_lshrrev_b32_e32 v4, 26, v4
	v_ashrrev_i32_e32 v3, 31, v2
	v_add_u32_e32 v4, v15, v4
	v_lshrrev_b32_e32 v3, 26, v3
	v_ashrrev_i32_e32 v13, 6, v4
	v_add_u32_e32 v3, v2, v3
	v_lshlrev_b32_e32 v4, 3, v13
	s_add_u32 s24, s4, 0x11400000
	v_ashrrev_i32_e32 v12, 6, v3
	v_and_b32_e32 v4, -16, v4
	s_addc_u32 s25, s5, 0
	v_add_u32_e32 v4, v12, v4
	s_add_u32 s26, s4, 0x1900000
	v_and_b32_e32 v5, 3, v12
	v_lshrrev_b32_e32 v6, 2, v4
	v_lshlrev_b32_e32 v7, 1, v4
	v_and_b32_e32 v3, 0xc0, v3
	s_addc_u32 s27, s5, 0
	s_ashr_i32 s9, s8, 6
	v_and_or_b32 v5, v4, s0, v5
	v_and_b32_e32 v6, 4, v6
	v_and_b32_e32 v7, 24, v7
	v_sub_u32_e32 v2, v2, v3
	s_ashr_i32 s10, s8, 8
	s_lshl_b32 s28, s9, 10
	v_or3_b32 v5, v5, v6, v7
	v_lshlrev_b32_e32 v6, 5, v13
	v_ashrrev_i16_sdwa v2, v241, sext(v2) dst_sel:DWORD dst_unused:UNUSED_PAD src0_sel:DWORD src1_sel:BYTE_0
	v_readlane_b32 s0, v255, 16
	v_and_b32_e32 v6, 32, v6
	v_bfe_i32 v14, v2, 0, 16
	v_readlane_b32 s1, v255, 17
	s_add_u32 s16, s26, s0
	v_add_lshl_u32 v2, v6, v14, 1
	s_addc_u32 s17, s27, s1
	s_add_i32 s29, s28, 0
	v_lshl_add_u32 v198, v5, 11, v2
	s_add_i32 m0, s29, 0x10000
	v_lshl_add_u32 v200, v4, 11, v2
	global_load_lds_dwordx4 v198, s[16:17]
	s_add_i32 m0, s29, 0x12000
	s_add_u32 s0, s16, 0x40000
	global_load_lds_dwordx4 v194, s[16:17]
	s_addc_u32 s1, s17, 0
	s_add_i32 m0, s29, 0x14000
	v_mov_b32_e32 v199, v1
	global_load_lds_dwordx4 v198, s[0:1]
	s_add_i32 m0, s29, 0x16000
	v_mov_b32_e32 v195, v1
	global_load_lds_dwordx4 v194, s[0:1]
	v_readlane_b32 s0, v255, 14
	v_readlane_b32 s1, v255, 15
	s_add_u32 s20, s24, s0
	s_addc_u32 s21, s25, s1
	s_add_i32 s30, s29, 0x2000
	s_mov_b32 m0, s29
	s_add_u32 s0, s20, 0x40000
	global_load_lds_dwordx4 v200, s[20:21]
	s_mov_b32 m0, s30
	s_addc_u32 s1, s21, 0
	s_add_i32 s31, s29, 0x4000
	global_load_lds_dwordx4 v196, s[20:21]
	s_mov_b32 m0, s31
	s_add_i32 s34, s29, 0x6000
	global_load_lds_dwordx4 v200, s[0:1]
	s_mov_b32 m0, s34
	v_mov_b32_e32 v201, v1
	global_load_lds_dwordx4 v196, s[0:1]
	v_mov_b32_e32 v197, v1
	s_cmp_eq_u32 s10, 1
	v_lshl_add_u64 v[8:9], s[16:17], 0, v[198:199]
	v_lshl_add_u64 v[6:7], s[16:17], 0, v[194:195]
	v_lshl_add_u64 v[2:3], s[20:21], 0, v[200:201]
	s_cselect_b64 s[0:1], -1, 0
	s_cmp_lg_u32 s10, 1
	v_lshl_add_u64 v[4:5], s[20:21], 0, v[196:197]
	s_cbranch_scc1 .LBB0_687
.LBB0_687:
	v_lshrrev_b32_e32 v17, 1, v15
	v_and_b32_e32 v17, 24, v17
	s_add_u32 s6, s4, 0x33400000
	v_and_b32_e32 v16, 15, v15
	v_lshlrev_b32_e32 v18, 1, v17
	v_lshlrev_b32_e32 v15, 2, v15
	s_addc_u32 s7, s5, 0
	v_lshl_or_b32 v230, s10, 6, v16
	v_lshl_or_b32 v16, v16, 6, v18
	s_lshl_b32 s4, s10, 13
	v_and_b32_e32 v15, 32, v15
	v_bitop3_b32 v18, v16, s4, v15 bitop3:0xde
	s_lshl_b32 s4, s9, 5
	s_and_b32 s10, s4, 0x60
	s_add_i32 m0, s29, 0x18000
	v_lshl_add_u64 v[8:9], v[8:9], 0, s[94:95]
	s_lshl_b32 s4, s10, 7
	s_waitcnt vmcnt(2)
	s_barrier
	global_load_lds_dwordx4 v[8:9], off
	v_lshl_add_u64 v[6:7], v[6:7], 0, s[94:95]
	s_add_i32 m0, s29, 0x1a000
	s_add_i32 s33, s29, 0x8000
	s_add_i32 s35, s29, 0xa000
	v_bitop3_b32 v231, v16, s4, v15 bitop3:0xde
	global_load_lds_dwordx4 v[6:7], off
	v_lshl_add_u64 v[2:3], v[2:3], 0, s[94:95]
	s_mov_b32 m0, s33
	s_add_u32 s4, s16, 0x40080
	global_load_lds_dwordx4 v[2:3], off
	v_lshl_add_u64 v[2:3], v[4:5], 0, s[94:95]
	s_mov_b32 m0, s35
	s_addc_u32 s5, s17, 0
	global_load_lds_dwordx4 v[2:3], off
	s_add_i32 m0, s29, 0x1c000
	v_lshl_add_u64 v[2:3], s[4:5], 0, v[198:199]
	global_load_lds_dwordx4 v[2:3], off
	v_lshl_add_u64 v[2:3], s[4:5], 0, v[194:195]
	s_add_i32 m0, s29, 0x1e000
	v_and_b32_e32 v4, 1, v13
	global_load_lds_dwordx4 v[2:3], off
	v_lshlrev_b32_e32 v3, 14, v13
	v_and_b32_e32 v3, 0xffff8000, v3
	v_lshl_add_u32 v3, v12, 11, v3
	v_lshl_or_b32 v3, v4, 6, v3
	v_lshl_add_u32 v202, v14, 1, v3
	v_lshlrev_b32_e32 v3, 14, v0
	v_and_b32_e32 v3, 0xffff8000, v3
	s_waitcnt vmcnt(6)
	v_lshl_add_u32 v3, v10, 11, v3
	v_and_b32_e32 v0, 1, v0
	s_cmpk_lt_u32 s8, 0x100
	v_or_b32_e32 v2, s10, v17
	v_lshl_or_b32 v0, v0, 6, v3
	v_readlane_b32 s4, v255, 18
	s_cselect_b64 s[8:9], -1, 0
	v_mov_b32_e32 v203, v1
	v_lshl_add_u32 v204, v11, 1, v0
	v_mov_b32_e32 v205, v1
	s_mov_b32 s36, 0
	v_add_u32_e32 v232, 0, v18
	v_lshlrev_b32_e32 v0, 1, v2
	v_readlane_b32 s37, v255, 9
	s_mov_b32 s38, s4
	s_barrier
	v_readlane_b32 s5, v255, 19
	s_branch .LBB0_690

;     __device__ __forceinline__ bool next(int i, Unit& u) const { const int L = i * G + c; if (L >= 512) return false; u.pm = L; u.pn = L >> 4; return true; }
; #define PG8_STAGE(bufoff, gbase, voff) do { _Pragma("unroll") for (int _i = 0; _i < 2; ++_i) \
;         __builtin_amdgcn_global_load_lds((const unsigned*)((const char*)(gbase) + (voff)[_i]), (PG8_LAS unsigned*)(lds + (bufoff) + ldsw + _i * 8192), 16, 0, 0); } while (0)
; #define PG8_LDA(dst, b, h) do { _Pragma("unroll") for (int m = 0; m < 4; ++m) _Pragma("unroll") for (int k = 0; k < 2; ++k) dst[m][k] = *(const PG8_LAS bf16x8*)(lds + PG8_SA(b, h) + aoff + m * 2048 + k * 1024); } while (0)
; #define PG8_LDB(dst, b, h) do { _Pragma("unroll") for (int n = 0; n < 2; ++n) _Pragma("unroll") for (int k = 0; k < 2; ++k) dst[n][k] = *(const PG8_LAS bf16x8*)(lds + PG8_SB(b, h) + boff + n * 2048 + k * 1024); } while (0)
; #define PG8_WAIT_V(n) asm volatile("s_waitcnt vmcnt(" #n ")" ::: "memory")
; template <class Epi, class Sched, bool ALIGN_EPI = false, bool SP2 = false>
; __device__ __forceinline__ void gemm_phase(PG8_LAS unsigned char* lds, const Gemm g, const Sched& S, const Epi& E) {
;     ...
;         const bool has_next = S.next(ui + 1, nxt);
;         const char* nA = has_next ? (const char*)g.A + (size_t)nxt.pm * tstep : cA; const char* nB = has_next ? (const char*)g.Bt + (size_t)nxt.pn * tstep : cB;
;         for (int t = 0; t < nt; t += 2) {
;             const bool last = (t == nt - 2);
;             const char* a1 = cA + (size_t)(t + 1) * kstep;
;             const char* a2 = last ? nA : cA + (size_t)(t + 2) * kstep; const char* b2 = last ? nB : cB + (size_t)(t + 2) * kstep;
;             const char* a3 = a2 + kstep; const char* b3 = b2 + kstep;
;             if (last && has_next) S.a_ready(nxt);
;             if constexpr (SP2) {
;             PG8_LDB(B0, 0, 0); PG8_LDB(B1, 0, 1); PG8_SCHED; PG8_LDA(At, 0, 0); PG8_STAGE(PG8_SA(1, 1), a1 + hstep, voffA);
;             PG8_WAIT_V(8); PG8_WAIT_L(0); PG8_BAR; PG8_MMA(0, 0, At, B0); PG8_MMA(0, 1, At, B1); PG8_BAR; PG8_SCHED;
;     ...
;         for (int a = 0; a < 2; ++a)
; #pragma unroll
;             for (int b = 0; b < 2; ++b)
; #pragma unroll
;                 for (int m = 0; m < 4; ++m)
; #pragma unroll
;                     for (int n = 0; n < 2; ++n) acc[a][b][m][n] = (f32x4){0.f, 0.f, 0.f, 0.f};
;         cur = nxt; cA = nA; cB = nB; ++ui;
.LBB0_696:
	s_ashr_i32 s13, s12, 31
	s_lshl_b64 s[14:15], s[12:13], 19
	s_add_u32 s14, s24, s14
	s_addc_u32 s15, s25, s15
	s_and_b64 s[18:19], s[4:5], exec
	s_cselect_b32 s13, s15, s21
	s_cselect_b32 s39, s14, s20
	s_ashr_i32 s11, s10, 31
	s_lshl_b64 s[18:19], s[10:11], 19
	s_add_u32 s18, s26, s18
	s_addc_u32 s19, s27, s19
	s_and_b64 s[22:23], s[4:5], exec
	s_cselect_b32 s11, s19, s17
	s_cselect_b32 s46, s18, s16
	s_add_u32 s20, s20, 0x40080
	s_addc_u32 s21, s21, 0
	s_add_u32 s55, s16, 0x100
	v_mov_b32_e32 v2, 0
	s_addc_u32 s56, s17, 0
	s_mov_b32 s50, -2
	v_mov_b32_e32 v3, v2
	v_mov_b32_e32 v4, v2
	v_mov_b32_e32 v5, v2
	v_mov_b32_e32 v6, v2
	v_mov_b32_e32 v7, v2
	v_mov_b32_e32 v8, v2
	v_mov_b32_e32 v9, v2
	v_mov_b32_e32 v14, v2
	v_mov_b32_e32 v15, v2
	v_mov_b32_e32 v16, v2
	v_mov_b32_e32 v17, v2
	v_mov_b32_e32 v22, v2
	v_mov_b32_e32 v23, v2
	v_mov_b32_e32 v24, v2
	v_mov_b32_e32 v25, v2
	v_mov_b32_e32 v30, v2
	v_mov_b32_e32 v31, v2
	v_mov_b32_e32 v32, v2
	v_mov_b32_e32 v33, v2
	v_mov_b32_e32 v38, v2
	v_mov_b32_e32 v39, v2
	v_mov_b32_e32 v40, v2
	v_mov_b32_e32 v41, v2
	v_mov_b32_e32 v46, v2
	v_mov_b32_e32 v47, v2
	v_mov_b32_e32 v48, v2
	v_mov_b32_e32 v49, v2
	v_mov_b32_e32 v54, v2
	v_mov_b32_e32 v55, v2
	v_mov_b32_e32 v56, v2
	v_mov_b32_e32 v57, v2
	v_mov_b32_e32 v10, v2
	v_mov_b32_e32 v11, v2
	v_mov_b32_e32 v12, v2
	v_mov_b32_e32 v13, v2
	v_mov_b32_e32 v18, v2
	v_mov_b32_e32 v19, v2
	v_mov_b32_e32 v20, v2
	v_mov_b32_e32 v21, v2
	v_mov_b32_e32 v26, v2
	v_mov_b32_e32 v27, v2
	v_mov_b32_e32 v28, v2
	v_mov_b32_e32 v29, v2
	v_mov_b32_e32 v34, v2
	v_mov_b32_e32 v35, v2
	v_mov_b32_e32 v36, v2
	v_mov_b32_e32 v37, v2
	v_mov_b32_e32 v42, v2
	v_mov_b32_e32 v43, v2
	v_mov_b32_e32 v44, v2
	v_mov_b32_e32 v45, v2
	v_mov_b32_e32 v50, v2
	v_mov_b32_e32 v51, v2
	v_mov_b32_e32 v52, v2
	v_mov_b32_e32 v53, v2
	v_mov_b32_e32 v58, v2
	v_mov_b32_e32 v59, v2
	v_mov_b32_e32 v60, v2
	v_mov_b32_e32 v61, v2
	v_mov_b32_e32 v62, v2
	v_mov_b32_e32 v63, v2
	v_mov_b32_e32 v64, v2
	v_mov_b32_e32 v65, v2
	v_mov_b32_e32 v66, v2
	v_mov_b32_e32 v67, v2
	v_mov_b32_e32 v68, v2
	v_mov_b32_e32 v69, v2
	v_mov_b32_e32 v70, v2
	v_mov_b32_e32 v71, v2
	v_mov_b32_e32 v72, v2
	v_mov_b32_e32 v73, v2
	v_mov_b32_e32 v78, v2
	v_mov_b32_e32 v79, v2
	v_mov_b32_e32 v80, v2
	v_mov_b32_e32 v81, v2
	v_mov_b32_e32 v86, v2
	v_mov_b32_e32 v87, v2
	v_mov_b32_e32 v88, v2
	v_mov_b32_e32 v89, v2
	v_mov_b32_e32 v94, v2
	v_mov_b32_e32 v95, v2
	v_mov_b32_e32 v96, v2
	v_mov_b32_e32 v97, v2
	v_mov_b32_e32 v102, v2
	v_mov_b32_e32 v103, v2
	v_mov_b32_e32 v104, v2
	v_mov_b32_e32 v105, v2
	v_mov_b32_e32 v110, v2
	v_mov_b32_e32 v111, v2
	v_mov_b32_e32 v112, v2
	v_mov_b32_e32 v113, v2
	v_mov_b32_e32 v118, v2
	v_mov_b32_e32 v119, v2
	v_mov_b32_e32 v120, v2
	v_mov_b32_e32 v121, v2
	v_mov_b32_e32 v74, v2
	v_mov_b32_e32 v75, v2
	v_mov_b32_e32 v76, v2
	v_mov_b32_e32 v77, v2
	v_mov_b32_e32 v82, v2
	v_mov_b32_e32 v83, v2
	v_mov_b32_e32 v84, v2
	v_mov_b32_e32 v85, v2
	v_mov_b32_e32 v90, v2
	v_mov_b32_e32 v91, v2
	v_mov_b32_e32 v92, v2
	v_mov_b32_e32 v93, v2
	v_mov_b32_e32 v98, v2
	v_mov_b32_e32 v99, v2
	v_mov_b32_e32 v100, v2
	v_mov_b32_e32 v101, v2
	v_mov_b32_e32 v106, v2
	v_mov_b32_e32 v107, v2
	v_mov_b32_e32 v108, v2
	v_mov_b32_e32 v109, v2
	v_mov_b32_e32 v114, v2
	v_mov_b32_e32 v115, v2
	v_mov_b32_e32 v116, v2
	v_mov_b32_e32 v117, v2
	v_mov_b32_e32 v122, v2
	v_mov_b32_e32 v123, v2
	v_mov_b32_e32 v124, v2
	v_mov_b32_e32 v125, v2
	v_mov_b32_e32 v126, v2
	v_mov_b32_e32 v127, v2
	v_mov_b32_e32 v128, v2
	v_mov_b32_e32 v129, v2
	s_cmp_eq_u64 s[0:1], 0
	s_cbranch_scc1 .Lboff_skip_I
	s_barrier
.Lboff_skip_I:
.LBB0_697:
	s_add_u32 s16, s20, 0xfffc0080
	s_addc_u32 s17, s21, -1
	s_add_i32 s52, 0, 0x10000
	s_cmp_eq_u32 s50, 12
	s_cselect_b32 s23, s13, s17
	s_cselect_b32 s22, s39, s16
	s_cselect_b32 s17, s11, s56
	s_cselect_b32 s16, s46, s55
	s_add_i32 s57, 0, 0x14000
	v_add_u32_e32 v142, s52, v231
	v_add_u32_e32 v158, s57, v231
	ds_read_b128 v[130:133], v142
	ds_read_b128 v[134:137], v142 offset:1024
	ds_read_b128 v[138:141], v142 offset:2048
	ds_read_b128 v[142:145], v142 offset:3072
	ds_read_b128 v[146:149], v158
	ds_read_b128 v[150:153], v158 offset:1024
	ds_read_b128 v[154:157], v158 offset:2048
	ds_read_b128 v[158:161], v158 offset:3072
	v_lshl_add_u64 v[206:207], s[20:21], 0, v[202:203]
	s_add_i32 m0, s29, 0xc000
	ds_read_b128 v[162:165], v232
	ds_read_b128 v[166:169], v232 offset:1024
	ds_read_b128 v[170:173], v232 offset:2048
	ds_read_b128 v[174:177], v232 offset:3072
	ds_read_b128 v[178:181], v232 offset:4096
	ds_read_b128 v[182:185], v232 offset:5120
	ds_read_b128 v[186:189], v232 offset:6144
	ds_read_b128 v[190:193], v232 offset:7168
	global_load_lds_dwordx4 v[206:207], off
	v_lshl_add_u64 v[206:207], s[20:21], 0, v[204:205]
	s_add_i32 m0, s29, 0xe000
	s_nop 0
	global_load_lds_dwordx4 v[206:207], off
	s_waitcnt vmcnt(8)
	s_waitcnt lgkmcnt(0)
	s_barrier
; #define PG8_STAGE(bufoff, gbase, voff) do { _Pragma("unroll") for (int _i = 0; _i < 2; ++_i) \
;         __builtin_amdgcn_global_load_lds((const unsigned*)((const char*)(gbase) + (voff)[_i]), (PG8_LAS unsigned*)(lds + (bufoff) + ldsw + _i * 8192), 16, 0, 0); } while (0)
; #define PG8_LDA(dst, b, h) do { _Pragma("unroll") for (int m = 0; m < 4; ++m) _Pragma("unroll") for (int k = 0; k < 2; ++k) dst[m][k] = *(const PG8_LAS bf16x8*)(lds + PG8_SA(b, h) + aoff + m * 2048 + k * 1024); } while (0)
; #define PG8_MMA(ai, bj, At, Bt) do { __builtin_amdgcn_s_setprio(1); _Pragma("unroll") for (int m = 0; m < 4; ++m) _Pragma("unroll") for (int n = 0; n < 2; ++n) _Pragma("unroll") for (int k = 0; k < 2; ++k) \
;         acc[ai][bj][m][n] = __builtin_amdgcn_mfma_f32_16x16x32_bf16(Bt[n][k], At[m][k], acc[ai][bj][m][n], 0, 0, 0); __builtin_amdgcn_s_setprio(0); } while (0)
; #define PG8_WAIT_V(n) asm volatile("s_waitcnt vmcnt(" #n ")" ::: "memory")
; #define PG8_WAIT_L(n) asm volatile("s_waitcnt lgkmcnt(" #n ")" ::: "memory")
; #define PG8_BAR __builtin_amdgcn_s_barrier()
; #define PG8_SCHED __builtin_amdgcn_sched_barrier(0)
; template <class Epi, class Sched, bool ALIGN_EPI = false, bool SP2 = false>
; __device__ __forceinline__ void gemm_phase(PG8_LAS unsigned char* lds, const Gemm g, const Sched& S, const Epi& E) {
;     ...
;             PG8_WAIT_V(8); PG8_WAIT_L(0); PG8_BAR; PG8_MMA(0, 0, At, B0); PG8_MMA(0, 1, At, B1); PG8_BAR; PG8_SCHED;
;             PG8_LDA(At, 0, 1); PG8_STAGE(PG8_SB(0, 0), b2, voffB); PG8_STAGE(PG8_SB(0, 1), b2 + hstep, voffB); PG8_STAGE(PG8_SA(0, 0), a2, voffA);
;             PG8_WAIT_V(8); PG8_WAIT_L(0); PG8_BAR; PG8_MMA(1, 0, At, B0); PG8_MMA(1, 1, At, B1); PG8_BAR; PG8_SCHED;
	s_setprio 1
	s_waitcnt lgkmcnt(0)
	v_mfma_f32_16x16x32_bf16 v[126:129], v[130:133], v[162:165], v[126:129]
	v_mfma_f32_16x16x32_bf16 v[122:125], v[138:141], v[162:165], v[122:125]
	v_mfma_f32_16x16x32_bf16 v[114:117], v[130:133], v[170:173], v[114:117]
	v_mfma_f32_16x16x32_bf16 v[106:109], v[138:141], v[170:173], v[106:109]
	v_mfma_f32_16x16x32_bf16 v[98:101], v[130:133], v[178:181], v[98:101]
	v_mfma_f32_16x16x32_bf16 v[90:93], v[138:141], v[178:181], v[90:93]
	v_mfma_f32_16x16x32_bf16 v[82:85], v[130:133], v[186:189], v[82:85]
	v_mfma_f32_16x16x32_bf16 v[74:77], v[138:141], v[186:189], v[74:77]
	v_mfma_f32_16x16x32_bf16 v[126:129], v[134:137], v[166:169], v[126:129]
	v_mfma_f32_16x16x32_bf16 v[122:125], v[142:145], v[166:169], v[122:125]
	v_mfma_f32_16x16x32_bf16 v[114:117], v[134:137], v[174:177], v[114:117]
	v_mfma_f32_16x16x32_bf16 v[106:109], v[142:145], v[174:177], v[106:109]
	v_mfma_f32_16x16x32_bf16 v[98:101], v[134:137], v[182:185], v[98:101]
	v_mfma_f32_16x16x32_bf16 v[90:93], v[142:145], v[182:185], v[90:93]
	v_mfma_f32_16x16x32_bf16 v[82:85], v[134:137], v[190:193], v[82:85]
	v_mfma_f32_16x16x32_bf16 v[74:77], v[142:145], v[190:193], v[74:77]
	s_setprio 0
	s_setprio 1
	v_mfma_f32_16x16x32_bf16 v[118:121], v[146:149], v[162:165], v[118:121]
	v_mfma_f32_16x16x32_bf16 v[110:113], v[154:157], v[162:165], v[110:113]
	v_mfma_f32_16x16x32_bf16 v[102:105], v[146:149], v[170:173], v[102:105]
	v_mfma_f32_16x16x32_bf16 v[94:97], v[154:157], v[170:173], v[94:97]
	v_mfma_f32_16x16x32_bf16 v[86:89], v[146:149], v[178:181], v[86:89]
	v_mfma_f32_16x16x32_bf16 v[78:81], v[154:157], v[178:181], v[78:81]
	v_mfma_f32_16x16x32_bf16 v[70:73], v[146:149], v[186:189], v[70:73]
	v_mfma_f32_16x16x32_bf16 v[66:69], v[154:157], v[186:189], v[66:69]
	v_mfma_f32_16x16x32_bf16 v[118:121], v[150:153], v[166:169], v[118:121]
	v_mfma_f32_16x16x32_bf16 v[110:113], v[158:161], v[166:169], v[110:113]
	v_mfma_f32_16x16x32_bf16 v[102:105], v[150:153], v[174:177], v[102:105]
	v_mfma_f32_16x16x32_bf16 v[94:97], v[158:161], v[174:177], v[94:97]
	v_mfma_f32_16x16x32_bf16 v[86:89], v[150:153], v[182:185], v[86:89]
	v_mfma_f32_16x16x32_bf16 v[78:81], v[158:161], v[182:185], v[78:81]
	v_mfma_f32_16x16x32_bf16 v[70:73], v[150:153], v[190:193], v[70:73]
	v_mfma_f32_16x16x32_bf16 v[66:69], v[158:161], v[190:193], v[66:69]
	s_setprio 0
	s_barrier
	s_add_i32 s52, s52, s28
	v_lshl_add_u64 v[206:207], s[16:17], 0, v[198:199]
	s_mov_b32 m0, s52
	ds_read_b128 v[162:165], v232 offset:16384
	ds_read_b128 v[166:169], v232 offset:17408
	ds_read_b128 v[170:173], v232 offset:18432
	ds_read_b128 v[174:177], v232 offset:19456
	ds_read_b128 v[178:181], v232 offset:20480
	ds_read_b128 v[182:185], v232 offset:21504
	ds_read_b128 v[186:189], v232 offset:22528
	ds_read_b128 v[190:193], v232 offset:23552
	global_load_lds_dwordx4 v[206:207], off
	s_add_i32 m0, s52, 0x2000
	s_add_u32 s52, s16, 0x40000
	v_lshl_add_u64 v[208:209], s[16:17], 0, v[194:195]
	s_addc_u32 s53, s17, 0
	s_add_i32 s57, s57, s28
	global_load_lds_dwordx4 v[208:209], off
	v_lshl_add_u64 v[210:211], s[52:53], 0, v[198:199]
	s_mov_b32 m0, s57
	v_lshl_add_u64 v[212:213], s[22:23], 0, v[196:197]
	global_load_lds_dwordx4 v[210:211], off
	v_lshl_add_u64 v[210:211], s[52:53], 0, v[194:195]
	s_add_i32 m0, s57, 0x2000
	s_nop 0
	global_load_lds_dwordx4 v[210:211], off
	v_lshl_add_u64 v[210:211], s[22:23], 0, v[200:201]
	s_mov_b32 m0, s29
	s_nop 0
	global_load_lds_dwordx4 v[210:211], off
	s_mov_b32 m0, s30
	s_nop 0
	global_load_lds_dwordx4 v[212:213], off
	s_waitcnt vmcnt(8)
	s_waitcnt lgkmcnt(0)
	s_barrier
	s_setprio 1
	s_waitcnt lgkmcnt(0)
	v_mfma_f32_16x16x32_bf16 v[62:65], v[130:133], v[162:165], v[62:65]
	v_mfma_f32_16x16x32_bf16 v[58:61], v[138:141], v[162:165], v[58:61]
	v_mfma_f32_16x16x32_bf16 v[50:53], v[130:133], v[170:173], v[50:53]
	v_mfma_f32_16x16x32_bf16 v[42:45], v[138:141], v[170:173], v[42:45]
	v_mfma_f32_16x16x32_bf16 v[34:37], v[130:133], v[178:181], v[34:37]
	v_mfma_f32_16x16x32_bf16 v[26:29], v[138:141], v[178:181], v[26:29]
	v_mfma_f32_16x16x32_bf16 v[18:21], v[130:133], v[186:189], v[18:21]
	v_mfma_f32_16x16x32_bf16 v[10:13], v[138:141], v[186:189], v[10:13]
	v_mfma_f32_16x16x32_bf16 v[62:65], v[134:137], v[166:169], v[62:65]
	v_mfma_f32_16x16x32_bf16 v[58:61], v[142:145], v[166:169], v[58:61]
	v_mfma_f32_16x16x32_bf16 v[50:53], v[134:137], v[174:177], v[50:53]
	v_mfma_f32_16x16x32_bf16 v[42:45], v[142:145], v[174:177], v[42:45]
	v_mfma_f32_16x16x32_bf16 v[34:37], v[134:137], v[182:185], v[34:37]
	v_mfma_f32_16x16x32_bf16 v[26:29], v[142:145], v[182:185], v[26:29]
	v_mfma_f32_16x16x32_bf16 v[18:21], v[134:137], v[190:193], v[18:21]
	v_mfma_f32_16x16x32_bf16 v[10:13], v[142:145], v[190:193], v[10:13]
	s_setprio 0
	s_setprio 1
	v_mfma_f32_16x16x32_bf16 v[54:57], v[146:149], v[162:165], v[54:57]
	v_mfma_f32_16x16x32_bf16 v[46:49], v[154:157], v[162:165], v[46:49]
	v_mfma_f32_16x16x32_bf16 v[38:41], v[146:149], v[170:173], v[38:41]
	v_mfma_f32_16x16x32_bf16 v[30:33], v[154:157], v[170:173], v[30:33]
	v_mfma_f32_16x16x32_bf16 v[22:25], v[146:149], v[178:181], v[22:25]
	v_mfma_f32_16x16x32_bf16 v[14:17], v[154:157], v[178:181], v[14:17]
	v_mfma_f32_16x16x32_bf16 v[6:9], v[146:149], v[186:189], v[6:9]
	v_mfma_f32_16x16x32_bf16 v[2:5], v[154:157], v[186:189], v[2:5]
	v_mfma_f32_16x16x32_bf16 v[54:57], v[150:153], v[166:169], v[54:57]
	v_mfma_f32_16x16x32_bf16 v[46:49], v[158:161], v[166:169], v[46:49]
	v_mfma_f32_16x16x32_bf16 v[38:41], v[150:153], v[174:177], v[38:41]
	v_mfma_f32_16x16x32_bf16 v[30:33], v[158:161], v[174:177], v[30:33]
	v_mfma_f32_16x16x32_bf16 v[22:25], v[150:153], v[182:185], v[22:25]
	v_mfma_f32_16x16x32_bf16 v[14:17], v[158:161], v[182:185], v[14:17]
	v_mfma_f32_16x16x32_bf16 v[6:9], v[150:153], v[190:193], v[6:9]
	v_mfma_f32_16x16x32_bf16 v[2:5], v[158:161], v[190:193], v[2:5]
	s_setprio 0
	s_barrier
; #define PG8_STAGE(bufoff, gbase, voff) do { _Pragma("unroll") for (int _i = 0; _i < 2; ++_i) \
;         __builtin_amdgcn_global_load_lds((const unsigned*)((const char*)(gbase) + (voff)[_i]), (PG8_LAS unsigned*)(lds + (bufoff) + ldsw + _i * 8192), 16, 0, 0); } while (0)
; #define PG8_LDA(dst, b, h) do { _Pragma("unroll") for (int m = 0; m < 4; ++m) _Pragma("unroll") for (int k = 0; k < 2; ++k) dst[m][k] = *(const PG8_LAS bf16x8*)(lds + PG8_SA(b, h) + aoff + m * 2048 + k * 1024); } while (0)
; #define PG8_LDB(dst, b, h) do { _Pragma("unroll") for (int n = 0; n < 2; ++n) _Pragma("unroll") for (int k = 0; k < 2; ++k) dst[n][k] = *(const PG8_LAS bf16x8*)(lds + PG8_SB(b, h) + boff + n * 2048 + k * 1024); } while (0)
; #define PG8_MMA(ai, bj, At, Bt) do { __builtin_amdgcn_s_setprio(1); _Pragma("unroll") for (int m = 0; m < 4; ++m) _Pragma("unroll") for (int n = 0; n < 2; ++n) _Pragma("unroll") for (int k = 0; k < 2; ++k) \
;         acc[ai][bj][m][n] = __builtin_amdgcn_mfma_f32_16x16x32_bf16(Bt[n][k], At[m][k], acc[ai][bj][m][n], 0, 0, 0); __builtin_amdgcn_s_setprio(0); } while (0)
; #define PG8_WAIT_V(n) asm volatile("s_waitcnt vmcnt(" #n ")" ::: "memory")
; #define PG8_WAIT_L(n) asm volatile("s_waitcnt lgkmcnt(" #n ")" ::: "memory")
; #define PG8_BAR __builtin_amdgcn_s_barrier()
; #define PG8_SCHED __builtin_amdgcn_sched_barrier(0)
; template <class Epi, class Sched, bool ALIGN_EPI = false, bool SP2 = false>
; __device__ __forceinline__ void gemm_phase(PG8_LAS unsigned char* lds, const Gemm g, const Sched& S, const Epi& E) {
;     ...
;             PG8_LDB(B0, 1, 0); PG8_LDB(B1, 1, 1); PG8_SCHED; PG8_LDA(At, 1, 0); PG8_STAGE(PG8_SA(0, 1), a2 + hstep, voffA);
;             PG8_WAIT_V(8); PG8_WAIT_L(0); PG8_BAR; PG8_MMA(0, 0, At, B0); PG8_MMA(0, 1, At, B1); PG8_BAR; PG8_SCHED;
;             PG8_LDA(At, 1, 1); PG8_STAGE(PG8_SB(1, 0), b3, voffB); PG8_STAGE(PG8_SB(1, 1), b3 + hstep, voffB); PG8_STAGE(PG8_SA(1, 0), a3, voffA);
	s_add_i32 s52, 0, 0x18000
	s_add_i32 s53, 0, 0x1c000
	v_add_u32_e32 v142, s52, v231
	v_add_u32_e32 v158, s53, v231
	ds_read_b128 v[130:133], v142
	ds_read_b128 v[134:137], v142 offset:1024
	ds_read_b128 v[138:141], v142 offset:2048
	ds_read_b128 v[142:145], v142 offset:3072
	ds_read_b128 v[146:149], v158
	ds_read_b128 v[150:153], v158 offset:1024
	ds_read_b128 v[154:157], v158 offset:2048
	ds_read_b128 v[158:161], v158 offset:3072
	s_add_u32 s22, s22, 0x40000
	s_addc_u32 s23, s23, 0
	s_mov_b32 m0, s31
	v_lshl_add_u64 v[214:215], s[22:23], 0, v[200:201]
	ds_read_b128 v[162:165], v232 offset:32768
	ds_read_b128 v[166:169], v232 offset:33792
	ds_read_b128 v[170:173], v232 offset:34816
	ds_read_b128 v[174:177], v232 offset:35840
	ds_read_b128 v[178:181], v232 offset:36864
	ds_read_b128 v[182:185], v232 offset:37888
	ds_read_b128 v[186:189], v232 offset:38912
	ds_read_b128 v[190:193], v232 offset:39936
	global_load_lds_dwordx4 v[214:215], off
	v_lshl_add_u64 v[214:215], s[22:23], 0, v[196:197]
	s_mov_b32 m0, s34
	s_nop 0
	global_load_lds_dwordx4 v[214:215], off
	s_waitcnt vmcnt(8)
	s_waitcnt lgkmcnt(0)
	s_barrier
	s_setprio 1
	s_waitcnt lgkmcnt(0)
	v_mfma_f32_16x16x32_bf16 v[126:129], v[130:133], v[162:165], v[126:129]
	v_mfma_f32_16x16x32_bf16 v[122:125], v[138:141], v[162:165], v[122:125]
	v_mfma_f32_16x16x32_bf16 v[114:117], v[130:133], v[170:173], v[114:117]
	v_mfma_f32_16x16x32_bf16 v[106:109], v[138:141], v[170:173], v[106:109]
	v_mfma_f32_16x16x32_bf16 v[98:101], v[130:133], v[178:181], v[98:101]
	v_mfma_f32_16x16x32_bf16 v[90:93], v[138:141], v[178:181], v[90:93]
	v_mfma_f32_16x16x32_bf16 v[82:85], v[130:133], v[186:189], v[82:85]
	v_mfma_f32_16x16x32_bf16 v[74:77], v[138:141], v[186:189], v[74:77]
	v_mfma_f32_16x16x32_bf16 v[126:129], v[134:137], v[166:169], v[126:129]
	v_mfma_f32_16x16x32_bf16 v[122:125], v[142:145], v[166:169], v[122:125]
	v_mfma_f32_16x16x32_bf16 v[114:117], v[134:137], v[174:177], v[114:117]
	v_mfma_f32_16x16x32_bf16 v[106:109], v[142:145], v[174:177], v[106:109]
	v_mfma_f32_16x16x32_bf16 v[98:101], v[134:137], v[182:185], v[98:101]
	v_mfma_f32_16x16x32_bf16 v[90:93], v[142:145], v[182:185], v[90:93]
	v_mfma_f32_16x16x32_bf16 v[82:85], v[134:137], v[190:193], v[82:85]
	v_mfma_f32_16x16x32_bf16 v[74:77], v[142:145], v[190:193], v[74:77]
	s_setprio 0
	s_setprio 1
	v_mfma_f32_16x16x32_bf16 v[118:121], v[146:149], v[162:165], v[118:121]
	v_mfma_f32_16x16x32_bf16 v[110:113], v[154:157], v[162:165], v[110:113]
	v_mfma_f32_16x16x32_bf16 v[102:105], v[146:149], v[170:173], v[102:105]
	v_mfma_f32_16x16x32_bf16 v[94:97], v[154:157], v[170:173], v[94:97]
	v_mfma_f32_16x16x32_bf16 v[86:89], v[146:149], v[178:181], v[86:89]
	v_mfma_f32_16x16x32_bf16 v[78:81], v[154:157], v[178:181], v[78:81]
	v_mfma_f32_16x16x32_bf16 v[70:73], v[146:149], v[186:189], v[70:73]
	v_mfma_f32_16x16x32_bf16 v[66:69], v[154:157], v[186:189], v[66:69]
	v_mfma_f32_16x16x32_bf16 v[118:121], v[150:153], v[166:169], v[118:121]
	v_mfma_f32_16x16x32_bf16 v[110:113], v[158:161], v[166:169], v[110:113]
	v_mfma_f32_16x16x32_bf16 v[102:105], v[150:153], v[174:177], v[102:105]
	v_mfma_f32_16x16x32_bf16 v[94:97], v[158:161], v[174:177], v[94:97]
	v_mfma_f32_16x16x32_bf16 v[86:89], v[150:153], v[182:185], v[86:89]
	v_mfma_f32_16x16x32_bf16 v[78:81], v[158:161], v[182:185], v[78:81]
	v_mfma_f32_16x16x32_bf16 v[70:73], v[150:153], v[190:193], v[70:73]
	v_mfma_f32_16x16x32_bf16 v[66:69], v[158:161], v[190:193], v[66:69]
	s_setprio 0
	s_barrier
	s_add_i32 s22, s52, s28
	v_lshl_add_u64 v[206:207], v[206:207], 0, s[94:95]
	s_mov_b32 m0, s22
	ds_read_b128 v[162:165], v232 offset:49152
	ds_read_b128 v[166:169], v232 offset:50176
	ds_read_b128 v[170:173], v232 offset:51200
	ds_read_b128 v[174:177], v232 offset:52224
	ds_read_b128 v[178:181], v232 offset:53248
	ds_read_b128 v[182:185], v232 offset:54272
	ds_read_b128 v[186:189], v232 offset:55296
	ds_read_b128 v[190:193], v232 offset:56320
	global_load_lds_dwordx4 v[206:207], off
	s_add_i32 m0, s22, 0x2000
	s_add_u32 s16, s16, 0x40080
	v_lshl_add_u64 v[206:207], v[208:209], 0, s[94:95]
	s_addc_u32 s17, s17, 0
	s_add_i32 s22, s53, s28
	global_load_lds_dwordx4 v[206:207], off
	v_lshl_add_u64 v[206:207], s[16:17], 0, v[198:199]
	s_mov_b32 m0, s22
	s_nop 0
	global_load_lds_dwordx4 v[206:207], off
	v_lshl_add_u64 v[206:207], s[16:17], 0, v[194:195]
	s_add_i32 m0, s22, 0x2000
	s_nop 0
	global_load_lds_dwordx4 v[206:207], off
	v_lshl_add_u64 v[206:207], v[210:211], 0, s[94:95]
	s_mov_b32 m0, s33
	s_nop 0
	global_load_lds_dwordx4 v[206:207], off
	v_lshl_add_u64 v[206:207], v[212:213], 0, s[94:95]
	s_mov_b32 m0, s35
	s_nop 0
	global_load_lds_dwordx4 v[206:207], off
	s_waitcnt vmcnt(8)
	s_waitcnt lgkmcnt(0)
	s_barrier
; #define PG8_STAGE(bufoff, gbase, voff) do { _Pragma("unroll") for (int _i = 0; _i < 2; ++_i) \
;         __builtin_amdgcn_global_load_lds((const unsigned*)((const char*)(gbase) + (voff)[_i]), (PG8_LAS unsigned*)(lds + (bufoff) + ldsw + _i * 8192), 16, 0, 0); } while (0)
;     __device__ __forceinline__ void operator()(const f32x4 (&acc)[2][2][4][2], const Unit& u, int wr, int wc, int fr, int fq) const {
;         u32x4 xo[2][4][2];
;         _Pragma("unroll") for (int ai = 0; ai < 2; ++ai) _Pragma("unroll") for (int m = 0; m < 4; ++m) _Pragma("unroll") for (int bj = 0; bj < 2; ++bj)
;             xo[ai][m][bj] = *(const u32x4*)(X + (size_t)EPI_ROW(ai, m) * 1024 + u.pn * BM + EPI_CT(bj));
; template <class Epi, class Sched, bool ALIGN_EPI = false, bool SP2 = false>
; __device__ __forceinline__ void gemm_phase(PG8_LAS unsigned char* lds, const Gemm g, const Sched& S, const Epi& E) {
;     ...
;             PG8_WAIT_V(8); PG8_WAIT_L(0); PG8_BAR; PG8_MMA(1, 0, At, B0); PG8_MMA(1, 1, At, B1); PG8_BAR; PG8_SCHED;
;             } else {
;             PG8_LDB(B0, 0, 0); PG8_SCHED; PG8_LDA(At, 0, 0); PG8_STAGE(PG8_SA(1, 1), a1 + hstep, voffA);
;             PG8_WAIT_L(8); PG8_BAR; PG8_WAIT_L(0); PG8_MMA(0, 0, At, B0); PG8_BAR; PG8_SCHED;
;             PG8_LDB(B1, 0, 1); PG8_STAGE(PG8_SB(0, 0), b2, voffB);
;             PG8_BAR; PG8_WAIT_L(0); PG8_MMA(0, 1, At, B1); PG8_BAR;
;             PG8_LDA(At, 0, 1); PG8_STAGE(PG8_SA(0, 0), a2, voffA);
;             PG8_BAR; PG8_WAIT_L(0); PG8_MMA(1, 0, At, B0); PG8_BAR; PG8_SCHED;
;             PG8_STAGE(PG8_SB(0, 1), b2 + hstep, voffB);
;             PG8_WAIT_V(6); PG8_BAR; PG8_MMA(1, 1, At, B1); PG8_BAR;
;             PG8_LDB(B0, 1, 0); PG8_SCHED; PG8_LDA(At, 1, 0); PG8_STAGE(PG8_SA(0, 1), a2 + hstep, voffA);
;             PG8_WAIT_L(8); PG8_BAR; PG8_WAIT_L(0); PG8_MMA(0, 0, At, B0); PG8_BAR; PG8_SCHED;
;             PG8_LDB(B1, 1, 1); PG8_STAGE(PG8_SB(1, 0), b3, voffB);
;             PG8_BAR; PG8_WAIT_L(0); PG8_MMA(0, 1, At, B1); PG8_BAR;
;             PG8_LDA(At, 1, 1); PG8_STAGE(PG8_SA(1, 0), a3, voffA);
;             PG8_BAR; PG8_WAIT_L(0); PG8_MMA(1, 0, At, B0); PG8_BAR; PG8_SCHED;
;             PG8_STAGE(PG8_SB(1, 1), b3 + hstep, voffB);
;             PG8_WAIT_V(6); PG8_BAR; PG8_MMA(1, 1, At, B1); PG8_BAR;
;             }
;         }
;         if constexpr (ALIGN_EPI) { if (wr == 0) PG8_BAR; }
	s_setprio 1
	s_waitcnt lgkmcnt(0)
	v_mfma_f32_16x16x32_bf16 v[62:65], v[130:133], v[162:165], v[62:65]
	v_mfma_f32_16x16x32_bf16 v[58:61], v[138:141], v[162:165], v[58:61]
	v_mfma_f32_16x16x32_bf16 v[50:53], v[130:133], v[170:173], v[50:53]
	v_mfma_f32_16x16x32_bf16 v[42:45], v[138:141], v[170:173], v[42:45]
	v_mfma_f32_16x16x32_bf16 v[34:37], v[130:133], v[178:181], v[34:37]
	v_mfma_f32_16x16x32_bf16 v[26:29], v[138:141], v[178:181], v[26:29]
	v_mfma_f32_16x16x32_bf16 v[18:21], v[130:133], v[186:189], v[18:21]
	v_mfma_f32_16x16x32_bf16 v[10:13], v[138:141], v[186:189], v[10:13]
	v_mfma_f32_16x16x32_bf16 v[62:65], v[134:137], v[166:169], v[62:65]
	v_mfma_f32_16x16x32_bf16 v[58:61], v[142:145], v[166:169], v[58:61]
	v_mfma_f32_16x16x32_bf16 v[50:53], v[134:137], v[174:177], v[50:53]
	v_mfma_f32_16x16x32_bf16 v[42:45], v[142:145], v[174:177], v[42:45]
	v_mfma_f32_16x16x32_bf16 v[34:37], v[134:137], v[182:185], v[34:37]
	v_mfma_f32_16x16x32_bf16 v[26:29], v[142:145], v[182:185], v[26:29]
	v_mfma_f32_16x16x32_bf16 v[18:21], v[134:137], v[190:193], v[18:21]
	v_mfma_f32_16x16x32_bf16 v[10:13], v[142:145], v[190:193], v[10:13]
	s_setprio 0
	s_setprio 1
	v_mfma_f32_16x16x32_bf16 v[54:57], v[146:149], v[162:165], v[54:57]
	v_mfma_f32_16x16x32_bf16 v[46:49], v[154:157], v[162:165], v[46:49]
	v_mfma_f32_16x16x32_bf16 v[38:41], v[146:149], v[170:173], v[38:41]
	v_mfma_f32_16x16x32_bf16 v[30:33], v[154:157], v[170:173], v[30:33]
	v_mfma_f32_16x16x32_bf16 v[22:25], v[146:149], v[178:181], v[22:25]
	v_mfma_f32_16x16x32_bf16 v[14:17], v[154:157], v[178:181], v[14:17]
	v_mfma_f32_16x16x32_bf16 v[6:9], v[146:149], v[186:189], v[6:9]
	v_mfma_f32_16x16x32_bf16 v[2:5], v[154:157], v[186:189], v[2:5]
	v_mfma_f32_16x16x32_bf16 v[54:57], v[150:153], v[166:169], v[54:57]
	v_mfma_f32_16x16x32_bf16 v[46:49], v[158:161], v[166:169], v[46:49]
	v_mfma_f32_16x16x32_bf16 v[38:41], v[150:153], v[174:177], v[38:41]
	v_mfma_f32_16x16x32_bf16 v[30:33], v[158:161], v[174:177], v[30:33]
	v_mfma_f32_16x16x32_bf16 v[22:25], v[150:153], v[182:185], v[22:25]
	v_mfma_f32_16x16x32_bf16 v[14:17], v[158:161], v[182:185], v[14:17]
	v_mfma_f32_16x16x32_bf16 v[6:9], v[150:153], v[190:193], v[6:9]
	v_mfma_f32_16x16x32_bf16 v[2:5], v[158:161], v[190:193], v[2:5]
	s_setprio 0
	s_barrier
	s_add_i32 s50, s50, 2
	s_add_u32 s20, s20, 0x100
	s_addc_u32 s21, s21, 0
	s_add_u32 s55, s55, 0x100
	s_addc_u32 s56, s56, 0
	s_cmp_gt_u32 s50, 13
	s_cbranch_scc0 .LBB0_697
	s_and_b64 vcc, exec, s[8:9]
	s_cbranch_vccz .LBB0_700
	s_barrier
.LBB0_700:
	s_lshl_b32 s16, s37, 8
	s_ashr_i32 s17, s16, 31
	v_lshl_add_u32 v134, s38, 8, v230
	s_lshl_b64 s[20:21], s[16:17], 1
	s_add_u32 s16, s6, s20
	v_ashrrev_i32_e32 v135, 31, v134
	s_addc_u32 s17, s7, s21
	v_lshlrev_b64 v[228:229], 11, v[134:135]
	v_lshl_add_u64 v[130:131], s[16:17], 0, v[228:229]
	v_lshl_add_u64 v[130:131], v[130:131], 0, v[0:1]
	global_load_dwordx4 v[190:193], v[130:131], off
	global_load_dwordx4 v[186:189], v[130:131], off offset:256
	v_or_b32_e32 v130, 16, v134
	v_ashrrev_i32_e32 v131, 31, v130
	v_lshlrev_b64 v[226:227], 11, v[130:131]
	v_lshl_add_u64 v[130:131], s[16:17], 0, v[226:227]
	v_lshl_add_u64 v[130:131], v[130:131], 0, v[0:1]
	global_load_dwordx4 v[182:185], v[130:131], off
	global_load_dwordx4 v[178:181], v[130:131], off offset:256
	v_or_b32_e32 v130, 32, v134
	v_ashrrev_i32_e32 v131, 31, v130
	v_lshlrev_b64 v[224:225], 11, v[130:131]
	v_lshl_add_u64 v[130:131], s[16:17], 0, v[224:225]
	v_lshl_add_u64 v[130:131], v[130:131], 0, v[0:1]
	global_load_dwordx4 v[174:177], v[130:131], off
	global_load_dwordx4 v[166:169], v[130:131], off offset:256
	v_or_b32_e32 v130, 48, v134
	v_ashrrev_i32_e32 v131, 31, v130
	v_lshlrev_b64 v[222:223], 11, v[130:131]
	v_lshl_add_u64 v[130:131], s[16:17], 0, v[222:223]
	v_lshl_add_u64 v[130:131], v[130:131], 0, v[0:1]
	global_load_dwordx4 v[170:173], v[130:131], off
	global_load_dwordx4 v[162:165], v[130:131], off offset:256
	v_add_u32_e32 v130, 0x80, v134
	v_ashrrev_i32_e32 v131, 31, v130
	v_lshlrev_b64 v[220:221], 11, v[130:131]
	v_lshl_add_u64 v[130:131], s[16:17], 0, v[220:221]
	v_lshl_add_u64 v[130:131], v[130:131], 0, v[0:1]
	global_load_dwordx4 v[158:161], v[130:131], off
	global_load_dwordx4 v[154:157], v[130:131], off offset:256
	v_add_u32_e32 v130, 0x90, v134
	v_ashrrev_i32_e32 v131, 31, v130
	v_lshlrev_b64 v[210:211], 11, v[130:131]
	v_lshl_add_u64 v[130:131], s[16:17], 0, v[210:211]
	v_lshl_add_u64 v[130:131], v[130:131], 0, v[0:1]
	global_load_dwordx4 v[150:153], v[130:131], off
	global_load_dwordx4 v[142:145], v[130:131], off offset:256
	v_add_u32_e32 v130, 0xa0, v134
	v_ashrrev_i32_e32 v131, 31, v130
	v_lshlrev_b64 v[206:207], 11, v[130:131]
	v_lshl_add_u64 v[130:131], s[16:17], 0, v[206:207]
	v_lshl_add_u64 v[130:131], v[130:131], 0, v[0:1]
	global_load_dwordx4 v[138:141], v[130:131], off
	s_nop 0
	global_load_dwordx4 v[130:133], v[130:131], off offset:256
	v_add_u32_e32 v134, 0xb0, v134
	v_ashrrev_i32_e32 v135, 31, v134
	v_lshlrev_b64 v[208:209], 11, v[134:135]
	v_lshl_add_u64 v[134:135], s[16:17], 0, v[208:209]
	v_lshl_add_u64 v[134:135], v[134:135], 0, v[0:1]
	global_load_dwordx4 v[146:149], v[134:135], off
	s_nop 0
	global_load_dwordx4 v[134:137], v[134:135], off offset:256
	s_mov_b64 s[16:17], -1
	s_andn2_b64 vcc, exec, s[4:5]
	s_waitcnt vmcnt(0)
; __device__ __forceinline__ u32x4 pack8(const f32x4 v0, const f32x4 v1) { u32x4 w; w.x = cvt_pk_bf16(v0[0], v0[1]); w.y = cvt_pk_bf16(v0[2], v0[3]); w.z = cvt_pk_bf16(v1[0], v1[1]); w.w = cvt_pk_bf16(v1[2], v1[3]); return w; }
; __device__ __forceinline__ float bf_lo(unsigned w) { return __uint_as_float(w << 16); }
; __device__ __forceinline__ float bf_hi(unsigned w) { return __uint_as_float(w & 0xffff0000u); }
;     __device__ __forceinline__ void operator()(const f32x4 (&acc)[2][2][4][2], const Unit& u, int wr, int wc, int fr, int fq) const {
;     ...
;         _Pragma("unroll") for (int ai = 0; ai < 2; ++ai) _Pragma("unroll") for (int m = 0; m < 4; ++m) _Pragma("unroll") for (int bj = 0; bj < 2; ++bj) {
;             f32x4 v0 = acc[ai][bj][m][0], v1 = acc[ai][bj][m][1]; const u32x4 o = xo[ai][m][bj];
;             v0[0] += bf_lo(o.x); v0[1] += bf_hi(o.x); v0[2] += bf_lo(o.y); v0[3] += bf_hi(o.y); v1[0] += bf_lo(o.z); v1[1] += bf_hi(o.z); v1[2] += bf_lo(o.w); v1[3] += bf_hi(o.w);
;             *(u32x4*)(X + (size_t)EPI_ROW(ai, m) * 1024 + u.pn * BM + EPI_CT(bj)) = pack8(v0, v1); }
	v_lshlrev_b32_e32 v212, 16, v190
	v_and_b32_e32 v213, 0xffff0000, v190
	v_lshlrev_b32_e32 v190, 16, v191
	v_and_b32_e32 v191, 0xffff0000, v191
	v_pk_add_f32 v[128:129], v[128:129], v[190:191]
	v_lshlrev_b32_e32 v190, 16, v192
	v_and_b32_e32 v191, 0xffff0000, v192
	v_pk_add_f32 v[126:127], v[126:127], v[212:213]
	v_pk_add_f32 v[190:191], v[122:123], v[190:191]
	v_lshlrev_b32_e32 v122, 16, v193
	v_and_b32_e32 v123, 0xffff0000, v193
	v_pk_add_f32 v[192:193], v[124:125], v[122:123]
	v_cvt_pk_bf16_f32 v122, v126, v127
	v_lshl_add_u64 v[126:127], s[6:7], 0, v[228:229]
	v_lshl_add_u64 v[126:127], v[126:127], 0, s[20:21]
	v_cvt_pk_bf16_f32 v123, v128, v129
	v_cvt_pk_bf16_f32 v124, v190, v191
	v_cvt_pk_bf16_f32 v125, v192, v193
	v_lshl_add_u64 v[126:127], v[126:127], 0, v[0:1]
	global_store_dwordx4 v[126:127], v[122:125], off
	s_nop 1
	v_lshlrev_b32_e32 v122, 16, v186
	v_and_b32_e32 v123, 0xffff0000, v186
	v_pk_add_f32 v[118:119], v[118:119], v[122:123]
	v_lshlrev_b32_e32 v122, 16, v187
	v_and_b32_e32 v123, 0xffff0000, v187
	v_pk_add_f32 v[120:121], v[120:121], v[122:123]
	v_lshlrev_b32_e32 v122, 16, v188
	v_and_b32_e32 v123, 0xffff0000, v188
	v_pk_add_f32 v[122:123], v[110:111], v[122:123]
	v_lshlrev_b32_e32 v110, 16, v189
	v_and_b32_e32 v111, 0xffff0000, v189
	v_pk_add_f32 v[124:125], v[112:113], v[110:111]
	v_cvt_pk_bf16_f32 v110, v118, v119
	v_cvt_pk_bf16_f32 v111, v120, v121
	v_cvt_pk_bf16_f32 v112, v122, v123
	v_cvt_pk_bf16_f32 v113, v124, v125
	global_store_dwordx4 v[126:127], v[110:113], off offset:256
	s_nop 1
	v_lshlrev_b32_e32 v110, 16, v182
	v_and_b32_e32 v111, 0xffff0000, v182
	v_pk_add_f32 v[110:111], v[114:115], v[110:111]
	v_lshlrev_b32_e32 v114, 16, v184
	v_and_b32_e32 v115, 0xffff0000, v184
	v_lshlrev_b32_e32 v112, 16, v183
	v_and_b32_e32 v113, 0xffff0000, v183
	v_pk_add_f32 v[114:115], v[106:107], v[114:115]
	v_lshlrev_b32_e32 v106, 16, v185
	v_and_b32_e32 v107, 0xffff0000, v185
	v_pk_add_f32 v[112:113], v[116:117], v[112:113]
	v_pk_add_f32 v[116:117], v[108:109], v[106:107]
	v_cvt_pk_bf16_f32 v106, v110, v111
	v_lshl_add_u64 v[110:111], s[6:7], 0, v[226:227]
	v_lshl_add_u64 v[110:111], v[110:111], 0, s[20:21]
	v_cvt_pk_bf16_f32 v107, v112, v113
	v_cvt_pk_bf16_f32 v108, v114, v115
	v_cvt_pk_bf16_f32 v109, v116, v117
	v_lshl_add_u64 v[110:111], v[110:111], 0, v[0:1]
	global_store_dwordx4 v[110:111], v[106:109], off
	s_nop 1
	v_lshlrev_b32_e32 v106, 16, v178
	v_and_b32_e32 v107, 0xffff0000, v178
	v_pk_add_f32 v[102:103], v[102:103], v[106:107]
	v_lshlrev_b32_e32 v106, 16, v179
	v_and_b32_e32 v107, 0xffff0000, v179
	v_pk_add_f32 v[104:105], v[104:105], v[106:107]
	v_lshlrev_b32_e32 v106, 16, v180
	v_and_b32_e32 v107, 0xffff0000, v180
	v_pk_add_f32 v[106:107], v[94:95], v[106:107]
	v_lshlrev_b32_e32 v94, 16, v181
	v_and_b32_e32 v95, 0xffff0000, v181
	v_pk_add_f32 v[108:109], v[96:97], v[94:95]
	v_cvt_pk_bf16_f32 v94, v102, v103
	v_cvt_pk_bf16_f32 v95, v104, v105
	v_cvt_pk_bf16_f32 v96, v106, v107
	v_cvt_pk_bf16_f32 v97, v108, v109
	global_store_dwordx4 v[110:111], v[94:97], off offset:256
	s_nop 1
	v_lshlrev_b32_e32 v94, 16, v174
	v_and_b32_e32 v95, 0xffff0000, v174
	v_pk_add_f32 v[94:95], v[98:99], v[94:95]
	v_lshlrev_b32_e32 v98, 16, v176
	v_and_b32_e32 v99, 0xffff0000, v176
	v_lshlrev_b32_e32 v96, 16, v175
	v_and_b32_e32 v97, 0xffff0000, v175
	v_pk_add_f32 v[98:99], v[90:91], v[98:99]
	v_lshlrev_b32_e32 v90, 16, v177
	v_and_b32_e32 v91, 0xffff0000, v177
	v_pk_add_f32 v[96:97], v[100:101], v[96:97]
	v_pk_add_f32 v[100:101], v[92:93], v[90:91]
	v_cvt_pk_bf16_f32 v90, v94, v95
	v_lshl_add_u64 v[94:95], s[6:7], 0, v[224:225]
	v_lshl_add_u64 v[94:95], v[94:95], 0, s[20:21]
	v_cvt_pk_bf16_f32 v91, v96, v97
	v_cvt_pk_bf16_f32 v92, v98, v99
	v_cvt_pk_bf16_f32 v93, v100, v101
	v_lshl_add_u64 v[94:95], v[94:95], 0, v[0:1]
	global_store_dwordx4 v[94:95], v[90:93], off
	s_nop 1
	v_lshlrev_b32_e32 v90, 16, v166
	v_and_b32_e32 v91, 0xffff0000, v166
	v_pk_add_f32 v[86:87], v[86:87], v[90:91]
	v_lshlrev_b32_e32 v90, 16, v167
	v_and_b32_e32 v91, 0xffff0000, v167
	v_pk_add_f32 v[88:89], v[88:89], v[90:91]
	v_lshlrev_b32_e32 v90, 16, v168
	v_and_b32_e32 v91, 0xffff0000, v168
	v_pk_add_f32 v[90:91], v[78:79], v[90:91]
	v_lshlrev_b32_e32 v78, 16, v169
	v_and_b32_e32 v79, 0xffff0000, v169
	v_pk_add_f32 v[92:93], v[80:81], v[78:79]
	v_cvt_pk_bf16_f32 v78, v86, v87
	v_cvt_pk_bf16_f32 v79, v88, v89
	v_cvt_pk_bf16_f32 v80, v90, v91
	v_cvt_pk_bf16_f32 v81, v92, v93
	global_store_dwordx4 v[94:95], v[78:81], off offset:256
	s_nop 1
	v_lshlrev_b32_e32 v78, 16, v170
	v_and_b32_e32 v79, 0xffff0000, v170
	v_pk_add_f32 v[78:79], v[82:83], v[78:79]
	v_lshlrev_b32_e32 v82, 16, v172
	v_and_b32_e32 v83, 0xffff0000, v172
	v_lshlrev_b32_e32 v80, 16, v171
	v_and_b32_e32 v81, 0xffff0000, v171
	v_pk_add_f32 v[82:83], v[74:75], v[82:83]
	v_lshlrev_b32_e32 v74, 16, v173
	v_and_b32_e32 v75, 0xffff0000, v173
	v_pk_add_f32 v[80:81], v[84:85], v[80:81]
	v_pk_add_f32 v[84:85], v[76:77], v[74:75]
	v_cvt_pk_bf16_f32 v74, v78, v79
	v_lshl_add_u64 v[78:79], s[6:7], 0, v[222:223]
	v_lshl_add_u64 v[78:79], v[78:79], 0, s[20:21]
	v_cvt_pk_bf16_f32 v75, v80, v81
	v_cvt_pk_bf16_f32 v76, v82, v83
	v_cvt_pk_bf16_f32 v77, v84, v85
	v_lshl_add_u64 v[78:79], v[78:79], 0, v[0:1]
	global_store_dwordx4 v[78:79], v[74:77], off
	s_nop 1
	v_lshlrev_b32_e32 v74, 16, v162
	v_and_b32_e32 v75, 0xffff0000, v162
	v_pk_add_f32 v[70:71], v[70:71], v[74:75]
	v_lshlrev_b32_e32 v74, 16, v163
	v_and_b32_e32 v75, 0xffff0000, v163
	v_pk_add_f32 v[72:73], v[72:73], v[74:75]
	v_lshlrev_b32_e32 v74, 16, v164
	v_and_b32_e32 v75, 0xffff0000, v164
	v_pk_add_f32 v[74:75], v[66:67], v[74:75]
	v_lshlrev_b32_e32 v66, 16, v165
; __device__ __forceinline__ u32x4 pack8(const f32x4 v0, const f32x4 v1) { u32x4 w; w.x = cvt_pk_bf16(v0[0], v0[1]); w.y = cvt_pk_bf16(v0[2], v0[3]); w.z = cvt_pk_bf16(v1[0], v1[1]); w.w = cvt_pk_bf16(v1[2], v1[3]); return w; }
; __device__ __forceinline__ float bf_lo(unsigned w) { return __uint_as_float(w << 16); }
; __device__ __forceinline__ float bf_hi(unsigned w) { return __uint_as_float(w & 0xffff0000u); }
; #define PG8_BAR __builtin_amdgcn_s_barrier()
;     __device__ __forceinline__ void operator()(const f32x4 (&acc)[2][2][4][2], const Unit& u, int wr, int wc, int fr, int fq) const {
;     ...
;         _Pragma("unroll") for (int ai = 0; ai < 2; ++ai) _Pragma("unroll") for (int m = 0; m < 4; ++m) _Pragma("unroll") for (int bj = 0; bj < 2; ++bj) {
;             f32x4 v0 = acc[ai][bj][m][0], v1 = acc[ai][bj][m][1]; const u32x4 o = xo[ai][m][bj];
;             v0[0] += bf_lo(o.x); v0[1] += bf_hi(o.x); v0[2] += bf_lo(o.y); v0[3] += bf_hi(o.y); v1[0] += bf_lo(o.z); v1[1] += bf_hi(o.z); v1[2] += bf_lo(o.w); v1[3] += bf_hi(o.w);
;             *(u32x4*)(X + (size_t)EPI_ROW(ai, m) * 1024 + u.pn * BM + EPI_CT(bj)) = pack8(v0, v1); }
; template <class Epi, class Sched, bool ALIGN_EPI = false, bool SP2 = false>
; __device__ __forceinline__ void gemm_phase(PG8_LAS unsigned char* lds, const Gemm g, const Sched& S, const Epi& E) {
;     ...
;         if (!has_next) break;
; #pragma unroll
;         for (int a = 0; a < 2; ++a)
; #pragma unroll
;             for (int b = 0; b < 2; ++b)
; #pragma unroll
;                 for (int m = 0; m < 4; ++m)
; #pragma unroll
;                     for (int n = 0; n < 2; ++n) acc[a][b][m][n] = (f32x4){0.f, 0.f, 0.f, 0.f};
;         cur = nxt; cA = nA; cB = nB; ++ui;
;         if constexpr (ALIGN_EPI) { if (wr == 1) PG8_BAR; }
;     }
	v_and_b32_e32 v67, 0xffff0000, v165
	v_pk_add_f32 v[76:77], v[68:69], v[66:67]
	v_cvt_pk_bf16_f32 v66, v70, v71
	v_cvt_pk_bf16_f32 v67, v72, v73
	v_cvt_pk_bf16_f32 v68, v74, v75
	v_cvt_pk_bf16_f32 v69, v76, v77
	global_store_dwordx4 v[78:79], v[66:69], off offset:256
	s_nop 1
	v_lshlrev_b32_e32 v66, 16, v158
	v_and_b32_e32 v67, 0xffff0000, v158
	v_pk_add_f32 v[62:63], v[62:63], v[66:67]
	v_lshlrev_b32_e32 v66, 16, v159
	v_and_b32_e32 v67, 0xffff0000, v159
	v_pk_add_f32 v[64:65], v[64:65], v[66:67]
	v_lshlrev_b32_e32 v66, 16, v160
	v_and_b32_e32 v67, 0xffff0000, v160
	v_pk_add_f32 v[66:67], v[58:59], v[66:67]
	v_lshlrev_b32_e32 v58, 16, v161
	v_and_b32_e32 v59, 0xffff0000, v161
	v_pk_add_f32 v[68:69], v[60:61], v[58:59]
	v_cvt_pk_bf16_f32 v58, v62, v63
	v_lshl_add_u64 v[62:63], s[6:7], 0, v[220:221]
	v_lshl_add_u64 v[62:63], v[62:63], 0, s[20:21]
	v_cvt_pk_bf16_f32 v59, v64, v65
	v_cvt_pk_bf16_f32 v60, v66, v67
	v_cvt_pk_bf16_f32 v61, v68, v69
	v_lshl_add_u64 v[62:63], v[62:63], 0, v[0:1]
	global_store_dwordx4 v[62:63], v[58:61], off
	s_nop 1
	v_lshlrev_b32_e32 v58, 16, v154
	v_and_b32_e32 v59, 0xffff0000, v154
	v_pk_add_f32 v[54:55], v[54:55], v[58:59]
	v_lshlrev_b32_e32 v58, 16, v155
	v_and_b32_e32 v59, 0xffff0000, v155
	v_pk_add_f32 v[56:57], v[56:57], v[58:59]
	v_lshlrev_b32_e32 v58, 16, v156
	v_and_b32_e32 v59, 0xffff0000, v156
	v_pk_add_f32 v[58:59], v[46:47], v[58:59]
	v_lshlrev_b32_e32 v46, 16, v157
	v_and_b32_e32 v47, 0xffff0000, v157
	v_pk_add_f32 v[60:61], v[48:49], v[46:47]
	v_cvt_pk_bf16_f32 v46, v54, v55
	v_cvt_pk_bf16_f32 v47, v56, v57
	v_cvt_pk_bf16_f32 v48, v58, v59
	v_cvt_pk_bf16_f32 v49, v60, v61
	global_store_dwordx4 v[62:63], v[46:49], off offset:256
	s_nop 1
	v_lshlrev_b32_e32 v46, 16, v150
	v_and_b32_e32 v47, 0xffff0000, v150
	v_pk_add_f32 v[46:47], v[50:51], v[46:47]
	v_lshlrev_b32_e32 v50, 16, v152
	v_and_b32_e32 v51, 0xffff0000, v152
	v_lshlrev_b32_e32 v48, 16, v151
	v_and_b32_e32 v49, 0xffff0000, v151
	v_pk_add_f32 v[50:51], v[42:43], v[50:51]
	v_lshlrev_b32_e32 v42, 16, v153
	v_and_b32_e32 v43, 0xffff0000, v153
	v_pk_add_f32 v[48:49], v[52:53], v[48:49]
	v_pk_add_f32 v[52:53], v[44:45], v[42:43]
	v_cvt_pk_bf16_f32 v42, v46, v47
	v_lshl_add_u64 v[46:47], s[6:7], 0, v[210:211]
	v_lshl_add_u64 v[46:47], v[46:47], 0, s[20:21]
	v_cvt_pk_bf16_f32 v43, v48, v49
	v_cvt_pk_bf16_f32 v44, v50, v51
	v_cvt_pk_bf16_f32 v45, v52, v53
	v_lshl_add_u64 v[46:47], v[46:47], 0, v[0:1]
	global_store_dwordx4 v[46:47], v[42:45], off
	s_nop 1
	v_lshlrev_b32_e32 v42, 16, v142
	v_and_b32_e32 v43, 0xffff0000, v142
	v_pk_add_f32 v[38:39], v[38:39], v[42:43]
	v_lshlrev_b32_e32 v42, 16, v143
	v_and_b32_e32 v43, 0xffff0000, v143
	v_pk_add_f32 v[40:41], v[40:41], v[42:43]
	v_lshlrev_b32_e32 v42, 16, v144
	v_and_b32_e32 v43, 0xffff0000, v144
	v_pk_add_f32 v[42:43], v[30:31], v[42:43]
	v_lshlrev_b32_e32 v30, 16, v145
	v_and_b32_e32 v31, 0xffff0000, v145
	v_pk_add_f32 v[44:45], v[32:33], v[30:31]
	v_cvt_pk_bf16_f32 v30, v38, v39
	v_cvt_pk_bf16_f32 v31, v40, v41
	v_cvt_pk_bf16_f32 v32, v42, v43
	v_cvt_pk_bf16_f32 v33, v44, v45
	global_store_dwordx4 v[46:47], v[30:33], off offset:256
	s_nop 1
	v_lshlrev_b32_e32 v30, 16, v138
	v_and_b32_e32 v31, 0xffff0000, v138
	v_pk_add_f32 v[30:31], v[34:35], v[30:31]
	v_lshlrev_b32_e32 v34, 16, v140
	v_and_b32_e32 v35, 0xffff0000, v140
	v_lshlrev_b32_e32 v32, 16, v139
	v_and_b32_e32 v33, 0xffff0000, v139
	v_pk_add_f32 v[34:35], v[26:27], v[34:35]
	v_lshlrev_b32_e32 v26, 16, v141
	v_and_b32_e32 v27, 0xffff0000, v141
	v_pk_add_f32 v[32:33], v[36:37], v[32:33]
	v_pk_add_f32 v[36:37], v[28:29], v[26:27]
	v_cvt_pk_bf16_f32 v26, v30, v31
	v_lshl_add_u64 v[30:31], s[6:7], 0, v[206:207]
	v_lshl_add_u64 v[30:31], v[30:31], 0, s[20:21]
	v_cvt_pk_bf16_f32 v27, v32, v33
	v_cvt_pk_bf16_f32 v28, v34, v35
	v_cvt_pk_bf16_f32 v29, v36, v37
	v_lshl_add_u64 v[30:31], v[30:31], 0, v[0:1]
	global_store_dwordx4 v[30:31], v[26:29], off
	s_nop 1
	v_lshlrev_b32_e32 v26, 16, v130
	v_and_b32_e32 v27, 0xffff0000, v130
	v_pk_add_f32 v[22:23], v[22:23], v[26:27]
	v_lshlrev_b32_e32 v26, 16, v131
	v_and_b32_e32 v27, 0xffff0000, v131
	v_pk_add_f32 v[24:25], v[24:25], v[26:27]
	v_lshlrev_b32_e32 v26, 16, v132
	v_and_b32_e32 v27, 0xffff0000, v132
	v_pk_add_f32 v[26:27], v[14:15], v[26:27]
	v_lshlrev_b32_e32 v14, 16, v133
	v_and_b32_e32 v15, 0xffff0000, v133
	v_pk_add_f32 v[28:29], v[16:17], v[14:15]
	v_cvt_pk_bf16_f32 v14, v22, v23
	v_cvt_pk_bf16_f32 v15, v24, v25
	v_cvt_pk_bf16_f32 v16, v26, v27
	v_cvt_pk_bf16_f32 v17, v28, v29
	global_store_dwordx4 v[30:31], v[14:17], off offset:256
	s_nop 1
	v_lshlrev_b32_e32 v14, 16, v146
	v_and_b32_e32 v15, 0xffff0000, v146
	v_pk_add_f32 v[14:15], v[18:19], v[14:15]
	v_lshlrev_b32_e32 v18, 16, v148
	v_and_b32_e32 v19, 0xffff0000, v148
	v_lshlrev_b32_e32 v16, 16, v147
	v_and_b32_e32 v17, 0xffff0000, v147
	v_pk_add_f32 v[18:19], v[10:11], v[18:19]
	v_lshlrev_b32_e32 v10, 16, v149
	v_and_b32_e32 v11, 0xffff0000, v149
	v_pk_add_f32 v[16:17], v[20:21], v[16:17]
	v_pk_add_f32 v[20:21], v[12:13], v[10:11]
	v_cvt_pk_bf16_f32 v10, v14, v15
	v_lshl_add_u64 v[14:15], s[6:7], 0, v[208:209]
	v_lshl_add_u64 v[14:15], v[14:15], 0, s[20:21]
	v_cvt_pk_bf16_f32 v11, v16, v17
	v_cvt_pk_bf16_f32 v12, v18, v19
	v_cvt_pk_bf16_f32 v13, v20, v21
	v_lshl_add_u64 v[14:15], v[14:15], 0, v[0:1]
	global_store_dwordx4 v[14:15], v[10:13], off
	s_nop 1
	v_lshlrev_b32_e32 v10, 16, v134
	v_and_b32_e32 v11, 0xffff0000, v134
	v_pk_add_f32 v[6:7], v[6:7], v[10:11]
	v_lshlrev_b32_e32 v10, 16, v135
	v_and_b32_e32 v11, 0xffff0000, v135
	v_pk_add_f32 v[8:9], v[8:9], v[10:11]
	v_lshlrev_b32_e32 v10, 16, v136
	v_and_b32_e32 v11, 0xffff0000, v136
	v_pk_add_f32 v[10:11], v[2:3], v[10:11]
	v_lshlrev_b32_e32 v2, 16, v137
	v_and_b32_e32 v3, 0xffff0000, v137
	v_pk_add_f32 v[12:13], v[4:5], v[2:3]
	v_cvt_pk_bf16_f32 v2, v6, v7
	v_cvt_pk_bf16_f32 v3, v8, v9
	v_cvt_pk_bf16_f32 v4, v10, v11
	v_cvt_pk_bf16_f32 v5, v12, v13
	global_store_dwordx4 v[14:15], v[2:5], off offset:256
	s_cbranch_vccnz .LBB0_689
	s_andn2_b64 vcc, exec, s[0:1]
	s_cbranch_vccnz .LBB0_688
	s_branch .LBB0_688

;     __device__ __forceinline__ bool next(int i, Unit& u) const { const int L = i * G + c; if (L >= 512) return false; u.pm = L; u.pn = L >> 4; return true; }
; #define PG8_WAIT_V(n) asm volatile("s_waitcnt vmcnt(" #n ")" ::: "memory")
; #define PG8_BAR __builtin_amdgcn_s_barrier()
; template <class Epi, class Sched, bool ALIGN_EPI = false, bool SP2 = false>
; __device__ __forceinline__ void gemm_phase(PG8_LAS unsigned char* lds, const Gemm g, const Sched& S, const Epi& E) {
;     int tid_ = threadIdx.x; asm volatile("" : "+v"(tid_));
;     const int tid = tid_, wid = __builtin_amdgcn_readfirstlane(tid >> 6), lane = tid & 63, wr = wid >> 2, wc = wid & 3, fr = lane & 15, fq = lane >> 4;
;     const int K = g.K, nt = K / BK, LD = g.ld ? g.ld : g.K;
;     unsigned voffA[2], voffB[2];
; #pragma unroll
;     for (int i = 0; i < 2; ++i) { int R, C; stage_rc(tid * 16 + i * 8192, R, C); const int Rb = Epi::PERM ? ((R & ~31) + perm32(R & 31)) : R;
;         voffA[i] = (unsigned)(R * LD + C) * 2u; voffB[i] = (unsigned)(Rb * LD + C) * 2u; }
;     const size_t kstep = (size_t)(BK * 2);
;     const size_t hstep = (size_t)HALF * LD * 2;
;     const size_t tstep = 2 * hstep;
;     const unsigned ldsw = (unsigned)wid * 1024u;
;     const int aoff = lds_byte(wr * 64 + fr, fq * 8), boff = lds_byte(wc * 32 + fr, fq * 8);
;     ...
;     Unit cur, nxt; int ui = 0;
;     if (!S.next(0, cur)) return;
;     f32x4 acc[2][2][4][2];
; #pragma unroll
;     for (int a = 0; a < 2; ++a)
; #pragma unroll
;         for (int b = 0; b < 2; ++b)
; #pragma unroll
;             for (int m = 0; m < 4; ++m)
; #pragma unroll
;                 for (int n = 0; n < 2; ++n) acc[a][b][m][n] = (f32x4){0.f, 0.f, 0.f, 0.f};
;     bf16x8 At[4][2], B0[2][2], B1[2][2];
;     const char* cA = (const char*)g.A + (size_t)cur.pm * tstep; const char* cB = (const char*)g.Bt + (size_t)cur.pn * tstep;
;     S.a_ready(cur);
;     if constexpr (SP2) {
;         PG8_STAGE(PG8_SB(0, 0), cB, voffB); PG8_STAGE(PG8_SB(0, 1), cB + hstep, voffB); PG8_STAGE(PG8_SA(0, 0), cA, voffA); PG8_STAGE(PG8_SA(0, 1), cA + hstep, voffA);
;         if (wr == 1) PG8_BAR;
;         PG8_WAIT_V(2); PG8_BAR;
;         PG8_STAGE(PG8_SB(1, 0), cB + kstep, voffB); PG8_STAGE(PG8_SA(1, 0), cA + kstep, voffA); PG8_STAGE(PG8_SB(1, 1), cB + hstep + kstep, voffB);
;         PG8_WAIT_V(6); PG8_BAR;
.LBB0_803:
	s_or_b64 exec, exec, s[36:37]
	s_mov_b64 s[4:5], s[72:73]
	v_mov_b32_e32 v15, v242
	s_waitcnt lgkmcnt(0)
	s_barrier
	s_and_b64 vcc, exec, s[58:59]
	v_readfirstlane_b32 s8, v15
	s_cbranch_vccz .LBB0_823
	v_lshlrev_b32_e32 v2, 4, v15
	v_add_u32_e32 v3, 0x2000, v2
	v_ashrrev_i32_e32 v0, 31, v3
	v_lshrrev_b32_e32 v0, 22, v0
	v_add_u32_e32 v0, v3, v0
	v_ashrrev_i32_e32 v0, 10, v0
	v_mul_i32_i24_e32 v4, 0x400, v0
	v_sub_u32_e32 v3, v3, v4
	v_lshrrev_b32_e32 v4, 4, v3
	v_bitop3_b32 v3, v4, v3, 32 bitop3:0x6c
	v_ashrrev_i32_e32 v4, 31, v3
	v_lshrrev_b32_e32 v4, 26, v4
	v_add_u32_e32 v4, v3, v4
	v_lshlrev_b32_e32 v5, 3, v0
	v_ashrrev_i32_e32 v10, 6, v4
	v_and_b32_e32 v5, -16, v5
	v_add_u32_e32 v5, v10, v5
	v_and_b32_e32 v6, 3, v10
	s_mov_b32 s0, 0x1fffe0
	v_lshrrev_b32_e32 v7, 2, v5
	v_lshlrev_b32_e32 v8, 1, v5
	v_and_b32_e32 v4, 0xc0, v4
	v_and_or_b32 v6, v5, s0, v6
	v_and_b32_e32 v7, 4, v7
	v_and_b32_e32 v8, 24, v8
	v_sub_u32_e32 v3, v3, v4
	v_or3_b32 v6, v6, v7, v8
	v_lshlrev_b32_e32 v7, 5, v0
	v_ashrrev_i16_sdwa v3, v241, sext(v3) dst_sel:DWORD dst_unused:UNUSED_PAD src0_sel:DWORD src1_sel:BYTE_0
	v_and_b32_e32 v7, 32, v7
	v_bfe_i32 v11, v3, 0, 16
	v_add_lshl_u32 v3, v7, v11, 1
	v_lshl_add_u32 v130, v6, 11, v3
	v_lshl_add_u32 v132, v5, 11, v3
	v_bfe_i32 v3, v15, 27, 1
	v_lshrrev_b32_e32 v3, 22, v3
	v_add_u32_e32 v3, v2, v3
	v_and_b32_e32 v3, 0xfffffc00, v3
	v_sub_u32_e32 v2, v2, v3
	v_lshrrev_b32_e32 v3, 4, v2
	v_ashrrev_i32_e32 v4, 31, v15
	v_bitop3_b32 v2, v3, v2, 32 bitop3:0x6c
	v_lshrrev_b32_e32 v4, 26, v4
	v_ashrrev_i32_e32 v3, 31, v2
	v_add_u32_e32 v4, v15, v4
	v_lshrrev_b32_e32 v3, 26, v3
	v_ashrrev_i32_e32 v13, 6, v4
	v_add_u32_e32 v3, v2, v3
	v_lshlrev_b32_e32 v4, 3, v13
	s_add_u32 s24, s4, 0x5400000
	v_ashrrev_i32_e32 v12, 6, v3
	v_and_b32_e32 v4, -16, v4
	s_addc_u32 s25, s5, 0
	v_add_u32_e32 v4, v12, v4
	s_add_u32 s26, s4, 0x900000
	v_and_b32_e32 v5, 3, v12
	v_lshrrev_b32_e32 v6, 2, v4
	v_lshlrev_b32_e32 v7, 1, v4
	v_and_b32_e32 v3, 0xc0, v3
	s_addc_u32 s27, s5, 0
	s_ashr_i32 s9, s8, 6
	v_and_or_b32 v5, v4, s0, v5
	v_and_b32_e32 v6, 4, v6
	v_and_b32_e32 v7, 24, v7
	v_sub_u32_e32 v2, v2, v3
	s_ashr_i32 s10, s8, 8
	s_lshl_b32 s28, s9, 10
	v_or3_b32 v5, v5, v6, v7
	v_lshlrev_b32_e32 v6, 5, v13
	v_ashrrev_i16_sdwa v2, v241, sext(v2) dst_sel:DWORD dst_unused:UNUSED_PAD src0_sel:DWORD src1_sel:BYTE_0
	v_readlane_b32 s0, v255, 0
	v_and_b32_e32 v6, 32, v6
	v_bfe_i32 v14, v2, 0, 16
	v_readlane_b32 s1, v255, 1
	s_add_u32 s16, s26, s0
	v_add_lshl_u32 v2, v6, v14, 1
	s_addc_u32 s17, s27, s1
	s_add_i32 s29, s28, 0
	v_lshl_add_u32 v134, v5, 11, v2
	s_add_i32 m0, s29, 0x10000
	v_lshl_add_u32 v136, v4, 11, v2
	global_load_lds_dwordx4 v134, s[16:17]
	s_add_i32 m0, s29, 0x12000
	s_add_u32 s0, s16, 0x40000
	global_load_lds_dwordx4 v130, s[16:17]
	s_addc_u32 s1, s17, 0
	s_add_i32 m0, s29, 0x14000
	v_mov_b32_e32 v135, v1
	global_load_lds_dwordx4 v134, s[0:1]
	s_add_i32 m0, s29, 0x16000
	v_mov_b32_e32 v131, v1
	global_load_lds_dwordx4 v130, s[0:1]
	v_readlane_b32 s0, v254, 62
	v_readlane_b32 s1, v254, 63
	s_add_u32 s20, s24, s0
	s_addc_u32 s21, s25, s1
	s_add_i32 s30, s29, 0x2000
	s_mov_b32 m0, s29
	s_add_u32 s0, s20, 0x40000
	global_load_lds_dwordx4 v136, s[20:21]
	s_mov_b32 m0, s30
	s_addc_u32 s1, s21, 0
	s_add_i32 s31, s29, 0x4000
	global_load_lds_dwordx4 v132, s[20:21]
	s_mov_b32 m0, s31
	s_add_i32 s33, s29, 0x6000
	global_load_lds_dwordx4 v136, s[0:1]
	s_mov_b32 m0, s33
	v_mov_b32_e32 v137, v1
	global_load_lds_dwordx4 v132, s[0:1]
	v_mov_b32_e32 v133, v1
	s_cmp_eq_u32 s10, 1
	v_lshl_add_u64 v[8:9], s[16:17], 0, v[134:135]
	v_lshl_add_u64 v[6:7], s[16:17], 0, v[130:131]
	v_lshl_add_u64 v[2:3], s[20:21], 0, v[136:137]
	s_cselect_b64 s[0:1], -1, 0
	s_cmp_lg_u32 s10, 1
	v_lshl_add_u64 v[4:5], s[20:21], 0, v[132:133]
	s_cbranch_scc1 .LBB0_806
.LBB0_806:
	v_lshrrev_b32_e32 v17, 1, v15
	v_and_b32_e32 v17, 24, v17
	s_add_u32 s6, s4, 0xd400000
	v_and_b32_e32 v16, 15, v15
	v_lshlrev_b32_e32 v18, 1, v17
	v_lshlrev_b32_e32 v15, 2, v15
	s_addc_u32 s7, s5, 0
	v_lshl_or_b32 v144, s10, 6, v16
	v_lshl_or_b32 v16, v16, 6, v18
	s_lshl_b32 s4, s10, 13
	v_and_b32_e32 v15, 32, v15
	v_bitop3_b32 v18, v16, s4, v15 bitop3:0xde
	s_lshl_b32 s4, s9, 5
	s_and_b32 s10, s4, 0x60
	s_add_i32 m0, s29, 0x18000
	v_lshl_add_u64 v[8:9], v[8:9], 0, s[94:95]
	s_lshl_b32 s4, s10, 7
	s_waitcnt vmcnt(2)
	s_barrier
	global_load_lds_dwordx4 v[8:9], off
	v_lshl_add_u64 v[6:7], v[6:7], 0, s[94:95]
	s_add_i32 m0, s29, 0x1a000
	s_add_i32 s34, s29, 0x8000
	s_add_i32 s35, s29, 0xa000
	v_bitop3_b32 v145, v16, s4, v15 bitop3:0xde
	global_load_lds_dwordx4 v[6:7], off
	v_lshl_add_u64 v[2:3], v[2:3], 0, s[94:95]
	s_mov_b32 m0, s34
	s_add_u32 s4, s16, 0x40080
	global_load_lds_dwordx4 v[2:3], off
	v_lshl_add_u64 v[2:3], v[4:5], 0, s[94:95]
	s_mov_b32 m0, s35
	s_addc_u32 s5, s17, 0
	global_load_lds_dwordx4 v[2:3], off
	s_add_i32 m0, s29, 0x1c000
	v_lshl_add_u64 v[2:3], s[4:5], 0, v[134:135]
	global_load_lds_dwordx4 v[2:3], off
	v_lshl_add_u64 v[2:3], s[4:5], 0, v[130:131]
	s_add_i32 m0, s29, 0x1e000
	v_and_b32_e32 v4, 1, v13
	global_load_lds_dwordx4 v[2:3], off
	v_lshlrev_b32_e32 v3, 14, v13
	v_and_b32_e32 v3, 0xffff8000, v3
	v_lshl_add_u32 v3, v12, 11, v3
	v_lshl_or_b32 v3, v4, 6, v3
	v_lshl_add_u32 v138, v14, 1, v3
	v_lshlrev_b32_e32 v3, 14, v0
	v_and_b32_e32 v3, 0xffff8000, v3
	s_waitcnt vmcnt(6)
	v_lshl_add_u32 v3, v10, 11, v3
	v_and_b32_e32 v0, 1, v0
	s_cmpk_lt_u32 s8, 0x100
	v_or_b32_e32 v2, s10, v17
	v_lshl_or_b32 v0, v0, 6, v3
	v_readlane_b32 s4, v254, 60
	s_cselect_b64 s[8:9], -1, 0
	v_mov_b32_e32 v139, v1
	v_lshl_add_u32 v140, v11, 1, v0
	v_mov_b32_e32 v141, v1
	s_mov_b32 s36, 0
	v_add_u32_e32 v146, 0, v18
	v_lshlrev_b32_e32 v0, 1, v2
	v_readlane_b32 s37, v254, 59
	s_mov_b32 s38, s4
	s_barrier
	v_readlane_b32 s5, v254, 61
	s_branch .LBB0_809

;     __device__ __forceinline__ bool next(int i, Unit& u) const { const int L = i * G + c; if (L >= 512) return false; u.pm = L; u.pn = L >> 4; return true; }
; #define PG8_STAGE(bufoff, gbase, voff) do { _Pragma("unroll") for (int _i = 0; _i < 2; ++_i) \
;         __builtin_amdgcn_global_load_lds((const unsigned*)((const char*)(gbase) + (voff)[_i]), (PG8_LAS unsigned*)(lds + (bufoff) + ldsw + _i * 8192), 16, 0, 0); } while (0)
; #define PG8_LDA(dst, b, h) do { _Pragma("unroll") for (int m = 0; m < 4; ++m) _Pragma("unroll") for (int k = 0; k < 2; ++k) dst[m][k] = *(const PG8_LAS bf16x8*)(lds + PG8_SA(b, h) + aoff + m * 2048 + k * 1024); } while (0)
; #define PG8_LDB(dst, b, h) do { _Pragma("unroll") for (int n = 0; n < 2; ++n) _Pragma("unroll") for (int k = 0; k < 2; ++k) dst[n][k] = *(const PG8_LAS bf16x8*)(lds + PG8_SB(b, h) + boff + n * 2048 + k * 1024); } while (0)
; #define PG8_WAIT_V(n) asm volatile("s_waitcnt vmcnt(" #n ")" ::: "memory")
; template <class Epi, class Sched, bool ALIGN_EPI = false, bool SP2 = false>
; __device__ __forceinline__ void gemm_phase(PG8_LAS unsigned char* lds, const Gemm g, const Sched& S, const Epi& E) {
;     ...
;         const bool has_next = S.next(ui + 1, nxt);
;         const char* nA = has_next ? (const char*)g.A + (size_t)nxt.pm * tstep : cA; const char* nB = has_next ? (const char*)g.Bt + (size_t)nxt.pn * tstep : cB;
;         for (int t = 0; t < nt; t += 2) {
;             const bool last = (t == nt - 2);
;             const char* a1 = cA + (size_t)(t + 1) * kstep;
;             const char* a2 = last ? nA : cA + (size_t)(t + 2) * kstep; const char* b2 = last ? nB : cB + (size_t)(t + 2) * kstep;
;             const char* a3 = a2 + kstep; const char* b3 = b2 + kstep;
;             if (last && has_next) S.a_ready(nxt);
;             if constexpr (SP2) {
;             PG8_LDB(B0, 0, 0); PG8_LDB(B1, 0, 1); PG8_SCHED; PG8_LDA(At, 0, 0); PG8_STAGE(PG8_SA(1, 1), a1 + hstep, voffA);
;             PG8_WAIT_V(8); PG8_WAIT_L(0); PG8_BAR; PG8_MMA(0, 0, At, B0); PG8_MMA(0, 1, At, B1); PG8_BAR; PG8_SCHED;
;     ...
;         for (int a = 0; a < 2; ++a)
; #pragma unroll
;             for (int b = 0; b < 2; ++b)
; #pragma unroll
;                 for (int m = 0; m < 4; ++m)
; #pragma unroll
;                     for (int n = 0; n < 2; ++n) acc[a][b][m][n] = (f32x4){0.f, 0.f, 0.f, 0.f};
;         cur = nxt; cA = nA; cB = nB; ++ui;
.LBB0_815:
	s_ashr_i32 s13, s12, 31
	s_lshl_b64 s[14:15], s[12:13], 19
	s_add_u32 s14, s24, s14
	s_addc_u32 s15, s25, s15
	s_and_b64 s[18:19], s[4:5], exec
	s_cselect_b32 s13, s15, s21
	s_cselect_b32 s39, s14, s20
	s_ashr_i32 s11, s10, 31
	s_lshl_b64 s[18:19], s[10:11], 19
	s_add_u32 s18, s26, s18
	s_addc_u32 s19, s27, s19
	s_and_b64 s[22:23], s[4:5], exec
	s_cselect_b32 s11, s19, s17
	s_cselect_b32 s46, s18, s16
	s_add_u32 s20, s20, 0x40080
	s_addc_u32 s21, s21, 0
	s_add_u32 s55, s16, 0x100
	v_mov_b32_e32 v2, 0
	s_addc_u32 s56, s17, 0
	s_mov_b32 s50, -2
	v_mov_b32_e32 v3, v2
	v_mov_b32_e32 v4, v2
	v_mov_b32_e32 v5, v2
	v_mov_b32_e32 v6, v2
	v_mov_b32_e32 v7, v2
	v_mov_b32_e32 v8, v2
	v_mov_b32_e32 v9, v2
	v_mov_b32_e32 v18, v2
	v_mov_b32_e32 v19, v2
	v_mov_b32_e32 v20, v2
	v_mov_b32_e32 v21, v2
	v_mov_b32_e32 v22, v2
	v_mov_b32_e32 v23, v2
	v_mov_b32_e32 v24, v2
	v_mov_b32_e32 v25, v2
	v_mov_b32_e32 v34, v2
	v_mov_b32_e32 v35, v2
	v_mov_b32_e32 v36, v2
	v_mov_b32_e32 v37, v2
	v_mov_b32_e32 v38, v2
	v_mov_b32_e32 v39, v2
	v_mov_b32_e32 v40, v2
	v_mov_b32_e32 v41, v2
	v_mov_b32_e32 v50, v2
	v_mov_b32_e32 v51, v2
	v_mov_b32_e32 v52, v2
	v_mov_b32_e32 v53, v2
	v_mov_b32_e32 v54, v2
	v_mov_b32_e32 v55, v2
	v_mov_b32_e32 v56, v2
	v_mov_b32_e32 v57, v2
	v_mov_b32_e32 v10, v2
	v_mov_b32_e32 v11, v2
	v_mov_b32_e32 v12, v2
	v_mov_b32_e32 v13, v2
	v_mov_b32_e32 v14, v2
	v_mov_b32_e32 v15, v2
	v_mov_b32_e32 v16, v2
	v_mov_b32_e32 v17, v2
	v_mov_b32_e32 v26, v2
	v_mov_b32_e32 v27, v2
	v_mov_b32_e32 v28, v2
	v_mov_b32_e32 v29, v2
	v_mov_b32_e32 v30, v2
	v_mov_b32_e32 v31, v2
	v_mov_b32_e32 v32, v2
	v_mov_b32_e32 v33, v2
	v_mov_b32_e32 v42, v2
	v_mov_b32_e32 v43, v2
	v_mov_b32_e32 v44, v2
	v_mov_b32_e32 v45, v2
	v_mov_b32_e32 v46, v2
	v_mov_b32_e32 v47, v2
	v_mov_b32_e32 v48, v2
	v_mov_b32_e32 v49, v2
	v_mov_b32_e32 v58, v2
	v_mov_b32_e32 v59, v2
	v_mov_b32_e32 v60, v2
	v_mov_b32_e32 v61, v2
	v_mov_b32_e32 v62, v2
	v_mov_b32_e32 v63, v2
	v_mov_b32_e32 v64, v2
	v_mov_b32_e32 v65, v2
	v_mov_b32_e32 v66, v2
	v_mov_b32_e32 v67, v2
	v_mov_b32_e32 v68, v2
	v_mov_b32_e32 v69, v2
	v_mov_b32_e32 v70, v2
	v_mov_b32_e32 v71, v2
	v_mov_b32_e32 v72, v2
	v_mov_b32_e32 v73, v2
	v_mov_b32_e32 v82, v2
	v_mov_b32_e32 v83, v2
	v_mov_b32_e32 v84, v2
	v_mov_b32_e32 v85, v2
	v_mov_b32_e32 v86, v2
	v_mov_b32_e32 v87, v2
	v_mov_b32_e32 v88, v2
	v_mov_b32_e32 v89, v2
	v_mov_b32_e32 v98, v2
	v_mov_b32_e32 v99, v2
	v_mov_b32_e32 v100, v2
	v_mov_b32_e32 v101, v2
	v_mov_b32_e32 v102, v2
	v_mov_b32_e32 v103, v2
	v_mov_b32_e32 v104, v2
	v_mov_b32_e32 v105, v2
	v_mov_b32_e32 v114, v2
	v_mov_b32_e32 v115, v2
	v_mov_b32_e32 v116, v2
	v_mov_b32_e32 v117, v2
	v_mov_b32_e32 v118, v2
	v_mov_b32_e32 v119, v2
	v_mov_b32_e32 v120, v2
	v_mov_b32_e32 v121, v2
	v_mov_b32_e32 v74, v2
	v_mov_b32_e32 v75, v2
	v_mov_b32_e32 v76, v2
	v_mov_b32_e32 v77, v2
	v_mov_b32_e32 v78, v2
	v_mov_b32_e32 v79, v2
	v_mov_b32_e32 v80, v2
	v_mov_b32_e32 v81, v2
	v_mov_b32_e32 v90, v2
	v_mov_b32_e32 v91, v2
	v_mov_b32_e32 v92, v2
	v_mov_b32_e32 v93, v2
	v_mov_b32_e32 v94, v2
	v_mov_b32_e32 v95, v2
	v_mov_b32_e32 v96, v2
	v_mov_b32_e32 v97, v2
	v_mov_b32_e32 v106, v2
	v_mov_b32_e32 v107, v2
	v_mov_b32_e32 v108, v2
	v_mov_b32_e32 v109, v2
	v_mov_b32_e32 v110, v2
	v_mov_b32_e32 v111, v2
	v_mov_b32_e32 v112, v2
	v_mov_b32_e32 v113, v2
	v_mov_b32_e32 v122, v2
	v_mov_b32_e32 v123, v2
	v_mov_b32_e32 v124, v2
	v_mov_b32_e32 v125, v2
	v_mov_b32_e32 v126, v2
	v_mov_b32_e32 v127, v2
	v_mov_b32_e32 v128, v2
	v_mov_b32_e32 v129, v2
	s_cmp_eq_u64 s[0:1], 0
	s_cbranch_scc1 .Lboff_skip_K
	s_barrier
.Lboff_skip_K:
.LBB0_816:
	s_add_u32 s16, s20, 0xfffc0080
	s_addc_u32 s17, s21, -1
	s_add_i32 s52, 0, 0x10000
	s_cmp_eq_u32 s50, 12
	s_cselect_b32 s23, s13, s17
	s_cselect_b32 s22, s39, s16
	v_add_u32_e32 v142, s52, v145
	s_cselect_b32 s17, s11, s56
	s_cselect_b32 s16, s46, s55
	s_add_i32 s57, 0, 0x14000
	ds_read_b128 v[148:151], v142
	ds_read_b128 v[152:155], v142 offset:1024
	ds_read_b128 v[156:159], v142 offset:2048
	ds_read_b128 v[160:163], v142 offset:3072
	v_add_u32_e32 v142, s57, v145
	ds_read_b128 v[164:167], v142
	ds_read_b128 v[168:171], v142 offset:1024
	ds_read_b128 v[172:175], v142 offset:2048
	ds_read_b128 v[176:179], v142 offset:3072
	v_lshl_add_u64 v[142:143], s[20:21], 0, v[138:139]
	s_add_i32 m0, s29, 0xc000
	ds_read_b128 v[180:183], v146
	ds_read_b128 v[184:187], v146 offset:1024
	ds_read_b128 v[188:191], v146 offset:2048
	ds_read_b128 v[192:195], v146 offset:3072
	ds_read_b128 v[196:199], v146 offset:4096
	ds_read_b128 v[200:203], v146 offset:5120
	ds_read_b128 v[204:207], v146 offset:6144
	ds_read_b128 v[208:211], v146 offset:7168
	global_load_lds_dwordx4 v[142:143], off
	v_lshl_add_u64 v[142:143], s[20:21], 0, v[140:141]
	s_add_i32 m0, s29, 0xe000
	s_nop 0
	global_load_lds_dwordx4 v[142:143], off
	s_waitcnt vmcnt(8)
	s_waitcnt lgkmcnt(0)
	s_barrier
; #define PG8_STAGE(bufoff, gbase, voff) do { _Pragma("unroll") for (int _i = 0; _i < 2; ++_i) \
;         __builtin_amdgcn_global_load_lds((const unsigned*)((const char*)(gbase) + (voff)[_i]), (PG8_LAS unsigned*)(lds + (bufoff) + ldsw + _i * 8192), 16, 0, 0); } while (0)
; #define PG8_LDA(dst, b, h) do { _Pragma("unroll") for (int m = 0; m < 4; ++m) _Pragma("unroll") for (int k = 0; k < 2; ++k) dst[m][k] = *(const PG8_LAS bf16x8*)(lds + PG8_SA(b, h) + aoff + m * 2048 + k * 1024); } while (0)
; #define PG8_MMA(ai, bj, At, Bt) do { __builtin_amdgcn_s_setprio(1); _Pragma("unroll") for (int m = 0; m < 4; ++m) _Pragma("unroll") for (int n = 0; n < 2; ++n) _Pragma("unroll") for (int k = 0; k < 2; ++k) \
;         acc[ai][bj][m][n] = __builtin_amdgcn_mfma_f32_16x16x32_bf16(Bt[n][k], At[m][k], acc[ai][bj][m][n], 0, 0, 0); __builtin_amdgcn_s_setprio(0); } while (0)
; #define PG8_WAIT_V(n) asm volatile("s_waitcnt vmcnt(" #n ")" ::: "memory")
; #define PG8_WAIT_L(n) asm volatile("s_waitcnt lgkmcnt(" #n ")" ::: "memory")
; #define PG8_BAR __builtin_amdgcn_s_barrier()
; #define PG8_SCHED __builtin_amdgcn_sched_barrier(0)
; template <class Epi, class Sched, bool ALIGN_EPI = false, bool SP2 = false>
; __device__ __forceinline__ void gemm_phase(PG8_LAS unsigned char* lds, const Gemm g, const Sched& S, const Epi& E) {
;     ...
;             PG8_WAIT_V(8); PG8_WAIT_L(0); PG8_BAR; PG8_MMA(0, 0, At, B0); PG8_MMA(0, 1, At, B1); PG8_BAR; PG8_SCHED;
;             PG8_LDA(At, 0, 1); PG8_STAGE(PG8_SB(0, 0), b2, voffB); PG8_STAGE(PG8_SB(0, 1), b2 + hstep, voffB); PG8_STAGE(PG8_SA(0, 0), a2, voffA);
;             PG8_WAIT_V(8); PG8_WAIT_L(0); PG8_BAR; PG8_MMA(1, 0, At, B0); PG8_MMA(1, 1, At, B1); PG8_BAR; PG8_SCHED;
	s_setprio 1
	s_waitcnt lgkmcnt(0)
	v_mfma_f32_16x16x32_bf16 v[126:129], v[148:151], v[180:183], v[126:129]
	v_mfma_f32_16x16x32_bf16 v[122:125], v[156:159], v[180:183], v[122:125]
	v_mfma_f32_16x16x32_bf16 v[110:113], v[148:151], v[188:191], v[110:113]
	v_mfma_f32_16x16x32_bf16 v[106:109], v[156:159], v[188:191], v[106:109]
	v_mfma_f32_16x16x32_bf16 v[94:97], v[148:151], v[196:199], v[94:97]
	v_mfma_f32_16x16x32_bf16 v[90:93], v[156:159], v[196:199], v[90:93]
	v_mfma_f32_16x16x32_bf16 v[78:81], v[148:151], v[204:207], v[78:81]
	v_mfma_f32_16x16x32_bf16 v[74:77], v[156:159], v[204:207], v[74:77]
	v_mfma_f32_16x16x32_bf16 v[126:129], v[152:155], v[184:187], v[126:129]
	v_mfma_f32_16x16x32_bf16 v[122:125], v[160:163], v[184:187], v[122:125]
	v_mfma_f32_16x16x32_bf16 v[110:113], v[152:155], v[192:195], v[110:113]
	v_mfma_f32_16x16x32_bf16 v[106:109], v[160:163], v[192:195], v[106:109]
	v_mfma_f32_16x16x32_bf16 v[94:97], v[152:155], v[200:203], v[94:97]
	v_mfma_f32_16x16x32_bf16 v[90:93], v[160:163], v[200:203], v[90:93]
	v_mfma_f32_16x16x32_bf16 v[78:81], v[152:155], v[208:211], v[78:81]
	v_mfma_f32_16x16x32_bf16 v[74:77], v[160:163], v[208:211], v[74:77]
	s_setprio 0
	s_setprio 1
	v_mfma_f32_16x16x32_bf16 v[118:121], v[164:167], v[180:183], v[118:121]
	v_mfma_f32_16x16x32_bf16 v[114:117], v[172:175], v[180:183], v[114:117]
	v_mfma_f32_16x16x32_bf16 v[102:105], v[164:167], v[188:191], v[102:105]
	v_mfma_f32_16x16x32_bf16 v[98:101], v[172:175], v[188:191], v[98:101]
	v_mfma_f32_16x16x32_bf16 v[86:89], v[164:167], v[196:199], v[86:89]
	v_mfma_f32_16x16x32_bf16 v[82:85], v[172:175], v[196:199], v[82:85]
	v_mfma_f32_16x16x32_bf16 v[70:73], v[164:167], v[204:207], v[70:73]
	v_mfma_f32_16x16x32_bf16 v[66:69], v[172:175], v[204:207], v[66:69]
	v_mfma_f32_16x16x32_bf16 v[118:121], v[168:171], v[184:187], v[118:121]
	v_mfma_f32_16x16x32_bf16 v[114:117], v[176:179], v[184:187], v[114:117]
	v_mfma_f32_16x16x32_bf16 v[102:105], v[168:171], v[192:195], v[102:105]
	v_mfma_f32_16x16x32_bf16 v[98:101], v[176:179], v[192:195], v[98:101]
	v_mfma_f32_16x16x32_bf16 v[86:89], v[168:171], v[200:203], v[86:89]
	v_mfma_f32_16x16x32_bf16 v[82:85], v[176:179], v[200:203], v[82:85]
	v_mfma_f32_16x16x32_bf16 v[70:73], v[168:171], v[208:211], v[70:73]
	v_mfma_f32_16x16x32_bf16 v[66:69], v[176:179], v[208:211], v[66:69]
	s_setprio 0
	s_barrier
	s_add_i32 s52, s52, s28
	v_lshl_add_u64 v[142:143], s[16:17], 0, v[134:135]
	s_mov_b32 m0, s52
	ds_read_b128 v[180:183], v146 offset:16384
	ds_read_b128 v[184:187], v146 offset:17408
	ds_read_b128 v[188:191], v146 offset:18432
	ds_read_b128 v[192:195], v146 offset:19456
	ds_read_b128 v[196:199], v146 offset:20480
	ds_read_b128 v[200:203], v146 offset:21504
	ds_read_b128 v[204:207], v146 offset:22528
	ds_read_b128 v[208:211], v146 offset:23552
	global_load_lds_dwordx4 v[142:143], off
	s_add_i32 m0, s52, 0x2000
	s_add_u32 s52, s16, 0x40000
	v_lshl_add_u64 v[212:213], s[16:17], 0, v[130:131]
	s_addc_u32 s53, s17, 0
	s_add_i32 s57, s57, s28
	global_load_lds_dwordx4 v[212:213], off
	v_lshl_add_u64 v[214:215], s[52:53], 0, v[134:135]
	s_mov_b32 m0, s57
	v_lshl_add_u64 v[216:217], s[22:23], 0, v[132:133]
	global_load_lds_dwordx4 v[214:215], off
	v_lshl_add_u64 v[214:215], s[52:53], 0, v[130:131]
	s_add_i32 m0, s57, 0x2000
	s_nop 0
	global_load_lds_dwordx4 v[214:215], off
	v_lshl_add_u64 v[214:215], s[22:23], 0, v[136:137]
	s_mov_b32 m0, s29
	s_nop 0
	global_load_lds_dwordx4 v[214:215], off
	s_mov_b32 m0, s30
	s_nop 0
	global_load_lds_dwordx4 v[216:217], off
	s_waitcnt vmcnt(8)
	s_waitcnt lgkmcnt(0)
	s_barrier
	s_setprio 1
	s_waitcnt lgkmcnt(0)
	v_mfma_f32_16x16x32_bf16 v[62:65], v[148:151], v[180:183], v[62:65]
	v_mfma_f32_16x16x32_bf16 v[58:61], v[156:159], v[180:183], v[58:61]
	v_mfma_f32_16x16x32_bf16 v[46:49], v[148:151], v[188:191], v[46:49]
	v_mfma_f32_16x16x32_bf16 v[42:45], v[156:159], v[188:191], v[42:45]
	v_mfma_f32_16x16x32_bf16 v[30:33], v[148:151], v[196:199], v[30:33]
	v_mfma_f32_16x16x32_bf16 v[26:29], v[156:159], v[196:199], v[26:29]
	v_mfma_f32_16x16x32_bf16 v[14:17], v[148:151], v[204:207], v[14:17]
	v_mfma_f32_16x16x32_bf16 v[10:13], v[156:159], v[204:207], v[10:13]
	v_mfma_f32_16x16x32_bf16 v[62:65], v[152:155], v[184:187], v[62:65]
	v_mfma_f32_16x16x32_bf16 v[58:61], v[160:163], v[184:187], v[58:61]
	v_mfma_f32_16x16x32_bf16 v[46:49], v[152:155], v[192:195], v[46:49]
	v_mfma_f32_16x16x32_bf16 v[42:45], v[160:163], v[192:195], v[42:45]
	v_mfma_f32_16x16x32_bf16 v[30:33], v[152:155], v[200:203], v[30:33]
	v_mfma_f32_16x16x32_bf16 v[26:29], v[160:163], v[200:203], v[26:29]
	v_mfma_f32_16x16x32_bf16 v[14:17], v[152:155], v[208:211], v[14:17]
	v_mfma_f32_16x16x32_bf16 v[10:13], v[160:163], v[208:211], v[10:13]
	s_setprio 0
	s_setprio 1
	v_mfma_f32_16x16x32_bf16 v[54:57], v[164:167], v[180:183], v[54:57]
	v_mfma_f32_16x16x32_bf16 v[50:53], v[172:175], v[180:183], v[50:53]
	v_mfma_f32_16x16x32_bf16 v[38:41], v[164:167], v[188:191], v[38:41]
	v_mfma_f32_16x16x32_bf16 v[34:37], v[172:175], v[188:191], v[34:37]
	v_mfma_f32_16x16x32_bf16 v[22:25], v[164:167], v[196:199], v[22:25]
	v_mfma_f32_16x16x32_bf16 v[18:21], v[172:175], v[196:199], v[18:21]
	v_mfma_f32_16x16x32_bf16 v[6:9], v[164:167], v[204:207], v[6:9]
	v_mfma_f32_16x16x32_bf16 v[2:5], v[172:175], v[204:207], v[2:5]
	v_mfma_f32_16x16x32_bf16 v[54:57], v[168:171], v[184:187], v[54:57]
	v_mfma_f32_16x16x32_bf16 v[50:53], v[176:179], v[184:187], v[50:53]
	v_mfma_f32_16x16x32_bf16 v[38:41], v[168:171], v[192:195], v[38:41]
	v_mfma_f32_16x16x32_bf16 v[34:37], v[176:179], v[192:195], v[34:37]
	v_mfma_f32_16x16x32_bf16 v[22:25], v[168:171], v[200:203], v[22:25]
	v_mfma_f32_16x16x32_bf16 v[18:21], v[176:179], v[200:203], v[18:21]
	v_mfma_f32_16x16x32_bf16 v[6:9], v[168:171], v[208:211], v[6:9]
	v_mfma_f32_16x16x32_bf16 v[2:5], v[176:179], v[208:211], v[2:5]
	s_setprio 0
	s_barrier
; #define PG8_STAGE(bufoff, gbase, voff) do { _Pragma("unroll") for (int _i = 0; _i < 2; ++_i) \
;         __builtin_amdgcn_global_load_lds((const unsigned*)((const char*)(gbase) + (voff)[_i]), (PG8_LAS unsigned*)(lds + (bufoff) + ldsw + _i * 8192), 16, 0, 0); } while (0)
; #define PG8_LDA(dst, b, h) do { _Pragma("unroll") for (int m = 0; m < 4; ++m) _Pragma("unroll") for (int k = 0; k < 2; ++k) dst[m][k] = *(const PG8_LAS bf16x8*)(lds + PG8_SA(b, h) + aoff + m * 2048 + k * 1024); } while (0)
; #define PG8_LDB(dst, b, h) do { _Pragma("unroll") for (int n = 0; n < 2; ++n) _Pragma("unroll") for (int k = 0; k < 2; ++k) dst[n][k] = *(const PG8_LAS bf16x8*)(lds + PG8_SB(b, h) + boff + n * 2048 + k * 1024); } while (0)
; #define PG8_MMA(ai, bj, At, Bt) do { __builtin_amdgcn_s_setprio(1); _Pragma("unroll") for (int m = 0; m < 4; ++m) _Pragma("unroll") for (int n = 0; n < 2; ++n) _Pragma("unroll") for (int k = 0; k < 2; ++k) \
;         acc[ai][bj][m][n] = __builtin_amdgcn_mfma_f32_16x16x32_bf16(Bt[n][k], At[m][k], acc[ai][bj][m][n], 0, 0, 0); __builtin_amdgcn_s_setprio(0); } while (0)
; #define PG8_WAIT_V(n) asm volatile("s_waitcnt vmcnt(" #n ")" ::: "memory")
; #define PG8_WAIT_L(n) asm volatile("s_waitcnt lgkmcnt(" #n ")" ::: "memory")
; #define PG8_BAR __builtin_amdgcn_s_barrier()
; #define PG8_SCHED __builtin_amdgcn_sched_barrier(0)
; template <class Epi, class Sched, bool ALIGN_EPI = false, bool SP2 = false>
; __device__ __forceinline__ void gemm_phase(PG8_LAS unsigned char* lds, const Gemm g, const Sched& S, const Epi& E) {
;     ...
;             PG8_LDB(B0, 1, 0); PG8_LDB(B1, 1, 1); PG8_SCHED; PG8_LDA(At, 1, 0); PG8_STAGE(PG8_SA(0, 1), a2 + hstep, voffA);
;             PG8_WAIT_V(8); PG8_WAIT_L(0); PG8_BAR; PG8_MMA(0, 0, At, B0); PG8_MMA(0, 1, At, B1); PG8_BAR; PG8_SCHED;
;             PG8_LDA(At, 1, 1); PG8_STAGE(PG8_SB(1, 0), b3, voffB); PG8_STAGE(PG8_SB(1, 1), b3 + hstep, voffB); PG8_STAGE(PG8_SA(1, 0), a3, voffA);
	s_add_i32 s52, 0, 0x18000
	v_add_u32_e32 v147, s52, v145
	s_add_i32 s53, 0, 0x1c000
	ds_read_b128 v[148:151], v147
	ds_read_b128 v[152:155], v147 offset:1024
	ds_read_b128 v[156:159], v147 offset:2048
	ds_read_b128 v[160:163], v147 offset:3072
	v_add_u32_e32 v147, s53, v145
	ds_read_b128 v[164:167], v147
	ds_read_b128 v[168:171], v147 offset:1024
	ds_read_b128 v[172:175], v147 offset:2048
	ds_read_b128 v[176:179], v147 offset:3072
	s_add_u32 s22, s22, 0x40000
	s_addc_u32 s23, s23, 0
	s_mov_b32 m0, s31
	v_lshl_add_u64 v[218:219], s[22:23], 0, v[136:137]
	ds_read_b128 v[180:183], v146 offset:32768
	ds_read_b128 v[184:187], v146 offset:33792
	ds_read_b128 v[188:191], v146 offset:34816
	ds_read_b128 v[192:195], v146 offset:35840
	ds_read_b128 v[196:199], v146 offset:36864
	ds_read_b128 v[200:203], v146 offset:37888
	ds_read_b128 v[204:207], v146 offset:38912
	ds_read_b128 v[208:211], v146 offset:39936
	global_load_lds_dwordx4 v[218:219], off
	v_lshl_add_u64 v[218:219], s[22:23], 0, v[132:133]
	s_mov_b32 m0, s33
	s_nop 0
	global_load_lds_dwordx4 v[218:219], off
	s_waitcnt vmcnt(8)
	s_waitcnt lgkmcnt(0)
	s_barrier
	s_setprio 1
	s_waitcnt lgkmcnt(0)
	v_mfma_f32_16x16x32_bf16 v[126:129], v[148:151], v[180:183], v[126:129]
	v_mfma_f32_16x16x32_bf16 v[122:125], v[156:159], v[180:183], v[122:125]
	v_mfma_f32_16x16x32_bf16 v[110:113], v[148:151], v[188:191], v[110:113]
	v_mfma_f32_16x16x32_bf16 v[106:109], v[156:159], v[188:191], v[106:109]
	v_mfma_f32_16x16x32_bf16 v[94:97], v[148:151], v[196:199], v[94:97]
	v_mfma_f32_16x16x32_bf16 v[90:93], v[156:159], v[196:199], v[90:93]
	v_mfma_f32_16x16x32_bf16 v[78:81], v[148:151], v[204:207], v[78:81]
	v_mfma_f32_16x16x32_bf16 v[74:77], v[156:159], v[204:207], v[74:77]
	v_mfma_f32_16x16x32_bf16 v[126:129], v[152:155], v[184:187], v[126:129]
	v_mfma_f32_16x16x32_bf16 v[122:125], v[160:163], v[184:187], v[122:125]
	v_mfma_f32_16x16x32_bf16 v[110:113], v[152:155], v[192:195], v[110:113]
	v_mfma_f32_16x16x32_bf16 v[106:109], v[160:163], v[192:195], v[106:109]
	v_mfma_f32_16x16x32_bf16 v[94:97], v[152:155], v[200:203], v[94:97]
	v_mfma_f32_16x16x32_bf16 v[90:93], v[160:163], v[200:203], v[90:93]
	v_mfma_f32_16x16x32_bf16 v[78:81], v[152:155], v[208:211], v[78:81]
	v_mfma_f32_16x16x32_bf16 v[74:77], v[160:163], v[208:211], v[74:77]
	s_setprio 0
	s_setprio 1
	v_mfma_f32_16x16x32_bf16 v[118:121], v[164:167], v[180:183], v[118:121]
	v_mfma_f32_16x16x32_bf16 v[114:117], v[172:175], v[180:183], v[114:117]
	v_mfma_f32_16x16x32_bf16 v[102:105], v[164:167], v[188:191], v[102:105]
	v_mfma_f32_16x16x32_bf16 v[98:101], v[172:175], v[188:191], v[98:101]
	v_mfma_f32_16x16x32_bf16 v[86:89], v[164:167], v[196:199], v[86:89]
	v_mfma_f32_16x16x32_bf16 v[82:85], v[172:175], v[196:199], v[82:85]
	v_mfma_f32_16x16x32_bf16 v[70:73], v[164:167], v[204:207], v[70:73]
	v_mfma_f32_16x16x32_bf16 v[66:69], v[172:175], v[204:207], v[66:69]
	v_mfma_f32_16x16x32_bf16 v[118:121], v[168:171], v[184:187], v[118:121]
	v_mfma_f32_16x16x32_bf16 v[114:117], v[176:179], v[184:187], v[114:117]
	v_mfma_f32_16x16x32_bf16 v[102:105], v[168:171], v[192:195], v[102:105]
	v_mfma_f32_16x16x32_bf16 v[98:101], v[176:179], v[192:195], v[98:101]
	v_mfma_f32_16x16x32_bf16 v[86:89], v[168:171], v[200:203], v[86:89]
	v_mfma_f32_16x16x32_bf16 v[82:85], v[176:179], v[200:203], v[82:85]
	v_mfma_f32_16x16x32_bf16 v[70:73], v[168:171], v[208:211], v[70:73]
	v_mfma_f32_16x16x32_bf16 v[66:69], v[176:179], v[208:211], v[66:69]
	s_setprio 0
	s_barrier
	s_add_i32 s22, s52, s28
	v_lshl_add_u64 v[142:143], v[142:143], 0, s[94:95]
	s_mov_b32 m0, s22
	ds_read_b128 v[180:183], v146 offset:49152
	ds_read_b128 v[184:187], v146 offset:50176
	ds_read_b128 v[188:191], v146 offset:51200
	ds_read_b128 v[192:195], v146 offset:52224
	ds_read_b128 v[196:199], v146 offset:53248
	ds_read_b128 v[200:203], v146 offset:54272
	ds_read_b128 v[204:207], v146 offset:55296
	ds_read_b128 v[208:211], v146 offset:56320
	global_load_lds_dwordx4 v[142:143], off
	s_add_i32 m0, s22, 0x2000
	s_add_u32 s16, s16, 0x40080
	v_lshl_add_u64 v[142:143], v[212:213], 0, s[94:95]
	s_addc_u32 s17, s17, 0
	s_add_i32 s22, s53, s28
	global_load_lds_dwordx4 v[142:143], off
	v_lshl_add_u64 v[142:143], s[16:17], 0, v[134:135]
	s_mov_b32 m0, s22
	s_nop 0
	global_load_lds_dwordx4 v[142:143], off
	v_lshl_add_u64 v[142:143], s[16:17], 0, v[130:131]
	s_add_i32 m0, s22, 0x2000
	s_nop 0
	global_load_lds_dwordx4 v[142:143], off
	v_lshl_add_u64 v[142:143], v[214:215], 0, s[94:95]
	s_mov_b32 m0, s34
	s_nop 0
	global_load_lds_dwordx4 v[142:143], off
	v_lshl_add_u64 v[142:143], v[216:217], 0, s[94:95]
	s_mov_b32 m0, s35
	s_nop 0
	global_load_lds_dwordx4 v[142:143], off
	s_waitcnt vmcnt(8)
	s_waitcnt lgkmcnt(0)
	s_barrier
; __device__ __forceinline__ u32x4 pack8(const f32x4 v0, const f32x4 v1) { u32x4 w; w.x = cvt_pk_bf16(v0[0], v0[1]); w.y = cvt_pk_bf16(v0[2], v0[3]); w.z = cvt_pk_bf16(v1[0], v1[1]); w.w = cvt_pk_bf16(v1[2], v1[3]); return w; }
; #define PG8_WAIT_V(n) asm volatile("s_waitcnt vmcnt(" #n ")" ::: "memory")
;     __device__ __forceinline__ void operator()(const f32x4 (&acc)[2][2][4][2], const Unit& u, int wr, int wc, int fr, int fq) const {
;         EPI_LOOP_BEGIN _Pragma("unroll") for (int e = 0; e < 4; ++e) { const float a = fmaxf(v0[e], 0.f), b = fmaxf(v1[e], 0.f); v0[e] = a * a; v1[e] = b * b; }
;             *(u32x4*)(O + (size_t)row * 4096 + u.pn * BM + ct) = pack8(v0, v1); EPI_LOOP_END
; template <class Epi, class Sched, bool ALIGN_EPI = false, bool SP2 = false>
; __device__ __forceinline__ void gemm_phase(PG8_LAS unsigned char* lds, const Gemm g, const Sched& S, const Epi& E) {
;     ...
;             PG8_WAIT_V(8); PG8_WAIT_L(0); PG8_BAR; PG8_MMA(1, 0, At, B0); PG8_MMA(1, 1, At, B1); PG8_BAR; PG8_SCHED;
;             } else {
;             PG8_LDB(B0, 0, 0); PG8_SCHED; PG8_LDA(At, 0, 0); PG8_STAGE(PG8_SA(1, 1), a1 + hstep, voffA);
;             PG8_WAIT_L(8); PG8_BAR; PG8_WAIT_L(0); PG8_MMA(0, 0, At, B0); PG8_BAR; PG8_SCHED;
;             PG8_LDB(B1, 0, 1); PG8_STAGE(PG8_SB(0, 0), b2, voffB);
;             PG8_BAR; PG8_WAIT_L(0); PG8_MMA(0, 1, At, B1); PG8_BAR;
;             PG8_LDA(At, 0, 1); PG8_STAGE(PG8_SA(0, 0), a2, voffA);
;             PG8_BAR; PG8_WAIT_L(0); PG8_MMA(1, 0, At, B0); PG8_BAR; PG8_SCHED;
;             PG8_STAGE(PG8_SB(0, 1), b2 + hstep, voffB);
;             PG8_WAIT_V(6); PG8_BAR; PG8_MMA(1, 1, At, B1); PG8_BAR;
;             PG8_LDB(B0, 1, 0); PG8_SCHED; PG8_LDA(At, 1, 0); PG8_STAGE(PG8_SA(0, 1), a2 + hstep, voffA);
;             PG8_WAIT_L(8); PG8_BAR; PG8_WAIT_L(0); PG8_MMA(0, 0, At, B0); PG8_BAR; PG8_SCHED;
;             PG8_LDB(B1, 1, 1); PG8_STAGE(PG8_SB(1, 0), b3, voffB);
;             PG8_BAR; PG8_WAIT_L(0); PG8_MMA(0, 1, At, B1); PG8_BAR;
;             PG8_LDA(At, 1, 1); PG8_STAGE(PG8_SA(1, 0), a3, voffA);
;             PG8_BAR; PG8_WAIT_L(0); PG8_MMA(1, 0, At, B0); PG8_BAR; PG8_SCHED;
;             PG8_STAGE(PG8_SB(1, 1), b3 + hstep, voffB);
;             PG8_WAIT_V(6); PG8_BAR; PG8_MMA(1, 1, At, B1); PG8_BAR;
;             }
;         }
;         if constexpr (ALIGN_EPI) { if (wr == 0) PG8_BAR; }
	s_setprio 1
	s_waitcnt lgkmcnt(0)
	v_mfma_f32_16x16x32_bf16 v[62:65], v[148:151], v[180:183], v[62:65]
	v_mfma_f32_16x16x32_bf16 v[58:61], v[156:159], v[180:183], v[58:61]
	v_mfma_f32_16x16x32_bf16 v[46:49], v[148:151], v[188:191], v[46:49]
	v_mfma_f32_16x16x32_bf16 v[42:45], v[156:159], v[188:191], v[42:45]
	v_mfma_f32_16x16x32_bf16 v[30:33], v[148:151], v[196:199], v[30:33]
	v_mfma_f32_16x16x32_bf16 v[26:29], v[156:159], v[196:199], v[26:29]
	v_mfma_f32_16x16x32_bf16 v[14:17], v[148:151], v[204:207], v[14:17]
	v_mfma_f32_16x16x32_bf16 v[10:13], v[156:159], v[204:207], v[10:13]
	v_mfma_f32_16x16x32_bf16 v[62:65], v[152:155], v[184:187], v[62:65]
	v_mfma_f32_16x16x32_bf16 v[58:61], v[160:163], v[184:187], v[58:61]
	v_mfma_f32_16x16x32_bf16 v[46:49], v[152:155], v[192:195], v[46:49]
	v_mfma_f32_16x16x32_bf16 v[42:45], v[160:163], v[192:195], v[42:45]
	v_mfma_f32_16x16x32_bf16 v[30:33], v[152:155], v[200:203], v[30:33]
	v_mfma_f32_16x16x32_bf16 v[26:29], v[160:163], v[200:203], v[26:29]
	v_mfma_f32_16x16x32_bf16 v[14:17], v[152:155], v[208:211], v[14:17]
	v_mfma_f32_16x16x32_bf16 v[10:13], v[160:163], v[208:211], v[10:13]
	s_setprio 0
	s_setprio 1
	v_mfma_f32_16x16x32_bf16 v[54:57], v[164:167], v[180:183], v[54:57]
	v_mfma_f32_16x16x32_bf16 v[50:53], v[172:175], v[180:183], v[50:53]
	v_mfma_f32_16x16x32_bf16 v[38:41], v[164:167], v[188:191], v[38:41]
	v_mfma_f32_16x16x32_bf16 v[34:37], v[172:175], v[188:191], v[34:37]
	v_mfma_f32_16x16x32_bf16 v[22:25], v[164:167], v[196:199], v[22:25]
	v_mfma_f32_16x16x32_bf16 v[18:21], v[172:175], v[196:199], v[18:21]
	v_mfma_f32_16x16x32_bf16 v[6:9], v[164:167], v[204:207], v[6:9]
	v_mfma_f32_16x16x32_bf16 v[2:5], v[172:175], v[204:207], v[2:5]
	v_mfma_f32_16x16x32_bf16 v[54:57], v[168:171], v[184:187], v[54:57]
	v_mfma_f32_16x16x32_bf16 v[50:53], v[176:179], v[184:187], v[50:53]
	v_mfma_f32_16x16x32_bf16 v[38:41], v[168:171], v[192:195], v[38:41]
	v_mfma_f32_16x16x32_bf16 v[34:37], v[176:179], v[192:195], v[34:37]
	v_mfma_f32_16x16x32_bf16 v[22:25], v[168:171], v[200:203], v[22:25]
	v_mfma_f32_16x16x32_bf16 v[18:21], v[176:179], v[200:203], v[18:21]
	v_mfma_f32_16x16x32_bf16 v[6:9], v[168:171], v[208:211], v[6:9]
	v_mfma_f32_16x16x32_bf16 v[2:5], v[176:179], v[208:211], v[2:5]
	s_setprio 0
	s_barrier
	s_add_i32 s50, s50, 2
	s_add_u32 s20, s20, 0x100
	s_addc_u32 s21, s21, 0
	s_add_u32 s55, s55, 0x100
	s_addc_u32 s56, s56, 0
	s_cmp_gt_u32 s50, 13
	s_cbranch_scc0 .LBB0_816
	s_and_b64 vcc, exec, s[8:9]
	s_cbranch_vccz .LBB0_819
	s_barrier
.LBB0_819:
	v_max_f32_e32 v122, v122, v122
	v_max_f32_e32 v123, v123, v123
	v_max_f32_e32 v122, 0, v122
	v_max_f32_e32 v123, 0, v123
	v_lshl_add_u32 v142, s38, 8, v144
	v_max_f32_e32 v126, v126, v126
	v_max_f32_e32 v127, v127, v127
	v_pk_mul_f32 v[150:151], v[122:123], v[122:123]
	v_max_f32_e32 v123, v124, v124
	s_lshl_b32 s16, s37, 8
	v_ashrrev_i32_e32 v143, 31, v142
	v_max_f32_e32 v126, 0, v126
	v_max_f32_e32 v127, 0, v127
	v_max_f32_e32 v122, v128, v128
	v_max_f32_e32 v124, 0, v123
	v_max_f32_e32 v123, v129, v129
	s_ashr_i32 s17, s16, 31
	v_lshlrev_b64 v[148:149], 13, v[142:143]
	v_pk_mul_f32 v[126:127], v[126:127], v[126:127]
	v_max_f32_e32 v122, 0, v122
	v_max_f32_e32 v123, 0, v123
	v_max_f32_e32 v125, v125, v125
	v_max_f32_e32 v125, 0, v125
	v_pk_mul_f32 v[128:129], v[122:123], v[122:123]
	v_cvt_pk_bf16_f32 v122, v126, v127
	v_lshl_add_u64 v[126:127], s[6:7], 0, v[148:149]
	s_lshl_b64 s[16:17], s[16:17], 1
	v_pk_mul_f32 v[152:153], v[124:125], v[124:125]
	v_lshl_add_u64 v[126:127], v[126:127], 0, s[16:17]
	v_max_f32_e32 v114, v114, v114
	v_max_f32_e32 v115, v115, v115
	v_cvt_pk_bf16_f32 v123, v128, v129
	v_cvt_pk_bf16_f32 v124, v150, v151
	v_cvt_pk_bf16_f32 v125, v152, v153
	v_lshl_add_u64 v[126:127], v[126:127], 0, v[0:1]
	v_max_f32_e32 v114, 0, v114
	v_max_f32_e32 v115, 0, v115
	global_store_dwordx4 v[126:127], v[122:125], off nt
	v_max_f32_e32 v118, v118, v118
	v_max_f32_e32 v119, v119, v119
	v_pk_mul_f32 v[122:123], v[114:115], v[114:115]
	v_max_f32_e32 v115, v116, v116
	v_max_f32_e32 v114, v120, v120
	v_max_f32_e32 v116, 0, v115
	v_max_f32_e32 v115, v121, v121
	v_max_f32_e32 v117, v117, v117
	v_max_f32_e32 v118, 0, v118
	v_max_f32_e32 v119, 0, v119
	v_max_f32_e32 v114, 0, v114
	v_max_f32_e32 v115, 0, v115
	v_max_f32_e32 v117, 0, v117
	v_pk_mul_f32 v[118:119], v[118:119], v[118:119]
	v_pk_mul_f32 v[120:121], v[114:115], v[114:115]
	v_pk_mul_f32 v[124:125], v[116:117], v[116:117]
	v_max_f32_e32 v106, v106, v106
	v_max_f32_e32 v107, v107, v107
	v_cvt_pk_bf16_f32 v114, v118, v119
	v_cvt_pk_bf16_f32 v115, v120, v121
	v_cvt_pk_bf16_f32 v116, v122, v123
	v_cvt_pk_bf16_f32 v117, v124, v125
	v_max_f32_e32 v106, 0, v106
	v_max_f32_e32 v107, 0, v107
	global_store_dwordx4 v[126:127], v[114:117], off offset:256 nt
	v_max_f32_e32 v110, v110, v110
	v_max_f32_e32 v111, v111, v111
	v_or_b32_e32 v114, 16, v142
	v_pk_mul_f32 v[116:117], v[106:107], v[106:107]
	v_max_f32_e32 v107, v108, v108
	v_ashrrev_i32_e32 v115, 31, v114
	v_max_f32_e32 v110, 0, v110
	v_max_f32_e32 v111, 0, v111
	v_max_f32_e32 v106, v112, v112
	v_max_f32_e32 v108, 0, v107
	v_max_f32_e32 v107, v113, v113
	v_lshlrev_b64 v[114:115], 13, v[114:115]
	v_pk_mul_f32 v[110:111], v[110:111], v[110:111]
	v_max_f32_e32 v106, 0, v106
	v_max_f32_e32 v107, 0, v107
	v_max_f32_e32 v109, v109, v109
	v_max_f32_e32 v109, 0, v109
	v_pk_mul_f32 v[112:113], v[106:107], v[106:107]
	v_cvt_pk_bf16_f32 v106, v110, v111
	v_lshl_add_u64 v[110:111], s[6:7], 0, v[114:115]
	v_pk_mul_f32 v[118:119], v[108:109], v[108:109]
	v_lshl_add_u64 v[110:111], v[110:111], 0, s[16:17]
	v_max_f32_e32 v98, v98, v98
	v_max_f32_e32 v99, v99, v99
; __device__ __forceinline__ u32x4 pack8(const f32x4 v0, const f32x4 v1) { u32x4 w; w.x = cvt_pk_bf16(v0[0], v0[1]); w.y = cvt_pk_bf16(v0[2], v0[3]); w.z = cvt_pk_bf16(v1[0], v1[1]); w.w = cvt_pk_bf16(v1[2], v1[3]); return w; }
;     __device__ __forceinline__ void operator()(const f32x4 (&acc)[2][2][4][2], const Unit& u, int wr, int wc, int fr, int fq) const {
;         EPI_LOOP_BEGIN _Pragma("unroll") for (int e = 0; e < 4; ++e) { const float a = fmaxf(v0[e], 0.f), b = fmaxf(v1[e], 0.f); v0[e] = a * a; v1[e] = b * b; }
;             *(u32x4*)(O + (size_t)row * 4096 + u.pn * BM + ct) = pack8(v0, v1); EPI_LOOP_END
	v_cvt_pk_bf16_f32 v107, v112, v113
	v_cvt_pk_bf16_f32 v108, v116, v117
	v_cvt_pk_bf16_f32 v109, v118, v119
	v_lshl_add_u64 v[110:111], v[110:111], 0, v[0:1]
	v_max_f32_e32 v98, 0, v98
	v_max_f32_e32 v99, 0, v99
	global_store_dwordx4 v[110:111], v[106:109], off nt
	v_max_f32_e32 v102, v102, v102
	v_max_f32_e32 v103, v103, v103
	v_pk_mul_f32 v[106:107], v[98:99], v[98:99]
	v_max_f32_e32 v99, v100, v100
	v_max_f32_e32 v98, v104, v104
	v_max_f32_e32 v100, 0, v99
	v_max_f32_e32 v99, v105, v105
	v_max_f32_e32 v101, v101, v101
	v_max_f32_e32 v102, 0, v102
	v_max_f32_e32 v103, 0, v103
	v_max_f32_e32 v98, 0, v98
	v_max_f32_e32 v99, 0, v99
	v_max_f32_e32 v101, 0, v101
	v_pk_mul_f32 v[102:103], v[102:103], v[102:103]
	v_pk_mul_f32 v[104:105], v[98:99], v[98:99]
	v_pk_mul_f32 v[108:109], v[100:101], v[100:101]
	v_max_f32_e32 v90, v90, v90
	v_max_f32_e32 v91, v91, v91
	v_cvt_pk_bf16_f32 v98, v102, v103
	v_cvt_pk_bf16_f32 v99, v104, v105
	v_cvt_pk_bf16_f32 v100, v106, v107
	v_cvt_pk_bf16_f32 v101, v108, v109
	v_max_f32_e32 v90, 0, v90
	v_max_f32_e32 v91, 0, v91
	global_store_dwordx4 v[110:111], v[98:101], off offset:256 nt
	v_max_f32_e32 v94, v94, v94
	v_max_f32_e32 v95, v95, v95
	v_or_b32_e32 v98, 32, v142
	v_pk_mul_f32 v[100:101], v[90:91], v[90:91]
	v_max_f32_e32 v91, v92, v92
	v_ashrrev_i32_e32 v99, 31, v98
	v_max_f32_e32 v94, 0, v94
	v_max_f32_e32 v95, 0, v95
	v_max_f32_e32 v90, v96, v96
	v_max_f32_e32 v92, 0, v91
	v_max_f32_e32 v91, v97, v97
	v_lshlrev_b64 v[98:99], 13, v[98:99]
	v_pk_mul_f32 v[94:95], v[94:95], v[94:95]
	v_max_f32_e32 v90, 0, v90
	v_max_f32_e32 v91, 0, v91
	v_max_f32_e32 v93, v93, v93
	v_max_f32_e32 v93, 0, v93
	v_pk_mul_f32 v[96:97], v[90:91], v[90:91]
	v_cvt_pk_bf16_f32 v90, v94, v95
	v_lshl_add_u64 v[94:95], s[6:7], 0, v[98:99]
	v_pk_mul_f32 v[102:103], v[92:93], v[92:93]
	v_lshl_add_u64 v[94:95], v[94:95], 0, s[16:17]
	v_max_f32_e32 v82, v82, v82
	v_max_f32_e32 v83, v83, v83
	v_cvt_pk_bf16_f32 v91, v96, v97
	v_cvt_pk_bf16_f32 v92, v100, v101
	v_cvt_pk_bf16_f32 v93, v102, v103
	v_lshl_add_u64 v[94:95], v[94:95], 0, v[0:1]
	v_max_f32_e32 v82, 0, v82
	v_max_f32_e32 v83, 0, v83
	global_store_dwordx4 v[94:95], v[90:93], off nt
	v_max_f32_e32 v86, v86, v86
	v_max_f32_e32 v87, v87, v87
	v_pk_mul_f32 v[90:91], v[82:83], v[82:83]
	v_max_f32_e32 v83, v84, v84
	v_max_f32_e32 v82, v88, v88
	v_max_f32_e32 v84, 0, v83
	v_max_f32_e32 v83, v89, v89
	v_max_f32_e32 v85, v85, v85
	v_max_f32_e32 v86, 0, v86
	v_max_f32_e32 v87, 0, v87
	v_max_f32_e32 v82, 0, v82
	v_max_f32_e32 v83, 0, v83
	v_max_f32_e32 v85, 0, v85
	v_pk_mul_f32 v[86:87], v[86:87], v[86:87]
	v_pk_mul_f32 v[88:89], v[82:83], v[82:83]
	v_pk_mul_f32 v[92:93], v[84:85], v[84:85]
	v_max_f32_e32 v74, v74, v74
	v_max_f32_e32 v75, v75, v75
	v_cvt_pk_bf16_f32 v82, v86, v87
	v_cvt_pk_bf16_f32 v83, v88, v89
	v_cvt_pk_bf16_f32 v84, v90, v91
	v_cvt_pk_bf16_f32 v85, v92, v93
	v_max_f32_e32 v74, 0, v74
	v_max_f32_e32 v75, 0, v75
	global_store_dwordx4 v[94:95], v[82:85], off offset:256 nt
	v_max_f32_e32 v78, v78, v78
	v_max_f32_e32 v79, v79, v79
	v_or_b32_e32 v82, 48, v142
	v_pk_mul_f32 v[84:85], v[74:75], v[74:75]
	v_max_f32_e32 v75, v76, v76
	v_ashrrev_i32_e32 v83, 31, v82
	v_max_f32_e32 v78, 0, v78
	v_max_f32_e32 v79, 0, v79
	v_max_f32_e32 v74, v80, v80
	v_max_f32_e32 v76, 0, v75
	v_max_f32_e32 v75, v81, v81
	v_lshlrev_b64 v[82:83], 13, v[82:83]
	v_pk_mul_f32 v[78:79], v[78:79], v[78:79]
	v_max_f32_e32 v74, 0, v74
	v_max_f32_e32 v75, 0, v75
	v_max_f32_e32 v77, v77, v77
	v_max_f32_e32 v77, 0, v77
	v_pk_mul_f32 v[80:81], v[74:75], v[74:75]
	v_cvt_pk_bf16_f32 v74, v78, v79
	v_lshl_add_u64 v[78:79], s[6:7], 0, v[82:83]
	v_pk_mul_f32 v[86:87], v[76:77], v[76:77]
	v_lshl_add_u64 v[78:79], v[78:79], 0, s[16:17]
	v_max_f32_e32 v66, v66, v66
	v_max_f32_e32 v67, v67, v67
	v_cvt_pk_bf16_f32 v75, v80, v81
	v_cvt_pk_bf16_f32 v76, v84, v85
	v_cvt_pk_bf16_f32 v77, v86, v87
	v_lshl_add_u64 v[78:79], v[78:79], 0, v[0:1]
	v_max_f32_e32 v66, 0, v66
	v_max_f32_e32 v67, 0, v67
	global_store_dwordx4 v[78:79], v[74:77], off nt
	v_max_f32_e32 v70, v70, v70
	v_max_f32_e32 v71, v71, v71
	v_pk_mul_f32 v[74:75], v[66:67], v[66:67]
	v_max_f32_e32 v67, v68, v68
	v_max_f32_e32 v66, v72, v72
	v_max_f32_e32 v68, 0, v67
	v_max_f32_e32 v67, v73, v73
	v_max_f32_e32 v69, v69, v69
	v_max_f32_e32 v70, 0, v70
	v_max_f32_e32 v71, 0, v71
	v_max_f32_e32 v66, 0, v66
	v_max_f32_e32 v67, 0, v67
	v_max_f32_e32 v69, 0, v69
	v_pk_mul_f32 v[70:71], v[70:71], v[70:71]
	v_pk_mul_f32 v[72:73], v[66:67], v[66:67]
	v_pk_mul_f32 v[76:77], v[68:69], v[68:69]
	v_max_f32_e32 v58, v58, v58
	v_max_f32_e32 v59, v59, v59
	v_cvt_pk_bf16_f32 v66, v70, v71
	v_cvt_pk_bf16_f32 v67, v72, v73
	v_cvt_pk_bf16_f32 v68, v74, v75
	v_cvt_pk_bf16_f32 v69, v76, v77
	v_max_f32_e32 v58, 0, v58
	v_max_f32_e32 v59, 0, v59
	global_store_dwordx4 v[78:79], v[66:69], off offset:256 nt
	v_max_f32_e32 v62, v62, v62
	v_max_f32_e32 v63, v63, v63
	v_add_u32_e32 v66, 0x80, v142
	v_pk_mul_f32 v[68:69], v[58:59], v[58:59]
	v_max_f32_e32 v59, v60, v60
	v_ashrrev_i32_e32 v67, 31, v66
	v_max_f32_e32 v62, 0, v62
	v_max_f32_e32 v63, 0, v63
	v_max_f32_e32 v58, v64, v64
	v_max_f32_e32 v60, 0, v59
	v_max_f32_e32 v59, v65, v65
	v_lshlrev_b64 v[66:67], 13, v[66:67]
	v_pk_mul_f32 v[62:63], v[62:63], v[62:63]
	v_max_f32_e32 v58, 0, v58
	v_max_f32_e32 v59, 0, v59
	v_max_f32_e32 v61, v61, v61
	v_max_f32_e32 v61, 0, v61
	v_pk_mul_f32 v[64:65], v[58:59], v[58:59]
	v_cvt_pk_bf16_f32 v58, v62, v63
	v_lshl_add_u64 v[62:63], s[6:7], 0, v[66:67]
	v_pk_mul_f32 v[70:71], v[60:61], v[60:61]
	v_lshl_add_u64 v[62:63], v[62:63], 0, s[16:17]
	v_max_f32_e32 v50, v50, v50
	v_max_f32_e32 v51, v51, v51
; __device__ __forceinline__ u32x4 pack8(const f32x4 v0, const f32x4 v1) { u32x4 w; w.x = cvt_pk_bf16(v0[0], v0[1]); w.y = cvt_pk_bf16(v0[2], v0[3]); w.z = cvt_pk_bf16(v1[0], v1[1]); w.w = cvt_pk_bf16(v1[2], v1[3]); return w; }
; #define PG8_BAR __builtin_amdgcn_s_barrier()
;     __device__ __forceinline__ void operator()(const f32x4 (&acc)[2][2][4][2], const Unit& u, int wr, int wc, int fr, int fq) const {
;         EPI_LOOP_BEGIN _Pragma("unroll") for (int e = 0; e < 4; ++e) { const float a = fmaxf(v0[e], 0.f), b = fmaxf(v1[e], 0.f); v0[e] = a * a; v1[e] = b * b; }
;             *(u32x4*)(O + (size_t)row * 4096 + u.pn * BM + ct) = pack8(v0, v1); EPI_LOOP_END
;     }
; template <class Epi, class Sched, bool ALIGN_EPI = false, bool SP2 = false>
; __device__ __forceinline__ void gemm_phase(PG8_LAS unsigned char* lds, const Gemm g, const Sched& S, const Epi& E) {
;     ...
;         cur = nxt; cA = nA; cB = nB; ++ui;
;         if constexpr (ALIGN_EPI) { if (wr == 1) PG8_BAR; }
	v_cvt_pk_bf16_f32 v59, v64, v65
	v_cvt_pk_bf16_f32 v60, v68, v69
	v_cvt_pk_bf16_f32 v61, v70, v71
	v_lshl_add_u64 v[62:63], v[62:63], 0, v[0:1]
	v_max_f32_e32 v50, 0, v50
	v_max_f32_e32 v51, 0, v51
	global_store_dwordx4 v[62:63], v[58:61], off nt
	v_max_f32_e32 v54, v54, v54
	v_max_f32_e32 v55, v55, v55
	v_pk_mul_f32 v[58:59], v[50:51], v[50:51]
	v_max_f32_e32 v51, v52, v52
	v_max_f32_e32 v50, v56, v56
	v_max_f32_e32 v52, 0, v51
	v_max_f32_e32 v51, v57, v57
	v_max_f32_e32 v53, v53, v53
	v_max_f32_e32 v54, 0, v54
	v_max_f32_e32 v55, 0, v55
	v_max_f32_e32 v50, 0, v50
	v_max_f32_e32 v51, 0, v51
	v_max_f32_e32 v53, 0, v53
	v_pk_mul_f32 v[54:55], v[54:55], v[54:55]
	v_pk_mul_f32 v[56:57], v[50:51], v[50:51]
	v_pk_mul_f32 v[60:61], v[52:53], v[52:53]
	v_max_f32_e32 v42, v42, v42
	v_max_f32_e32 v43, v43, v43
	v_cvt_pk_bf16_f32 v50, v54, v55
	v_cvt_pk_bf16_f32 v51, v56, v57
	v_cvt_pk_bf16_f32 v52, v58, v59
	v_cvt_pk_bf16_f32 v53, v60, v61
	v_max_f32_e32 v42, 0, v42
	v_max_f32_e32 v43, 0, v43
	global_store_dwordx4 v[62:63], v[50:53], off offset:256 nt
	v_max_f32_e32 v46, v46, v46
	v_max_f32_e32 v47, v47, v47
	v_add_u32_e32 v50, 0x90, v142
	v_pk_mul_f32 v[52:53], v[42:43], v[42:43]
	v_max_f32_e32 v43, v44, v44
	v_ashrrev_i32_e32 v51, 31, v50
	v_max_f32_e32 v46, 0, v46
	v_max_f32_e32 v47, 0, v47
	v_max_f32_e32 v42, v48, v48
	v_max_f32_e32 v44, 0, v43
	v_max_f32_e32 v43, v49, v49
	v_lshlrev_b64 v[50:51], 13, v[50:51]
	v_pk_mul_f32 v[46:47], v[46:47], v[46:47]
	v_max_f32_e32 v42, 0, v42
	v_max_f32_e32 v43, 0, v43
	v_max_f32_e32 v45, v45, v45
	v_max_f32_e32 v45, 0, v45
	v_pk_mul_f32 v[48:49], v[42:43], v[42:43]
	v_cvt_pk_bf16_f32 v42, v46, v47
	v_lshl_add_u64 v[46:47], s[6:7], 0, v[50:51]
	v_pk_mul_f32 v[54:55], v[44:45], v[44:45]
	v_lshl_add_u64 v[46:47], v[46:47], 0, s[16:17]
	v_max_f32_e32 v34, v34, v34
	v_max_f32_e32 v35, v35, v35
	v_cvt_pk_bf16_f32 v43, v48, v49
	v_cvt_pk_bf16_f32 v44, v52, v53
	v_cvt_pk_bf16_f32 v45, v54, v55
	v_lshl_add_u64 v[46:47], v[46:47], 0, v[0:1]
	v_max_f32_e32 v34, 0, v34
	v_max_f32_e32 v35, 0, v35
	global_store_dwordx4 v[46:47], v[42:45], off nt
	v_max_f32_e32 v38, v38, v38
	v_max_f32_e32 v39, v39, v39
	v_pk_mul_f32 v[42:43], v[34:35], v[34:35]
	v_max_f32_e32 v35, v36, v36
	v_max_f32_e32 v34, v40, v40
	v_max_f32_e32 v36, 0, v35
	v_max_f32_e32 v35, v41, v41
	v_max_f32_e32 v37, v37, v37
	v_max_f32_e32 v38, 0, v38
	v_max_f32_e32 v39, 0, v39
	v_max_f32_e32 v34, 0, v34
	v_max_f32_e32 v35, 0, v35
	v_max_f32_e32 v37, 0, v37
	v_pk_mul_f32 v[38:39], v[38:39], v[38:39]
	v_pk_mul_f32 v[40:41], v[34:35], v[34:35]
	v_pk_mul_f32 v[44:45], v[36:37], v[36:37]
	v_max_f32_e32 v26, v26, v26
	v_max_f32_e32 v27, v27, v27
	v_cvt_pk_bf16_f32 v34, v38, v39
	v_cvt_pk_bf16_f32 v35, v40, v41
	v_cvt_pk_bf16_f32 v36, v42, v43
	v_cvt_pk_bf16_f32 v37, v44, v45
	v_max_f32_e32 v26, 0, v26
	v_max_f32_e32 v27, 0, v27
	global_store_dwordx4 v[46:47], v[34:37], off offset:256 nt
	v_max_f32_e32 v30, v30, v30
	v_max_f32_e32 v31, v31, v31
	v_add_u32_e32 v34, 0xa0, v142
	v_pk_mul_f32 v[36:37], v[26:27], v[26:27]
	v_max_f32_e32 v27, v28, v28
	v_ashrrev_i32_e32 v35, 31, v34
	v_max_f32_e32 v30, 0, v30
	v_max_f32_e32 v31, 0, v31
	v_max_f32_e32 v26, v32, v32
	v_max_f32_e32 v28, 0, v27
	v_max_f32_e32 v27, v33, v33
	v_lshlrev_b64 v[34:35], 13, v[34:35]
	v_pk_mul_f32 v[30:31], v[30:31], v[30:31]
	v_max_f32_e32 v26, 0, v26
	v_max_f32_e32 v27, 0, v27
	v_max_f32_e32 v29, v29, v29
	v_max_f32_e32 v29, 0, v29
	v_pk_mul_f32 v[32:33], v[26:27], v[26:27]
	v_cvt_pk_bf16_f32 v26, v30, v31
	v_lshl_add_u64 v[30:31], s[6:7], 0, v[34:35]
	v_pk_mul_f32 v[38:39], v[28:29], v[28:29]
	v_lshl_add_u64 v[30:31], v[30:31], 0, s[16:17]
	v_max_f32_e32 v18, v18, v18
	v_max_f32_e32 v19, v19, v19
	v_cvt_pk_bf16_f32 v27, v32, v33
	v_cvt_pk_bf16_f32 v28, v36, v37
	v_cvt_pk_bf16_f32 v29, v38, v39
	v_lshl_add_u64 v[30:31], v[30:31], 0, v[0:1]
	v_max_f32_e32 v18, 0, v18
	v_max_f32_e32 v19, 0, v19
	global_store_dwordx4 v[30:31], v[26:29], off nt
	v_max_f32_e32 v22, v22, v22
	v_max_f32_e32 v23, v23, v23
	v_pk_mul_f32 v[26:27], v[18:19], v[18:19]
	v_max_f32_e32 v19, v20, v20
	v_max_f32_e32 v18, v24, v24
	v_max_f32_e32 v20, 0, v19
	v_max_f32_e32 v19, v25, v25
	v_max_f32_e32 v21, v21, v21
	v_max_f32_e32 v22, 0, v22
	v_max_f32_e32 v23, 0, v23
	v_max_f32_e32 v18, 0, v18
	v_max_f32_e32 v19, 0, v19
	v_max_f32_e32 v21, 0, v21
	v_pk_mul_f32 v[22:23], v[22:23], v[22:23]
	v_pk_mul_f32 v[24:25], v[18:19], v[18:19]
	v_pk_mul_f32 v[28:29], v[20:21], v[20:21]
	v_max_f32_e32 v10, v10, v10
	v_max_f32_e32 v11, v11, v11
	v_cvt_pk_bf16_f32 v18, v22, v23
	v_cvt_pk_bf16_f32 v19, v24, v25
	v_cvt_pk_bf16_f32 v20, v26, v27
	v_cvt_pk_bf16_f32 v21, v28, v29
	v_max_f32_e32 v10, 0, v10
	v_max_f32_e32 v11, 0, v11
	global_store_dwordx4 v[30:31], v[18:21], off offset:256 nt
	v_max_f32_e32 v14, v14, v14
	v_max_f32_e32 v15, v15, v15
	v_add_u32_e32 v18, 0xb0, v142
	v_pk_mul_f32 v[20:21], v[10:11], v[10:11]
	v_max_f32_e32 v11, v12, v12
	v_ashrrev_i32_e32 v19, 31, v18
	v_max_f32_e32 v14, 0, v14
	v_max_f32_e32 v15, 0, v15
	v_max_f32_e32 v10, v16, v16
	v_max_f32_e32 v12, 0, v11
	v_max_f32_e32 v11, v17, v17
	v_lshlrev_b64 v[18:19], 13, v[18:19]
	v_pk_mul_f32 v[14:15], v[14:15], v[14:15]
	v_max_f32_e32 v10, 0, v10
	v_max_f32_e32 v11, 0, v11
	v_max_f32_e32 v13, v13, v13
	v_max_f32_e32 v13, 0, v13
	v_pk_mul_f32 v[16:17], v[10:11], v[10:11]
	v_cvt_pk_bf16_f32 v10, v14, v15
	v_lshl_add_u64 v[14:15], s[6:7], 0, v[18:19]
	v_pk_mul_f32 v[22:23], v[12:13], v[12:13]
	v_lshl_add_u64 v[14:15], v[14:15], 0, s[16:17]
	v_max_f32_e32 v2, v2, v2
	v_max_f32_e32 v3, v3, v3
	v_cvt_pk_bf16_f32 v11, v16, v17
	v_cvt_pk_bf16_f32 v12, v20, v21
	v_cvt_pk_bf16_f32 v13, v22, v23
	v_lshl_add_u64 v[14:15], v[14:15], 0, v[0:1]
	v_max_f32_e32 v2, 0, v2
	v_max_f32_e32 v3, 0, v3
	global_store_dwordx4 v[14:15], v[10:13], off nt
	v_max_f32_e32 v6, v6, v6
	v_max_f32_e32 v7, v7, v7
	v_pk_mul_f32 v[10:11], v[2:3], v[2:3]
	v_max_f32_e32 v3, v4, v4
	v_max_f32_e32 v2, v8, v8
	v_max_f32_e32 v4, 0, v3
	v_max_f32_e32 v3, v9, v9
	v_max_f32_e32 v5, v5, v5
	v_max_f32_e32 v6, 0, v6
	v_max_f32_e32 v7, 0, v7
	v_max_f32_e32 v2, 0, v2
	v_max_f32_e32 v3, 0, v3
	v_max_f32_e32 v5, 0, v5
	v_pk_mul_f32 v[6:7], v[6:7], v[6:7]
	v_pk_mul_f32 v[8:9], v[2:3], v[2:3]
	v_pk_mul_f32 v[12:13], v[4:5], v[4:5]
	v_cvt_pk_bf16_f32 v2, v6, v7
	v_cvt_pk_bf16_f32 v3, v8, v9
	v_cvt_pk_bf16_f32 v4, v10, v11
	v_cvt_pk_bf16_f32 v5, v12, v13
	s_andn2_b64 vcc, exec, s[4:5]
	s_mov_b64 s[4:5], -1
	global_store_dwordx4 v[14:15], v[2:5], off offset:256 nt
	s_cbranch_vccnz .LBB0_808
	s_andn2_b64 vcc, exec, s[0:1]
	s_cbranch_vccnz .LBB0_807
	s_branch .LBB0_807

;     __device__ __forceinline__ bool next(int i, Unit& u) const { const int L = i * G + c; if (L >= 512) return false; u.pm = L; u.pn = L >> 4; return true; }
; #define PG8_WAIT_V(n) asm volatile("s_waitcnt vmcnt(" #n ")" ::: "memory")
; #define PG8_BAR __builtin_amdgcn_s_barrier()
; template <class Epi, class Sched, bool ALIGN_EPI = false, bool SP2 = false>
; __device__ __forceinline__ void gemm_phase(PG8_LAS unsigned char* lds, const Gemm g, const Sched& S, const Epi& E) {
;     ...
;     const int tid = tid_, wid = __builtin_amdgcn_readfirstlane(tid >> 6), lane = tid & 63, wr = wid >> 2, wc = wid & 3, fr = lane & 15, fq = lane >> 4;
;     const int K = g.K, nt = K / BK, LD = g.ld ? g.ld : g.K;
;     unsigned voffA[2], voffB[2];
; #pragma unroll
;     for (int i = 0; i < 2; ++i) { int R, C; stage_rc(tid * 16 + i * 8192, R, C); const int Rb = Epi::PERM ? ((R & ~31) + perm32(R & 31)) : R;
;         voffA[i] = (unsigned)(R * LD + C) * 2u; voffB[i] = (unsigned)(Rb * LD + C) * 2u; }
;     const size_t kstep = (size_t)(BK * 2);
;     const size_t hstep = (size_t)HALF * LD * 2;
;     const size_t tstep = 2 * hstep;
;     const unsigned ldsw = (unsigned)wid * 1024u;
;     const int aoff = lds_byte(wr * 64 + fr, fq * 8), boff = lds_byte(wc * 32 + fr, fq * 8);
;     ...
;     Unit cur, nxt; int ui = 0;
;     if (!S.next(0, cur)) return;
;     f32x4 acc[2][2][4][2];
; #pragma unroll
;     for (int a = 0; a < 2; ++a)
; #pragma unroll
;         for (int b = 0; b < 2; ++b)
; #pragma unroll
;             for (int m = 0; m < 4; ++m)
; #pragma unroll
;                 for (int n = 0; n < 2; ++n) acc[a][b][m][n] = (f32x4){0.f, 0.f, 0.f, 0.f};
;     bf16x8 At[4][2], B0[2][2], B1[2][2];
;     const char* cA = (const char*)g.A + (size_t)cur.pm * tstep; const char* cB = (const char*)g.Bt + (size_t)cur.pn * tstep;
;     S.a_ready(cur);
;     if constexpr (SP2) {
;         PG8_STAGE(PG8_SB(0, 0), cB, voffB); PG8_STAGE(PG8_SB(0, 1), cB + hstep, voffB); PG8_STAGE(PG8_SA(0, 0), cA, voffA); PG8_STAGE(PG8_SA(0, 1), cA + hstep, voffA);
;         if (wr == 1) PG8_BAR;
;         PG8_WAIT_V(2); PG8_BAR;
;         PG8_STAGE(PG8_SB(1, 0), cB + kstep, voffB); PG8_STAGE(PG8_SA(1, 0), cA + kstep, voffA); PG8_STAGE(PG8_SB(1, 1), cB + hstep + kstep, voffB);
;         PG8_WAIT_V(6); PG8_BAR;
.LBB0_868:
	s_or_b64 exec, exec, s[36:37]
	v_readlane_b32 s0, v254, 56
	s_mov_b64 s[4:5], s[72:73]
	v_mov_b32_e32 v15, v242
	v_readlane_b32 s1, v254, 57
	s_waitcnt lgkmcnt(0)
	s_barrier
	s_and_b64 vcc, exec, s[0:1]
	v_readfirstlane_b32 s8, v15
	s_cbranch_vccz .LBB0_888
	v_lshlrev_b32_e32 v2, 4, v15
	v_add_u32_e32 v3, 0x2000, v2
	v_ashrrev_i32_e32 v0, 31, v3
	v_lshrrev_b32_e32 v0, 22, v0
	v_add_u32_e32 v0, v3, v0
	v_ashrrev_i32_e32 v0, 10, v0
	v_mul_i32_i24_e32 v4, 0x400, v0
	v_sub_u32_e32 v3, v3, v4
	v_lshrrev_b32_e32 v4, 4, v3
	v_bitop3_b32 v3, v4, v3, 32 bitop3:0x6c
	v_ashrrev_i32_e32 v4, 31, v3
	v_lshrrev_b32_e32 v4, 26, v4
	v_add_u32_e32 v4, v3, v4
	v_lshlrev_b32_e32 v5, 3, v0
	v_ashrrev_i32_e32 v10, 6, v4
	v_and_b32_e32 v5, -16, v5
	v_add_u32_e32 v5, v10, v5
	v_and_b32_e32 v6, 3, v10
	s_mov_b32 s0, 0x7ffe0
	v_lshrrev_b32_e32 v7, 2, v5
	v_lshlrev_b32_e32 v8, 1, v5
	v_and_b32_e32 v4, 0xc0, v4
	v_and_or_b32 v6, v5, s0, v6
	v_and_b32_e32 v7, 4, v7
	v_and_b32_e32 v8, 24, v8
	v_sub_u32_e32 v3, v3, v4
	v_or3_b32 v6, v6, v7, v8
	v_lshlrev_b32_e32 v7, 5, v0
	v_ashrrev_i16_sdwa v3, v241, sext(v3) dst_sel:DWORD dst_unused:UNUSED_PAD src0_sel:DWORD src1_sel:BYTE_0
	v_and_b32_e32 v7, 32, v7
	v_bfe_i32 v11, v3, 0, 16
	v_add_lshl_u32 v3, v7, v11, 1
	v_lshl_add_u32 v194, v6, 13, v3
	v_lshl_add_u32 v196, v5, 13, v3
	v_bfe_i32 v3, v15, 27, 1
	v_lshrrev_b32_e32 v3, 22, v3
	v_add_u32_e32 v3, v2, v3
	v_and_b32_e32 v3, 0xfffffc00, v3
	v_sub_u32_e32 v2, v2, v3
	v_lshrrev_b32_e32 v3, 4, v2
	v_ashrrev_i32_e32 v4, 31, v15
	v_bitop3_b32 v2, v3, v2, 32 bitop3:0x6c
	v_lshrrev_b32_e32 v4, 26, v4
	v_ashrrev_i32_e32 v3, 31, v2
	v_add_u32_e32 v4, v15, v4
	v_lshrrev_b32_e32 v3, 26, v3
	v_ashrrev_i32_e32 v13, 6, v4
	v_add_u32_e32 v3, v2, v3
	v_lshlrev_b32_e32 v4, 3, v13
	s_add_u32 s24, s4, 0xd400000
	v_ashrrev_i32_e32 v12, 6, v3
	v_and_b32_e32 v4, -16, v4
	s_addc_u32 s25, s5, 0
	v_add_u32_e32 v4, v12, v4
	s_add_u32 s26, s4, 0x1100000
	v_and_b32_e32 v5, 3, v12
	v_lshrrev_b32_e32 v6, 2, v4
	v_lshlrev_b32_e32 v7, 1, v4
	v_and_b32_e32 v3, 0xc0, v3
	s_addc_u32 s27, s5, 0
	s_ashr_i32 s9, s8, 6
	v_and_or_b32 v5, v4, s0, v5
	v_and_b32_e32 v6, 4, v6
	v_and_b32_e32 v7, 24, v7
	v_sub_u32_e32 v2, v2, v3
	s_ashr_i32 s10, s8, 8
	s_lshl_b32 s28, s9, 10
	v_or3_b32 v5, v5, v6, v7
	v_lshlrev_b32_e32 v6, 5, v13
	v_ashrrev_i16_sdwa v2, v241, sext(v2) dst_sel:DWORD dst_unused:UNUSED_PAD src0_sel:DWORD src1_sel:BYTE_0
	v_readlane_b32 s0, v255, 22
	v_and_b32_e32 v6, 32, v6
	v_bfe_i32 v14, v2, 0, 16
	v_readlane_b32 s1, v255, 23
	s_add_u32 s16, s26, s0
	v_add_lshl_u32 v2, v6, v14, 1
	s_addc_u32 s17, s27, s1
	s_add_i32 s29, s28, 0
	v_lshl_add_u32 v198, v5, 13, v2
	s_add_i32 m0, s29, 0x10000
	v_lshl_add_u32 v200, v4, 13, v2
	global_load_lds_dwordx4 v198, s[16:17]
	s_add_i32 m0, s29, 0x12000
	s_add_u32 s0, s16, 0x100000
	global_load_lds_dwordx4 v194, s[16:17]
	s_addc_u32 s1, s17, 0
	s_add_i32 m0, s29, 0x14000
	v_mov_b32_e32 v199, v1
	global_load_lds_dwordx4 v198, s[0:1]
	s_add_i32 m0, s29, 0x16000
	v_mov_b32_e32 v195, v1
	global_load_lds_dwordx4 v194, s[0:1]
	v_readlane_b32 s0, v255, 20
	v_readlane_b32 s1, v255, 21
	s_add_u32 s20, s24, s0
	s_addc_u32 s21, s25, s1
	s_add_i32 s30, s29, 0x2000
	s_mov_b32 m0, s29
	s_add_u32 s0, s20, 0x100000
	global_load_lds_dwordx4 v200, s[20:21]
	s_mov_b32 m0, s30
	s_addc_u32 s1, s21, 0
	s_add_i32 s31, s29, 0x4000
	global_load_lds_dwordx4 v196, s[20:21]
	s_mov_b32 m0, s31
	s_add_i32 s34, s29, 0x6000
	global_load_lds_dwordx4 v200, s[0:1]
	s_mov_b32 m0, s34
	v_mov_b32_e32 v201, v1
	global_load_lds_dwordx4 v196, s[0:1]
	v_mov_b32_e32 v197, v1
	s_cmp_eq_u32 s10, 1
	v_lshl_add_u64 v[8:9], s[16:17], 0, v[198:199]
	v_lshl_add_u64 v[6:7], s[16:17], 0, v[194:195]
	v_lshl_add_u64 v[2:3], s[20:21], 0, v[200:201]
	s_cselect_b64 s[0:1], -1, 0
	s_cmp_lg_u32 s10, 1
	v_lshl_add_u64 v[4:5], s[20:21], 0, v[196:197]
	s_cbranch_scc1 .LBB0_871
.LBB0_871:
	v_lshrrev_b32_e32 v17, 1, v15
	v_and_b32_e32 v17, 24, v17
	s_add_u32 s6, s4, 0x33400000
	v_and_b32_e32 v16, 15, v15
	v_lshlrev_b32_e32 v18, 1, v17
	v_lshlrev_b32_e32 v15, 2, v15
	s_addc_u32 s7, s5, 0
	v_lshl_or_b32 v230, s10, 6, v16
	v_lshl_or_b32 v16, v16, 6, v18
	s_lshl_b32 s4, s10, 13
	v_and_b32_e32 v15, 32, v15
	v_bitop3_b32 v18, v16, s4, v15 bitop3:0xde
	s_lshl_b32 s4, s9, 5
	s_and_b32 s10, s4, 0x60
	s_add_i32 m0, s29, 0x18000
	v_lshl_add_u64 v[8:9], v[8:9], 0, s[94:95]
	s_lshl_b32 s4, s10, 7
	s_waitcnt vmcnt(2)
	s_barrier
	global_load_lds_dwordx4 v[8:9], off
	v_lshl_add_u64 v[6:7], v[6:7], 0, s[94:95]
	s_add_i32 m0, s29, 0x1a000
	s_add_i32 s33, s29, 0x8000
	s_add_i32 s35, s29, 0xa000
	v_bitop3_b32 v231, v16, s4, v15 bitop3:0xde
	global_load_lds_dwordx4 v[6:7], off
	v_lshl_add_u64 v[2:3], v[2:3], 0, s[94:95]
	s_mov_b32 m0, s33
	s_add_u32 s4, s16, 0x100080
	global_load_lds_dwordx4 v[2:3], off
	v_lshl_add_u64 v[2:3], v[4:5], 0, s[94:95]
	s_mov_b32 m0, s35
	s_addc_u32 s5, s17, 0
	global_load_lds_dwordx4 v[2:3], off
	s_add_i32 m0, s29, 0x1c000
	v_lshl_add_u64 v[2:3], s[4:5], 0, v[198:199]
	global_load_lds_dwordx4 v[2:3], off
	v_lshl_add_u64 v[2:3], s[4:5], 0, v[194:195]
	s_add_i32 m0, s29, 0x1e000
	v_and_b32_e32 v4, 1, v13
	global_load_lds_dwordx4 v[2:3], off
	v_lshlrev_b32_e32 v3, 16, v13
	v_and_b32_e32 v3, 0xfffe0000, v3
	v_lshl_add_u32 v3, v12, 13, v3
	v_lshl_or_b32 v3, v4, 6, v3
	v_lshl_add_u32 v202, v14, 1, v3
	v_lshlrev_b32_e32 v3, 16, v0
	v_and_b32_e32 v3, 0xfffe0000, v3
	s_waitcnt vmcnt(6)
	v_lshl_add_u32 v3, v10, 13, v3
	v_and_b32_e32 v0, 1, v0
	s_cmpk_lt_u32 s8, 0x100
	v_or_b32_e32 v2, s10, v17
	v_lshl_or_b32 v0, v0, 6, v3
	v_readlane_b32 s4, v255, 18
	s_cselect_b64 s[8:9], -1, 0
	v_mov_b32_e32 v203, v1
	v_lshl_add_u32 v204, v11, 1, v0
	v_mov_b32_e32 v205, v1
	s_mov_b32 s36, 0
	v_add_u32_e32 v232, 0, v18
	v_lshlrev_b32_e32 v0, 1, v2
	v_readlane_b32 s37, v255, 9
	s_mov_b32 s38, s4
	s_barrier
	v_readlane_b32 s5, v255, 19
	s_branch .LBB0_874

;     __device__ __forceinline__ bool next(int i, Unit& u) const { const int L = i * G + c; if (L >= 512) return false; u.pm = L; u.pn = L >> 4; return true; }
; #define PG8_STAGE(bufoff, gbase, voff) do { _Pragma("unroll") for (int _i = 0; _i < 2; ++_i) \
;         __builtin_amdgcn_global_load_lds((const unsigned*)((const char*)(gbase) + (voff)[_i]), (PG8_LAS unsigned*)(lds + (bufoff) + ldsw + _i * 8192), 16, 0, 0); } while (0)
; #define PG8_LDA(dst, b, h) do { _Pragma("unroll") for (int m = 0; m < 4; ++m) _Pragma("unroll") for (int k = 0; k < 2; ++k) dst[m][k] = *(const PG8_LAS bf16x8*)(lds + PG8_SA(b, h) + aoff + m * 2048 + k * 1024); } while (0)
; #define PG8_LDB(dst, b, h) do { _Pragma("unroll") for (int n = 0; n < 2; ++n) _Pragma("unroll") for (int k = 0; k < 2; ++k) dst[n][k] = *(const PG8_LAS bf16x8*)(lds + PG8_SB(b, h) + boff + n * 2048 + k * 1024); } while (0)
; template <class Epi, class Sched, bool ALIGN_EPI = false, bool SP2 = false>
; __device__ __forceinline__ void gemm_phase(PG8_LAS unsigned char* lds, const Gemm g, const Sched& S, const Epi& E) {
;     ...
;         const bool has_next = S.next(ui + 1, nxt);
;         const char* nA = has_next ? (const char*)g.A + (size_t)nxt.pm * tstep : cA; const char* nB = has_next ? (const char*)g.Bt + (size_t)nxt.pn * tstep : cB;
;         for (int t = 0; t < nt; t += 2) {
;             const bool last = (t == nt - 2);
;             const char* a1 = cA + (size_t)(t + 1) * kstep;
;             const char* a2 = last ? nA : cA + (size_t)(t + 2) * kstep; const char* b2 = last ? nB : cB + (size_t)(t + 2) * kstep;
;             const char* a3 = a2 + kstep; const char* b3 = b2 + kstep;
;             if (last && has_next) S.a_ready(nxt);
;             if constexpr (SP2) {
;             PG8_LDB(B0, 0, 0); PG8_LDB(B1, 0, 1); PG8_SCHED; PG8_LDA(At, 0, 0); PG8_STAGE(PG8_SA(1, 1), a1 + hstep, voffA);
;             PG8_WAIT_V(8); PG8_WAIT_L(0); PG8_BAR; PG8_MMA(0, 0, At, B0); PG8_MMA(0, 1, At, B1); PG8_BAR; PG8_SCHED;
;     ...
; #pragma unroll
;         for (int a = 0; a < 2; ++a)
; #pragma unroll
;             for (int b = 0; b < 2; ++b)
; #pragma unroll
;                 for (int m = 0; m < 4; ++m)
; #pragma unroll
;                     for (int n = 0; n < 2; ++n) acc[a][b][m][n] = (f32x4){0.f, 0.f, 0.f, 0.f};
;         cur = nxt; cA = nA; cB = nB; ++ui;
;         if constexpr (ALIGN_EPI) { if (wr == 1) PG8_BAR; }
.LBB0_880:
	s_ashr_i32 s13, s12, 31
	s_lshl_b64 s[14:15], s[12:13], 21
	s_add_u32 s14, s24, s14
	s_addc_u32 s15, s25, s15
	s_and_b64 s[18:19], s[4:5], exec
	s_cselect_b32 s13, s15, s21
	s_cselect_b32 s39, s14, s20
	s_ashr_i32 s11, s10, 31
	s_lshl_b64 s[18:19], s[10:11], 21
	s_add_u32 s18, s26, s18
	s_addc_u32 s19, s27, s19
	s_and_b64 s[22:23], s[4:5], exec
	s_cselect_b32 s11, s19, s17
	s_cselect_b32 s46, s18, s16
	s_add_u32 s20, s20, 0x100080
	s_addc_u32 s21, s21, 0
	s_add_u32 s55, s16, 0x100
	v_mov_b32_e32 v2, 0
	s_addc_u32 s56, s17, 0
	s_mov_b32 s50, -2
	v_mov_b32_e32 v3, v2
	v_mov_b32_e32 v4, v2
	v_mov_b32_e32 v5, v2
	v_mov_b32_e32 v6, v2
	v_mov_b32_e32 v7, v2
	v_mov_b32_e32 v8, v2
	v_mov_b32_e32 v9, v2
	v_mov_b32_e32 v14, v2
	v_mov_b32_e32 v15, v2
	v_mov_b32_e32 v16, v2
	v_mov_b32_e32 v17, v2
	v_mov_b32_e32 v22, v2
	v_mov_b32_e32 v23, v2
	v_mov_b32_e32 v24, v2
	v_mov_b32_e32 v25, v2
	v_mov_b32_e32 v30, v2
	v_mov_b32_e32 v31, v2
	v_mov_b32_e32 v32, v2
	v_mov_b32_e32 v33, v2
	v_mov_b32_e32 v38, v2
	v_mov_b32_e32 v39, v2
	v_mov_b32_e32 v40, v2
	v_mov_b32_e32 v41, v2
	v_mov_b32_e32 v46, v2
	v_mov_b32_e32 v47, v2
	v_mov_b32_e32 v48, v2
	v_mov_b32_e32 v49, v2
	v_mov_b32_e32 v54, v2
	v_mov_b32_e32 v55, v2
	v_mov_b32_e32 v56, v2
	v_mov_b32_e32 v57, v2
	v_mov_b32_e32 v10, v2
	v_mov_b32_e32 v11, v2
	v_mov_b32_e32 v12, v2
	v_mov_b32_e32 v13, v2
	v_mov_b32_e32 v18, v2
	v_mov_b32_e32 v19, v2
	v_mov_b32_e32 v20, v2
	v_mov_b32_e32 v21, v2
	v_mov_b32_e32 v26, v2
	v_mov_b32_e32 v27, v2
	v_mov_b32_e32 v28, v2
	v_mov_b32_e32 v29, v2
	v_mov_b32_e32 v34, v2
	v_mov_b32_e32 v35, v2
	v_mov_b32_e32 v36, v2
	v_mov_b32_e32 v37, v2
	v_mov_b32_e32 v42, v2
	v_mov_b32_e32 v43, v2
	v_mov_b32_e32 v44, v2
	v_mov_b32_e32 v45, v2
	v_mov_b32_e32 v50, v2
	v_mov_b32_e32 v51, v2
	v_mov_b32_e32 v52, v2
	v_mov_b32_e32 v53, v2
	v_mov_b32_e32 v58, v2
	v_mov_b32_e32 v59, v2
	v_mov_b32_e32 v60, v2
	v_mov_b32_e32 v61, v2
	v_mov_b32_e32 v62, v2
	v_mov_b32_e32 v63, v2
	v_mov_b32_e32 v64, v2
	v_mov_b32_e32 v65, v2
	v_mov_b32_e32 v66, v2
	v_mov_b32_e32 v67, v2
	v_mov_b32_e32 v68, v2
	v_mov_b32_e32 v69, v2
	v_mov_b32_e32 v70, v2
	v_mov_b32_e32 v71, v2
	v_mov_b32_e32 v72, v2
	v_mov_b32_e32 v73, v2
	v_mov_b32_e32 v78, v2
	v_mov_b32_e32 v79, v2
	v_mov_b32_e32 v80, v2
	v_mov_b32_e32 v81, v2
	v_mov_b32_e32 v86, v2
	v_mov_b32_e32 v87, v2
	v_mov_b32_e32 v88, v2
	v_mov_b32_e32 v89, v2
	v_mov_b32_e32 v94, v2
	v_mov_b32_e32 v95, v2
	v_mov_b32_e32 v96, v2
	v_mov_b32_e32 v97, v2
	v_mov_b32_e32 v102, v2
	v_mov_b32_e32 v103, v2
	v_mov_b32_e32 v104, v2
	v_mov_b32_e32 v105, v2
	v_mov_b32_e32 v110, v2
	v_mov_b32_e32 v111, v2
	v_mov_b32_e32 v112, v2
	v_mov_b32_e32 v113, v2
	v_mov_b32_e32 v118, v2
	v_mov_b32_e32 v119, v2
	v_mov_b32_e32 v120, v2
	v_mov_b32_e32 v121, v2
	v_mov_b32_e32 v74, v2
	v_mov_b32_e32 v75, v2
	v_mov_b32_e32 v76, v2
	v_mov_b32_e32 v77, v2
	v_mov_b32_e32 v82, v2
	v_mov_b32_e32 v83, v2
	v_mov_b32_e32 v84, v2
	v_mov_b32_e32 v85, v2
	v_mov_b32_e32 v90, v2
	v_mov_b32_e32 v91, v2
	v_mov_b32_e32 v92, v2
	v_mov_b32_e32 v93, v2
	v_mov_b32_e32 v98, v2
	v_mov_b32_e32 v99, v2
	v_mov_b32_e32 v100, v2
	v_mov_b32_e32 v101, v2
	v_mov_b32_e32 v106, v2
	v_mov_b32_e32 v107, v2
	v_mov_b32_e32 v108, v2
	v_mov_b32_e32 v109, v2
	v_mov_b32_e32 v114, v2
	v_mov_b32_e32 v115, v2
	v_mov_b32_e32 v116, v2
	v_mov_b32_e32 v117, v2
	v_mov_b32_e32 v122, v2
	v_mov_b32_e32 v123, v2
	v_mov_b32_e32 v124, v2
	v_mov_b32_e32 v125, v2
	v_mov_b32_e32 v126, v2
	v_mov_b32_e32 v127, v2
	v_mov_b32_e32 v128, v2
	v_mov_b32_e32 v129, v2
	s_cmp_eq_u64 s[0:1], 0
	s_cbranch_scc1 .Lboff_skip_L
	s_barrier
.Lboff_skip_L:
.LBB0_881:
	s_add_u32 s16, s20, 0xfff00080
	s_addc_u32 s17, s21, -1
	s_add_i32 s52, 0, 0x10000
	s_cmp_eq_u32 s50, 60
	s_cselect_b32 s23, s13, s17
	s_cselect_b32 s22, s39, s16
	s_cselect_b32 s17, s11, s56
	s_cselect_b32 s16, s46, s55
	s_add_i32 s57, 0, 0x14000
	v_add_u32_e32 v142, s52, v231
	v_add_u32_e32 v158, s57, v231
	ds_read_b128 v[130:133], v142
	ds_read_b128 v[134:137], v142 offset:1024
	ds_read_b128 v[138:141], v142 offset:2048
	ds_read_b128 v[142:145], v142 offset:3072
	ds_read_b128 v[146:149], v158
	ds_read_b128 v[150:153], v158 offset:1024
	ds_read_b128 v[154:157], v158 offset:2048
	ds_read_b128 v[158:161], v158 offset:3072
	v_lshl_add_u64 v[206:207], s[20:21], 0, v[202:203]
	s_add_i32 m0, s29, 0xc000
	ds_read_b128 v[162:165], v232
	ds_read_b128 v[166:169], v232 offset:1024
	ds_read_b128 v[170:173], v232 offset:2048
	ds_read_b128 v[174:177], v232 offset:3072
	ds_read_b128 v[178:181], v232 offset:4096
	ds_read_b128 v[182:185], v232 offset:5120
	ds_read_b128 v[186:189], v232 offset:6144
	ds_read_b128 v[190:193], v232 offset:7168
	global_load_lds_dwordx4 v[206:207], off
	v_lshl_add_u64 v[206:207], s[20:21], 0, v[204:205]
	s_add_i32 m0, s29, 0xe000
	s_nop 0
	global_load_lds_dwordx4 v[206:207], off
	s_waitcnt vmcnt(8)
	s_waitcnt lgkmcnt(0)
	s_barrier
; #define PG8_STAGE(bufoff, gbase, voff) do { _Pragma("unroll") for (int _i = 0; _i < 2; ++_i) \
;         __builtin_amdgcn_global_load_lds((const unsigned*)((const char*)(gbase) + (voff)[_i]), (PG8_LAS unsigned*)(lds + (bufoff) + ldsw + _i * 8192), 16, 0, 0); } while (0)
; #define PG8_LDA(dst, b, h) do { _Pragma("unroll") for (int m = 0; m < 4; ++m) _Pragma("unroll") for (int k = 0; k < 2; ++k) dst[m][k] = *(const PG8_LAS bf16x8*)(lds + PG8_SA(b, h) + aoff + m * 2048 + k * 1024); } while (0)
; #define PG8_MMA(ai, bj, At, Bt) do { __builtin_amdgcn_s_setprio(1); _Pragma("unroll") for (int m = 0; m < 4; ++m) _Pragma("unroll") for (int n = 0; n < 2; ++n) _Pragma("unroll") for (int k = 0; k < 2; ++k) \
;         acc[ai][bj][m][n] = __builtin_amdgcn_mfma_f32_16x16x32_bf16(Bt[n][k], At[m][k], acc[ai][bj][m][n], 0, 0, 0); __builtin_amdgcn_s_setprio(0); } while (0)
; #define PG8_WAIT_V(n) asm volatile("s_waitcnt vmcnt(" #n ")" ::: "memory")
; #define PG8_WAIT_L(n) asm volatile("s_waitcnt lgkmcnt(" #n ")" ::: "memory")
; #define PG8_BAR __builtin_amdgcn_s_barrier()
; #define PG8_SCHED __builtin_amdgcn_sched_barrier(0)
; template <class Epi, class Sched, bool ALIGN_EPI = false, bool SP2 = false>
; __device__ __forceinline__ void gemm_phase(PG8_LAS unsigned char* lds, const Gemm g, const Sched& S, const Epi& E) {
;     ...
;             PG8_WAIT_V(8); PG8_WAIT_L(0); PG8_BAR; PG8_MMA(0, 0, At, B0); PG8_MMA(0, 1, At, B1); PG8_BAR; PG8_SCHED;
;             PG8_LDA(At, 0, 1); PG8_STAGE(PG8_SB(0, 0), b2, voffB); PG8_STAGE(PG8_SB(0, 1), b2 + hstep, voffB); PG8_STAGE(PG8_SA(0, 0), a2, voffA);
;             PG8_WAIT_V(8); PG8_WAIT_L(0); PG8_BAR; PG8_MMA(1, 0, At, B0); PG8_MMA(1, 1, At, B1); PG8_BAR; PG8_SCHED;
	s_setprio 1
	s_waitcnt lgkmcnt(0)
	v_mfma_f32_16x16x32_bf16 v[126:129], v[130:133], v[162:165], v[126:129]
	v_mfma_f32_16x16x32_bf16 v[122:125], v[138:141], v[162:165], v[122:125]
	v_mfma_f32_16x16x32_bf16 v[114:117], v[130:133], v[170:173], v[114:117]
	v_mfma_f32_16x16x32_bf16 v[106:109], v[138:141], v[170:173], v[106:109]
	v_mfma_f32_16x16x32_bf16 v[98:101], v[130:133], v[178:181], v[98:101]
	v_mfma_f32_16x16x32_bf16 v[90:93], v[138:141], v[178:181], v[90:93]
	v_mfma_f32_16x16x32_bf16 v[82:85], v[130:133], v[186:189], v[82:85]
	v_mfma_f32_16x16x32_bf16 v[74:77], v[138:141], v[186:189], v[74:77]
	v_mfma_f32_16x16x32_bf16 v[126:129], v[134:137], v[166:169], v[126:129]
	v_mfma_f32_16x16x32_bf16 v[122:125], v[142:145], v[166:169], v[122:125]
	v_mfma_f32_16x16x32_bf16 v[114:117], v[134:137], v[174:177], v[114:117]
	v_mfma_f32_16x16x32_bf16 v[106:109], v[142:145], v[174:177], v[106:109]
	v_mfma_f32_16x16x32_bf16 v[98:101], v[134:137], v[182:185], v[98:101]
	v_mfma_f32_16x16x32_bf16 v[90:93], v[142:145], v[182:185], v[90:93]
	v_mfma_f32_16x16x32_bf16 v[82:85], v[134:137], v[190:193], v[82:85]
	v_mfma_f32_16x16x32_bf16 v[74:77], v[142:145], v[190:193], v[74:77]
	s_setprio 0
	s_setprio 1
	v_mfma_f32_16x16x32_bf16 v[118:121], v[146:149], v[162:165], v[118:121]
	v_mfma_f32_16x16x32_bf16 v[110:113], v[154:157], v[162:165], v[110:113]
	v_mfma_f32_16x16x32_bf16 v[102:105], v[146:149], v[170:173], v[102:105]
	v_mfma_f32_16x16x32_bf16 v[94:97], v[154:157], v[170:173], v[94:97]
	v_mfma_f32_16x16x32_bf16 v[86:89], v[146:149], v[178:181], v[86:89]
	v_mfma_f32_16x16x32_bf16 v[78:81], v[154:157], v[178:181], v[78:81]
	v_mfma_f32_16x16x32_bf16 v[70:73], v[146:149], v[186:189], v[70:73]
	v_mfma_f32_16x16x32_bf16 v[66:69], v[154:157], v[186:189], v[66:69]
	v_mfma_f32_16x16x32_bf16 v[118:121], v[150:153], v[166:169], v[118:121]
	v_mfma_f32_16x16x32_bf16 v[110:113], v[158:161], v[166:169], v[110:113]
	v_mfma_f32_16x16x32_bf16 v[102:105], v[150:153], v[174:177], v[102:105]
	v_mfma_f32_16x16x32_bf16 v[94:97], v[158:161], v[174:177], v[94:97]
	v_mfma_f32_16x16x32_bf16 v[86:89], v[150:153], v[182:185], v[86:89]
	v_mfma_f32_16x16x32_bf16 v[78:81], v[158:161], v[182:185], v[78:81]
	v_mfma_f32_16x16x32_bf16 v[70:73], v[150:153], v[190:193], v[70:73]
	v_mfma_f32_16x16x32_bf16 v[66:69], v[158:161], v[190:193], v[66:69]
	s_setprio 0
	s_barrier
	s_add_i32 s52, s52, s28
	v_lshl_add_u64 v[206:207], s[16:17], 0, v[198:199]
	s_mov_b32 m0, s52
	ds_read_b128 v[162:165], v232 offset:16384
	ds_read_b128 v[166:169], v232 offset:17408
	ds_read_b128 v[170:173], v232 offset:18432
	ds_read_b128 v[174:177], v232 offset:19456
	ds_read_b128 v[178:181], v232 offset:20480
	ds_read_b128 v[182:185], v232 offset:21504
	ds_read_b128 v[186:189], v232 offset:22528
	ds_read_b128 v[190:193], v232 offset:23552
	global_load_lds_dwordx4 v[206:207], off
	s_add_i32 m0, s52, 0x2000
	s_add_u32 s52, s16, 0x100000
	v_lshl_add_u64 v[208:209], s[16:17], 0, v[194:195]
	s_addc_u32 s53, s17, 0
	s_add_i32 s57, s57, s28
	global_load_lds_dwordx4 v[208:209], off
	v_lshl_add_u64 v[210:211], s[52:53], 0, v[198:199]
	s_mov_b32 m0, s57
	v_lshl_add_u64 v[212:213], s[22:23], 0, v[196:197]
	global_load_lds_dwordx4 v[210:211], off
	v_lshl_add_u64 v[210:211], s[52:53], 0, v[194:195]
	s_add_i32 m0, s57, 0x2000
	s_nop 0
	global_load_lds_dwordx4 v[210:211], off
	v_lshl_add_u64 v[210:211], s[22:23], 0, v[200:201]
	s_mov_b32 m0, s29
	s_nop 0
	global_load_lds_dwordx4 v[210:211], off
	s_mov_b32 m0, s30
	s_nop 0
	global_load_lds_dwordx4 v[212:213], off
	s_waitcnt vmcnt(8)
	s_waitcnt lgkmcnt(0)
	s_barrier
	s_setprio 1
	s_waitcnt lgkmcnt(0)
	v_mfma_f32_16x16x32_bf16 v[62:65], v[130:133], v[162:165], v[62:65]
	v_mfma_f32_16x16x32_bf16 v[58:61], v[138:141], v[162:165], v[58:61]
	v_mfma_f32_16x16x32_bf16 v[50:53], v[130:133], v[170:173], v[50:53]
	v_mfma_f32_16x16x32_bf16 v[42:45], v[138:141], v[170:173], v[42:45]
	v_mfma_f32_16x16x32_bf16 v[34:37], v[130:133], v[178:181], v[34:37]
	v_mfma_f32_16x16x32_bf16 v[26:29], v[138:141], v[178:181], v[26:29]
	v_mfma_f32_16x16x32_bf16 v[18:21], v[130:133], v[186:189], v[18:21]
	v_mfma_f32_16x16x32_bf16 v[10:13], v[138:141], v[186:189], v[10:13]
	v_mfma_f32_16x16x32_bf16 v[62:65], v[134:137], v[166:169], v[62:65]
	v_mfma_f32_16x16x32_bf16 v[58:61], v[142:145], v[166:169], v[58:61]
	v_mfma_f32_16x16x32_bf16 v[50:53], v[134:137], v[174:177], v[50:53]
	v_mfma_f32_16x16x32_bf16 v[42:45], v[142:145], v[174:177], v[42:45]
	v_mfma_f32_16x16x32_bf16 v[34:37], v[134:137], v[182:185], v[34:37]
	v_mfma_f32_16x16x32_bf16 v[26:29], v[142:145], v[182:185], v[26:29]
	v_mfma_f32_16x16x32_bf16 v[18:21], v[134:137], v[190:193], v[18:21]
	v_mfma_f32_16x16x32_bf16 v[10:13], v[142:145], v[190:193], v[10:13]
	s_setprio 0
	s_setprio 1
	v_mfma_f32_16x16x32_bf16 v[54:57], v[146:149], v[162:165], v[54:57]
	v_mfma_f32_16x16x32_bf16 v[46:49], v[154:157], v[162:165], v[46:49]
	v_mfma_f32_16x16x32_bf16 v[38:41], v[146:149], v[170:173], v[38:41]
	v_mfma_f32_16x16x32_bf16 v[30:33], v[154:157], v[170:173], v[30:33]
	v_mfma_f32_16x16x32_bf16 v[22:25], v[146:149], v[178:181], v[22:25]
	v_mfma_f32_16x16x32_bf16 v[14:17], v[154:157], v[178:181], v[14:17]
	v_mfma_f32_16x16x32_bf16 v[6:9], v[146:149], v[186:189], v[6:9]
	v_mfma_f32_16x16x32_bf16 v[2:5], v[154:157], v[186:189], v[2:5]
	v_mfma_f32_16x16x32_bf16 v[54:57], v[150:153], v[166:169], v[54:57]
	v_mfma_f32_16x16x32_bf16 v[46:49], v[158:161], v[166:169], v[46:49]
	v_mfma_f32_16x16x32_bf16 v[38:41], v[150:153], v[174:177], v[38:41]
	v_mfma_f32_16x16x32_bf16 v[30:33], v[158:161], v[174:177], v[30:33]
	v_mfma_f32_16x16x32_bf16 v[22:25], v[150:153], v[182:185], v[22:25]
	v_mfma_f32_16x16x32_bf16 v[14:17], v[158:161], v[182:185], v[14:17]
	v_mfma_f32_16x16x32_bf16 v[6:9], v[150:153], v[190:193], v[6:9]
	v_mfma_f32_16x16x32_bf16 v[2:5], v[158:161], v[190:193], v[2:5]
	s_setprio 0
	s_barrier
; #define PG8_STAGE(bufoff, gbase, voff) do { _Pragma("unroll") for (int _i = 0; _i < 2; ++_i) \
;         __builtin_amdgcn_global_load_lds((const unsigned*)((const char*)(gbase) + (voff)[_i]), (PG8_LAS unsigned*)(lds + (bufoff) + ldsw + _i * 8192), 16, 0, 0); } while (0)
; #define PG8_LDA(dst, b, h) do { _Pragma("unroll") for (int m = 0; m < 4; ++m) _Pragma("unroll") for (int k = 0; k < 2; ++k) dst[m][k] = *(const PG8_LAS bf16x8*)(lds + PG8_SA(b, h) + aoff + m * 2048 + k * 1024); } while (0)
; #define PG8_LDB(dst, b, h) do { _Pragma("unroll") for (int n = 0; n < 2; ++n) _Pragma("unroll") for (int k = 0; k < 2; ++k) dst[n][k] = *(const PG8_LAS bf16x8*)(lds + PG8_SB(b, h) + boff + n * 2048 + k * 1024); } while (0)
; #define PG8_MMA(ai, bj, At, Bt) do { __builtin_amdgcn_s_setprio(1); _Pragma("unroll") for (int m = 0; m < 4; ++m) _Pragma("unroll") for (int n = 0; n < 2; ++n) _Pragma("unroll") for (int k = 0; k < 2; ++k) \
;         acc[ai][bj][m][n] = __builtin_amdgcn_mfma_f32_16x16x32_bf16(Bt[n][k], At[m][k], acc[ai][bj][m][n], 0, 0, 0); __builtin_amdgcn_s_setprio(0); } while (0)
; #define PG8_WAIT_V(n) asm volatile("s_waitcnt vmcnt(" #n ")" ::: "memory")
; #define PG8_WAIT_L(n) asm volatile("s_waitcnt lgkmcnt(" #n ")" ::: "memory")
; #define PG8_BAR __builtin_amdgcn_s_barrier()
; #define PG8_SCHED __builtin_amdgcn_sched_barrier(0)
; template <class Epi, class Sched, bool ALIGN_EPI = false, bool SP2 = false>
; __device__ __forceinline__ void gemm_phase(PG8_LAS unsigned char* lds, const Gemm g, const Sched& S, const Epi& E) {
;     ...
;             PG8_LDB(B0, 1, 0); PG8_LDB(B1, 1, 1); PG8_SCHED; PG8_LDA(At, 1, 0); PG8_STAGE(PG8_SA(0, 1), a2 + hstep, voffA);
;             PG8_WAIT_V(8); PG8_WAIT_L(0); PG8_BAR; PG8_MMA(0, 0, At, B0); PG8_MMA(0, 1, At, B1); PG8_BAR; PG8_SCHED;
	s_add_i32 s52, 0, 0x18000
	s_add_i32 s53, 0, 0x1c000
	v_add_u32_e32 v142, s52, v231
	v_add_u32_e32 v158, s53, v231
	ds_read_b128 v[130:133], v142
	ds_read_b128 v[134:137], v142 offset:1024
	ds_read_b128 v[138:141], v142 offset:2048
	ds_read_b128 v[142:145], v142 offset:3072
	ds_read_b128 v[146:149], v158
	ds_read_b128 v[150:153], v158 offset:1024
	ds_read_b128 v[154:157], v158 offset:2048
	ds_read_b128 v[158:161], v158 offset:3072
	s_add_u32 s22, s22, 0x100000
	s_addc_u32 s23, s23, 0
	s_mov_b32 m0, s31
	v_lshl_add_u64 v[214:215], s[22:23], 0, v[200:201]
	ds_read_b128 v[162:165], v232 offset:32768
	ds_read_b128 v[166:169], v232 offset:33792
	ds_read_b128 v[170:173], v232 offset:34816
	ds_read_b128 v[174:177], v232 offset:35840
	ds_read_b128 v[178:181], v232 offset:36864
	ds_read_b128 v[182:185], v232 offset:37888
	ds_read_b128 v[186:189], v232 offset:38912
	ds_read_b128 v[190:193], v232 offset:39936
	global_load_lds_dwordx4 v[214:215], off
	v_lshl_add_u64 v[214:215], s[22:23], 0, v[196:197]
	s_mov_b32 m0, s34
	s_nop 0
	global_load_lds_dwordx4 v[214:215], off
	s_waitcnt vmcnt(8)
	s_waitcnt lgkmcnt(0)
	s_barrier
	s_setprio 1
	s_waitcnt lgkmcnt(0)
	v_mfma_f32_16x16x32_bf16 v[126:129], v[130:133], v[162:165], v[126:129]
	v_mfma_f32_16x16x32_bf16 v[122:125], v[138:141], v[162:165], v[122:125]
	v_mfma_f32_16x16x32_bf16 v[114:117], v[130:133], v[170:173], v[114:117]
	v_mfma_f32_16x16x32_bf16 v[106:109], v[138:141], v[170:173], v[106:109]
	v_mfma_f32_16x16x32_bf16 v[98:101], v[130:133], v[178:181], v[98:101]
	v_mfma_f32_16x16x32_bf16 v[90:93], v[138:141], v[178:181], v[90:93]
	v_mfma_f32_16x16x32_bf16 v[82:85], v[130:133], v[186:189], v[82:85]
	v_mfma_f32_16x16x32_bf16 v[74:77], v[138:141], v[186:189], v[74:77]
	v_mfma_f32_16x16x32_bf16 v[126:129], v[134:137], v[166:169], v[126:129]
	v_mfma_f32_16x16x32_bf16 v[122:125], v[142:145], v[166:169], v[122:125]
	v_mfma_f32_16x16x32_bf16 v[114:117], v[134:137], v[174:177], v[114:117]
	v_mfma_f32_16x16x32_bf16 v[106:109], v[142:145], v[174:177], v[106:109]
	v_mfma_f32_16x16x32_bf16 v[98:101], v[134:137], v[182:185], v[98:101]
	v_mfma_f32_16x16x32_bf16 v[90:93], v[142:145], v[182:185], v[90:93]
	v_mfma_f32_16x16x32_bf16 v[82:85], v[134:137], v[190:193], v[82:85]
	v_mfma_f32_16x16x32_bf16 v[74:77], v[142:145], v[190:193], v[74:77]
	s_setprio 0
	s_setprio 1
	v_mfma_f32_16x16x32_bf16 v[118:121], v[146:149], v[162:165], v[118:121]
	v_mfma_f32_16x16x32_bf16 v[110:113], v[154:157], v[162:165], v[110:113]
	v_mfma_f32_16x16x32_bf16 v[102:105], v[146:149], v[170:173], v[102:105]
	v_mfma_f32_16x16x32_bf16 v[94:97], v[154:157], v[170:173], v[94:97]
	v_mfma_f32_16x16x32_bf16 v[86:89], v[146:149], v[178:181], v[86:89]
	v_mfma_f32_16x16x32_bf16 v[78:81], v[154:157], v[178:181], v[78:81]
	v_mfma_f32_16x16x32_bf16 v[70:73], v[146:149], v[186:189], v[70:73]
	v_mfma_f32_16x16x32_bf16 v[66:69], v[154:157], v[186:189], v[66:69]
	v_mfma_f32_16x16x32_bf16 v[118:121], v[150:153], v[166:169], v[118:121]
	v_mfma_f32_16x16x32_bf16 v[110:113], v[158:161], v[166:169], v[110:113]
	v_mfma_f32_16x16x32_bf16 v[102:105], v[150:153], v[174:177], v[102:105]
	v_mfma_f32_16x16x32_bf16 v[94:97], v[158:161], v[174:177], v[94:97]
	v_mfma_f32_16x16x32_bf16 v[86:89], v[150:153], v[182:185], v[86:89]
	v_mfma_f32_16x16x32_bf16 v[78:81], v[158:161], v[182:185], v[78:81]
	v_mfma_f32_16x16x32_bf16 v[70:73], v[150:153], v[190:193], v[70:73]
	v_mfma_f32_16x16x32_bf16 v[66:69], v[158:161], v[190:193], v[66:69]
	s_setprio 0
	s_barrier
; #define PG8_STAGE(bufoff, gbase, voff) do { _Pragma("unroll") for (int _i = 0; _i < 2; ++_i) \
;         __builtin_amdgcn_global_load_lds((const unsigned*)((const char*)(gbase) + (voff)[_i]), (PG8_LAS unsigned*)(lds + (bufoff) + ldsw + _i * 8192), 16, 0, 0); } while (0)
; #define PG8_LDA(dst, b, h) do { _Pragma("unroll") for (int m = 0; m < 4; ++m) _Pragma("unroll") for (int k = 0; k < 2; ++k) dst[m][k] = *(const PG8_LAS bf16x8*)(lds + PG8_SA(b, h) + aoff + m * 2048 + k * 1024); } while (0)
; #define PG8_MMA(ai, bj, At, Bt) do { __builtin_amdgcn_s_setprio(1); _Pragma("unroll") for (int m = 0; m < 4; ++m) _Pragma("unroll") for (int n = 0; n < 2; ++n) _Pragma("unroll") for (int k = 0; k < 2; ++k) \
;         acc[ai][bj][m][n] = __builtin_amdgcn_mfma_f32_16x16x32_bf16(Bt[n][k], At[m][k], acc[ai][bj][m][n], 0, 0, 0); __builtin_amdgcn_s_setprio(0); } while (0)
; #define PG8_WAIT_V(n) asm volatile("s_waitcnt vmcnt(" #n ")" ::: "memory")
; #define PG8_WAIT_L(n) asm volatile("s_waitcnt lgkmcnt(" #n ")" ::: "memory")
; #define PG8_BAR __builtin_amdgcn_s_barrier()
; #define PG8_SCHED __builtin_amdgcn_sched_barrier(0)
; template <class Epi, class Sched, bool ALIGN_EPI = false, bool SP2 = false>
; __device__ __forceinline__ void gemm_phase(PG8_LAS unsigned char* lds, const Gemm g, const Sched& S, const Epi& E) {
;     ...
;         for (int t = 0; t < nt; t += 2) {
;     ...
;             PG8_LDA(At, 1, 1); PG8_STAGE(PG8_SB(1, 0), b3, voffB); PG8_STAGE(PG8_SB(1, 1), b3 + hstep, voffB); PG8_STAGE(PG8_SA(1, 0), a3, voffA);
;             PG8_WAIT_V(8); PG8_WAIT_L(0); PG8_BAR; PG8_MMA(1, 0, At, B0); PG8_MMA(1, 1, At, B1); PG8_BAR; PG8_SCHED;
;     ...
;         if constexpr (ALIGN_EPI) { if (wr == 0) PG8_BAR; }
	s_add_i32 s22, s52, s28
	v_lshl_add_u64 v[206:207], v[206:207], 0, s[94:95]
	s_mov_b32 m0, s22
	ds_read_b128 v[162:165], v232 offset:49152
	ds_read_b128 v[166:169], v232 offset:50176
	ds_read_b128 v[170:173], v232 offset:51200
	ds_read_b128 v[174:177], v232 offset:52224
	ds_read_b128 v[178:181], v232 offset:53248
	ds_read_b128 v[182:185], v232 offset:54272
	ds_read_b128 v[186:189], v232 offset:55296
	ds_read_b128 v[190:193], v232 offset:56320
	global_load_lds_dwordx4 v[206:207], off
	s_add_i32 m0, s22, 0x2000
	s_add_u32 s16, s16, 0x100080
	v_lshl_add_u64 v[206:207], v[208:209], 0, s[94:95]
	s_addc_u32 s17, s17, 0
	s_add_i32 s22, s53, s28
	global_load_lds_dwordx4 v[206:207], off
	v_lshl_add_u64 v[206:207], s[16:17], 0, v[198:199]
	s_mov_b32 m0, s22
	s_nop 0
	global_load_lds_dwordx4 v[206:207], off
	v_lshl_add_u64 v[206:207], s[16:17], 0, v[194:195]
	s_add_i32 m0, s22, 0x2000
	s_nop 0
	global_load_lds_dwordx4 v[206:207], off
	v_lshl_add_u64 v[206:207], v[210:211], 0, s[94:95]
	s_mov_b32 m0, s33
	s_nop 0
	global_load_lds_dwordx4 v[206:207], off
	v_lshl_add_u64 v[206:207], v[212:213], 0, s[94:95]
	s_mov_b32 m0, s35
	s_nop 0
	global_load_lds_dwordx4 v[206:207], off
	s_waitcnt vmcnt(8)
	s_waitcnt lgkmcnt(0)
	s_barrier
	s_setprio 1
	s_waitcnt lgkmcnt(0)
	v_mfma_f32_16x16x32_bf16 v[62:65], v[130:133], v[162:165], v[62:65]
	v_mfma_f32_16x16x32_bf16 v[58:61], v[138:141], v[162:165], v[58:61]
	v_mfma_f32_16x16x32_bf16 v[50:53], v[130:133], v[170:173], v[50:53]
	v_mfma_f32_16x16x32_bf16 v[42:45], v[138:141], v[170:173], v[42:45]
	v_mfma_f32_16x16x32_bf16 v[34:37], v[130:133], v[178:181], v[34:37]
	v_mfma_f32_16x16x32_bf16 v[26:29], v[138:141], v[178:181], v[26:29]
	v_mfma_f32_16x16x32_bf16 v[18:21], v[130:133], v[186:189], v[18:21]
	v_mfma_f32_16x16x32_bf16 v[10:13], v[138:141], v[186:189], v[10:13]
	v_mfma_f32_16x16x32_bf16 v[62:65], v[134:137], v[166:169], v[62:65]
	v_mfma_f32_16x16x32_bf16 v[58:61], v[142:145], v[166:169], v[58:61]
	v_mfma_f32_16x16x32_bf16 v[50:53], v[134:137], v[174:177], v[50:53]
	v_mfma_f32_16x16x32_bf16 v[42:45], v[142:145], v[174:177], v[42:45]
	v_mfma_f32_16x16x32_bf16 v[34:37], v[134:137], v[182:185], v[34:37]
	v_mfma_f32_16x16x32_bf16 v[26:29], v[142:145], v[182:185], v[26:29]
	v_mfma_f32_16x16x32_bf16 v[18:21], v[134:137], v[190:193], v[18:21]
	v_mfma_f32_16x16x32_bf16 v[10:13], v[142:145], v[190:193], v[10:13]
	s_setprio 0
	s_setprio 1
	v_mfma_f32_16x16x32_bf16 v[54:57], v[146:149], v[162:165], v[54:57]
	v_mfma_f32_16x16x32_bf16 v[46:49], v[154:157], v[162:165], v[46:49]
	v_mfma_f32_16x16x32_bf16 v[38:41], v[146:149], v[170:173], v[38:41]
	v_mfma_f32_16x16x32_bf16 v[30:33], v[154:157], v[170:173], v[30:33]
	v_mfma_f32_16x16x32_bf16 v[22:25], v[146:149], v[178:181], v[22:25]
	v_mfma_f32_16x16x32_bf16 v[14:17], v[154:157], v[178:181], v[14:17]
	v_mfma_f32_16x16x32_bf16 v[6:9], v[146:149], v[186:189], v[6:9]
	v_mfma_f32_16x16x32_bf16 v[2:5], v[154:157], v[186:189], v[2:5]
	v_mfma_f32_16x16x32_bf16 v[54:57], v[150:153], v[166:169], v[54:57]
	v_mfma_f32_16x16x32_bf16 v[46:49], v[158:161], v[166:169], v[46:49]
	v_mfma_f32_16x16x32_bf16 v[38:41], v[150:153], v[174:177], v[38:41]
	v_mfma_f32_16x16x32_bf16 v[30:33], v[158:161], v[174:177], v[30:33]
	v_mfma_f32_16x16x32_bf16 v[22:25], v[150:153], v[182:185], v[22:25]
	v_mfma_f32_16x16x32_bf16 v[14:17], v[158:161], v[182:185], v[14:17]
	v_mfma_f32_16x16x32_bf16 v[6:9], v[150:153], v[190:193], v[6:9]
	v_mfma_f32_16x16x32_bf16 v[2:5], v[158:161], v[190:193], v[2:5]
	s_setprio 0
	s_barrier
	s_add_i32 s50, s50, 2
	s_add_u32 s20, s20, 0x100
	s_addc_u32 s21, s21, 0
	s_add_u32 s55, s55, 0x100
	s_addc_u32 s56, s56, 0
	s_cmp_gt_u32 s50, 61
	s_cbranch_scc0 .LBB0_881
	s_and_b64 vcc, exec, s[8:9]
	s_cbranch_vccz .LBB0_884
	s_barrier
